# c13: c12 + K-loop MFMAs reordered so the two k-steps of each accumulator issue back to back (same-D accumulate chain, SrcC forwarding)
# speedup vs baseline: 1.0171x; 1.0171x over previous
.LBB0_343:
	s_ashr_i32 s11, s10, 31
	s_lshl_b64 s[12:13], s[10:11], 20
	s_add_u32 s12, s26, s12
	s_addc_u32 s13, s27, s13
	s_and_b64 s[14:15], s[2:3], exec
	s_cselect_b32 s11, s13, s21
	s_cselect_b32 s75, s12, s20
	s_ashr_i32 s9, s8, 31
	s_lshl_b64 s[14:15], s[8:9], 20
	s_add_u32 s14, s28, s14
	s_addc_u32 s15, s29, s15
	s_and_b64 s[22:23], s[2:3], exec
	s_cselect_b32 s9, s15, s19
	s_cselect_b32 s76, s14, s18
	s_add_u32 s77, s18, 0x100
	s_addc_u32 s78, s19, 0
	s_add_u32 s18, s20, 0x80080
	s_addc_u32 s19, s21, 0
	s_add_u32 s79, s20, 0x100
	s_addc_u32 s80, s21, 0
	s_mov_b32 s81, -2
	ds_read_b128 v[148:151], v143
	ds_read_b128 v[152:155], v143 offset:1024
	ds_read_b128 v[156:159], v143 offset:2048
	ds_read_b128 v[160:163], v143 offset:3072
	ds_read_b128 v[164:167], v144
	ds_read_b128 v[168:171], v144 offset:1024
	ds_read_b128 v[172:175], v144 offset:2048
	ds_read_b128 v[176:179], v144 offset:3072
	s_cmp_eq_u32 s81, 28
	s_cselect_b32 s21, s9, s78
	s_cselect_b32 s20, s76, s77
	s_cselect_b32 s23, s11, s80
	s_cselect_b32 s22, s75, s79
	ds_read_b128 v[180:183], v145
	ds_read_b128 v[184:187], v145 offset:1024
	ds_read_b128 v[188:191], v145 offset:2048
	ds_read_b128 v[192:195], v145 offset:3072
	ds_read_b128 v[196:199], v145 offset:4096
	ds_read_b128 v[200:203], v145 offset:5120
	ds_read_b128 v[204:207], v145 offset:6144
	ds_read_b128 v[208:211], v145 offset:7168
	s_add_u32 s82, s18, 0xfff80000
	s_addc_u32 s83, s19, -1
	s_mov_b32 s86, m0
	s_mov_b32 m0, s64
	s_nop 0
	global_load_lds_dwordx4 v138, s[82:83]
	s_mov_b32 m0, s86
	s_nop 0
	s_mov_b32 s86, m0
	s_mov_b32 m0, s67
	s_nop 0
	global_load_lds_dwordx4 v140, s[82:83]
	s_mov_b32 m0, s86
	s_mov_b32 s82, m0
	s_mov_b32 m0, s65
	s_nop 0
	global_load_lds_dwordx4 v138, s[18:19]
	s_mov_b32 m0, s82
	s_nop 0
	s_mov_b32 s82, m0
	s_mov_b32 m0, s73
	s_nop 0
	global_load_lds_dwordx4 v140, s[18:19]
	s_mov_b32 m0, s82
	s_waitcnt vmcnt(8)
	s_waitcnt lgkmcnt(0)
	s_barrier
	s_setprio 1
	s_waitcnt lgkmcnt(7)
	v_mfma_f32_16x16x32_bf16 v[126:129], v[148:151], v[180:183], 0
	v_mfma_f32_16x16x32_bf16 v[126:129], v[152:155], v[184:187], v[126:129]
	s_waitcnt lgkmcnt(5)
	v_mfma_f32_16x16x32_bf16 v[122:125], v[156:159], v[180:183], 0
	v_mfma_f32_16x16x32_bf16 v[122:125], v[160:163], v[184:187], v[122:125]
	s_waitcnt lgkmcnt(3)
	v_mfma_f32_16x16x32_bf16 v[106:109], v[156:159], v[188:191], 0
	v_mfma_f32_16x16x32_bf16 v[106:109], v[160:163], v[192:195], v[106:109]
	s_waitcnt lgkmcnt(1)
	v_mfma_f32_16x16x32_bf16 v[110:113], v[148:151], v[188:191], 0
	v_mfma_f32_16x16x32_bf16 v[110:113], v[152:155], v[192:195], v[110:113]
	v_mfma_f32_16x16x32_bf16 v[94:97], v[148:151], v[196:199], 0
	v_mfma_f32_16x16x32_bf16 v[94:97], v[152:155], v[200:203], v[94:97]
	v_mfma_f32_16x16x32_bf16 v[90:93], v[156:159], v[196:199], 0
	v_mfma_f32_16x16x32_bf16 v[90:93], v[160:163], v[200:203], v[90:93]
	v_mfma_f32_16x16x32_bf16 v[74:77], v[156:159], v[204:207], 0
	v_mfma_f32_16x16x32_bf16 v[74:77], v[160:163], v[208:211], v[74:77]
	s_waitcnt lgkmcnt(0)
	v_mfma_f32_16x16x32_bf16 v[78:81], v[148:151], v[204:207], 0
	v_mfma_f32_16x16x32_bf16 v[78:81], v[152:155], v[208:211], v[78:81]
	s_setprio 0
	s_setprio 1
	v_mfma_f32_16x16x32_bf16 v[118:121], v[164:167], v[180:183], 0
	v_mfma_f32_16x16x32_bf16 v[118:121], v[168:171], v[184:187], v[118:121]
	v_mfma_f32_16x16x32_bf16 v[114:117], v[172:175], v[180:183], 0
	v_mfma_f32_16x16x32_bf16 v[114:117], v[176:179], v[184:187], v[114:117]
	v_mfma_f32_16x16x32_bf16 v[98:101], v[172:175], v[188:191], 0
	v_mfma_f32_16x16x32_bf16 v[98:101], v[176:179], v[192:195], v[98:101]
	v_mfma_f32_16x16x32_bf16 v[102:105], v[164:167], v[188:191], 0
	v_mfma_f32_16x16x32_bf16 v[102:105], v[168:171], v[192:195], v[102:105]
	v_mfma_f32_16x16x32_bf16 v[86:89], v[164:167], v[196:199], 0
	v_mfma_f32_16x16x32_bf16 v[86:89], v[168:171], v[200:203], v[86:89]
	v_mfma_f32_16x16x32_bf16 v[82:85], v[172:175], v[196:199], 0
	v_mfma_f32_16x16x32_bf16 v[82:85], v[176:179], v[200:203], v[82:85]
	v_mfma_f32_16x16x32_bf16 v[66:69], v[172:175], v[204:207], 0
	v_mfma_f32_16x16x32_bf16 v[66:69], v[176:179], v[208:211], v[66:69]
	s_setprio 2
	s_barrier
	v_mfma_f32_16x16x32_bf16 v[70:73], v[164:167], v[204:207], 0
	v_mfma_f32_16x16x32_bf16 v[70:73], v[168:171], v[208:211], v[70:73]
	s_setprio 0
	ds_read_b128 v[180:183], v145 offset:16384
	ds_read_b128 v[184:187], v145 offset:17408
	ds_read_b128 v[188:191], v145 offset:18432
	ds_read_b128 v[192:195], v145 offset:19456
	ds_read_b128 v[196:199], v145 offset:20480
	ds_read_b128 v[200:203], v145 offset:21504
	ds_read_b128 v[204:207], v145 offset:22528
	ds_read_b128 v[208:211], v145 offset:23552
	s_mov_b32 s82, m0
	s_mov_b32 m0, s35
	s_nop 0
	global_load_lds_dwordx4 v139, s[20:21]
	s_mov_b32 m0, s82
	s_nop 0
	s_mov_b32 s82, m0
	s_mov_b32 m0, s36
	s_nop 0
	global_load_lds_dwordx4 v141, s[20:21]
	s_mov_b32 m0, s82
	s_add_u32 s82, s20, 0x80000
	s_addc_u32 s83, s21, 0
	s_mov_b32 s86, m0
	s_mov_b32 m0, s37
	s_nop 0
	global_load_lds_dwordx4 v139, s[82:83]
	s_mov_b32 m0, s86
	s_nop 0
	s_mov_b32 s86, m0
	s_mov_b32 m0, s42
	s_nop 0
	global_load_lds_dwordx4 v141, s[82:83]
	s_mov_b32 m0, s86
	s_waitcnt vmcnt(4)
	s_waitcnt lgkmcnt(0)
	s_barrier
	s_setprio 1
	s_waitcnt lgkmcnt(7)
	v_mfma_f32_16x16x32_bf16 v[62:65], v[148:151], v[180:183], 0
	v_mfma_f32_16x16x32_bf16 v[62:65], v[152:155], v[184:187], v[62:65]
	s_waitcnt lgkmcnt(5)
	v_mfma_f32_16x16x32_bf16 v[58:61], v[156:159], v[180:183], 0
	v_mfma_f32_16x16x32_bf16 v[58:61], v[160:163], v[184:187], v[58:61]
	s_waitcnt lgkmcnt(3)
	v_mfma_f32_16x16x32_bf16 v[42:45], v[156:159], v[188:191], 0
	v_mfma_f32_16x16x32_bf16 v[42:45], v[160:163], v[192:195], v[42:45]
	s_waitcnt lgkmcnt(1)
	v_mfma_f32_16x16x32_bf16 v[46:49], v[148:151], v[188:191], 0
	v_mfma_f32_16x16x32_bf16 v[46:49], v[152:155], v[192:195], v[46:49]
	v_mfma_f32_16x16x32_bf16 v[30:33], v[148:151], v[196:199], 0
	v_mfma_f32_16x16x32_bf16 v[30:33], v[152:155], v[200:203], v[30:33]
	v_mfma_f32_16x16x32_bf16 v[26:29], v[156:159], v[196:199], 0
	v_mfma_f32_16x16x32_bf16 v[26:29], v[160:163], v[200:203], v[26:29]
	v_mfma_f32_16x16x32_bf16 v[10:13], v[156:159], v[204:207], 0
	v_mfma_f32_16x16x32_bf16 v[10:13], v[160:163], v[208:211], v[10:13]
	s_waitcnt lgkmcnt(0)
	v_mfma_f32_16x16x32_bf16 v[14:17], v[148:151], v[204:207], 0
	v_mfma_f32_16x16x32_bf16 v[14:17], v[152:155], v[208:211], v[14:17]
	s_setprio 0
	s_setprio 1
	v_mfma_f32_16x16x32_bf16 v[54:57], v[164:167], v[180:183], 0
	v_mfma_f32_16x16x32_bf16 v[54:57], v[168:171], v[184:187], v[54:57]
	v_mfma_f32_16x16x32_bf16 v[50:53], v[172:175], v[180:183], 0
	v_mfma_f32_16x16x32_bf16 v[50:53], v[176:179], v[184:187], v[50:53]
	v_mfma_f32_16x16x32_bf16 v[34:37], v[172:175], v[188:191], 0
	v_mfma_f32_16x16x32_bf16 v[34:37], v[176:179], v[192:195], v[34:37]
	v_mfma_f32_16x16x32_bf16 v[38:41], v[164:167], v[188:191], 0
	v_mfma_f32_16x16x32_bf16 v[38:41], v[168:171], v[192:195], v[38:41]
	v_mfma_f32_16x16x32_bf16 v[22:25], v[164:167], v[196:199], 0
	v_mfma_f32_16x16x32_bf16 v[22:25], v[168:171], v[200:203], v[22:25]
	v_mfma_f32_16x16x32_bf16 v[18:21], v[172:175], v[196:199], 0
	v_mfma_f32_16x16x32_bf16 v[18:21], v[176:179], v[200:203], v[18:21]
	v_mfma_f32_16x16x32_bf16 v[2:5], v[172:175], v[204:207], 0
	v_mfma_f32_16x16x32_bf16 v[2:5], v[176:179], v[208:211], v[2:5]
	s_setprio 2
	s_barrier
	v_mfma_f32_16x16x32_bf16 v[6:9], v[164:167], v[204:207], 0
	v_mfma_f32_16x16x32_bf16 v[6:9], v[168:171], v[208:211], v[6:9]
	s_setprio 0
	ds_read_b128 v[148:151], v146
	ds_read_b128 v[152:155], v146 offset:1024
	ds_read_b128 v[156:159], v146 offset:2048
	ds_read_b128 v[160:163], v146 offset:3072
	ds_read_b128 v[164:167], v147
	ds_read_b128 v[168:171], v147 offset:1024
	ds_read_b128 v[172:175], v147 offset:2048
	ds_read_b128 v[176:179], v147 offset:3072
	ds_read_b128 v[180:183], v145 offset:32768
	ds_read_b128 v[184:187], v145 offset:33792
	ds_read_b128 v[188:191], v145 offset:34816
	ds_read_b128 v[192:195], v145 offset:35840
	ds_read_b128 v[196:199], v145 offset:36864
	ds_read_b128 v[200:203], v145 offset:37888
	ds_read_b128 v[204:207], v145 offset:38912
	ds_read_b128 v[208:211], v145 offset:39936
	s_mov_b32 s82, m0
	s_mov_b32 m0, s31
	s_nop 0
	global_load_lds_dwordx4 v138, s[22:23]
	s_mov_b32 m0, s82
	s_nop 0
	s_mov_b32 s82, m0
	s_mov_b32 m0, s43
	s_nop 0
	global_load_lds_dwordx4 v140, s[22:23]
	s_mov_b32 m0, s82
	s_add_u32 s22, s22, 0x80000
	s_addc_u32 s23, s23, 0
	s_mov_b32 s82, m0
	s_mov_b32 m0, s46
	s_nop 0
	global_load_lds_dwordx4 v138, s[22:23]
	s_mov_b32 m0, s82
	s_nop 0
	s_mov_b32 s82, m0
	s_mov_b32 m0, s47
	s_nop 0
	global_load_lds_dwordx4 v140, s[22:23]
	s_mov_b32 m0, s82
	s_waitcnt vmcnt(8)
	s_waitcnt lgkmcnt(0)
	s_barrier
	s_setprio 1
	s_waitcnt lgkmcnt(7)
	v_mfma_f32_16x16x32_bf16 v[126:129], v[148:151], v[180:183], v[126:129]
	v_mfma_f32_16x16x32_bf16 v[126:129], v[152:155], v[184:187], v[126:129]
	s_waitcnt lgkmcnt(5)
	v_mfma_f32_16x16x32_bf16 v[122:125], v[156:159], v[180:183], v[122:125]
	v_mfma_f32_16x16x32_bf16 v[122:125], v[160:163], v[184:187], v[122:125]
	s_waitcnt lgkmcnt(3)
	v_mfma_f32_16x16x32_bf16 v[106:109], v[156:159], v[188:191], v[106:109]
	v_mfma_f32_16x16x32_bf16 v[106:109], v[160:163], v[192:195], v[106:109]
	s_waitcnt lgkmcnt(1)
	v_mfma_f32_16x16x32_bf16 v[110:113], v[148:151], v[188:191], v[110:113]
	v_mfma_f32_16x16x32_bf16 v[110:113], v[152:155], v[192:195], v[110:113]
	v_mfma_f32_16x16x32_bf16 v[94:97], v[148:151], v[196:199], v[94:97]
	v_mfma_f32_16x16x32_bf16 v[94:97], v[152:155], v[200:203], v[94:97]
	v_mfma_f32_16x16x32_bf16 v[90:93], v[156:159], v[196:199], v[90:93]
	v_mfma_f32_16x16x32_bf16 v[90:93], v[160:163], v[200:203], v[90:93]
	v_mfma_f32_16x16x32_bf16 v[74:77], v[156:159], v[204:207], v[74:77]
	v_mfma_f32_16x16x32_bf16 v[74:77], v[160:163], v[208:211], v[74:77]
	s_waitcnt lgkmcnt(0)
	v_mfma_f32_16x16x32_bf16 v[78:81], v[148:151], v[204:207], v[78:81]
	v_mfma_f32_16x16x32_bf16 v[78:81], v[152:155], v[208:211], v[78:81]
	s_setprio 0
	s_setprio 1
	v_mfma_f32_16x16x32_bf16 v[118:121], v[164:167], v[180:183], v[118:121]
	v_mfma_f32_16x16x32_bf16 v[118:121], v[168:171], v[184:187], v[118:121]
	v_mfma_f32_16x16x32_bf16 v[114:117], v[172:175], v[180:183], v[114:117]
	v_mfma_f32_16x16x32_bf16 v[114:117], v[176:179], v[184:187], v[114:117]
	v_mfma_f32_16x16x32_bf16 v[98:101], v[172:175], v[188:191], v[98:101]
	v_mfma_f32_16x16x32_bf16 v[98:101], v[176:179], v[192:195], v[98:101]
	v_mfma_f32_16x16x32_bf16 v[102:105], v[164:167], v[188:191], v[102:105]
	v_mfma_f32_16x16x32_bf16 v[102:105], v[168:171], v[192:195], v[102:105]
	v_mfma_f32_16x16x32_bf16 v[86:89], v[164:167], v[196:199], v[86:89]
	v_mfma_f32_16x16x32_bf16 v[86:89], v[168:171], v[200:203], v[86:89]
	v_mfma_f32_16x16x32_bf16 v[82:85], v[172:175], v[196:199], v[82:85]
	v_mfma_f32_16x16x32_bf16 v[82:85], v[176:179], v[200:203], v[82:85]
	v_mfma_f32_16x16x32_bf16 v[66:69], v[172:175], v[204:207], v[66:69]
	v_mfma_f32_16x16x32_bf16 v[66:69], v[176:179], v[208:211], v[66:69]
	s_setprio 2
	s_barrier
	v_mfma_f32_16x16x32_bf16 v[70:73], v[164:167], v[204:207], v[70:73]
	v_mfma_f32_16x16x32_bf16 v[70:73], v[168:171], v[208:211], v[70:73]
	s_setprio 0
	ds_read_b128 v[180:183], v145 offset:49152
	ds_read_b128 v[184:187], v145 offset:50176
	ds_read_b128 v[188:191], v145 offset:51200
	ds_read_b128 v[192:195], v145 offset:52224
	ds_read_b128 v[196:199], v145 offset:53248
	ds_read_b128 v[200:203], v145 offset:54272
	ds_read_b128 v[204:207], v145 offset:55296
	ds_read_b128 v[208:211], v145 offset:56320
	s_add_u32 s22, s20, 0x80
	s_addc_u32 s23, s21, 0
	s_mov_b32 s82, m0
	s_mov_b32 m0, s48
	s_nop 0
	global_load_lds_dwordx4 v139, s[22:23]
	s_mov_b32 m0, s82
	s_add_u32 s20, s20, 0x80080
	s_mov_b32 s82, m0
	s_mov_b32 m0, s49
	s_nop 0
	global_load_lds_dwordx4 v141, s[22:23]
	s_mov_b32 m0, s82
	s_addc_u32 s21, s21, 0
	s_mov_b32 s22, m0
	s_mov_b32 m0, s56
	s_nop 0
	global_load_lds_dwordx4 v139, s[20:21]
	s_mov_b32 m0, s22
	s_nop 0
	s_mov_b32 s22, m0
	s_mov_b32 m0, s57
	s_nop 0
	global_load_lds_dwordx4 v141, s[20:21]
	s_mov_b32 m0, s22
	s_waitcnt vmcnt(4)
	s_waitcnt lgkmcnt(0)
	s_barrier
	s_setprio 1
	s_waitcnt lgkmcnt(7)
	v_mfma_f32_16x16x32_bf16 v[62:65], v[148:151], v[180:183], v[62:65]
	v_mfma_f32_16x16x32_bf16 v[62:65], v[152:155], v[184:187], v[62:65]
	s_waitcnt lgkmcnt(5)
	v_mfma_f32_16x16x32_bf16 v[58:61], v[156:159], v[180:183], v[58:61]
	v_mfma_f32_16x16x32_bf16 v[58:61], v[160:163], v[184:187], v[58:61]
	s_waitcnt lgkmcnt(3)
	v_mfma_f32_16x16x32_bf16 v[42:45], v[156:159], v[188:191], v[42:45]
	v_mfma_f32_16x16x32_bf16 v[42:45], v[160:163], v[192:195], v[42:45]
	s_waitcnt lgkmcnt(1)
	v_mfma_f32_16x16x32_bf16 v[46:49], v[148:151], v[188:191], v[46:49]
	v_mfma_f32_16x16x32_bf16 v[46:49], v[152:155], v[192:195], v[46:49]
	v_mfma_f32_16x16x32_bf16 v[30:33], v[148:151], v[196:199], v[30:33]
	v_mfma_f32_16x16x32_bf16 v[30:33], v[152:155], v[200:203], v[30:33]
	v_mfma_f32_16x16x32_bf16 v[26:29], v[156:159], v[196:199], v[26:29]
	v_mfma_f32_16x16x32_bf16 v[26:29], v[160:163], v[200:203], v[26:29]
	v_mfma_f32_16x16x32_bf16 v[10:13], v[156:159], v[204:207], v[10:13]
	v_mfma_f32_16x16x32_bf16 v[10:13], v[160:163], v[208:211], v[10:13]
	s_waitcnt lgkmcnt(0)
	v_mfma_f32_16x16x32_bf16 v[14:17], v[148:151], v[204:207], v[14:17]
	v_mfma_f32_16x16x32_bf16 v[14:17], v[152:155], v[208:211], v[14:17]
	s_setprio 0
	s_setprio 1
	v_mfma_f32_16x16x32_bf16 v[54:57], v[164:167], v[180:183], v[54:57]
	v_mfma_f32_16x16x32_bf16 v[54:57], v[168:171], v[184:187], v[54:57]
	v_mfma_f32_16x16x32_bf16 v[50:53], v[172:175], v[180:183], v[50:53]
	v_mfma_f32_16x16x32_bf16 v[50:53], v[176:179], v[184:187], v[50:53]
	v_mfma_f32_16x16x32_bf16 v[34:37], v[172:175], v[188:191], v[34:37]
	v_mfma_f32_16x16x32_bf16 v[34:37], v[176:179], v[192:195], v[34:37]
	v_mfma_f32_16x16x32_bf16 v[38:41], v[164:167], v[188:191], v[38:41]
	v_mfma_f32_16x16x32_bf16 v[38:41], v[168:171], v[192:195], v[38:41]
	v_mfma_f32_16x16x32_bf16 v[22:25], v[164:167], v[196:199], v[22:25]
	v_mfma_f32_16x16x32_bf16 v[22:25], v[168:171], v[200:203], v[22:25]
	v_mfma_f32_16x16x32_bf16 v[18:21], v[172:175], v[196:199], v[18:21]
	v_mfma_f32_16x16x32_bf16 v[18:21], v[176:179], v[200:203], v[18:21]
	v_mfma_f32_16x16x32_bf16 v[2:5], v[172:175], v[204:207], v[2:5]
	v_mfma_f32_16x16x32_bf16 v[2:5], v[176:179], v[208:211], v[2:5]
	s_setprio 2
	s_barrier
	v_mfma_f32_16x16x32_bf16 v[6:9], v[164:167], v[204:207], v[6:9]
	v_mfma_f32_16x16x32_bf16 v[6:9], v[168:171], v[208:211], v[6:9]
	s_setprio 0
	s_add_i32 s81, s81, 2
	s_add_u32 s77, s77, 0x100
	s_addc_u32 s78, s78, 0
	s_add_u32 s18, s18, 0x100
	s_addc_u32 s19, s19, 0
	s_add_u32 s79, s79, 0x100
	s_addc_u32 s80, s80, 0
	s_cmp_gt_u32 s81, 29
	.p2align 6
.LBB0_344:
	ds_read_b128 v[148:151], v143
	ds_read_b128 v[152:155], v143 offset:1024
	ds_read_b128 v[156:159], v143 offset:2048
	ds_read_b128 v[160:163], v143 offset:3072
	ds_read_b128 v[164:167], v144
	ds_read_b128 v[168:171], v144 offset:1024
	ds_read_b128 v[172:175], v144 offset:2048
	ds_read_b128 v[176:179], v144 offset:3072
	s_cmp_eq_u32 s81, 28
	s_cselect_b32 s21, s9, s78
	s_cselect_b32 s20, s76, s77
	s_cselect_b32 s23, s11, s80
	s_cselect_b32 s22, s75, s79
	ds_read_b128 v[180:183], v145
	ds_read_b128 v[184:187], v145 offset:1024
	ds_read_b128 v[188:191], v145 offset:2048
	ds_read_b128 v[192:195], v145 offset:3072
	ds_read_b128 v[196:199], v145 offset:4096
	ds_read_b128 v[200:203], v145 offset:5120
	ds_read_b128 v[204:207], v145 offset:6144
	ds_read_b128 v[208:211], v145 offset:7168
	s_add_u32 s82, s18, 0xfff80000
	s_addc_u32 s83, s19, -1
	s_mov_b32 s86, m0
	s_mov_b32 m0, s64
	s_nop 0
	global_load_lds_dwordx4 v138, s[82:83]
	s_mov_b32 m0, s86
	s_nop 0
	s_mov_b32 s86, m0
	s_mov_b32 m0, s67
	s_nop 0
	global_load_lds_dwordx4 v140, s[82:83]
	s_mov_b32 m0, s86
	s_mov_b32 s82, m0
	s_mov_b32 m0, s65
	s_nop 0
	global_load_lds_dwordx4 v138, s[18:19]
	s_mov_b32 m0, s82
	s_nop 0
	s_mov_b32 s82, m0
	s_mov_b32 m0, s73
	s_nop 0
	global_load_lds_dwordx4 v140, s[18:19]
	s_mov_b32 m0, s82
	s_waitcnt vmcnt(8)
	s_waitcnt lgkmcnt(0)
	s_barrier
	s_setprio 1
	s_waitcnt lgkmcnt(7)
	v_mfma_f32_16x16x32_bf16 v[126:129], v[148:151], v[180:183], v[126:129]
	v_mfma_f32_16x16x32_bf16 v[126:129], v[152:155], v[184:187], v[126:129]
	s_waitcnt lgkmcnt(5)
	v_mfma_f32_16x16x32_bf16 v[122:125], v[156:159], v[180:183], v[122:125]
	v_mfma_f32_16x16x32_bf16 v[122:125], v[160:163], v[184:187], v[122:125]
	s_waitcnt lgkmcnt(3)
	v_mfma_f32_16x16x32_bf16 v[106:109], v[156:159], v[188:191], v[106:109]
	v_mfma_f32_16x16x32_bf16 v[106:109], v[160:163], v[192:195], v[106:109]
	s_waitcnt lgkmcnt(1)
	v_mfma_f32_16x16x32_bf16 v[110:113], v[148:151], v[188:191], v[110:113]
	v_mfma_f32_16x16x32_bf16 v[110:113], v[152:155], v[192:195], v[110:113]
	v_mfma_f32_16x16x32_bf16 v[94:97], v[148:151], v[196:199], v[94:97]
	v_mfma_f32_16x16x32_bf16 v[94:97], v[152:155], v[200:203], v[94:97]
	v_mfma_f32_16x16x32_bf16 v[90:93], v[156:159], v[196:199], v[90:93]
	v_mfma_f32_16x16x32_bf16 v[90:93], v[160:163], v[200:203], v[90:93]
	v_mfma_f32_16x16x32_bf16 v[74:77], v[156:159], v[204:207], v[74:77]
	v_mfma_f32_16x16x32_bf16 v[74:77], v[160:163], v[208:211], v[74:77]
	s_waitcnt lgkmcnt(0)
	v_mfma_f32_16x16x32_bf16 v[78:81], v[148:151], v[204:207], v[78:81]
	v_mfma_f32_16x16x32_bf16 v[78:81], v[152:155], v[208:211], v[78:81]
	s_setprio 0
	s_setprio 1
	v_mfma_f32_16x16x32_bf16 v[118:121], v[164:167], v[180:183], v[118:121]
	v_mfma_f32_16x16x32_bf16 v[118:121], v[168:171], v[184:187], v[118:121]
	v_mfma_f32_16x16x32_bf16 v[114:117], v[172:175], v[180:183], v[114:117]
	v_mfma_f32_16x16x32_bf16 v[114:117], v[176:179], v[184:187], v[114:117]
	v_mfma_f32_16x16x32_bf16 v[98:101], v[172:175], v[188:191], v[98:101]
	v_mfma_f32_16x16x32_bf16 v[98:101], v[176:179], v[192:195], v[98:101]
	v_mfma_f32_16x16x32_bf16 v[102:105], v[164:167], v[188:191], v[102:105]
	v_mfma_f32_16x16x32_bf16 v[102:105], v[168:171], v[192:195], v[102:105]
	v_mfma_f32_16x16x32_bf16 v[86:89], v[164:167], v[196:199], v[86:89]
	v_mfma_f32_16x16x32_bf16 v[86:89], v[168:171], v[200:203], v[86:89]
	v_mfma_f32_16x16x32_bf16 v[82:85], v[172:175], v[196:199], v[82:85]
	v_mfma_f32_16x16x32_bf16 v[82:85], v[176:179], v[200:203], v[82:85]
	v_mfma_f32_16x16x32_bf16 v[66:69], v[172:175], v[204:207], v[66:69]
	v_mfma_f32_16x16x32_bf16 v[66:69], v[176:179], v[208:211], v[66:69]
	s_setprio 2
	s_barrier
	v_mfma_f32_16x16x32_bf16 v[70:73], v[164:167], v[204:207], v[70:73]
	v_mfma_f32_16x16x32_bf16 v[70:73], v[168:171], v[208:211], v[70:73]
	s_setprio 0
	ds_read_b128 v[180:183], v145 offset:16384
	ds_read_b128 v[184:187], v145 offset:17408
	ds_read_b128 v[188:191], v145 offset:18432
	ds_read_b128 v[192:195], v145 offset:19456
	ds_read_b128 v[196:199], v145 offset:20480
	ds_read_b128 v[200:203], v145 offset:21504
	ds_read_b128 v[204:207], v145 offset:22528
	ds_read_b128 v[208:211], v145 offset:23552
	s_mov_b32 s82, m0
	s_mov_b32 m0, s35
	s_nop 0
	global_load_lds_dwordx4 v139, s[20:21]
	s_mov_b32 m0, s82
	s_nop 0
	s_mov_b32 s82, m0
	s_mov_b32 m0, s36
	s_nop 0
	global_load_lds_dwordx4 v141, s[20:21]
	s_mov_b32 m0, s82
	s_add_u32 s82, s20, 0x80000
	s_addc_u32 s83, s21, 0
	s_mov_b32 s86, m0
	s_mov_b32 m0, s37
	s_nop 0
	global_load_lds_dwordx4 v139, s[82:83]
	s_mov_b32 m0, s86
	s_nop 0
	s_mov_b32 s86, m0
	s_mov_b32 m0, s42
	s_nop 0
	global_load_lds_dwordx4 v141, s[82:83]
	s_mov_b32 m0, s86
	s_waitcnt vmcnt(4)
	s_waitcnt lgkmcnt(0)
	s_barrier
	s_setprio 1
	s_waitcnt lgkmcnt(7)
	v_mfma_f32_16x16x32_bf16 v[62:65], v[148:151], v[180:183], v[62:65]
	v_mfma_f32_16x16x32_bf16 v[62:65], v[152:155], v[184:187], v[62:65]
	s_waitcnt lgkmcnt(5)
	v_mfma_f32_16x16x32_bf16 v[58:61], v[156:159], v[180:183], v[58:61]
	v_mfma_f32_16x16x32_bf16 v[58:61], v[160:163], v[184:187], v[58:61]
	s_waitcnt lgkmcnt(3)
	v_mfma_f32_16x16x32_bf16 v[42:45], v[156:159], v[188:191], v[42:45]
	v_mfma_f32_16x16x32_bf16 v[42:45], v[160:163], v[192:195], v[42:45]
	s_waitcnt lgkmcnt(1)
	v_mfma_f32_16x16x32_bf16 v[46:49], v[148:151], v[188:191], v[46:49]
	v_mfma_f32_16x16x32_bf16 v[46:49], v[152:155], v[192:195], v[46:49]
	v_mfma_f32_16x16x32_bf16 v[30:33], v[148:151], v[196:199], v[30:33]
	v_mfma_f32_16x16x32_bf16 v[30:33], v[152:155], v[200:203], v[30:33]
	v_mfma_f32_16x16x32_bf16 v[26:29], v[156:159], v[196:199], v[26:29]
	v_mfma_f32_16x16x32_bf16 v[26:29], v[160:163], v[200:203], v[26:29]
	v_mfma_f32_16x16x32_bf16 v[10:13], v[156:159], v[204:207], v[10:13]
	v_mfma_f32_16x16x32_bf16 v[10:13], v[160:163], v[208:211], v[10:13]
	s_waitcnt lgkmcnt(0)
	v_mfma_f32_16x16x32_bf16 v[14:17], v[148:151], v[204:207], v[14:17]
	v_mfma_f32_16x16x32_bf16 v[14:17], v[152:155], v[208:211], v[14:17]
	s_setprio 0
	s_setprio 1
	v_mfma_f32_16x16x32_bf16 v[54:57], v[164:167], v[180:183], v[54:57]
	v_mfma_f32_16x16x32_bf16 v[54:57], v[168:171], v[184:187], v[54:57]
	v_mfma_f32_16x16x32_bf16 v[50:53], v[172:175], v[180:183], v[50:53]
	v_mfma_f32_16x16x32_bf16 v[50:53], v[176:179], v[184:187], v[50:53]
	v_mfma_f32_16x16x32_bf16 v[34:37], v[172:175], v[188:191], v[34:37]
	v_mfma_f32_16x16x32_bf16 v[34:37], v[176:179], v[192:195], v[34:37]
	v_mfma_f32_16x16x32_bf16 v[38:41], v[164:167], v[188:191], v[38:41]
	v_mfma_f32_16x16x32_bf16 v[38:41], v[168:171], v[192:195], v[38:41]
	v_mfma_f32_16x16x32_bf16 v[22:25], v[164:167], v[196:199], v[22:25]
	v_mfma_f32_16x16x32_bf16 v[22:25], v[168:171], v[200:203], v[22:25]
	v_mfma_f32_16x16x32_bf16 v[18:21], v[172:175], v[196:199], v[18:21]
	v_mfma_f32_16x16x32_bf16 v[18:21], v[176:179], v[200:203], v[18:21]
	v_mfma_f32_16x16x32_bf16 v[2:5], v[172:175], v[204:207], v[2:5]
	v_mfma_f32_16x16x32_bf16 v[2:5], v[176:179], v[208:211], v[2:5]
	s_setprio 2
	s_barrier
	v_mfma_f32_16x16x32_bf16 v[6:9], v[164:167], v[204:207], v[6:9]
	v_mfma_f32_16x16x32_bf16 v[6:9], v[168:171], v[208:211], v[6:9]
	s_setprio 0
	ds_read_b128 v[148:151], v146
	ds_read_b128 v[152:155], v146 offset:1024
	ds_read_b128 v[156:159], v146 offset:2048
	ds_read_b128 v[160:163], v146 offset:3072
	ds_read_b128 v[164:167], v147
	ds_read_b128 v[168:171], v147 offset:1024
	ds_read_b128 v[172:175], v147 offset:2048
	ds_read_b128 v[176:179], v147 offset:3072
	ds_read_b128 v[180:183], v145 offset:32768
	ds_read_b128 v[184:187], v145 offset:33792
	ds_read_b128 v[188:191], v145 offset:34816
	ds_read_b128 v[192:195], v145 offset:35840
	ds_read_b128 v[196:199], v145 offset:36864
	ds_read_b128 v[200:203], v145 offset:37888
	ds_read_b128 v[204:207], v145 offset:38912
	ds_read_b128 v[208:211], v145 offset:39936
	s_mov_b32 s82, m0
	s_mov_b32 m0, s31
	s_nop 0
	global_load_lds_dwordx4 v138, s[22:23]
	s_mov_b32 m0, s82
	s_nop 0
	s_mov_b32 s82, m0
	s_mov_b32 m0, s43
	s_nop 0
	global_load_lds_dwordx4 v140, s[22:23]
	s_mov_b32 m0, s82
	s_add_u32 s22, s22, 0x80000
	s_addc_u32 s23, s23, 0
	s_mov_b32 s82, m0
	s_mov_b32 m0, s46
	s_nop 0
	global_load_lds_dwordx4 v138, s[22:23]
	s_mov_b32 m0, s82
	s_nop 0
	s_mov_b32 s82, m0
	s_mov_b32 m0, s47
	s_nop 0
	global_load_lds_dwordx4 v140, s[22:23]
	s_mov_b32 m0, s82
	s_waitcnt vmcnt(8)
	s_waitcnt lgkmcnt(0)
	s_barrier
	s_setprio 1
	s_waitcnt lgkmcnt(7)
	v_mfma_f32_16x16x32_bf16 v[126:129], v[148:151], v[180:183], v[126:129]
	v_mfma_f32_16x16x32_bf16 v[126:129], v[152:155], v[184:187], v[126:129]
	s_waitcnt lgkmcnt(5)
	v_mfma_f32_16x16x32_bf16 v[122:125], v[156:159], v[180:183], v[122:125]
	v_mfma_f32_16x16x32_bf16 v[122:125], v[160:163], v[184:187], v[122:125]
	s_waitcnt lgkmcnt(3)
	v_mfma_f32_16x16x32_bf16 v[106:109], v[156:159], v[188:191], v[106:109]
	v_mfma_f32_16x16x32_bf16 v[106:109], v[160:163], v[192:195], v[106:109]
	s_waitcnt lgkmcnt(1)
	v_mfma_f32_16x16x32_bf16 v[110:113], v[148:151], v[188:191], v[110:113]
	v_mfma_f32_16x16x32_bf16 v[110:113], v[152:155], v[192:195], v[110:113]
	v_mfma_f32_16x16x32_bf16 v[94:97], v[148:151], v[196:199], v[94:97]
	v_mfma_f32_16x16x32_bf16 v[94:97], v[152:155], v[200:203], v[94:97]
	v_mfma_f32_16x16x32_bf16 v[90:93], v[156:159], v[196:199], v[90:93]
	v_mfma_f32_16x16x32_bf16 v[90:93], v[160:163], v[200:203], v[90:93]
	v_mfma_f32_16x16x32_bf16 v[74:77], v[156:159], v[204:207], v[74:77]
	v_mfma_f32_16x16x32_bf16 v[74:77], v[160:163], v[208:211], v[74:77]
	s_waitcnt lgkmcnt(0)
	v_mfma_f32_16x16x32_bf16 v[78:81], v[148:151], v[204:207], v[78:81]
	v_mfma_f32_16x16x32_bf16 v[78:81], v[152:155], v[208:211], v[78:81]
	s_setprio 0
	s_setprio 1
	v_mfma_f32_16x16x32_bf16 v[118:121], v[164:167], v[180:183], v[118:121]
	v_mfma_f32_16x16x32_bf16 v[118:121], v[168:171], v[184:187], v[118:121]
	v_mfma_f32_16x16x32_bf16 v[114:117], v[172:175], v[180:183], v[114:117]
	v_mfma_f32_16x16x32_bf16 v[114:117], v[176:179], v[184:187], v[114:117]
	v_mfma_f32_16x16x32_bf16 v[98:101], v[172:175], v[188:191], v[98:101]
	v_mfma_f32_16x16x32_bf16 v[98:101], v[176:179], v[192:195], v[98:101]
	v_mfma_f32_16x16x32_bf16 v[102:105], v[164:167], v[188:191], v[102:105]
	v_mfma_f32_16x16x32_bf16 v[102:105], v[168:171], v[192:195], v[102:105]
	v_mfma_f32_16x16x32_bf16 v[86:89], v[164:167], v[196:199], v[86:89]
	v_mfma_f32_16x16x32_bf16 v[86:89], v[168:171], v[200:203], v[86:89]
	v_mfma_f32_16x16x32_bf16 v[82:85], v[172:175], v[196:199], v[82:85]
	v_mfma_f32_16x16x32_bf16 v[82:85], v[176:179], v[200:203], v[82:85]
	v_mfma_f32_16x16x32_bf16 v[66:69], v[172:175], v[204:207], v[66:69]
	v_mfma_f32_16x16x32_bf16 v[66:69], v[176:179], v[208:211], v[66:69]
	s_setprio 2
	s_barrier
	v_mfma_f32_16x16x32_bf16 v[70:73], v[164:167], v[204:207], v[70:73]
	v_mfma_f32_16x16x32_bf16 v[70:73], v[168:171], v[208:211], v[70:73]
	s_setprio 0
	ds_read_b128 v[180:183], v145 offset:49152
	ds_read_b128 v[184:187], v145 offset:50176
	ds_read_b128 v[188:191], v145 offset:51200
	ds_read_b128 v[192:195], v145 offset:52224
	ds_read_b128 v[196:199], v145 offset:53248
	ds_read_b128 v[200:203], v145 offset:54272
	ds_read_b128 v[204:207], v145 offset:55296
	ds_read_b128 v[208:211], v145 offset:56320
	s_add_u32 s22, s20, 0x80
	s_addc_u32 s23, s21, 0
	s_mov_b32 s82, m0
	s_mov_b32 m0, s48
	s_nop 0
	global_load_lds_dwordx4 v139, s[22:23]
	s_mov_b32 m0, s82
	s_add_u32 s20, s20, 0x80080
	s_mov_b32 s82, m0
	s_mov_b32 m0, s49
	s_nop 0
	global_load_lds_dwordx4 v141, s[22:23]
	s_mov_b32 m0, s82
	s_addc_u32 s21, s21, 0
	s_mov_b32 s22, m0
	s_mov_b32 m0, s56
	s_nop 0
	global_load_lds_dwordx4 v139, s[20:21]
	s_mov_b32 m0, s22
	s_nop 0
	s_mov_b32 s22, m0
	s_mov_b32 m0, s57
	s_nop 0
	global_load_lds_dwordx4 v141, s[20:21]
	s_mov_b32 m0, s22
	s_waitcnt vmcnt(4)
	s_waitcnt lgkmcnt(0)
	s_barrier
	s_setprio 1
	s_waitcnt lgkmcnt(7)
	v_mfma_f32_16x16x32_bf16 v[62:65], v[148:151], v[180:183], v[62:65]
	v_mfma_f32_16x16x32_bf16 v[62:65], v[152:155], v[184:187], v[62:65]
	s_waitcnt lgkmcnt(5)
	v_mfma_f32_16x16x32_bf16 v[58:61], v[156:159], v[180:183], v[58:61]
	v_mfma_f32_16x16x32_bf16 v[58:61], v[160:163], v[184:187], v[58:61]
	s_waitcnt lgkmcnt(3)
	v_mfma_f32_16x16x32_bf16 v[42:45], v[156:159], v[188:191], v[42:45]
	v_mfma_f32_16x16x32_bf16 v[42:45], v[160:163], v[192:195], v[42:45]
	s_waitcnt lgkmcnt(1)
	v_mfma_f32_16x16x32_bf16 v[46:49], v[148:151], v[188:191], v[46:49]
	v_mfma_f32_16x16x32_bf16 v[46:49], v[152:155], v[192:195], v[46:49]
	v_mfma_f32_16x16x32_bf16 v[30:33], v[148:151], v[196:199], v[30:33]
	v_mfma_f32_16x16x32_bf16 v[30:33], v[152:155], v[200:203], v[30:33]
	v_mfma_f32_16x16x32_bf16 v[26:29], v[156:159], v[196:199], v[26:29]
	v_mfma_f32_16x16x32_bf16 v[26:29], v[160:163], v[200:203], v[26:29]
	v_mfma_f32_16x16x32_bf16 v[10:13], v[156:159], v[204:207], v[10:13]
	v_mfma_f32_16x16x32_bf16 v[10:13], v[160:163], v[208:211], v[10:13]
	s_waitcnt lgkmcnt(0)
	v_mfma_f32_16x16x32_bf16 v[14:17], v[148:151], v[204:207], v[14:17]
	v_mfma_f32_16x16x32_bf16 v[14:17], v[152:155], v[208:211], v[14:17]
	s_setprio 0
	s_setprio 1
	v_mfma_f32_16x16x32_bf16 v[54:57], v[164:167], v[180:183], v[54:57]
	v_mfma_f32_16x16x32_bf16 v[54:57], v[168:171], v[184:187], v[54:57]
	v_mfma_f32_16x16x32_bf16 v[50:53], v[172:175], v[180:183], v[50:53]
	v_mfma_f32_16x16x32_bf16 v[50:53], v[176:179], v[184:187], v[50:53]
	v_mfma_f32_16x16x32_bf16 v[34:37], v[172:175], v[188:191], v[34:37]
	v_mfma_f32_16x16x32_bf16 v[34:37], v[176:179], v[192:195], v[34:37]
	v_mfma_f32_16x16x32_bf16 v[38:41], v[164:167], v[188:191], v[38:41]
	v_mfma_f32_16x16x32_bf16 v[38:41], v[168:171], v[192:195], v[38:41]
	v_mfma_f32_16x16x32_bf16 v[22:25], v[164:167], v[196:199], v[22:25]
	v_mfma_f32_16x16x32_bf16 v[22:25], v[168:171], v[200:203], v[22:25]
	v_mfma_f32_16x16x32_bf16 v[18:21], v[172:175], v[196:199], v[18:21]
	v_mfma_f32_16x16x32_bf16 v[18:21], v[176:179], v[200:203], v[18:21]
	v_mfma_f32_16x16x32_bf16 v[2:5], v[172:175], v[204:207], v[2:5]
	v_mfma_f32_16x16x32_bf16 v[2:5], v[176:179], v[208:211], v[2:5]
	s_setprio 2
	s_barrier
	v_mfma_f32_16x16x32_bf16 v[6:9], v[164:167], v[204:207], v[6:9]
	v_mfma_f32_16x16x32_bf16 v[6:9], v[168:171], v[208:211], v[6:9]
	s_setprio 0
	s_add_i32 s81, s81, 2
	s_add_u32 s77, s77, 0x100
	s_addc_u32 s78, s78, 0
	s_add_u32 s18, s18, 0x100
	s_addc_u32 s19, s19, 0
	s_add_u32 s79, s79, 0x100
	s_addc_u32 s80, s80, 0
	s_cmp_gt_u32 s81, 29
	s_cbranch_scc0 .LBB0_344
	s_and_b64 vcc, exec, s[6:7]
	s_cbranch_vccz .LBB0_347
	s_barrier

.LBB0_472:
	s_ashr_i32 s13, s12, 31
	s_lshl_b64 s[14:15], s[12:13], 15
	s_add_u32 s14, s28, s14
	s_addc_u32 s15, s29, s15
	s_and_b64 s[16:17], s[2:3], exec
	s_cselect_b32 s13, s15, s23
	s_cselect_b32 s76, s14, s22
	s_ashr_i32 s11, s10, 31
	s_lshl_b64 s[16:17], s[10:11], 15
	s_add_u32 s16, s30, s16
	s_addc_u32 s17, s31, s17
	s_and_b64 s[24:25], s[2:3], exec
	s_cselect_b32 s11, s17, s21
	s_cselect_b32 s77, s16, s20
	s_add_u32 s78, s20, 0x80000
	s_addc_u32 s79, s21, 0
	s_add_u32 s20, s22, 0x204000
	s_addc_u32 s21, s23, 0
	s_add_u32 s80, s22, 0x400000
	s_addc_u32 s81, s23, 0
	s_mov_b32 s82, -2
	s_waitcnt vmcnt(25)
	s_waitcnt vmcnt(24)
	s_waitcnt vmcnt(23)
	s_waitcnt vmcnt(22)
	s_waitcnt vmcnt(21)
	s_waitcnt vmcnt(20)
	s_waitcnt vmcnt(15)
	s_waitcnt vmcnt(14)
	s_waitcnt vmcnt(13)
	s_waitcnt vmcnt(12)
	s_waitcnt vmcnt(7)
	s_waitcnt vmcnt(6)
	s_waitcnt vmcnt(5)
	s_waitcnt vmcnt(4)
	s_waitcnt vmcnt(3)
	s_waitcnt vmcnt(2)
	s_waitcnt vmcnt(1)
	s_waitcnt vmcnt(0)
	ds_read_b128 v[134:137], v161
	ds_read_b128 v[138:141], v161 offset:1024
	ds_read_b128 v[142:145], v161 offset:2048
	ds_read_b128 v[146:149], v161 offset:3072
	ds_read_b128 v[150:153], v162
	ds_read_b128 v[166:169], v162 offset:1024
	ds_read_b128 v[170:173], v162 offset:2048
	ds_read_b128 v[174:177], v162 offset:3072
	s_cmpk_eq_i32 s82, 0x52
	s_cselect_b32 s23, s11, s79
	s_cselect_b32 s22, s77, s78
	s_cselect_b32 s25, s13, s81
	s_cselect_b32 s24, s76, s80
	ds_read_b128 v[178:181], v163
	ds_read_b128 v[182:185], v163 offset:1024
	ds_read_b128 v[186:189], v163 offset:2048
	ds_read_b128 v[190:193], v163 offset:3072
	ds_read_b128 v[194:197], v163 offset:4096
	ds_read_b128 v[198:201], v163 offset:5120
	ds_read_b128 v[202:205], v163 offset:6144
	ds_read_b128 v[206:209], v163 offset:7168
	s_add_u32 s86, s20, 0xffffc000
	s_addc_u32 s87, s21, -1
	s_mov_b32 s83, m0
	s_mov_b32 m0, s65
	s_nop 0
	global_load_lds_dwordx4 v1, s[86:87]
	s_mov_b32 m0, s83
	s_nop 0
	s_mov_b32 s83, m0
	s_mov_b32 m0, s67
	s_nop 0
	global_load_lds_dwordx4 v157, s[86:87]
	s_mov_b32 m0, s83
	s_nop 0
	s_mov_b32 s83, m0
	s_mov_b32 m0, s66
	s_nop 0
	global_load_lds_dwordx4 v1, s[20:21]
	s_mov_b32 m0, s83
	s_nop 0
	s_mov_b32 s83, m0
	s_mov_b32 m0, s73
	s_nop 0
	global_load_lds_dwordx4 v157, s[20:21]
	s_mov_b32 m0, s83
	s_waitcnt vmcnt(8)
	s_waitcnt lgkmcnt(0)
	s_barrier
	s_setprio 1
	s_waitcnt lgkmcnt(7)
	v_mfma_f32_16x16x32_bf16 v[126:129], v[134:137], v[178:181], 0
	v_mfma_f32_16x16x32_bf16 v[126:129], v[138:141], v[182:185], v[126:129]
	s_waitcnt lgkmcnt(5)
	v_mfma_f32_16x16x32_bf16 v[122:125], v[142:145], v[178:181], 0
	v_mfma_f32_16x16x32_bf16 v[122:125], v[146:149], v[182:185], v[122:125]
	s_waitcnt lgkmcnt(3)
	v_mfma_f32_16x16x32_bf16 v[114:117], v[142:145], v[186:189], 0
	v_mfma_f32_16x16x32_bf16 v[114:117], v[146:149], v[190:193], v[114:117]
	s_waitcnt lgkmcnt(1)
	v_mfma_f32_16x16x32_bf16 v[118:121], v[134:137], v[186:189], 0
	v_mfma_f32_16x16x32_bf16 v[118:121], v[138:141], v[190:193], v[118:121]
	v_mfma_f32_16x16x32_bf16 v[102:105], v[134:137], v[194:197], 0
	v_mfma_f32_16x16x32_bf16 v[102:105], v[138:141], v[198:201], v[102:105]
	v_mfma_f32_16x16x32_bf16 v[94:97], v[142:145], v[194:197], 0
	v_mfma_f32_16x16x32_bf16 v[94:97], v[146:149], v[198:201], v[94:97]
	v_mfma_f32_16x16x32_bf16 v[78:81], v[142:145], v[202:205], 0
	v_mfma_f32_16x16x32_bf16 v[78:81], v[146:149], v[206:209], v[78:81]
	s_waitcnt lgkmcnt(0)
	v_mfma_f32_16x16x32_bf16 v[86:89], v[134:137], v[202:205], 0
	v_mfma_f32_16x16x32_bf16 v[86:89], v[138:141], v[206:209], v[86:89]
	s_setprio 0
	s_setprio 1
	v_mfma_f32_16x16x32_bf16 v[110:113], v[150:153], v[178:181], 0
	v_mfma_f32_16x16x32_bf16 v[110:113], v[166:169], v[182:185], v[110:113]
	v_mfma_f32_16x16x32_bf16 v[106:109], v[170:173], v[178:181], 0
	v_mfma_f32_16x16x32_bf16 v[106:109], v[174:177], v[182:185], v[106:109]
	v_mfma_f32_16x16x32_bf16 v[90:93], v[170:173], v[186:189], 0
	v_mfma_f32_16x16x32_bf16 v[90:93], v[174:177], v[190:193], v[90:93]
	v_mfma_f32_16x16x32_bf16 v[98:101], v[150:153], v[186:189], 0
	v_mfma_f32_16x16x32_bf16 v[98:101], v[166:169], v[190:193], v[98:101]
	v_mfma_f32_16x16x32_bf16 v[82:85], v[150:153], v[194:197], 0
	v_mfma_f32_16x16x32_bf16 v[82:85], v[166:169], v[198:201], v[82:85]
	v_mfma_f32_16x16x32_bf16 v[74:77], v[170:173], v[194:197], 0
	v_mfma_f32_16x16x32_bf16 v[74:77], v[174:177], v[198:201], v[74:77]
	v_mfma_f32_16x16x32_bf16 v[66:69], v[170:173], v[202:205], 0
	v_mfma_f32_16x16x32_bf16 v[66:69], v[174:177], v[206:209], v[66:69]
	s_setprio 2
	s_barrier
	v_mfma_f32_16x16x32_bf16 v[70:73], v[150:153], v[202:205], 0
	v_mfma_f32_16x16x32_bf16 v[70:73], v[166:169], v[206:209], v[70:73]
	s_setprio 0
	ds_read_b128 v[178:181], v163 offset:16384
	ds_read_b128 v[182:185], v163 offset:17408
	ds_read_b128 v[186:189], v163 offset:18432
	ds_read_b128 v[190:193], v163 offset:19456
	ds_read_b128 v[194:197], v163 offset:20480
	ds_read_b128 v[198:201], v163 offset:21504
	ds_read_b128 v[202:205], v163 offset:22528
	ds_read_b128 v[206:209], v163 offset:23552
	s_mov_b32 s83, m0
	s_mov_b32 m0, s19
	s_nop 0
	global_load_lds_dwordx4 v156, s[22:23]
	s_mov_b32 m0, s83
	s_add_u32 s86, s22, 0x4000
	s_mov_b32 s83, m0
	s_mov_b32 m0, s35
	s_nop 0
	global_load_lds_dwordx4 v158, s[22:23]
	s_mov_b32 m0, s83
	s_addc_u32 s87, s23, 0
	s_mov_b32 s83, m0
	s_mov_b32 m0, s36
	s_nop 0
	global_load_lds_dwordx4 v156, s[86:87]
	s_mov_b32 m0, s83
	s_nop 0
	s_mov_b32 s83, m0
	s_mov_b32 m0, s37
	s_nop 0
	global_load_lds_dwordx4 v158, s[86:87]
	s_mov_b32 m0, s83
	s_waitcnt vmcnt(4)
	s_waitcnt lgkmcnt(0)
	s_barrier
	s_setprio 1
	s_waitcnt lgkmcnt(7)
	v_mfma_f32_16x16x32_bf16 v[62:65], v[134:137], v[178:181], 0
	v_mfma_f32_16x16x32_bf16 v[62:65], v[138:141], v[182:185], v[62:65]
	s_waitcnt lgkmcnt(5)
	v_mfma_f32_16x16x32_bf16 v[58:61], v[142:145], v[178:181], 0
	v_mfma_f32_16x16x32_bf16 v[58:61], v[146:149], v[182:185], v[58:61]
	s_waitcnt lgkmcnt(3)
	v_mfma_f32_16x16x32_bf16 v[46:49], v[142:145], v[186:189], 0
	v_mfma_f32_16x16x32_bf16 v[46:49], v[146:149], v[190:193], v[46:49]
	s_waitcnt lgkmcnt(1)
	v_mfma_f32_16x16x32_bf16 v[54:57], v[134:137], v[186:189], 0
	v_mfma_f32_16x16x32_bf16 v[54:57], v[138:141], v[190:193], v[54:57]
	v_mfma_f32_16x16x32_bf16 v[38:41], v[134:137], v[194:197], 0
	v_mfma_f32_16x16x32_bf16 v[38:41], v[138:141], v[198:201], v[38:41]
	v_mfma_f32_16x16x32_bf16 v[30:33], v[142:145], v[194:197], 0
	v_mfma_f32_16x16x32_bf16 v[30:33], v[146:149], v[198:201], v[30:33]
	v_mfma_f32_16x16x32_bf16 v[14:17], v[142:145], v[202:205], 0
	v_mfma_f32_16x16x32_bf16 v[14:17], v[146:149], v[206:209], v[14:17]
	s_waitcnt lgkmcnt(0)
	v_mfma_f32_16x16x32_bf16 v[22:25], v[134:137], v[202:205], 0
	v_mfma_f32_16x16x32_bf16 v[22:25], v[138:141], v[206:209], v[22:25]
	s_setprio 0
	s_setprio 1
	v_mfma_f32_16x16x32_bf16 v[50:53], v[150:153], v[178:181], 0
	v_mfma_f32_16x16x32_bf16 v[50:53], v[166:169], v[182:185], v[50:53]
	v_mfma_f32_16x16x32_bf16 v[42:45], v[170:173], v[178:181], 0
	v_mfma_f32_16x16x32_bf16 v[42:45], v[174:177], v[182:185], v[42:45]
	v_mfma_f32_16x16x32_bf16 v[26:29], v[170:173], v[186:189], 0
	v_mfma_f32_16x16x32_bf16 v[26:29], v[174:177], v[190:193], v[26:29]
	v_mfma_f32_16x16x32_bf16 v[34:37], v[150:153], v[186:189], 0
	v_mfma_f32_16x16x32_bf16 v[34:37], v[166:169], v[190:193], v[34:37]
	v_mfma_f32_16x16x32_bf16 v[18:21], v[150:153], v[194:197], 0
	v_mfma_f32_16x16x32_bf16 v[18:21], v[166:169], v[198:201], v[18:21]
	v_mfma_f32_16x16x32_bf16 v[10:13], v[170:173], v[194:197], 0
	v_mfma_f32_16x16x32_bf16 v[10:13], v[174:177], v[198:201], v[10:13]
	v_mfma_f32_16x16x32_bf16 v[2:5], v[170:173], v[202:205], 0
	v_mfma_f32_16x16x32_bf16 v[2:5], v[174:177], v[206:209], v[2:5]
	s_setprio 2
	s_barrier
	v_mfma_f32_16x16x32_bf16 v[6:9], v[150:153], v[202:205], 0
	v_mfma_f32_16x16x32_bf16 v[6:9], v[166:169], v[206:209], v[6:9]
	s_setprio 0
	ds_read_b128 v[134:137], v164
	ds_read_b128 v[138:141], v164 offset:1024
	ds_read_b128 v[142:145], v164 offset:2048
	ds_read_b128 v[146:149], v164 offset:3072
	ds_read_b128 v[150:153], v165
	ds_read_b128 v[166:169], v165 offset:1024
	ds_read_b128 v[170:173], v165 offset:2048
	ds_read_b128 v[174:177], v165 offset:3072
	ds_read_b128 v[178:181], v163 offset:32768
	ds_read_b128 v[182:185], v163 offset:33792
	ds_read_b128 v[186:189], v163 offset:34816
	ds_read_b128 v[190:193], v163 offset:35840
	ds_read_b128 v[194:197], v163 offset:36864
	ds_read_b128 v[198:201], v163 offset:37888
	ds_read_b128 v[202:205], v163 offset:38912
	ds_read_b128 v[206:209], v163 offset:39936
	s_mov_b32 s83, m0
	s_mov_b32 m0, s34
	s_nop 0
	global_load_lds_dwordx4 v1, s[24:25]
	s_mov_b32 m0, s83
	s_nop 0
	s_mov_b32 s83, m0
	s_mov_b32 m0, s42
	s_nop 0
	global_load_lds_dwordx4 v157, s[24:25]
	s_mov_b32 m0, s83
	s_add_u32 s24, s24, 0x4000
	s_addc_u32 s25, s25, 0
	s_mov_b32 s83, m0
	s_mov_b32 m0, s43
	s_nop 0
	global_load_lds_dwordx4 v1, s[24:25]
	s_mov_b32 m0, s83
	s_nop 0
	s_mov_b32 s83, m0
	s_mov_b32 m0, s46
	s_nop 0
	global_load_lds_dwordx4 v157, s[24:25]
	s_mov_b32 m0, s83
	s_waitcnt vmcnt(8)
	s_waitcnt lgkmcnt(0)
	s_barrier
	s_setprio 1
	s_waitcnt lgkmcnt(7)
	v_mfma_f32_16x16x32_bf16 v[126:129], v[134:137], v[178:181], v[126:129]
	v_mfma_f32_16x16x32_bf16 v[126:129], v[138:141], v[182:185], v[126:129]
	s_waitcnt lgkmcnt(5)
	v_mfma_f32_16x16x32_bf16 v[122:125], v[142:145], v[178:181], v[122:125]
	v_mfma_f32_16x16x32_bf16 v[122:125], v[146:149], v[182:185], v[122:125]
	s_waitcnt lgkmcnt(3)
	v_mfma_f32_16x16x32_bf16 v[114:117], v[142:145], v[186:189], v[114:117]
	v_mfma_f32_16x16x32_bf16 v[114:117], v[146:149], v[190:193], v[114:117]
	s_waitcnt lgkmcnt(1)
	v_mfma_f32_16x16x32_bf16 v[118:121], v[134:137], v[186:189], v[118:121]
	v_mfma_f32_16x16x32_bf16 v[118:121], v[138:141], v[190:193], v[118:121]
	v_mfma_f32_16x16x32_bf16 v[102:105], v[134:137], v[194:197], v[102:105]
	v_mfma_f32_16x16x32_bf16 v[102:105], v[138:141], v[198:201], v[102:105]
	v_mfma_f32_16x16x32_bf16 v[94:97], v[142:145], v[194:197], v[94:97]
	v_mfma_f32_16x16x32_bf16 v[94:97], v[146:149], v[198:201], v[94:97]
	v_mfma_f32_16x16x32_bf16 v[78:81], v[142:145], v[202:205], v[78:81]
	v_mfma_f32_16x16x32_bf16 v[78:81], v[146:149], v[206:209], v[78:81]
	s_waitcnt lgkmcnt(0)
	v_mfma_f32_16x16x32_bf16 v[86:89], v[134:137], v[202:205], v[86:89]
	v_mfma_f32_16x16x32_bf16 v[86:89], v[138:141], v[206:209], v[86:89]
	s_setprio 0
	s_setprio 1
	v_mfma_f32_16x16x32_bf16 v[110:113], v[150:153], v[178:181], v[110:113]
	v_mfma_f32_16x16x32_bf16 v[110:113], v[166:169], v[182:185], v[110:113]
	v_mfma_f32_16x16x32_bf16 v[106:109], v[170:173], v[178:181], v[106:109]
	v_mfma_f32_16x16x32_bf16 v[106:109], v[174:177], v[182:185], v[106:109]
	v_mfma_f32_16x16x32_bf16 v[90:93], v[170:173], v[186:189], v[90:93]
	v_mfma_f32_16x16x32_bf16 v[90:93], v[174:177], v[190:193], v[90:93]
	v_mfma_f32_16x16x32_bf16 v[98:101], v[150:153], v[186:189], v[98:101]
	v_mfma_f32_16x16x32_bf16 v[98:101], v[166:169], v[190:193], v[98:101]
	v_mfma_f32_16x16x32_bf16 v[82:85], v[150:153], v[194:197], v[82:85]
	v_mfma_f32_16x16x32_bf16 v[82:85], v[166:169], v[198:201], v[82:85]
	v_mfma_f32_16x16x32_bf16 v[74:77], v[170:173], v[194:197], v[74:77]
	v_mfma_f32_16x16x32_bf16 v[74:77], v[174:177], v[198:201], v[74:77]
	v_mfma_f32_16x16x32_bf16 v[66:69], v[170:173], v[202:205], v[66:69]
	v_mfma_f32_16x16x32_bf16 v[66:69], v[174:177], v[206:209], v[66:69]
	s_setprio 2
	s_barrier
	v_mfma_f32_16x16x32_bf16 v[70:73], v[150:153], v[202:205], v[70:73]
	v_mfma_f32_16x16x32_bf16 v[70:73], v[166:169], v[206:209], v[70:73]
	s_setprio 0
	ds_read_b128 v[178:181], v163 offset:49152
	ds_read_b128 v[182:185], v163 offset:50176
	ds_read_b128 v[186:189], v163 offset:51200
	ds_read_b128 v[190:193], v163 offset:52224
	ds_read_b128 v[194:197], v163 offset:53248
	ds_read_b128 v[198:201], v163 offset:54272
	ds_read_b128 v[202:205], v163 offset:55296
	ds_read_b128 v[206:209], v163 offset:56320
	s_add_u32 s24, s22, 0x40000
	s_addc_u32 s25, s23, 0
	s_mov_b32 s83, m0
	s_mov_b32 m0, s47
	s_nop 0
	global_load_lds_dwordx4 v156, s[24:25]
	s_mov_b32 m0, s83
	s_add_u32 s22, s22, 0x44000
	s_mov_b32 s83, m0
	s_mov_b32 m0, s48
	s_nop 0
	global_load_lds_dwordx4 v158, s[24:25]
	s_mov_b32 m0, s83
	s_addc_u32 s23, s23, 0
	s_mov_b32 s24, m0
	s_mov_b32 m0, s49
	s_nop 0
	global_load_lds_dwordx4 v156, s[22:23]
	s_mov_b32 m0, s24
	s_nop 0
	s_mov_b32 s24, m0
	s_mov_b32 m0, s56
	s_nop 0
	global_load_lds_dwordx4 v158, s[22:23]
	s_mov_b32 m0, s24
	s_waitcnt vmcnt(4)
	s_waitcnt lgkmcnt(0)
	s_barrier
	s_setprio 1
	s_waitcnt lgkmcnt(7)
	v_mfma_f32_16x16x32_bf16 v[62:65], v[134:137], v[178:181], v[62:65]
	v_mfma_f32_16x16x32_bf16 v[62:65], v[138:141], v[182:185], v[62:65]
	s_waitcnt lgkmcnt(5)
	v_mfma_f32_16x16x32_bf16 v[58:61], v[142:145], v[178:181], v[58:61]
	v_mfma_f32_16x16x32_bf16 v[58:61], v[146:149], v[182:185], v[58:61]
	s_waitcnt lgkmcnt(3)
	v_mfma_f32_16x16x32_bf16 v[46:49], v[142:145], v[186:189], v[46:49]
	v_mfma_f32_16x16x32_bf16 v[46:49], v[146:149], v[190:193], v[46:49]
	s_waitcnt lgkmcnt(1)
	v_mfma_f32_16x16x32_bf16 v[54:57], v[134:137], v[186:189], v[54:57]
	v_mfma_f32_16x16x32_bf16 v[54:57], v[138:141], v[190:193], v[54:57]
	v_mfma_f32_16x16x32_bf16 v[38:41], v[134:137], v[194:197], v[38:41]
	v_mfma_f32_16x16x32_bf16 v[38:41], v[138:141], v[198:201], v[38:41]
	v_mfma_f32_16x16x32_bf16 v[30:33], v[142:145], v[194:197], v[30:33]
	v_mfma_f32_16x16x32_bf16 v[30:33], v[146:149], v[198:201], v[30:33]
	v_mfma_f32_16x16x32_bf16 v[14:17], v[142:145], v[202:205], v[14:17]
	v_mfma_f32_16x16x32_bf16 v[14:17], v[146:149], v[206:209], v[14:17]
	s_waitcnt lgkmcnt(0)
	v_mfma_f32_16x16x32_bf16 v[22:25], v[134:137], v[202:205], v[22:25]
	v_mfma_f32_16x16x32_bf16 v[22:25], v[138:141], v[206:209], v[22:25]
	s_setprio 0
	s_setprio 1
	v_mfma_f32_16x16x32_bf16 v[50:53], v[150:153], v[178:181], v[50:53]
	v_mfma_f32_16x16x32_bf16 v[50:53], v[166:169], v[182:185], v[50:53]
	v_mfma_f32_16x16x32_bf16 v[42:45], v[170:173], v[178:181], v[42:45]
	v_mfma_f32_16x16x32_bf16 v[42:45], v[174:177], v[182:185], v[42:45]
	v_mfma_f32_16x16x32_bf16 v[26:29], v[170:173], v[186:189], v[26:29]
	v_mfma_f32_16x16x32_bf16 v[26:29], v[174:177], v[190:193], v[26:29]
	v_mfma_f32_16x16x32_bf16 v[34:37], v[150:153], v[186:189], v[34:37]
	v_mfma_f32_16x16x32_bf16 v[34:37], v[166:169], v[190:193], v[34:37]
	v_mfma_f32_16x16x32_bf16 v[18:21], v[150:153], v[194:197], v[18:21]
	v_mfma_f32_16x16x32_bf16 v[18:21], v[166:169], v[198:201], v[18:21]
	v_mfma_f32_16x16x32_bf16 v[10:13], v[170:173], v[194:197], v[10:13]
	v_mfma_f32_16x16x32_bf16 v[10:13], v[174:177], v[198:201], v[10:13]
	v_mfma_f32_16x16x32_bf16 v[2:5], v[170:173], v[202:205], v[2:5]
	v_mfma_f32_16x16x32_bf16 v[2:5], v[174:177], v[206:209], v[2:5]
	s_setprio 2
	s_barrier
	v_mfma_f32_16x16x32_bf16 v[6:9], v[150:153], v[202:205], v[6:9]
	v_mfma_f32_16x16x32_bf16 v[6:9], v[166:169], v[206:209], v[6:9]
	s_setprio 0
	s_add_i32 s82, s82, 2
	s_add_u32 s78, s78, 0x80000
	s_addc_u32 s79, s79, 0
	s_add_u32 s20, s20, 0x400000
	s_addc_u32 s21, s21, 0
	s_add_u32 s80, s80, 0x400000
	s_addc_u32 s81, s81, 0
	s_cmpk_gt_u32 s82, 0x53
	.p2align 6
.LBB0_473:
	ds_read_b128 v[134:137], v161
	ds_read_b128 v[138:141], v161 offset:1024
	ds_read_b128 v[142:145], v161 offset:2048
	ds_read_b128 v[146:149], v161 offset:3072
	ds_read_b128 v[150:153], v162
	ds_read_b128 v[166:169], v162 offset:1024
	ds_read_b128 v[170:173], v162 offset:2048
	ds_read_b128 v[174:177], v162 offset:3072
	s_cmpk_eq_i32 s82, 0x52
	s_cselect_b32 s23, s11, s79
	s_cselect_b32 s22, s77, s78
	s_cselect_b32 s25, s13, s81
	s_cselect_b32 s24, s76, s80
	ds_read_b128 v[178:181], v163
	ds_read_b128 v[182:185], v163 offset:1024
	ds_read_b128 v[186:189], v163 offset:2048
	ds_read_b128 v[190:193], v163 offset:3072
	ds_read_b128 v[194:197], v163 offset:4096
	ds_read_b128 v[198:201], v163 offset:5120
	ds_read_b128 v[202:205], v163 offset:6144
	ds_read_b128 v[206:209], v163 offset:7168
	s_add_u32 s86, s20, 0xffffc000
	s_addc_u32 s87, s21, -1
	s_mov_b32 s83, m0
	s_mov_b32 m0, s65
	s_nop 0
	global_load_lds_dwordx4 v1, s[86:87]
	s_mov_b32 m0, s83
	s_nop 0
	s_mov_b32 s83, m0
	s_mov_b32 m0, s67
	s_nop 0
	global_load_lds_dwordx4 v157, s[86:87]
	s_mov_b32 m0, s83
	s_nop 0
	s_mov_b32 s83, m0
	s_mov_b32 m0, s66
	s_nop 0
	global_load_lds_dwordx4 v1, s[20:21]
	s_mov_b32 m0, s83
	s_nop 0
	s_mov_b32 s83, m0
	s_mov_b32 m0, s73
	s_nop 0
	global_load_lds_dwordx4 v157, s[20:21]
	s_mov_b32 m0, s83
	s_waitcnt vmcnt(8)
	s_waitcnt lgkmcnt(0)
	s_barrier
	s_setprio 1
	s_waitcnt lgkmcnt(7)
	v_mfma_f32_16x16x32_bf16 v[126:129], v[134:137], v[178:181], v[126:129]
	v_mfma_f32_16x16x32_bf16 v[126:129], v[138:141], v[182:185], v[126:129]
	s_waitcnt lgkmcnt(5)
	v_mfma_f32_16x16x32_bf16 v[122:125], v[142:145], v[178:181], v[122:125]
	v_mfma_f32_16x16x32_bf16 v[122:125], v[146:149], v[182:185], v[122:125]
	s_waitcnt lgkmcnt(3)
	v_mfma_f32_16x16x32_bf16 v[114:117], v[142:145], v[186:189], v[114:117]
	v_mfma_f32_16x16x32_bf16 v[114:117], v[146:149], v[190:193], v[114:117]
	s_waitcnt lgkmcnt(1)
	v_mfma_f32_16x16x32_bf16 v[118:121], v[134:137], v[186:189], v[118:121]
	v_mfma_f32_16x16x32_bf16 v[118:121], v[138:141], v[190:193], v[118:121]
	v_mfma_f32_16x16x32_bf16 v[102:105], v[134:137], v[194:197], v[102:105]
	v_mfma_f32_16x16x32_bf16 v[102:105], v[138:141], v[198:201], v[102:105]
	v_mfma_f32_16x16x32_bf16 v[94:97], v[142:145], v[194:197], v[94:97]
	v_mfma_f32_16x16x32_bf16 v[94:97], v[146:149], v[198:201], v[94:97]
	v_mfma_f32_16x16x32_bf16 v[78:81], v[142:145], v[202:205], v[78:81]
	v_mfma_f32_16x16x32_bf16 v[78:81], v[146:149], v[206:209], v[78:81]
	s_waitcnt lgkmcnt(0)
	v_mfma_f32_16x16x32_bf16 v[86:89], v[134:137], v[202:205], v[86:89]
	v_mfma_f32_16x16x32_bf16 v[86:89], v[138:141], v[206:209], v[86:89]
	s_setprio 0
	s_setprio 1
	v_mfma_f32_16x16x32_bf16 v[110:113], v[150:153], v[178:181], v[110:113]
	v_mfma_f32_16x16x32_bf16 v[110:113], v[166:169], v[182:185], v[110:113]
	v_mfma_f32_16x16x32_bf16 v[106:109], v[170:173], v[178:181], v[106:109]
	v_mfma_f32_16x16x32_bf16 v[106:109], v[174:177], v[182:185], v[106:109]
	v_mfma_f32_16x16x32_bf16 v[90:93], v[170:173], v[186:189], v[90:93]
	v_mfma_f32_16x16x32_bf16 v[90:93], v[174:177], v[190:193], v[90:93]
	v_mfma_f32_16x16x32_bf16 v[98:101], v[150:153], v[186:189], v[98:101]
	v_mfma_f32_16x16x32_bf16 v[98:101], v[166:169], v[190:193], v[98:101]
	v_mfma_f32_16x16x32_bf16 v[82:85], v[150:153], v[194:197], v[82:85]
	v_mfma_f32_16x16x32_bf16 v[82:85], v[166:169], v[198:201], v[82:85]
	v_mfma_f32_16x16x32_bf16 v[74:77], v[170:173], v[194:197], v[74:77]
	v_mfma_f32_16x16x32_bf16 v[74:77], v[174:177], v[198:201], v[74:77]
	v_mfma_f32_16x16x32_bf16 v[66:69], v[170:173], v[202:205], v[66:69]
	v_mfma_f32_16x16x32_bf16 v[66:69], v[174:177], v[206:209], v[66:69]
	s_setprio 2
	s_barrier
	v_mfma_f32_16x16x32_bf16 v[70:73], v[150:153], v[202:205], v[70:73]
	v_mfma_f32_16x16x32_bf16 v[70:73], v[166:169], v[206:209], v[70:73]
	s_setprio 0
	ds_read_b128 v[178:181], v163 offset:16384
	ds_read_b128 v[182:185], v163 offset:17408
	ds_read_b128 v[186:189], v163 offset:18432
	ds_read_b128 v[190:193], v163 offset:19456
	ds_read_b128 v[194:197], v163 offset:20480
	ds_read_b128 v[198:201], v163 offset:21504
	ds_read_b128 v[202:205], v163 offset:22528
	ds_read_b128 v[206:209], v163 offset:23552
	s_mov_b32 s83, m0
	s_mov_b32 m0, s19
	s_nop 0
	global_load_lds_dwordx4 v156, s[22:23]
	s_mov_b32 m0, s83
	s_add_u32 s86, s22, 0x4000
	s_mov_b32 s83, m0
	s_mov_b32 m0, s35
	s_nop 0
	global_load_lds_dwordx4 v158, s[22:23]
	s_mov_b32 m0, s83
	s_addc_u32 s87, s23, 0
	s_mov_b32 s83, m0
	s_mov_b32 m0, s36
	s_nop 0
	global_load_lds_dwordx4 v156, s[86:87]
	s_mov_b32 m0, s83
	s_nop 0
	s_mov_b32 s83, m0
	s_mov_b32 m0, s37
	s_nop 0
	global_load_lds_dwordx4 v158, s[86:87]
	s_mov_b32 m0, s83
	s_waitcnt vmcnt(4)
	s_waitcnt lgkmcnt(0)
	s_barrier
	s_setprio 1
	s_waitcnt lgkmcnt(7)
	v_mfma_f32_16x16x32_bf16 v[62:65], v[134:137], v[178:181], v[62:65]
	v_mfma_f32_16x16x32_bf16 v[62:65], v[138:141], v[182:185], v[62:65]
	s_waitcnt lgkmcnt(5)
	v_mfma_f32_16x16x32_bf16 v[58:61], v[142:145], v[178:181], v[58:61]
	v_mfma_f32_16x16x32_bf16 v[58:61], v[146:149], v[182:185], v[58:61]
	s_waitcnt lgkmcnt(3)
	v_mfma_f32_16x16x32_bf16 v[46:49], v[142:145], v[186:189], v[46:49]
	v_mfma_f32_16x16x32_bf16 v[46:49], v[146:149], v[190:193], v[46:49]
	s_waitcnt lgkmcnt(1)
	v_mfma_f32_16x16x32_bf16 v[54:57], v[134:137], v[186:189], v[54:57]
	v_mfma_f32_16x16x32_bf16 v[54:57], v[138:141], v[190:193], v[54:57]
	v_mfma_f32_16x16x32_bf16 v[38:41], v[134:137], v[194:197], v[38:41]
	v_mfma_f32_16x16x32_bf16 v[38:41], v[138:141], v[198:201], v[38:41]
	v_mfma_f32_16x16x32_bf16 v[30:33], v[142:145], v[194:197], v[30:33]
	v_mfma_f32_16x16x32_bf16 v[30:33], v[146:149], v[198:201], v[30:33]
	v_mfma_f32_16x16x32_bf16 v[14:17], v[142:145], v[202:205], v[14:17]
	v_mfma_f32_16x16x32_bf16 v[14:17], v[146:149], v[206:209], v[14:17]
	s_waitcnt lgkmcnt(0)
	v_mfma_f32_16x16x32_bf16 v[22:25], v[134:137], v[202:205], v[22:25]
	v_mfma_f32_16x16x32_bf16 v[22:25], v[138:141], v[206:209], v[22:25]
	s_setprio 0
	s_setprio 1
	v_mfma_f32_16x16x32_bf16 v[50:53], v[150:153], v[178:181], v[50:53]
	v_mfma_f32_16x16x32_bf16 v[50:53], v[166:169], v[182:185], v[50:53]
	v_mfma_f32_16x16x32_bf16 v[42:45], v[170:173], v[178:181], v[42:45]
	v_mfma_f32_16x16x32_bf16 v[42:45], v[174:177], v[182:185], v[42:45]
	v_mfma_f32_16x16x32_bf16 v[26:29], v[170:173], v[186:189], v[26:29]
	v_mfma_f32_16x16x32_bf16 v[26:29], v[174:177], v[190:193], v[26:29]
	v_mfma_f32_16x16x32_bf16 v[34:37], v[150:153], v[186:189], v[34:37]
	v_mfma_f32_16x16x32_bf16 v[34:37], v[166:169], v[190:193], v[34:37]
	v_mfma_f32_16x16x32_bf16 v[18:21], v[150:153], v[194:197], v[18:21]
	v_mfma_f32_16x16x32_bf16 v[18:21], v[166:169], v[198:201], v[18:21]
	v_mfma_f32_16x16x32_bf16 v[10:13], v[170:173], v[194:197], v[10:13]
	v_mfma_f32_16x16x32_bf16 v[10:13], v[174:177], v[198:201], v[10:13]
	v_mfma_f32_16x16x32_bf16 v[2:5], v[170:173], v[202:205], v[2:5]
	v_mfma_f32_16x16x32_bf16 v[2:5], v[174:177], v[206:209], v[2:5]
	s_setprio 2
	s_barrier
	v_mfma_f32_16x16x32_bf16 v[6:9], v[150:153], v[202:205], v[6:9]
	v_mfma_f32_16x16x32_bf16 v[6:9], v[166:169], v[206:209], v[6:9]
	s_setprio 0
	ds_read_b128 v[134:137], v164
	ds_read_b128 v[138:141], v164 offset:1024
	ds_read_b128 v[142:145], v164 offset:2048
	ds_read_b128 v[146:149], v164 offset:3072
	ds_read_b128 v[150:153], v165
	ds_read_b128 v[166:169], v165 offset:1024
	ds_read_b128 v[170:173], v165 offset:2048
	ds_read_b128 v[174:177], v165 offset:3072
	ds_read_b128 v[178:181], v163 offset:32768
	ds_read_b128 v[182:185], v163 offset:33792
	ds_read_b128 v[186:189], v163 offset:34816
	ds_read_b128 v[190:193], v163 offset:35840
	ds_read_b128 v[194:197], v163 offset:36864
	ds_read_b128 v[198:201], v163 offset:37888
	ds_read_b128 v[202:205], v163 offset:38912
	ds_read_b128 v[206:209], v163 offset:39936
	s_mov_b32 s83, m0
	s_mov_b32 m0, s34
	s_nop 0
	global_load_lds_dwordx4 v1, s[24:25]
	s_mov_b32 m0, s83
	s_nop 0
	s_mov_b32 s83, m0
	s_mov_b32 m0, s42
	s_nop 0
	global_load_lds_dwordx4 v157, s[24:25]
	s_mov_b32 m0, s83
	s_add_u32 s24, s24, 0x4000
	s_addc_u32 s25, s25, 0
	s_mov_b32 s83, m0
	s_mov_b32 m0, s43
	s_nop 0
	global_load_lds_dwordx4 v1, s[24:25]
	s_mov_b32 m0, s83
	s_nop 0
	s_mov_b32 s83, m0
	s_mov_b32 m0, s46
	s_nop 0
	global_load_lds_dwordx4 v157, s[24:25]
	s_mov_b32 m0, s83
	s_waitcnt vmcnt(8)
	s_waitcnt lgkmcnt(0)
	s_barrier
	s_setprio 1
	s_waitcnt lgkmcnt(7)
	v_mfma_f32_16x16x32_bf16 v[126:129], v[134:137], v[178:181], v[126:129]
	v_mfma_f32_16x16x32_bf16 v[126:129], v[138:141], v[182:185], v[126:129]
	s_waitcnt lgkmcnt(5)
	v_mfma_f32_16x16x32_bf16 v[122:125], v[142:145], v[178:181], v[122:125]
	v_mfma_f32_16x16x32_bf16 v[122:125], v[146:149], v[182:185], v[122:125]
	s_waitcnt lgkmcnt(3)
	v_mfma_f32_16x16x32_bf16 v[114:117], v[142:145], v[186:189], v[114:117]
	v_mfma_f32_16x16x32_bf16 v[114:117], v[146:149], v[190:193], v[114:117]
	s_waitcnt lgkmcnt(1)
	v_mfma_f32_16x16x32_bf16 v[118:121], v[134:137], v[186:189], v[118:121]
	v_mfma_f32_16x16x32_bf16 v[118:121], v[138:141], v[190:193], v[118:121]
	v_mfma_f32_16x16x32_bf16 v[102:105], v[134:137], v[194:197], v[102:105]
	v_mfma_f32_16x16x32_bf16 v[102:105], v[138:141], v[198:201], v[102:105]
	v_mfma_f32_16x16x32_bf16 v[94:97], v[142:145], v[194:197], v[94:97]
	v_mfma_f32_16x16x32_bf16 v[94:97], v[146:149], v[198:201], v[94:97]
	v_mfma_f32_16x16x32_bf16 v[78:81], v[142:145], v[202:205], v[78:81]
	v_mfma_f32_16x16x32_bf16 v[78:81], v[146:149], v[206:209], v[78:81]
	s_waitcnt lgkmcnt(0)
	v_mfma_f32_16x16x32_bf16 v[86:89], v[134:137], v[202:205], v[86:89]
	v_mfma_f32_16x16x32_bf16 v[86:89], v[138:141], v[206:209], v[86:89]
	s_setprio 0
	s_setprio 1
	v_mfma_f32_16x16x32_bf16 v[110:113], v[150:153], v[178:181], v[110:113]
	v_mfma_f32_16x16x32_bf16 v[110:113], v[166:169], v[182:185], v[110:113]
	v_mfma_f32_16x16x32_bf16 v[106:109], v[170:173], v[178:181], v[106:109]
	v_mfma_f32_16x16x32_bf16 v[106:109], v[174:177], v[182:185], v[106:109]
	v_mfma_f32_16x16x32_bf16 v[90:93], v[170:173], v[186:189], v[90:93]
	v_mfma_f32_16x16x32_bf16 v[90:93], v[174:177], v[190:193], v[90:93]
	v_mfma_f32_16x16x32_bf16 v[98:101], v[150:153], v[186:189], v[98:101]
	v_mfma_f32_16x16x32_bf16 v[98:101], v[166:169], v[190:193], v[98:101]
	v_mfma_f32_16x16x32_bf16 v[82:85], v[150:153], v[194:197], v[82:85]
	v_mfma_f32_16x16x32_bf16 v[82:85], v[166:169], v[198:201], v[82:85]
	v_mfma_f32_16x16x32_bf16 v[74:77], v[170:173], v[194:197], v[74:77]
	v_mfma_f32_16x16x32_bf16 v[74:77], v[174:177], v[198:201], v[74:77]
	v_mfma_f32_16x16x32_bf16 v[66:69], v[170:173], v[202:205], v[66:69]
	v_mfma_f32_16x16x32_bf16 v[66:69], v[174:177], v[206:209], v[66:69]
	s_setprio 2
	s_barrier
	v_mfma_f32_16x16x32_bf16 v[70:73], v[150:153], v[202:205], v[70:73]
	v_mfma_f32_16x16x32_bf16 v[70:73], v[166:169], v[206:209], v[70:73]
	s_setprio 0
	ds_read_b128 v[178:181], v163 offset:49152
	ds_read_b128 v[182:185], v163 offset:50176
	ds_read_b128 v[186:189], v163 offset:51200
	ds_read_b128 v[190:193], v163 offset:52224
	ds_read_b128 v[194:197], v163 offset:53248
	ds_read_b128 v[198:201], v163 offset:54272
	ds_read_b128 v[202:205], v163 offset:55296
	ds_read_b128 v[206:209], v163 offset:56320
	s_add_u32 s24, s22, 0x40000
	s_addc_u32 s25, s23, 0
	s_mov_b32 s83, m0
	s_mov_b32 m0, s47
	s_nop 0
	global_load_lds_dwordx4 v156, s[24:25]
	s_mov_b32 m0, s83
	s_add_u32 s22, s22, 0x44000
	s_mov_b32 s83, m0
	s_mov_b32 m0, s48
	s_nop 0
	global_load_lds_dwordx4 v158, s[24:25]
	s_mov_b32 m0, s83
	s_addc_u32 s23, s23, 0
	s_mov_b32 s24, m0
	s_mov_b32 m0, s49
	s_nop 0
	global_load_lds_dwordx4 v156, s[22:23]
	s_mov_b32 m0, s24
	s_nop 0
	s_mov_b32 s24, m0
	s_mov_b32 m0, s56
	s_nop 0
	global_load_lds_dwordx4 v158, s[22:23]
	s_mov_b32 m0, s24
	s_waitcnt vmcnt(4)
	s_waitcnt lgkmcnt(0)
	s_barrier
	s_setprio 1
	s_waitcnt lgkmcnt(7)
	v_mfma_f32_16x16x32_bf16 v[62:65], v[134:137], v[178:181], v[62:65]
	v_mfma_f32_16x16x32_bf16 v[62:65], v[138:141], v[182:185], v[62:65]
	s_waitcnt lgkmcnt(5)
	v_mfma_f32_16x16x32_bf16 v[58:61], v[142:145], v[178:181], v[58:61]
	v_mfma_f32_16x16x32_bf16 v[58:61], v[146:149], v[182:185], v[58:61]
	s_waitcnt lgkmcnt(3)
	v_mfma_f32_16x16x32_bf16 v[46:49], v[142:145], v[186:189], v[46:49]
	v_mfma_f32_16x16x32_bf16 v[46:49], v[146:149], v[190:193], v[46:49]
	s_waitcnt lgkmcnt(1)
	v_mfma_f32_16x16x32_bf16 v[54:57], v[134:137], v[186:189], v[54:57]
	v_mfma_f32_16x16x32_bf16 v[54:57], v[138:141], v[190:193], v[54:57]
	v_mfma_f32_16x16x32_bf16 v[38:41], v[134:137], v[194:197], v[38:41]
	v_mfma_f32_16x16x32_bf16 v[38:41], v[138:141], v[198:201], v[38:41]
	v_mfma_f32_16x16x32_bf16 v[30:33], v[142:145], v[194:197], v[30:33]
	v_mfma_f32_16x16x32_bf16 v[30:33], v[146:149], v[198:201], v[30:33]
	v_mfma_f32_16x16x32_bf16 v[14:17], v[142:145], v[202:205], v[14:17]
	v_mfma_f32_16x16x32_bf16 v[14:17], v[146:149], v[206:209], v[14:17]
	s_waitcnt lgkmcnt(0)
	v_mfma_f32_16x16x32_bf16 v[22:25], v[134:137], v[202:205], v[22:25]
	v_mfma_f32_16x16x32_bf16 v[22:25], v[138:141], v[206:209], v[22:25]
	s_setprio 0
	s_setprio 1
	v_mfma_f32_16x16x32_bf16 v[50:53], v[150:153], v[178:181], v[50:53]
	v_mfma_f32_16x16x32_bf16 v[50:53], v[166:169], v[182:185], v[50:53]
	v_mfma_f32_16x16x32_bf16 v[42:45], v[170:173], v[178:181], v[42:45]
	v_mfma_f32_16x16x32_bf16 v[42:45], v[174:177], v[182:185], v[42:45]
	v_mfma_f32_16x16x32_bf16 v[26:29], v[170:173], v[186:189], v[26:29]
	v_mfma_f32_16x16x32_bf16 v[26:29], v[174:177], v[190:193], v[26:29]
	v_mfma_f32_16x16x32_bf16 v[34:37], v[150:153], v[186:189], v[34:37]
	v_mfma_f32_16x16x32_bf16 v[34:37], v[166:169], v[190:193], v[34:37]
	v_mfma_f32_16x16x32_bf16 v[18:21], v[150:153], v[194:197], v[18:21]
	v_mfma_f32_16x16x32_bf16 v[18:21], v[166:169], v[198:201], v[18:21]
	v_mfma_f32_16x16x32_bf16 v[10:13], v[170:173], v[194:197], v[10:13]
	v_mfma_f32_16x16x32_bf16 v[10:13], v[174:177], v[198:201], v[10:13]
	v_mfma_f32_16x16x32_bf16 v[2:5], v[170:173], v[202:205], v[2:5]
	v_mfma_f32_16x16x32_bf16 v[2:5], v[174:177], v[206:209], v[2:5]
	s_setprio 2
	s_barrier
	v_mfma_f32_16x16x32_bf16 v[6:9], v[150:153], v[202:205], v[6:9]
	v_mfma_f32_16x16x32_bf16 v[6:9], v[166:169], v[206:209], v[6:9]
	s_setprio 0
	s_add_i32 s82, s82, 2
	s_add_u32 s78, s78, 0x80000
	s_addc_u32 s79, s79, 0
	s_add_u32 s20, s20, 0x400000
	s_addc_u32 s21, s21, 0
	s_add_u32 s80, s80, 0x400000
	s_addc_u32 s81, s81, 0
	s_cmpk_gt_u32 s82, 0x53
	s_cbranch_scc0 .LBB0_473
	s_and_b64 vcc, exec, s[8:9]
	s_cbranch_vccz .LBB0_476
	s_barrier

.LBB0_653:
	s_ashr_i32 s23, s22, 31
	s_lshl_b64 s[24:25], s[22:23], 20
	s_add_u32 s24, s35, s24
	s_addc_u32 s25, s36, s25
	s_and_b64 s[26:27], s[2:3], exec
	s_cselect_b32 s7, s25, s11
	s_cselect_b32 s9, s24, s10
	s_ashr_i32 s21, s20, 31
	s_lshl_b64 s[26:27], s[20:21], 20
	s_add_u32 s26, s37, s26
	s_addc_u32 s27, s40, s27
	s_and_b64 s[28:29], s[2:3], exec
	s_cselect_b32 s21, s27, s5
	s_cselect_b32 s23, s26, s4
	s_add_u32 s30, s4, 0x100
	s_addc_u32 s31, s5, 0
	s_add_u32 s4, s10, 0x80080
	s_addc_u32 s5, s11, 0
	s_add_u32 s33, s10, 0x100
	s_addc_u32 s73, s11, 0
	s_mov_b32 s74, -2
	s_waitcnt vmcnt(25)
	s_waitcnt vmcnt(24)
	s_waitcnt vmcnt(15)
	s_waitcnt vmcnt(14)
	s_waitcnt vmcnt(13)
	s_waitcnt vmcnt(12)
	s_waitcnt vmcnt(11)
	s_waitcnt vmcnt(10)
	s_waitcnt vmcnt(9)
	s_waitcnt vmcnt(8)
	s_waitcnt vmcnt(7)
	s_waitcnt vmcnt(6)
	s_waitcnt vmcnt(5)
	s_waitcnt vmcnt(4)
	s_waitcnt vmcnt(3)
	s_waitcnt vmcnt(2)
	s_waitcnt vmcnt(1)
	s_waitcnt vmcnt(0)
	ds_read_b128 v[130:133], v161
	ds_read_b128 v[138:141], v161 offset:1024
	ds_read_b128 v[142:145], v161 offset:2048
	ds_read_b128 v[146:149], v161 offset:3072
	ds_read_b128 v[150:153], v162
	ds_read_b128 v[168:171], v162 offset:1024
	ds_read_b128 v[172:175], v162 offset:2048
	ds_read_b128 v[176:179], v162 offset:3072
	s_cmp_eq_u32 s74, 28
	s_cselect_b32 s11, s21, s31
	s_cselect_b32 s10, s23, s30
	s_cselect_b32 s29, s7, s73
	s_cselect_b32 s28, s9, s33
	ds_read_b128 v[180:183], v163
	ds_read_b128 v[184:187], v163 offset:1024
	ds_read_b128 v[188:191], v163 offset:2048
	ds_read_b128 v[192:195], v163 offset:3072
	ds_read_b128 v[196:199], v163 offset:4096
	ds_read_b128 v[200:203], v163 offset:5120
	ds_read_b128 v[204:207], v163 offset:6144
	ds_read_b128 v[208:211], v163 offset:7168
	s_add_u32 s76, s4, 0xfff80000
	s_addc_u32 s77, s5, -1
	s_mov_b32 s75, m0
	s_mov_b32 m0, s80
	s_nop 0
	global_load_lds_dwordx4 v1, s[76:77]
	s_mov_b32 m0, s75
	s_nop 0
	s_mov_b32 s75, m0
	s_mov_b32 m0, s82
	s_nop 0
	global_load_lds_dwordx4 v157, s[76:77]
	s_mov_b32 m0, s75
	s_nop 0
	s_mov_b32 s75, m0
	s_mov_b32 m0, s81
	s_nop 0
	global_load_lds_dwordx4 v1, s[4:5]
	s_mov_b32 m0, s75
	s_nop 0
	s_mov_b32 s75, m0
	s_mov_b32 m0, s83
	s_nop 0
	global_load_lds_dwordx4 v157, s[4:5]
	s_mov_b32 m0, s75
	s_waitcnt vmcnt(8)
	s_waitcnt lgkmcnt(0)
	s_barrier
	s_setprio 1
	s_waitcnt lgkmcnt(7)
	v_mfma_f32_16x16x32_bf16 v[126:129], v[130:133], v[180:183], 0
	v_mfma_f32_16x16x32_bf16 v[126:129], v[138:141], v[184:187], v[126:129]
	s_waitcnt lgkmcnt(5)
	v_mfma_f32_16x16x32_bf16 v[122:125], v[142:145], v[180:183], 0
	v_mfma_f32_16x16x32_bf16 v[122:125], v[146:149], v[184:187], v[122:125]
	s_waitcnt lgkmcnt(3)
	v_mfma_f32_16x16x32_bf16 v[106:109], v[142:145], v[188:191], 0
	v_mfma_f32_16x16x32_bf16 v[106:109], v[146:149], v[192:195], v[106:109]
	s_waitcnt lgkmcnt(1)
	v_mfma_f32_16x16x32_bf16 v[110:113], v[130:133], v[188:191], 0
	v_mfma_f32_16x16x32_bf16 v[110:113], v[138:141], v[192:195], v[110:113]
	v_mfma_f32_16x16x32_bf16 v[94:97], v[130:133], v[196:199], 0
	v_mfma_f32_16x16x32_bf16 v[94:97], v[138:141], v[200:203], v[94:97]
	v_mfma_f32_16x16x32_bf16 v[90:93], v[142:145], v[196:199], 0
	v_mfma_f32_16x16x32_bf16 v[90:93], v[146:149], v[200:203], v[90:93]
	v_mfma_f32_16x16x32_bf16 v[74:77], v[142:145], v[204:207], 0
	v_mfma_f32_16x16x32_bf16 v[74:77], v[146:149], v[208:211], v[74:77]
	s_waitcnt lgkmcnt(0)
	v_mfma_f32_16x16x32_bf16 v[78:81], v[130:133], v[204:207], 0
	v_mfma_f32_16x16x32_bf16 v[78:81], v[138:141], v[208:211], v[78:81]
	s_setprio 0
	s_setprio 1
	v_mfma_f32_16x16x32_bf16 v[118:121], v[150:153], v[180:183], 0
	v_mfma_f32_16x16x32_bf16 v[118:121], v[168:171], v[184:187], v[118:121]
	v_mfma_f32_16x16x32_bf16 v[114:117], v[172:175], v[180:183], 0
	v_mfma_f32_16x16x32_bf16 v[114:117], v[176:179], v[184:187], v[114:117]
	v_mfma_f32_16x16x32_bf16 v[98:101], v[172:175], v[188:191], 0
	v_mfma_f32_16x16x32_bf16 v[98:101], v[176:179], v[192:195], v[98:101]
	v_mfma_f32_16x16x32_bf16 v[102:105], v[150:153], v[188:191], 0
	v_mfma_f32_16x16x32_bf16 v[102:105], v[168:171], v[192:195], v[102:105]
	v_mfma_f32_16x16x32_bf16 v[86:89], v[150:153], v[196:199], 0
	v_mfma_f32_16x16x32_bf16 v[86:89], v[168:171], v[200:203], v[86:89]
	v_mfma_f32_16x16x32_bf16 v[82:85], v[172:175], v[196:199], 0
	v_mfma_f32_16x16x32_bf16 v[82:85], v[176:179], v[200:203], v[82:85]
	v_mfma_f32_16x16x32_bf16 v[66:69], v[172:175], v[204:207], 0
	v_mfma_f32_16x16x32_bf16 v[66:69], v[176:179], v[208:211], v[66:69]
	s_setprio 2
	s_barrier
	v_mfma_f32_16x16x32_bf16 v[70:73], v[150:153], v[204:207], 0
	v_mfma_f32_16x16x32_bf16 v[70:73], v[168:171], v[208:211], v[70:73]
	s_setprio 0
	ds_read_b128 v[180:183], v163 offset:16384
	ds_read_b128 v[184:187], v163 offset:17408
	ds_read_b128 v[188:191], v163 offset:18432
	ds_read_b128 v[192:195], v163 offset:19456
	ds_read_b128 v[196:199], v163 offset:20480
	ds_read_b128 v[200:203], v163 offset:21504
	ds_read_b128 v[204:207], v163 offset:22528
	ds_read_b128 v[208:211], v163 offset:23552
	s_mov_b32 s75, m0
	s_mov_b32 m0, s43
	s_nop 0
	global_load_lds_dwordx4 v156, s[10:11]
	s_mov_b32 m0, s75
	s_add_u32 s76, s10, 0x80000
	s_mov_b32 s75, m0
	s_mov_b32 m0, s46
	s_nop 0
	global_load_lds_dwordx4 v158, s[10:11]
	s_mov_b32 m0, s75
	s_addc_u32 s77, s11, 0
	s_mov_b32 s75, m0
	s_mov_b32 m0, s47
	s_nop 0
	global_load_lds_dwordx4 v156, s[76:77]
	s_mov_b32 m0, s75
	s_nop 0
	s_mov_b32 s75, m0
	s_mov_b32 m0, s48
	s_nop 0
	global_load_lds_dwordx4 v158, s[76:77]
	s_mov_b32 m0, s75
	s_waitcnt vmcnt(4)
	s_waitcnt lgkmcnt(0)
	s_barrier
	s_setprio 1
	s_waitcnt lgkmcnt(7)
	v_mfma_f32_16x16x32_bf16 v[62:65], v[130:133], v[180:183], 0
	v_mfma_f32_16x16x32_bf16 v[62:65], v[138:141], v[184:187], v[62:65]
	s_waitcnt lgkmcnt(5)
	v_mfma_f32_16x16x32_bf16 v[58:61], v[142:145], v[180:183], 0
	v_mfma_f32_16x16x32_bf16 v[58:61], v[146:149], v[184:187], v[58:61]
	s_waitcnt lgkmcnt(3)
	v_mfma_f32_16x16x32_bf16 v[42:45], v[142:145], v[188:191], 0
	v_mfma_f32_16x16x32_bf16 v[42:45], v[146:149], v[192:195], v[42:45]
	s_waitcnt lgkmcnt(1)
	v_mfma_f32_16x16x32_bf16 v[46:49], v[130:133], v[188:191], 0
	v_mfma_f32_16x16x32_bf16 v[46:49], v[138:141], v[192:195], v[46:49]
	v_mfma_f32_16x16x32_bf16 v[30:33], v[130:133], v[196:199], 0
	v_mfma_f32_16x16x32_bf16 v[30:33], v[138:141], v[200:203], v[30:33]
	v_mfma_f32_16x16x32_bf16 v[26:29], v[142:145], v[196:199], 0
	v_mfma_f32_16x16x32_bf16 v[26:29], v[146:149], v[200:203], v[26:29]
	v_mfma_f32_16x16x32_bf16 v[10:13], v[142:145], v[204:207], 0
	v_mfma_f32_16x16x32_bf16 v[10:13], v[146:149], v[208:211], v[10:13]
	s_waitcnt lgkmcnt(0)
	v_mfma_f32_16x16x32_bf16 v[14:17], v[130:133], v[204:207], 0
	v_mfma_f32_16x16x32_bf16 v[14:17], v[138:141], v[208:211], v[14:17]
	s_setprio 0
	s_setprio 1
	v_mfma_f32_16x16x32_bf16 v[54:57], v[150:153], v[180:183], 0
	v_mfma_f32_16x16x32_bf16 v[54:57], v[168:171], v[184:187], v[54:57]
	v_mfma_f32_16x16x32_bf16 v[50:53], v[172:175], v[180:183], 0
	v_mfma_f32_16x16x32_bf16 v[50:53], v[176:179], v[184:187], v[50:53]
	v_mfma_f32_16x16x32_bf16 v[34:37], v[172:175], v[188:191], 0
	v_mfma_f32_16x16x32_bf16 v[34:37], v[176:179], v[192:195], v[34:37]
	v_mfma_f32_16x16x32_bf16 v[38:41], v[150:153], v[188:191], 0
	v_mfma_f32_16x16x32_bf16 v[38:41], v[168:171], v[192:195], v[38:41]
	v_mfma_f32_16x16x32_bf16 v[22:25], v[150:153], v[196:199], 0
	v_mfma_f32_16x16x32_bf16 v[22:25], v[168:171], v[200:203], v[22:25]
	v_mfma_f32_16x16x32_bf16 v[18:21], v[172:175], v[196:199], 0
	v_mfma_f32_16x16x32_bf16 v[18:21], v[176:179], v[200:203], v[18:21]
	v_mfma_f32_16x16x32_bf16 v[2:5], v[172:175], v[204:207], 0
	v_mfma_f32_16x16x32_bf16 v[2:5], v[176:179], v[208:211], v[2:5]
	s_setprio 2
	s_barrier
	v_mfma_f32_16x16x32_bf16 v[6:9], v[150:153], v[204:207], 0
	v_mfma_f32_16x16x32_bf16 v[6:9], v[168:171], v[208:211], v[6:9]
	s_setprio 0
	ds_read_b128 v[130:133], v164
	ds_read_b128 v[138:141], v164 offset:1024
	ds_read_b128 v[142:145], v164 offset:2048
	ds_read_b128 v[146:149], v164 offset:3072
	ds_read_b128 v[150:153], v165
	ds_read_b128 v[168:171], v165 offset:1024
	ds_read_b128 v[172:175], v165 offset:2048
	ds_read_b128 v[176:179], v165 offset:3072
	ds_read_b128 v[180:183], v163 offset:32768
	ds_read_b128 v[184:187], v163 offset:33792
	ds_read_b128 v[188:191], v163 offset:34816
	ds_read_b128 v[192:195], v163 offset:35840
	ds_read_b128 v[196:199], v163 offset:36864
	ds_read_b128 v[200:203], v163 offset:37888
	ds_read_b128 v[204:207], v163 offset:38912
	ds_read_b128 v[208:211], v163 offset:39936
	s_mov_b32 s75, m0
	s_mov_b32 m0, s42
	s_nop 0
	global_load_lds_dwordx4 v1, s[28:29]
	s_mov_b32 m0, s75
	s_nop 0
	s_mov_b32 s75, m0
	s_mov_b32 m0, s49
	s_nop 0
	global_load_lds_dwordx4 v157, s[28:29]
	s_mov_b32 m0, s75
	s_add_u32 s28, s28, 0x80000
	s_addc_u32 s29, s29, 0
	s_mov_b32 s75, m0
	s_mov_b32 m0, s56
	s_nop 0
	global_load_lds_dwordx4 v1, s[28:29]
	s_mov_b32 m0, s75
	s_nop 0
	s_mov_b32 s75, m0
	s_mov_b32 m0, s57
	s_nop 0
	global_load_lds_dwordx4 v157, s[28:29]
	s_mov_b32 m0, s75
	s_waitcnt vmcnt(8)
	s_waitcnt lgkmcnt(0)
	s_barrier
	s_setprio 1
	s_waitcnt lgkmcnt(7)
	v_mfma_f32_16x16x32_bf16 v[126:129], v[130:133], v[180:183], v[126:129]
	v_mfma_f32_16x16x32_bf16 v[126:129], v[138:141], v[184:187], v[126:129]
	s_waitcnt lgkmcnt(5)
	v_mfma_f32_16x16x32_bf16 v[122:125], v[142:145], v[180:183], v[122:125]
	v_mfma_f32_16x16x32_bf16 v[122:125], v[146:149], v[184:187], v[122:125]
	s_waitcnt lgkmcnt(3)
	v_mfma_f32_16x16x32_bf16 v[106:109], v[142:145], v[188:191], v[106:109]
	v_mfma_f32_16x16x32_bf16 v[106:109], v[146:149], v[192:195], v[106:109]
	s_waitcnt lgkmcnt(1)
	v_mfma_f32_16x16x32_bf16 v[110:113], v[130:133], v[188:191], v[110:113]
	v_mfma_f32_16x16x32_bf16 v[110:113], v[138:141], v[192:195], v[110:113]
	v_mfma_f32_16x16x32_bf16 v[94:97], v[130:133], v[196:199], v[94:97]
	v_mfma_f32_16x16x32_bf16 v[94:97], v[138:141], v[200:203], v[94:97]
	v_mfma_f32_16x16x32_bf16 v[90:93], v[142:145], v[196:199], v[90:93]
	v_mfma_f32_16x16x32_bf16 v[90:93], v[146:149], v[200:203], v[90:93]
	v_mfma_f32_16x16x32_bf16 v[74:77], v[142:145], v[204:207], v[74:77]
	v_mfma_f32_16x16x32_bf16 v[74:77], v[146:149], v[208:211], v[74:77]
	s_waitcnt lgkmcnt(0)
	v_mfma_f32_16x16x32_bf16 v[78:81], v[130:133], v[204:207], v[78:81]
	v_mfma_f32_16x16x32_bf16 v[78:81], v[138:141], v[208:211], v[78:81]
	s_setprio 0
	s_setprio 1
	v_mfma_f32_16x16x32_bf16 v[118:121], v[150:153], v[180:183], v[118:121]
	v_mfma_f32_16x16x32_bf16 v[118:121], v[168:171], v[184:187], v[118:121]
	v_mfma_f32_16x16x32_bf16 v[114:117], v[172:175], v[180:183], v[114:117]
	v_mfma_f32_16x16x32_bf16 v[114:117], v[176:179], v[184:187], v[114:117]
	v_mfma_f32_16x16x32_bf16 v[98:101], v[172:175], v[188:191], v[98:101]
	v_mfma_f32_16x16x32_bf16 v[98:101], v[176:179], v[192:195], v[98:101]
	v_mfma_f32_16x16x32_bf16 v[102:105], v[150:153], v[188:191], v[102:105]
	v_mfma_f32_16x16x32_bf16 v[102:105], v[168:171], v[192:195], v[102:105]
	v_mfma_f32_16x16x32_bf16 v[86:89], v[150:153], v[196:199], v[86:89]
	v_mfma_f32_16x16x32_bf16 v[86:89], v[168:171], v[200:203], v[86:89]
	v_mfma_f32_16x16x32_bf16 v[82:85], v[172:175], v[196:199], v[82:85]
	v_mfma_f32_16x16x32_bf16 v[82:85], v[176:179], v[200:203], v[82:85]
	v_mfma_f32_16x16x32_bf16 v[66:69], v[172:175], v[204:207], v[66:69]
	v_mfma_f32_16x16x32_bf16 v[66:69], v[176:179], v[208:211], v[66:69]
	s_setprio 2
	s_barrier
	v_mfma_f32_16x16x32_bf16 v[70:73], v[150:153], v[204:207], v[70:73]
	v_mfma_f32_16x16x32_bf16 v[70:73], v[168:171], v[208:211], v[70:73]
	s_setprio 0
	ds_read_b128 v[180:183], v163 offset:49152
	ds_read_b128 v[184:187], v163 offset:50176
	ds_read_b128 v[188:191], v163 offset:51200
	ds_read_b128 v[192:195], v163 offset:52224
	ds_read_b128 v[196:199], v163 offset:53248
	ds_read_b128 v[200:203], v163 offset:54272
	ds_read_b128 v[204:207], v163 offset:55296
	ds_read_b128 v[208:211], v163 offset:56320
	s_add_u32 s28, s10, 0x80
	s_addc_u32 s29, s11, 0
	s_mov_b32 s75, m0
	s_mov_b32 m0, s64
	s_nop 0
	global_load_lds_dwordx4 v156, s[28:29]
	s_mov_b32 m0, s75
	s_add_u32 s10, s10, 0x80080
	s_mov_b32 s75, m0
	s_mov_b32 m0, s65
	s_nop 0
	global_load_lds_dwordx4 v158, s[28:29]
	s_mov_b32 m0, s75
	s_addc_u32 s11, s11, 0
	s_mov_b32 s28, m0
	s_mov_b32 m0, s66
	s_nop 0
	global_load_lds_dwordx4 v156, s[10:11]
	s_mov_b32 m0, s28
	s_nop 0
	s_mov_b32 s28, m0
	s_mov_b32 m0, s67
	s_nop 0
	global_load_lds_dwordx4 v158, s[10:11]
	s_mov_b32 m0, s28
	s_waitcnt vmcnt(4)
	s_waitcnt lgkmcnt(0)
	s_barrier
	s_setprio 1
	s_waitcnt lgkmcnt(7)
	v_mfma_f32_16x16x32_bf16 v[62:65], v[130:133], v[180:183], v[62:65]
	v_mfma_f32_16x16x32_bf16 v[62:65], v[138:141], v[184:187], v[62:65]
	s_waitcnt lgkmcnt(5)
	v_mfma_f32_16x16x32_bf16 v[58:61], v[142:145], v[180:183], v[58:61]
	v_mfma_f32_16x16x32_bf16 v[58:61], v[146:149], v[184:187], v[58:61]
	s_waitcnt lgkmcnt(3)
	v_mfma_f32_16x16x32_bf16 v[42:45], v[142:145], v[188:191], v[42:45]
	v_mfma_f32_16x16x32_bf16 v[42:45], v[146:149], v[192:195], v[42:45]
	s_waitcnt lgkmcnt(1)
	v_mfma_f32_16x16x32_bf16 v[46:49], v[130:133], v[188:191], v[46:49]
	v_mfma_f32_16x16x32_bf16 v[46:49], v[138:141], v[192:195], v[46:49]
	v_mfma_f32_16x16x32_bf16 v[30:33], v[130:133], v[196:199], v[30:33]
	v_mfma_f32_16x16x32_bf16 v[30:33], v[138:141], v[200:203], v[30:33]
	v_mfma_f32_16x16x32_bf16 v[26:29], v[142:145], v[196:199], v[26:29]
	v_mfma_f32_16x16x32_bf16 v[26:29], v[146:149], v[200:203], v[26:29]
	v_mfma_f32_16x16x32_bf16 v[10:13], v[142:145], v[204:207], v[10:13]
	v_mfma_f32_16x16x32_bf16 v[10:13], v[146:149], v[208:211], v[10:13]
	s_waitcnt lgkmcnt(0)
	v_mfma_f32_16x16x32_bf16 v[14:17], v[130:133], v[204:207], v[14:17]
	v_mfma_f32_16x16x32_bf16 v[14:17], v[138:141], v[208:211], v[14:17]
	s_setprio 0
	s_setprio 1
	v_mfma_f32_16x16x32_bf16 v[54:57], v[150:153], v[180:183], v[54:57]
	v_mfma_f32_16x16x32_bf16 v[54:57], v[168:171], v[184:187], v[54:57]
	v_mfma_f32_16x16x32_bf16 v[50:53], v[172:175], v[180:183], v[50:53]
	v_mfma_f32_16x16x32_bf16 v[50:53], v[176:179], v[184:187], v[50:53]
	v_mfma_f32_16x16x32_bf16 v[34:37], v[172:175], v[188:191], v[34:37]
	v_mfma_f32_16x16x32_bf16 v[34:37], v[176:179], v[192:195], v[34:37]
	v_mfma_f32_16x16x32_bf16 v[38:41], v[150:153], v[188:191], v[38:41]
	v_mfma_f32_16x16x32_bf16 v[38:41], v[168:171], v[192:195], v[38:41]
	v_mfma_f32_16x16x32_bf16 v[22:25], v[150:153], v[196:199], v[22:25]
	v_mfma_f32_16x16x32_bf16 v[22:25], v[168:171], v[200:203], v[22:25]
	v_mfma_f32_16x16x32_bf16 v[18:21], v[172:175], v[196:199], v[18:21]
	v_mfma_f32_16x16x32_bf16 v[18:21], v[176:179], v[200:203], v[18:21]
	v_mfma_f32_16x16x32_bf16 v[2:5], v[172:175], v[204:207], v[2:5]
	v_mfma_f32_16x16x32_bf16 v[2:5], v[176:179], v[208:211], v[2:5]
	s_setprio 2
	s_barrier
	v_mfma_f32_16x16x32_bf16 v[6:9], v[150:153], v[204:207], v[6:9]
	v_mfma_f32_16x16x32_bf16 v[6:9], v[168:171], v[208:211], v[6:9]
	s_setprio 0
	s_add_i32 s74, s74, 2
	s_add_u32 s30, s30, 0x100
	s_addc_u32 s31, s31, 0
	s_add_u32 s4, s4, 0x100
	s_addc_u32 s5, s5, 0
	s_add_u32 s33, s33, 0x100
	s_addc_u32 s73, s73, 0
	s_cmp_gt_u32 s74, 29
	.p2align 6
.LBB0_654:
	ds_read_b128 v[130:133], v161
	ds_read_b128 v[138:141], v161 offset:1024
	ds_read_b128 v[142:145], v161 offset:2048
	ds_read_b128 v[146:149], v161 offset:3072
	ds_read_b128 v[150:153], v162
	ds_read_b128 v[168:171], v162 offset:1024
	ds_read_b128 v[172:175], v162 offset:2048
	ds_read_b128 v[176:179], v162 offset:3072
	s_cmp_eq_u32 s74, 28
	s_cselect_b32 s11, s21, s31
	s_cselect_b32 s10, s23, s30
	s_cselect_b32 s29, s7, s73
	s_cselect_b32 s28, s9, s33
	ds_read_b128 v[180:183], v163
	ds_read_b128 v[184:187], v163 offset:1024
	ds_read_b128 v[188:191], v163 offset:2048
	ds_read_b128 v[192:195], v163 offset:3072
	ds_read_b128 v[196:199], v163 offset:4096
	ds_read_b128 v[200:203], v163 offset:5120
	ds_read_b128 v[204:207], v163 offset:6144
	ds_read_b128 v[208:211], v163 offset:7168
	s_add_u32 s76, s4, 0xfff80000
	s_addc_u32 s77, s5, -1
	s_mov_b32 s75, m0
	s_mov_b32 m0, s80
	s_nop 0
	global_load_lds_dwordx4 v1, s[76:77]
	s_mov_b32 m0, s75
	s_nop 0
	s_mov_b32 s75, m0
	s_mov_b32 m0, s82
	s_nop 0
	global_load_lds_dwordx4 v157, s[76:77]
	s_mov_b32 m0, s75
	s_nop 0
	s_mov_b32 s75, m0
	s_mov_b32 m0, s81
	s_nop 0
	global_load_lds_dwordx4 v1, s[4:5]
	s_mov_b32 m0, s75
	s_nop 0
	s_mov_b32 s75, m0
	s_mov_b32 m0, s83
	s_nop 0
	global_load_lds_dwordx4 v157, s[4:5]
	s_mov_b32 m0, s75
	s_waitcnt vmcnt(8)
	s_waitcnt lgkmcnt(0)
	s_barrier
	s_setprio 1
	s_waitcnt lgkmcnt(7)
	v_mfma_f32_16x16x32_bf16 v[126:129], v[130:133], v[180:183], v[126:129]
	v_mfma_f32_16x16x32_bf16 v[126:129], v[138:141], v[184:187], v[126:129]
	s_waitcnt lgkmcnt(5)
	v_mfma_f32_16x16x32_bf16 v[122:125], v[142:145], v[180:183], v[122:125]
	v_mfma_f32_16x16x32_bf16 v[122:125], v[146:149], v[184:187], v[122:125]
	s_waitcnt lgkmcnt(3)
	v_mfma_f32_16x16x32_bf16 v[106:109], v[142:145], v[188:191], v[106:109]
	v_mfma_f32_16x16x32_bf16 v[106:109], v[146:149], v[192:195], v[106:109]
	s_waitcnt lgkmcnt(1)
	v_mfma_f32_16x16x32_bf16 v[110:113], v[130:133], v[188:191], v[110:113]
	v_mfma_f32_16x16x32_bf16 v[110:113], v[138:141], v[192:195], v[110:113]
	v_mfma_f32_16x16x32_bf16 v[94:97], v[130:133], v[196:199], v[94:97]
	v_mfma_f32_16x16x32_bf16 v[94:97], v[138:141], v[200:203], v[94:97]
	v_mfma_f32_16x16x32_bf16 v[90:93], v[142:145], v[196:199], v[90:93]
	v_mfma_f32_16x16x32_bf16 v[90:93], v[146:149], v[200:203], v[90:93]
	v_mfma_f32_16x16x32_bf16 v[74:77], v[142:145], v[204:207], v[74:77]
	v_mfma_f32_16x16x32_bf16 v[74:77], v[146:149], v[208:211], v[74:77]
	s_waitcnt lgkmcnt(0)
	v_mfma_f32_16x16x32_bf16 v[78:81], v[130:133], v[204:207], v[78:81]
	v_mfma_f32_16x16x32_bf16 v[78:81], v[138:141], v[208:211], v[78:81]
	s_setprio 0
	s_setprio 1
	v_mfma_f32_16x16x32_bf16 v[118:121], v[150:153], v[180:183], v[118:121]
	v_mfma_f32_16x16x32_bf16 v[118:121], v[168:171], v[184:187], v[118:121]
	v_mfma_f32_16x16x32_bf16 v[114:117], v[172:175], v[180:183], v[114:117]
	v_mfma_f32_16x16x32_bf16 v[114:117], v[176:179], v[184:187], v[114:117]
	v_mfma_f32_16x16x32_bf16 v[98:101], v[172:175], v[188:191], v[98:101]
	v_mfma_f32_16x16x32_bf16 v[98:101], v[176:179], v[192:195], v[98:101]
	v_mfma_f32_16x16x32_bf16 v[102:105], v[150:153], v[188:191], v[102:105]
	v_mfma_f32_16x16x32_bf16 v[102:105], v[168:171], v[192:195], v[102:105]
	v_mfma_f32_16x16x32_bf16 v[86:89], v[150:153], v[196:199], v[86:89]
	v_mfma_f32_16x16x32_bf16 v[86:89], v[168:171], v[200:203], v[86:89]
	v_mfma_f32_16x16x32_bf16 v[82:85], v[172:175], v[196:199], v[82:85]
	v_mfma_f32_16x16x32_bf16 v[82:85], v[176:179], v[200:203], v[82:85]
	v_mfma_f32_16x16x32_bf16 v[66:69], v[172:175], v[204:207], v[66:69]
	v_mfma_f32_16x16x32_bf16 v[66:69], v[176:179], v[208:211], v[66:69]
	s_setprio 2
	s_barrier
	v_mfma_f32_16x16x32_bf16 v[70:73], v[150:153], v[204:207], v[70:73]
	v_mfma_f32_16x16x32_bf16 v[70:73], v[168:171], v[208:211], v[70:73]
	s_setprio 0
	ds_read_b128 v[180:183], v163 offset:16384
	ds_read_b128 v[184:187], v163 offset:17408
	ds_read_b128 v[188:191], v163 offset:18432
	ds_read_b128 v[192:195], v163 offset:19456
	ds_read_b128 v[196:199], v163 offset:20480
	ds_read_b128 v[200:203], v163 offset:21504
	ds_read_b128 v[204:207], v163 offset:22528
	ds_read_b128 v[208:211], v163 offset:23552
	s_mov_b32 s75, m0
	s_mov_b32 m0, s43
	s_nop 0
	global_load_lds_dwordx4 v156, s[10:11]
	s_mov_b32 m0, s75
	s_add_u32 s76, s10, 0x80000
	s_mov_b32 s75, m0
	s_mov_b32 m0, s46
	s_nop 0
	global_load_lds_dwordx4 v158, s[10:11]
	s_mov_b32 m0, s75
	s_addc_u32 s77, s11, 0
	s_mov_b32 s75, m0
	s_mov_b32 m0, s47
	s_nop 0
	global_load_lds_dwordx4 v156, s[76:77]
	s_mov_b32 m0, s75
	s_nop 0
	s_mov_b32 s75, m0
	s_mov_b32 m0, s48
	s_nop 0
	global_load_lds_dwordx4 v158, s[76:77]
	s_mov_b32 m0, s75
	s_waitcnt vmcnt(4)
	s_waitcnt lgkmcnt(0)
	s_barrier
	s_setprio 1
	s_waitcnt lgkmcnt(7)
	v_mfma_f32_16x16x32_bf16 v[62:65], v[130:133], v[180:183], v[62:65]
	v_mfma_f32_16x16x32_bf16 v[62:65], v[138:141], v[184:187], v[62:65]
	s_waitcnt lgkmcnt(5)
	v_mfma_f32_16x16x32_bf16 v[58:61], v[142:145], v[180:183], v[58:61]
	v_mfma_f32_16x16x32_bf16 v[58:61], v[146:149], v[184:187], v[58:61]
	s_waitcnt lgkmcnt(3)
	v_mfma_f32_16x16x32_bf16 v[42:45], v[142:145], v[188:191], v[42:45]
	v_mfma_f32_16x16x32_bf16 v[42:45], v[146:149], v[192:195], v[42:45]
	s_waitcnt lgkmcnt(1)
	v_mfma_f32_16x16x32_bf16 v[46:49], v[130:133], v[188:191], v[46:49]
	v_mfma_f32_16x16x32_bf16 v[46:49], v[138:141], v[192:195], v[46:49]
	v_mfma_f32_16x16x32_bf16 v[30:33], v[130:133], v[196:199], v[30:33]
	v_mfma_f32_16x16x32_bf16 v[30:33], v[138:141], v[200:203], v[30:33]
	v_mfma_f32_16x16x32_bf16 v[26:29], v[142:145], v[196:199], v[26:29]
	v_mfma_f32_16x16x32_bf16 v[26:29], v[146:149], v[200:203], v[26:29]
	v_mfma_f32_16x16x32_bf16 v[10:13], v[142:145], v[204:207], v[10:13]
	v_mfma_f32_16x16x32_bf16 v[10:13], v[146:149], v[208:211], v[10:13]
	s_waitcnt lgkmcnt(0)
	v_mfma_f32_16x16x32_bf16 v[14:17], v[130:133], v[204:207], v[14:17]
	v_mfma_f32_16x16x32_bf16 v[14:17], v[138:141], v[208:211], v[14:17]
	s_setprio 0
	s_setprio 1
	v_mfma_f32_16x16x32_bf16 v[54:57], v[150:153], v[180:183], v[54:57]
	v_mfma_f32_16x16x32_bf16 v[54:57], v[168:171], v[184:187], v[54:57]
	v_mfma_f32_16x16x32_bf16 v[50:53], v[172:175], v[180:183], v[50:53]
	v_mfma_f32_16x16x32_bf16 v[50:53], v[176:179], v[184:187], v[50:53]
	v_mfma_f32_16x16x32_bf16 v[34:37], v[172:175], v[188:191], v[34:37]
	v_mfma_f32_16x16x32_bf16 v[34:37], v[176:179], v[192:195], v[34:37]
	v_mfma_f32_16x16x32_bf16 v[38:41], v[150:153], v[188:191], v[38:41]
	v_mfma_f32_16x16x32_bf16 v[38:41], v[168:171], v[192:195], v[38:41]
	v_mfma_f32_16x16x32_bf16 v[22:25], v[150:153], v[196:199], v[22:25]
	v_mfma_f32_16x16x32_bf16 v[22:25], v[168:171], v[200:203], v[22:25]
	v_mfma_f32_16x16x32_bf16 v[18:21], v[172:175], v[196:199], v[18:21]
	v_mfma_f32_16x16x32_bf16 v[18:21], v[176:179], v[200:203], v[18:21]
	v_mfma_f32_16x16x32_bf16 v[2:5], v[172:175], v[204:207], v[2:5]
	v_mfma_f32_16x16x32_bf16 v[2:5], v[176:179], v[208:211], v[2:5]
	s_setprio 2
	s_barrier
	v_mfma_f32_16x16x32_bf16 v[6:9], v[150:153], v[204:207], v[6:9]
	v_mfma_f32_16x16x32_bf16 v[6:9], v[168:171], v[208:211], v[6:9]
	s_setprio 0
	ds_read_b128 v[130:133], v164
	ds_read_b128 v[138:141], v164 offset:1024
	ds_read_b128 v[142:145], v164 offset:2048
	ds_read_b128 v[146:149], v164 offset:3072
	ds_read_b128 v[150:153], v165
	ds_read_b128 v[168:171], v165 offset:1024
	ds_read_b128 v[172:175], v165 offset:2048
	ds_read_b128 v[176:179], v165 offset:3072
	ds_read_b128 v[180:183], v163 offset:32768
	ds_read_b128 v[184:187], v163 offset:33792
	ds_read_b128 v[188:191], v163 offset:34816
	ds_read_b128 v[192:195], v163 offset:35840
	ds_read_b128 v[196:199], v163 offset:36864
	ds_read_b128 v[200:203], v163 offset:37888
	ds_read_b128 v[204:207], v163 offset:38912
	ds_read_b128 v[208:211], v163 offset:39936
	s_mov_b32 s75, m0
	s_mov_b32 m0, s42
	s_nop 0
	global_load_lds_dwordx4 v1, s[28:29]
	s_mov_b32 m0, s75
	s_nop 0
	s_mov_b32 s75, m0
	s_mov_b32 m0, s49
	s_nop 0
	global_load_lds_dwordx4 v157, s[28:29]
	s_mov_b32 m0, s75
	s_add_u32 s28, s28, 0x80000
	s_addc_u32 s29, s29, 0
	s_mov_b32 s75, m0
	s_mov_b32 m0, s56
	s_nop 0
	global_load_lds_dwordx4 v1, s[28:29]
	s_mov_b32 m0, s75
	s_nop 0
	s_mov_b32 s75, m0
	s_mov_b32 m0, s57
	s_nop 0
	global_load_lds_dwordx4 v157, s[28:29]
	s_mov_b32 m0, s75
	s_waitcnt vmcnt(8)
	s_waitcnt lgkmcnt(0)
	s_barrier
	s_setprio 1
	s_waitcnt lgkmcnt(7)
	v_mfma_f32_16x16x32_bf16 v[126:129], v[130:133], v[180:183], v[126:129]
	v_mfma_f32_16x16x32_bf16 v[126:129], v[138:141], v[184:187], v[126:129]
	s_waitcnt lgkmcnt(5)
	v_mfma_f32_16x16x32_bf16 v[122:125], v[142:145], v[180:183], v[122:125]
	v_mfma_f32_16x16x32_bf16 v[122:125], v[146:149], v[184:187], v[122:125]
	s_waitcnt lgkmcnt(3)
	v_mfma_f32_16x16x32_bf16 v[106:109], v[142:145], v[188:191], v[106:109]
	v_mfma_f32_16x16x32_bf16 v[106:109], v[146:149], v[192:195], v[106:109]
	s_waitcnt lgkmcnt(1)
	v_mfma_f32_16x16x32_bf16 v[110:113], v[130:133], v[188:191], v[110:113]
	v_mfma_f32_16x16x32_bf16 v[110:113], v[138:141], v[192:195], v[110:113]
	v_mfma_f32_16x16x32_bf16 v[94:97], v[130:133], v[196:199], v[94:97]
	v_mfma_f32_16x16x32_bf16 v[94:97], v[138:141], v[200:203], v[94:97]
	v_mfma_f32_16x16x32_bf16 v[90:93], v[142:145], v[196:199], v[90:93]
	v_mfma_f32_16x16x32_bf16 v[90:93], v[146:149], v[200:203], v[90:93]
	v_mfma_f32_16x16x32_bf16 v[74:77], v[142:145], v[204:207], v[74:77]
	v_mfma_f32_16x16x32_bf16 v[74:77], v[146:149], v[208:211], v[74:77]
	s_waitcnt lgkmcnt(0)
	v_mfma_f32_16x16x32_bf16 v[78:81], v[130:133], v[204:207], v[78:81]
	v_mfma_f32_16x16x32_bf16 v[78:81], v[138:141], v[208:211], v[78:81]
	s_setprio 0
	s_setprio 1
	v_mfma_f32_16x16x32_bf16 v[118:121], v[150:153], v[180:183], v[118:121]
	v_mfma_f32_16x16x32_bf16 v[118:121], v[168:171], v[184:187], v[118:121]
	v_mfma_f32_16x16x32_bf16 v[114:117], v[172:175], v[180:183], v[114:117]
	v_mfma_f32_16x16x32_bf16 v[114:117], v[176:179], v[184:187], v[114:117]
	v_mfma_f32_16x16x32_bf16 v[98:101], v[172:175], v[188:191], v[98:101]
	v_mfma_f32_16x16x32_bf16 v[98:101], v[176:179], v[192:195], v[98:101]
	v_mfma_f32_16x16x32_bf16 v[102:105], v[150:153], v[188:191], v[102:105]
	v_mfma_f32_16x16x32_bf16 v[102:105], v[168:171], v[192:195], v[102:105]
	v_mfma_f32_16x16x32_bf16 v[86:89], v[150:153], v[196:199], v[86:89]
	v_mfma_f32_16x16x32_bf16 v[86:89], v[168:171], v[200:203], v[86:89]
	v_mfma_f32_16x16x32_bf16 v[82:85], v[172:175], v[196:199], v[82:85]
	v_mfma_f32_16x16x32_bf16 v[82:85], v[176:179], v[200:203], v[82:85]
	v_mfma_f32_16x16x32_bf16 v[66:69], v[172:175], v[204:207], v[66:69]
	v_mfma_f32_16x16x32_bf16 v[66:69], v[176:179], v[208:211], v[66:69]
	s_setprio 2
	s_barrier
	v_mfma_f32_16x16x32_bf16 v[70:73], v[150:153], v[204:207], v[70:73]
	v_mfma_f32_16x16x32_bf16 v[70:73], v[168:171], v[208:211], v[70:73]
	s_setprio 0
	ds_read_b128 v[180:183], v163 offset:49152
	ds_read_b128 v[184:187], v163 offset:50176
	ds_read_b128 v[188:191], v163 offset:51200
	ds_read_b128 v[192:195], v163 offset:52224
	ds_read_b128 v[196:199], v163 offset:53248
	ds_read_b128 v[200:203], v163 offset:54272
	ds_read_b128 v[204:207], v163 offset:55296
	ds_read_b128 v[208:211], v163 offset:56320
	s_add_u32 s28, s10, 0x80
	s_addc_u32 s29, s11, 0
	s_mov_b32 s75, m0
	s_mov_b32 m0, s64
	s_nop 0
	global_load_lds_dwordx4 v156, s[28:29]
	s_mov_b32 m0, s75
	s_add_u32 s10, s10, 0x80080
	s_mov_b32 s75, m0
	s_mov_b32 m0, s65
	s_nop 0
	global_load_lds_dwordx4 v158, s[28:29]
	s_mov_b32 m0, s75
	s_addc_u32 s11, s11, 0
	s_mov_b32 s28, m0
	s_mov_b32 m0, s66
	s_nop 0
	global_load_lds_dwordx4 v156, s[10:11]
	s_mov_b32 m0, s28
	s_nop 0
	s_mov_b32 s28, m0
	s_mov_b32 m0, s67
	s_nop 0
	global_load_lds_dwordx4 v158, s[10:11]
	s_mov_b32 m0, s28
	s_waitcnt vmcnt(4)
	s_waitcnt lgkmcnt(0)
	s_barrier
	s_setprio 1
	s_waitcnt lgkmcnt(7)
	v_mfma_f32_16x16x32_bf16 v[62:65], v[130:133], v[180:183], v[62:65]
	v_mfma_f32_16x16x32_bf16 v[62:65], v[138:141], v[184:187], v[62:65]
	s_waitcnt lgkmcnt(5)
	v_mfma_f32_16x16x32_bf16 v[58:61], v[142:145], v[180:183], v[58:61]
	v_mfma_f32_16x16x32_bf16 v[58:61], v[146:149], v[184:187], v[58:61]
	s_waitcnt lgkmcnt(3)
	v_mfma_f32_16x16x32_bf16 v[42:45], v[142:145], v[188:191], v[42:45]
	v_mfma_f32_16x16x32_bf16 v[42:45], v[146:149], v[192:195], v[42:45]
	s_waitcnt lgkmcnt(1)
	v_mfma_f32_16x16x32_bf16 v[46:49], v[130:133], v[188:191], v[46:49]
	v_mfma_f32_16x16x32_bf16 v[46:49], v[138:141], v[192:195], v[46:49]
	v_mfma_f32_16x16x32_bf16 v[30:33], v[130:133], v[196:199], v[30:33]
	v_mfma_f32_16x16x32_bf16 v[30:33], v[138:141], v[200:203], v[30:33]
	v_mfma_f32_16x16x32_bf16 v[26:29], v[142:145], v[196:199], v[26:29]
	v_mfma_f32_16x16x32_bf16 v[26:29], v[146:149], v[200:203], v[26:29]
	v_mfma_f32_16x16x32_bf16 v[10:13], v[142:145], v[204:207], v[10:13]
	v_mfma_f32_16x16x32_bf16 v[10:13], v[146:149], v[208:211], v[10:13]
	s_waitcnt lgkmcnt(0)
	v_mfma_f32_16x16x32_bf16 v[14:17], v[130:133], v[204:207], v[14:17]
	v_mfma_f32_16x16x32_bf16 v[14:17], v[138:141], v[208:211], v[14:17]
	s_setprio 0
	s_setprio 1
	v_mfma_f32_16x16x32_bf16 v[54:57], v[150:153], v[180:183], v[54:57]
	v_mfma_f32_16x16x32_bf16 v[54:57], v[168:171], v[184:187], v[54:57]
	v_mfma_f32_16x16x32_bf16 v[50:53], v[172:175], v[180:183], v[50:53]
	v_mfma_f32_16x16x32_bf16 v[50:53], v[176:179], v[184:187], v[50:53]
	v_mfma_f32_16x16x32_bf16 v[34:37], v[172:175], v[188:191], v[34:37]
	v_mfma_f32_16x16x32_bf16 v[34:37], v[176:179], v[192:195], v[34:37]
	v_mfma_f32_16x16x32_bf16 v[38:41], v[150:153], v[188:191], v[38:41]
	v_mfma_f32_16x16x32_bf16 v[38:41], v[168:171], v[192:195], v[38:41]
	v_mfma_f32_16x16x32_bf16 v[22:25], v[150:153], v[196:199], v[22:25]
	v_mfma_f32_16x16x32_bf16 v[22:25], v[168:171], v[200:203], v[22:25]
	v_mfma_f32_16x16x32_bf16 v[18:21], v[172:175], v[196:199], v[18:21]
	v_mfma_f32_16x16x32_bf16 v[18:21], v[176:179], v[200:203], v[18:21]
	v_mfma_f32_16x16x32_bf16 v[2:5], v[172:175], v[204:207], v[2:5]
	v_mfma_f32_16x16x32_bf16 v[2:5], v[176:179], v[208:211], v[2:5]
	s_setprio 2
	s_barrier
	v_mfma_f32_16x16x32_bf16 v[6:9], v[150:153], v[204:207], v[6:9]
	v_mfma_f32_16x16x32_bf16 v[6:9], v[168:171], v[208:211], v[6:9]
	s_setprio 0
	s_add_i32 s74, s74, 2
	s_add_u32 s30, s30, 0x100
	s_addc_u32 s31, s31, 0
	s_add_u32 s4, s4, 0x100
	s_addc_u32 s5, s5, 0
	s_add_u32 s33, s33, 0x100
	s_addc_u32 s73, s73, 0
	s_cmp_gt_u32 s74, 29
	s_cbranch_scc0 .LBB0_654
	s_and_b64 vcc, exec, s[18:19]
	s_cbranch_vccz .LBB0_657
	s_barrier

.LBB0_1052:
	s_ashr_i32 s13, s12, 31
	s_lshl_b64 s[14:15], s[12:13], 20
	s_add_u32 s14, s28, s14
	s_addc_u32 s15, s29, s15
	s_and_b64 s[16:17], s[2:3], exec
	s_cselect_b32 s13, s15, s23
	s_cselect_b32 s67, s14, s22
	s_ashr_i32 s11, s10, 31
	s_lshl_b64 s[16:17], s[10:11], 20
	s_add_u32 s16, s30, s16
	s_addc_u32 s17, s31, s17
	s_and_b64 s[24:25], s[2:3], exec
	s_cselect_b32 s11, s17, s21
	s_cselect_b32 s73, s16, s20
	s_add_u32 s74, s20, 0x100
	s_addc_u32 s75, s21, 0
	s_add_u32 s20, s22, 0x80080
	s_addc_u32 s21, s23, 0
	s_add_u32 s76, s22, 0x100
	s_addc_u32 s77, s23, 0
	s_mov_b32 s78, -2
	s_waitcnt vmcnt(25)
	s_waitcnt vmcnt(24)
	s_waitcnt vmcnt(15)
	s_waitcnt vmcnt(14)
	s_waitcnt vmcnt(13)
	s_waitcnt vmcnt(12)
	s_waitcnt vmcnt(11)
	s_waitcnt vmcnt(10)
	s_waitcnt vmcnt(9)
	s_waitcnt vmcnt(8)
	s_waitcnt vmcnt(7)
	s_waitcnt vmcnt(6)
	s_waitcnt vmcnt(5)
	s_waitcnt vmcnt(4)
	s_waitcnt vmcnt(3)
	s_waitcnt vmcnt(2)
	s_waitcnt vmcnt(1)
	s_waitcnt vmcnt(0)
	ds_read_b128 v[130:133], v181
	ds_read_b128 v[134:137], v181 offset:1024
	ds_read_b128 v[138:141], v181 offset:2048
	ds_read_b128 v[142:145], v181 offset:3072
	ds_read_b128 v[146:149], v182
	ds_read_b128 v[150:153], v182 offset:1024
	ds_read_b128 v[154:157], v182 offset:2048
	ds_read_b128 v[158:161], v182 offset:3072
	s_cmp_eq_u32 s78, 28
	s_cselect_b32 s23, s11, s75
	s_cselect_b32 s22, s73, s74
	s_cselect_b32 s25, s13, s77
	s_cselect_b32 s24, s67, s76
	ds_read_b128 v[166:169], v183
	ds_read_b128 v[170:173], v183 offset:1024
	ds_read_b128 v[186:189], v183 offset:2048
	ds_read_b128 v[190:193], v183 offset:3072
	ds_read_b128 v[194:197], v183 offset:4096
	ds_read_b128 v[198:201], v183 offset:5120
	ds_read_b128 v[202:205], v183 offset:6144
	ds_read_b128 v[206:209], v183 offset:7168
	s_add_u32 s80, s20, 0xfff80000
	s_addc_u32 s81, s21, -1
	s_mov_b32 s79, m0
	s_mov_b32 m0, s58
	s_nop 0
	global_load_lds_dwordx4 v1, s[80:81]
	s_mov_b32 m0, s79
	s_nop 0
	s_mov_b32 s79, m0
	s_mov_b32 m0, s64
	s_nop 0
	global_load_lds_dwordx4 v177, s[80:81]
	s_mov_b32 m0, s79
	s_nop 0
	s_mov_b32 s79, m0
	s_mov_b32 m0, s59
	s_nop 0
	global_load_lds_dwordx4 v1, s[20:21]
	s_mov_b32 m0, s79
	s_nop 0
	s_mov_b32 s79, m0
	s_mov_b32 m0, s65
	s_nop 0
	global_load_lds_dwordx4 v177, s[20:21]
	s_mov_b32 m0, s79
	s_waitcnt vmcnt(8)
	s_waitcnt lgkmcnt(0)
	s_barrier
	s_setprio 1
	s_waitcnt lgkmcnt(7)
	v_mfma_f32_16x16x32_bf16 v[126:129], v[130:133], v[166:169], 0
	v_mfma_f32_16x16x32_bf16 v[126:129], v[134:137], v[170:173], v[126:129]
	s_waitcnt lgkmcnt(5)
	v_mfma_f32_16x16x32_bf16 v[122:125], v[138:141], v[166:169], 0
	v_mfma_f32_16x16x32_bf16 v[122:125], v[142:145], v[170:173], v[122:125]
	s_waitcnt lgkmcnt(3)
	v_mfma_f32_16x16x32_bf16 v[114:117], v[138:141], v[186:189], 0
	v_mfma_f32_16x16x32_bf16 v[114:117], v[142:145], v[190:193], v[114:117]
	s_waitcnt lgkmcnt(1)
	v_mfma_f32_16x16x32_bf16 v[118:121], v[130:133], v[186:189], 0
	v_mfma_f32_16x16x32_bf16 v[118:121], v[134:137], v[190:193], v[118:121]
	v_mfma_f32_16x16x32_bf16 v[94:97], v[130:133], v[194:197], 0
	v_mfma_f32_16x16x32_bf16 v[94:97], v[134:137], v[198:201], v[94:97]
	v_mfma_f32_16x16x32_bf16 v[90:93], v[138:141], v[194:197], 0
	v_mfma_f32_16x16x32_bf16 v[90:93], v[142:145], v[198:201], v[90:93]
	v_mfma_f32_16x16x32_bf16 v[78:81], v[138:141], v[202:205], 0
	v_mfma_f32_16x16x32_bf16 v[78:81], v[142:145], v[206:209], v[78:81]
	s_waitcnt lgkmcnt(0)
	v_mfma_f32_16x16x32_bf16 v[86:89], v[130:133], v[202:205], 0
	v_mfma_f32_16x16x32_bf16 v[86:89], v[134:137], v[206:209], v[86:89]
	s_setprio 0
	s_setprio 1
	v_mfma_f32_16x16x32_bf16 v[110:113], v[146:149], v[166:169], 0
	v_mfma_f32_16x16x32_bf16 v[110:113], v[150:153], v[170:173], v[110:113]
	v_mfma_f32_16x16x32_bf16 v[106:109], v[154:157], v[166:169], 0
	v_mfma_f32_16x16x32_bf16 v[106:109], v[158:161], v[170:173], v[106:109]
	v_mfma_f32_16x16x32_bf16 v[98:101], v[154:157], v[186:189], 0
	v_mfma_f32_16x16x32_bf16 v[98:101], v[158:161], v[190:193], v[98:101]
	v_mfma_f32_16x16x32_bf16 v[102:105], v[146:149], v[186:189], 0
	v_mfma_f32_16x16x32_bf16 v[102:105], v[150:153], v[190:193], v[102:105]
	v_mfma_f32_16x16x32_bf16 v[82:85], v[146:149], v[194:197], 0
	v_mfma_f32_16x16x32_bf16 v[82:85], v[150:153], v[198:201], v[82:85]
	v_mfma_f32_16x16x32_bf16 v[74:77], v[154:157], v[194:197], 0
	v_mfma_f32_16x16x32_bf16 v[74:77], v[158:161], v[198:201], v[74:77]
	v_mfma_f32_16x16x32_bf16 v[66:69], v[154:157], v[202:205], 0
	v_mfma_f32_16x16x32_bf16 v[66:69], v[158:161], v[206:209], v[66:69]
	s_setprio 2
	s_barrier
	v_mfma_f32_16x16x32_bf16 v[70:73], v[146:149], v[202:205], 0
	v_mfma_f32_16x16x32_bf16 v[70:73], v[150:153], v[206:209], v[70:73]
	s_setprio 0
	ds_read_b128 v[166:169], v183 offset:16384
	ds_read_b128 v[170:173], v183 offset:17408
	ds_read_b128 v[186:189], v183 offset:18432
	ds_read_b128 v[190:193], v183 offset:19456
	ds_read_b128 v[194:197], v183 offset:20480
	ds_read_b128 v[198:201], v183 offset:21504
	ds_read_b128 v[202:205], v183 offset:22528
	ds_read_b128 v[206:209], v183 offset:23552
	s_mov_b32 s79, m0
	s_mov_b32 m0, s35
	s_nop 0
	global_load_lds_dwordx4 v176, s[22:23]
	s_mov_b32 m0, s79
	s_add_u32 s80, s22, 0x80000
	s_mov_b32 s79, m0
	s_mov_b32 m0, s36
	s_nop 0
	global_load_lds_dwordx4 v178, s[22:23]
	s_mov_b32 m0, s79
	s_addc_u32 s81, s23, 0
	s_mov_b32 s79, m0
	s_mov_b32 m0, s37
	s_nop 0
	global_load_lds_dwordx4 v176, s[80:81]
	s_mov_b32 m0, s79
	s_nop 0
	s_mov_b32 s79, m0
	s_mov_b32 m0, s40
	s_nop 0
	global_load_lds_dwordx4 v178, s[80:81]
	s_mov_b32 m0, s79
	s_waitcnt vmcnt(4)
	s_waitcnt lgkmcnt(0)
	s_barrier
	s_setprio 1
	s_waitcnt lgkmcnt(7)
	v_mfma_f32_16x16x32_bf16 v[62:65], v[130:133], v[166:169], 0
	v_mfma_f32_16x16x32_bf16 v[62:65], v[134:137], v[170:173], v[62:65]
	s_waitcnt lgkmcnt(5)
	v_mfma_f32_16x16x32_bf16 v[58:61], v[138:141], v[166:169], 0
	v_mfma_f32_16x16x32_bf16 v[58:61], v[142:145], v[170:173], v[58:61]
	s_waitcnt lgkmcnt(3)
	v_mfma_f32_16x16x32_bf16 v[42:45], v[138:141], v[186:189], 0
	v_mfma_f32_16x16x32_bf16 v[42:45], v[142:145], v[190:193], v[42:45]
	s_waitcnt lgkmcnt(1)
	v_mfma_f32_16x16x32_bf16 v[46:49], v[130:133], v[186:189], 0
	v_mfma_f32_16x16x32_bf16 v[46:49], v[134:137], v[190:193], v[46:49]
	v_mfma_f32_16x16x32_bf16 v[30:33], v[130:133], v[194:197], 0
	v_mfma_f32_16x16x32_bf16 v[30:33], v[134:137], v[198:201], v[30:33]
	v_mfma_f32_16x16x32_bf16 v[26:29], v[138:141], v[194:197], 0
	v_mfma_f32_16x16x32_bf16 v[26:29], v[142:145], v[198:201], v[26:29]
	v_mfma_f32_16x16x32_bf16 v[10:13], v[138:141], v[202:205], 0
	v_mfma_f32_16x16x32_bf16 v[10:13], v[142:145], v[206:209], v[10:13]
	s_waitcnt lgkmcnt(0)
	v_mfma_f32_16x16x32_bf16 v[14:17], v[130:133], v[202:205], 0
	v_mfma_f32_16x16x32_bf16 v[14:17], v[134:137], v[206:209], v[14:17]
	s_setprio 0
	s_setprio 1
	v_mfma_f32_16x16x32_bf16 v[54:57], v[146:149], v[166:169], 0
	v_mfma_f32_16x16x32_bf16 v[54:57], v[150:153], v[170:173], v[54:57]
	v_mfma_f32_16x16x32_bf16 v[50:53], v[154:157], v[166:169], 0
	v_mfma_f32_16x16x32_bf16 v[50:53], v[158:161], v[170:173], v[50:53]
	v_mfma_f32_16x16x32_bf16 v[34:37], v[154:157], v[186:189], 0
	v_mfma_f32_16x16x32_bf16 v[34:37], v[158:161], v[190:193], v[34:37]
	v_mfma_f32_16x16x32_bf16 v[38:41], v[146:149], v[186:189], 0
	v_mfma_f32_16x16x32_bf16 v[38:41], v[150:153], v[190:193], v[38:41]
	v_mfma_f32_16x16x32_bf16 v[22:25], v[146:149], v[194:197], 0
	v_mfma_f32_16x16x32_bf16 v[22:25], v[150:153], v[198:201], v[22:25]
	v_mfma_f32_16x16x32_bf16 v[18:21], v[154:157], v[194:197], 0
	v_mfma_f32_16x16x32_bf16 v[18:21], v[158:161], v[198:201], v[18:21]
	v_mfma_f32_16x16x32_bf16 v[2:5], v[154:157], v[202:205], 0
	v_mfma_f32_16x16x32_bf16 v[2:5], v[158:161], v[206:209], v[2:5]
	s_setprio 2
	s_barrier
	v_mfma_f32_16x16x32_bf16 v[6:9], v[146:149], v[202:205], 0
	v_mfma_f32_16x16x32_bf16 v[6:9], v[150:153], v[206:209], v[6:9]
	s_setprio 0
	ds_read_b128 v[130:133], v184
	ds_read_b128 v[134:137], v184 offset:1024
	ds_read_b128 v[138:141], v184 offset:2048
	ds_read_b128 v[142:145], v184 offset:3072
	ds_read_b128 v[146:149], v185
	ds_read_b128 v[150:153], v185 offset:1024
	ds_read_b128 v[154:157], v185 offset:2048
	ds_read_b128 v[158:161], v185 offset:3072
	ds_read_b128 v[166:169], v183 offset:32768
	ds_read_b128 v[170:173], v183 offset:33792
	ds_read_b128 v[186:189], v183 offset:34816
	ds_read_b128 v[190:193], v183 offset:35840
	ds_read_b128 v[194:197], v183 offset:36864
	ds_read_b128 v[198:201], v183 offset:37888
	ds_read_b128 v[202:205], v183 offset:38912
	ds_read_b128 v[206:209], v183 offset:39936
	s_mov_b32 s79, m0
	s_mov_b32 m0, s34
	s_nop 0
	global_load_lds_dwordx4 v1, s[24:25]
	s_mov_b32 m0, s79
	s_nop 0
	s_mov_b32 s79, m0
	s_mov_b32 m0, s41
	s_nop 0
	global_load_lds_dwordx4 v177, s[24:25]
	s_mov_b32 m0, s79
	s_add_u32 s24, s24, 0x80000
	s_addc_u32 s25, s25, 0
	s_mov_b32 s79, m0
	s_mov_b32 m0, s42
	s_nop 0
	global_load_lds_dwordx4 v1, s[24:25]
	s_mov_b32 m0, s79
	s_nop 0
	s_mov_b32 s79, m0
	s_mov_b32 m0, s43
	s_nop 0
	global_load_lds_dwordx4 v177, s[24:25]
	s_mov_b32 m0, s79
	s_waitcnt vmcnt(8)
	s_waitcnt lgkmcnt(0)
	s_barrier
	s_setprio 1
	s_waitcnt lgkmcnt(7)
	v_mfma_f32_16x16x32_bf16 v[126:129], v[130:133], v[166:169], v[126:129]
	v_mfma_f32_16x16x32_bf16 v[126:129], v[134:137], v[170:173], v[126:129]
	s_waitcnt lgkmcnt(5)
	v_mfma_f32_16x16x32_bf16 v[122:125], v[138:141], v[166:169], v[122:125]
	v_mfma_f32_16x16x32_bf16 v[122:125], v[142:145], v[170:173], v[122:125]
	s_waitcnt lgkmcnt(3)
	v_mfma_f32_16x16x32_bf16 v[114:117], v[138:141], v[186:189], v[114:117]
	v_mfma_f32_16x16x32_bf16 v[114:117], v[142:145], v[190:193], v[114:117]
	s_waitcnt lgkmcnt(1)
	v_mfma_f32_16x16x32_bf16 v[118:121], v[130:133], v[186:189], v[118:121]
	v_mfma_f32_16x16x32_bf16 v[118:121], v[134:137], v[190:193], v[118:121]
	v_mfma_f32_16x16x32_bf16 v[94:97], v[130:133], v[194:197], v[94:97]
	v_mfma_f32_16x16x32_bf16 v[94:97], v[134:137], v[198:201], v[94:97]
	v_mfma_f32_16x16x32_bf16 v[90:93], v[138:141], v[194:197], v[90:93]
	v_mfma_f32_16x16x32_bf16 v[90:93], v[142:145], v[198:201], v[90:93]
	v_mfma_f32_16x16x32_bf16 v[78:81], v[138:141], v[202:205], v[78:81]
	v_mfma_f32_16x16x32_bf16 v[78:81], v[142:145], v[206:209], v[78:81]
	s_waitcnt lgkmcnt(0)
	v_mfma_f32_16x16x32_bf16 v[86:89], v[130:133], v[202:205], v[86:89]
	v_mfma_f32_16x16x32_bf16 v[86:89], v[134:137], v[206:209], v[86:89]
	s_setprio 0
	s_setprio 1
	v_mfma_f32_16x16x32_bf16 v[110:113], v[146:149], v[166:169], v[110:113]
	v_mfma_f32_16x16x32_bf16 v[110:113], v[150:153], v[170:173], v[110:113]
	v_mfma_f32_16x16x32_bf16 v[106:109], v[154:157], v[166:169], v[106:109]
	v_mfma_f32_16x16x32_bf16 v[106:109], v[158:161], v[170:173], v[106:109]
	v_mfma_f32_16x16x32_bf16 v[98:101], v[154:157], v[186:189], v[98:101]
	v_mfma_f32_16x16x32_bf16 v[98:101], v[158:161], v[190:193], v[98:101]
	v_mfma_f32_16x16x32_bf16 v[102:105], v[146:149], v[186:189], v[102:105]
	v_mfma_f32_16x16x32_bf16 v[102:105], v[150:153], v[190:193], v[102:105]
	v_mfma_f32_16x16x32_bf16 v[82:85], v[146:149], v[194:197], v[82:85]
	v_mfma_f32_16x16x32_bf16 v[82:85], v[150:153], v[198:201], v[82:85]
	v_mfma_f32_16x16x32_bf16 v[74:77], v[154:157], v[194:197], v[74:77]
	v_mfma_f32_16x16x32_bf16 v[74:77], v[158:161], v[198:201], v[74:77]
	v_mfma_f32_16x16x32_bf16 v[66:69], v[154:157], v[202:205], v[66:69]
	v_mfma_f32_16x16x32_bf16 v[66:69], v[158:161], v[206:209], v[66:69]
	s_setprio 2
	s_barrier
	v_mfma_f32_16x16x32_bf16 v[70:73], v[146:149], v[202:205], v[70:73]
	v_mfma_f32_16x16x32_bf16 v[70:73], v[150:153], v[206:209], v[70:73]
	s_setprio 0
	ds_read_b128 v[166:169], v183 offset:49152
	ds_read_b128 v[170:173], v183 offset:50176
	ds_read_b128 v[186:189], v183 offset:51200
	ds_read_b128 v[190:193], v183 offset:52224
	ds_read_b128 v[194:197], v183 offset:53248
	ds_read_b128 v[198:201], v183 offset:54272
	ds_read_b128 v[202:205], v183 offset:55296
	ds_read_b128 v[206:209], v183 offset:56320
	s_add_u32 s24, s22, 0x80
	s_addc_u32 s25, s23, 0
	s_mov_b32 s79, m0
	s_mov_b32 m0, s46
	s_nop 0
	global_load_lds_dwordx4 v176, s[24:25]
	s_mov_b32 m0, s79
	s_add_u32 s22, s22, 0x80080
	s_mov_b32 s79, m0
	s_mov_b32 m0, s47
	s_nop 0
	global_load_lds_dwordx4 v178, s[24:25]
	s_mov_b32 m0, s79
	s_addc_u32 s23, s23, 0
	s_mov_b32 s24, m0
	s_mov_b32 m0, s48
	s_nop 0
	global_load_lds_dwordx4 v176, s[22:23]
	s_mov_b32 m0, s24
	s_nop 0
	s_mov_b32 s24, m0
	s_mov_b32 m0, s49
	s_nop 0
	global_load_lds_dwordx4 v178, s[22:23]
	s_mov_b32 m0, s24
	s_waitcnt vmcnt(4)
	s_waitcnt lgkmcnt(0)
	s_barrier
	s_setprio 1
	s_waitcnt lgkmcnt(7)
	v_mfma_f32_16x16x32_bf16 v[62:65], v[130:133], v[166:169], v[62:65]
	v_mfma_f32_16x16x32_bf16 v[62:65], v[134:137], v[170:173], v[62:65]
	s_waitcnt lgkmcnt(5)
	v_mfma_f32_16x16x32_bf16 v[58:61], v[138:141], v[166:169], v[58:61]
	v_mfma_f32_16x16x32_bf16 v[58:61], v[142:145], v[170:173], v[58:61]
	s_waitcnt lgkmcnt(3)
	v_mfma_f32_16x16x32_bf16 v[42:45], v[138:141], v[186:189], v[42:45]
	v_mfma_f32_16x16x32_bf16 v[42:45], v[142:145], v[190:193], v[42:45]
	s_waitcnt lgkmcnt(1)
	v_mfma_f32_16x16x32_bf16 v[46:49], v[130:133], v[186:189], v[46:49]
	v_mfma_f32_16x16x32_bf16 v[46:49], v[134:137], v[190:193], v[46:49]
	v_mfma_f32_16x16x32_bf16 v[30:33], v[130:133], v[194:197], v[30:33]
	v_mfma_f32_16x16x32_bf16 v[30:33], v[134:137], v[198:201], v[30:33]
	v_mfma_f32_16x16x32_bf16 v[26:29], v[138:141], v[194:197], v[26:29]
	v_mfma_f32_16x16x32_bf16 v[26:29], v[142:145], v[198:201], v[26:29]
	v_mfma_f32_16x16x32_bf16 v[10:13], v[138:141], v[202:205], v[10:13]
	v_mfma_f32_16x16x32_bf16 v[10:13], v[142:145], v[206:209], v[10:13]
	s_waitcnt lgkmcnt(0)
	v_mfma_f32_16x16x32_bf16 v[14:17], v[130:133], v[202:205], v[14:17]
	v_mfma_f32_16x16x32_bf16 v[14:17], v[134:137], v[206:209], v[14:17]
	s_setprio 0
	s_setprio 1
	v_mfma_f32_16x16x32_bf16 v[54:57], v[146:149], v[166:169], v[54:57]
	v_mfma_f32_16x16x32_bf16 v[54:57], v[150:153], v[170:173], v[54:57]
	v_mfma_f32_16x16x32_bf16 v[50:53], v[154:157], v[166:169], v[50:53]
	v_mfma_f32_16x16x32_bf16 v[50:53], v[158:161], v[170:173], v[50:53]
	v_mfma_f32_16x16x32_bf16 v[34:37], v[154:157], v[186:189], v[34:37]
	v_mfma_f32_16x16x32_bf16 v[34:37], v[158:161], v[190:193], v[34:37]
	v_mfma_f32_16x16x32_bf16 v[38:41], v[146:149], v[186:189], v[38:41]
	v_mfma_f32_16x16x32_bf16 v[38:41], v[150:153], v[190:193], v[38:41]
	v_mfma_f32_16x16x32_bf16 v[22:25], v[146:149], v[194:197], v[22:25]
	v_mfma_f32_16x16x32_bf16 v[22:25], v[150:153], v[198:201], v[22:25]
	v_mfma_f32_16x16x32_bf16 v[18:21], v[154:157], v[194:197], v[18:21]
	v_mfma_f32_16x16x32_bf16 v[18:21], v[158:161], v[198:201], v[18:21]
	v_mfma_f32_16x16x32_bf16 v[2:5], v[154:157], v[202:205], v[2:5]
	v_mfma_f32_16x16x32_bf16 v[2:5], v[158:161], v[206:209], v[2:5]
	s_setprio 2
	s_barrier
	v_mfma_f32_16x16x32_bf16 v[6:9], v[146:149], v[202:205], v[6:9]
	v_mfma_f32_16x16x32_bf16 v[6:9], v[150:153], v[206:209], v[6:9]
	s_setprio 0
	s_add_i32 s78, s78, 2
	s_add_u32 s74, s74, 0x100
	s_addc_u32 s75, s75, 0
	s_add_u32 s20, s20, 0x100
	s_addc_u32 s21, s21, 0
	s_add_u32 s76, s76, 0x100
	s_addc_u32 s77, s77, 0
	s_cmp_gt_u32 s78, 29
	.p2align 6
.LBB0_1053:
	ds_read_b128 v[130:133], v181
	ds_read_b128 v[134:137], v181 offset:1024
	ds_read_b128 v[138:141], v181 offset:2048
	ds_read_b128 v[142:145], v181 offset:3072
	ds_read_b128 v[146:149], v182
	ds_read_b128 v[150:153], v182 offset:1024
	ds_read_b128 v[154:157], v182 offset:2048
	ds_read_b128 v[158:161], v182 offset:3072
	s_cmp_eq_u32 s78, 28
	s_cselect_b32 s23, s11, s75
	s_cselect_b32 s22, s73, s74
	s_cselect_b32 s25, s13, s77
	s_cselect_b32 s24, s67, s76
	ds_read_b128 v[166:169], v183
	ds_read_b128 v[170:173], v183 offset:1024
	ds_read_b128 v[186:189], v183 offset:2048
	ds_read_b128 v[190:193], v183 offset:3072
	ds_read_b128 v[194:197], v183 offset:4096
	ds_read_b128 v[198:201], v183 offset:5120
	ds_read_b128 v[202:205], v183 offset:6144
	ds_read_b128 v[206:209], v183 offset:7168
	s_add_u32 s80, s20, 0xfff80000
	s_addc_u32 s81, s21, -1
	s_mov_b32 s79, m0
	s_mov_b32 m0, s58
	s_nop 0
	global_load_lds_dwordx4 v1, s[80:81]
	s_mov_b32 m0, s79
	s_nop 0
	s_mov_b32 s79, m0
	s_mov_b32 m0, s64
	s_nop 0
	global_load_lds_dwordx4 v177, s[80:81]
	s_mov_b32 m0, s79
	s_nop 0
	s_mov_b32 s79, m0
	s_mov_b32 m0, s59
	s_nop 0
	global_load_lds_dwordx4 v1, s[20:21]
	s_mov_b32 m0, s79
	s_nop 0
	s_mov_b32 s79, m0
	s_mov_b32 m0, s65
	s_nop 0
	global_load_lds_dwordx4 v177, s[20:21]
	s_mov_b32 m0, s79
	s_waitcnt vmcnt(8)
	s_waitcnt lgkmcnt(0)
	s_barrier
	s_setprio 1
	s_waitcnt lgkmcnt(7)
	v_mfma_f32_16x16x32_bf16 v[126:129], v[130:133], v[166:169], v[126:129]
	v_mfma_f32_16x16x32_bf16 v[126:129], v[134:137], v[170:173], v[126:129]
	s_waitcnt lgkmcnt(5)
	v_mfma_f32_16x16x32_bf16 v[122:125], v[138:141], v[166:169], v[122:125]
	v_mfma_f32_16x16x32_bf16 v[122:125], v[142:145], v[170:173], v[122:125]
	s_waitcnt lgkmcnt(3)
	v_mfma_f32_16x16x32_bf16 v[114:117], v[138:141], v[186:189], v[114:117]
	v_mfma_f32_16x16x32_bf16 v[114:117], v[142:145], v[190:193], v[114:117]
	s_waitcnt lgkmcnt(1)
	v_mfma_f32_16x16x32_bf16 v[118:121], v[130:133], v[186:189], v[118:121]
	v_mfma_f32_16x16x32_bf16 v[118:121], v[134:137], v[190:193], v[118:121]
	v_mfma_f32_16x16x32_bf16 v[94:97], v[130:133], v[194:197], v[94:97]
	v_mfma_f32_16x16x32_bf16 v[94:97], v[134:137], v[198:201], v[94:97]
	v_mfma_f32_16x16x32_bf16 v[90:93], v[138:141], v[194:197], v[90:93]
	v_mfma_f32_16x16x32_bf16 v[90:93], v[142:145], v[198:201], v[90:93]
	v_mfma_f32_16x16x32_bf16 v[78:81], v[138:141], v[202:205], v[78:81]
	v_mfma_f32_16x16x32_bf16 v[78:81], v[142:145], v[206:209], v[78:81]
	s_waitcnt lgkmcnt(0)
	v_mfma_f32_16x16x32_bf16 v[86:89], v[130:133], v[202:205], v[86:89]
	v_mfma_f32_16x16x32_bf16 v[86:89], v[134:137], v[206:209], v[86:89]
	s_setprio 0
	s_setprio 1
	v_mfma_f32_16x16x32_bf16 v[110:113], v[146:149], v[166:169], v[110:113]
	v_mfma_f32_16x16x32_bf16 v[110:113], v[150:153], v[170:173], v[110:113]
	v_mfma_f32_16x16x32_bf16 v[106:109], v[154:157], v[166:169], v[106:109]
	v_mfma_f32_16x16x32_bf16 v[106:109], v[158:161], v[170:173], v[106:109]
	v_mfma_f32_16x16x32_bf16 v[98:101], v[154:157], v[186:189], v[98:101]
	v_mfma_f32_16x16x32_bf16 v[98:101], v[158:161], v[190:193], v[98:101]
	v_mfma_f32_16x16x32_bf16 v[102:105], v[146:149], v[186:189], v[102:105]
	v_mfma_f32_16x16x32_bf16 v[102:105], v[150:153], v[190:193], v[102:105]
	v_mfma_f32_16x16x32_bf16 v[82:85], v[146:149], v[194:197], v[82:85]
	v_mfma_f32_16x16x32_bf16 v[82:85], v[150:153], v[198:201], v[82:85]
	v_mfma_f32_16x16x32_bf16 v[74:77], v[154:157], v[194:197], v[74:77]
	v_mfma_f32_16x16x32_bf16 v[74:77], v[158:161], v[198:201], v[74:77]
	v_mfma_f32_16x16x32_bf16 v[66:69], v[154:157], v[202:205], v[66:69]
	v_mfma_f32_16x16x32_bf16 v[66:69], v[158:161], v[206:209], v[66:69]
	s_setprio 2
	s_barrier
	v_mfma_f32_16x16x32_bf16 v[70:73], v[146:149], v[202:205], v[70:73]
	v_mfma_f32_16x16x32_bf16 v[70:73], v[150:153], v[206:209], v[70:73]
	s_setprio 0
	ds_read_b128 v[166:169], v183 offset:16384
	ds_read_b128 v[170:173], v183 offset:17408
	ds_read_b128 v[186:189], v183 offset:18432
	ds_read_b128 v[190:193], v183 offset:19456
	ds_read_b128 v[194:197], v183 offset:20480
	ds_read_b128 v[198:201], v183 offset:21504
	ds_read_b128 v[202:205], v183 offset:22528
	ds_read_b128 v[206:209], v183 offset:23552
	s_mov_b32 s79, m0
	s_mov_b32 m0, s35
	s_nop 0
	global_load_lds_dwordx4 v176, s[22:23]
	s_mov_b32 m0, s79
	s_add_u32 s80, s22, 0x80000
	s_mov_b32 s79, m0
	s_mov_b32 m0, s36
	s_nop 0
	global_load_lds_dwordx4 v178, s[22:23]
	s_mov_b32 m0, s79
	s_addc_u32 s81, s23, 0
	s_mov_b32 s79, m0
	s_mov_b32 m0, s37
	s_nop 0
	global_load_lds_dwordx4 v176, s[80:81]
	s_mov_b32 m0, s79
	s_nop 0
	s_mov_b32 s79, m0
	s_mov_b32 m0, s40
	s_nop 0
	global_load_lds_dwordx4 v178, s[80:81]
	s_mov_b32 m0, s79
	s_waitcnt vmcnt(4)
	s_waitcnt lgkmcnt(0)
	s_barrier
	s_setprio 1
	s_waitcnt lgkmcnt(7)
	v_mfma_f32_16x16x32_bf16 v[62:65], v[130:133], v[166:169], v[62:65]
	v_mfma_f32_16x16x32_bf16 v[62:65], v[134:137], v[170:173], v[62:65]
	s_waitcnt lgkmcnt(5)
	v_mfma_f32_16x16x32_bf16 v[58:61], v[138:141], v[166:169], v[58:61]
	v_mfma_f32_16x16x32_bf16 v[58:61], v[142:145], v[170:173], v[58:61]
	s_waitcnt lgkmcnt(3)
	v_mfma_f32_16x16x32_bf16 v[42:45], v[138:141], v[186:189], v[42:45]
	v_mfma_f32_16x16x32_bf16 v[42:45], v[142:145], v[190:193], v[42:45]
	s_waitcnt lgkmcnt(1)
	v_mfma_f32_16x16x32_bf16 v[46:49], v[130:133], v[186:189], v[46:49]
	v_mfma_f32_16x16x32_bf16 v[46:49], v[134:137], v[190:193], v[46:49]
	v_mfma_f32_16x16x32_bf16 v[30:33], v[130:133], v[194:197], v[30:33]
	v_mfma_f32_16x16x32_bf16 v[30:33], v[134:137], v[198:201], v[30:33]
	v_mfma_f32_16x16x32_bf16 v[26:29], v[138:141], v[194:197], v[26:29]
	v_mfma_f32_16x16x32_bf16 v[26:29], v[142:145], v[198:201], v[26:29]
	v_mfma_f32_16x16x32_bf16 v[10:13], v[138:141], v[202:205], v[10:13]
	v_mfma_f32_16x16x32_bf16 v[10:13], v[142:145], v[206:209], v[10:13]
	s_waitcnt lgkmcnt(0)
	v_mfma_f32_16x16x32_bf16 v[14:17], v[130:133], v[202:205], v[14:17]
	v_mfma_f32_16x16x32_bf16 v[14:17], v[134:137], v[206:209], v[14:17]
	s_setprio 0
	s_setprio 1
	v_mfma_f32_16x16x32_bf16 v[54:57], v[146:149], v[166:169], v[54:57]
	v_mfma_f32_16x16x32_bf16 v[54:57], v[150:153], v[170:173], v[54:57]
	v_mfma_f32_16x16x32_bf16 v[50:53], v[154:157], v[166:169], v[50:53]
	v_mfma_f32_16x16x32_bf16 v[50:53], v[158:161], v[170:173], v[50:53]
	v_mfma_f32_16x16x32_bf16 v[34:37], v[154:157], v[186:189], v[34:37]
	v_mfma_f32_16x16x32_bf16 v[34:37], v[158:161], v[190:193], v[34:37]
	v_mfma_f32_16x16x32_bf16 v[38:41], v[146:149], v[186:189], v[38:41]
	v_mfma_f32_16x16x32_bf16 v[38:41], v[150:153], v[190:193], v[38:41]
	v_mfma_f32_16x16x32_bf16 v[22:25], v[146:149], v[194:197], v[22:25]
	v_mfma_f32_16x16x32_bf16 v[22:25], v[150:153], v[198:201], v[22:25]
	v_mfma_f32_16x16x32_bf16 v[18:21], v[154:157], v[194:197], v[18:21]
	v_mfma_f32_16x16x32_bf16 v[18:21], v[158:161], v[198:201], v[18:21]
	v_mfma_f32_16x16x32_bf16 v[2:5], v[154:157], v[202:205], v[2:5]
	v_mfma_f32_16x16x32_bf16 v[2:5], v[158:161], v[206:209], v[2:5]
	s_setprio 2
	s_barrier
	v_mfma_f32_16x16x32_bf16 v[6:9], v[146:149], v[202:205], v[6:9]
	v_mfma_f32_16x16x32_bf16 v[6:9], v[150:153], v[206:209], v[6:9]
	s_setprio 0
	ds_read_b128 v[130:133], v184
	ds_read_b128 v[134:137], v184 offset:1024
	ds_read_b128 v[138:141], v184 offset:2048
	ds_read_b128 v[142:145], v184 offset:3072
	ds_read_b128 v[146:149], v185
	ds_read_b128 v[150:153], v185 offset:1024
	ds_read_b128 v[154:157], v185 offset:2048
	ds_read_b128 v[158:161], v185 offset:3072
	ds_read_b128 v[166:169], v183 offset:32768
	ds_read_b128 v[170:173], v183 offset:33792
	ds_read_b128 v[186:189], v183 offset:34816
	ds_read_b128 v[190:193], v183 offset:35840
	ds_read_b128 v[194:197], v183 offset:36864
	ds_read_b128 v[198:201], v183 offset:37888
	ds_read_b128 v[202:205], v183 offset:38912
	ds_read_b128 v[206:209], v183 offset:39936
	s_mov_b32 s79, m0
	s_mov_b32 m0, s34
	s_nop 0
	global_load_lds_dwordx4 v1, s[24:25]
	s_mov_b32 m0, s79
	s_nop 0
	s_mov_b32 s79, m0
	s_mov_b32 m0, s41
	s_nop 0
	global_load_lds_dwordx4 v177, s[24:25]
	s_mov_b32 m0, s79
	s_add_u32 s24, s24, 0x80000
	s_addc_u32 s25, s25, 0
	s_mov_b32 s79, m0
	s_mov_b32 m0, s42
	s_nop 0
	global_load_lds_dwordx4 v1, s[24:25]
	s_mov_b32 m0, s79
	s_nop 0
	s_mov_b32 s79, m0
	s_mov_b32 m0, s43
	s_nop 0
	global_load_lds_dwordx4 v177, s[24:25]
	s_mov_b32 m0, s79
	s_waitcnt vmcnt(8)
	s_waitcnt lgkmcnt(0)
	s_barrier
	s_setprio 1
	s_waitcnt lgkmcnt(7)
	v_mfma_f32_16x16x32_bf16 v[126:129], v[130:133], v[166:169], v[126:129]
	v_mfma_f32_16x16x32_bf16 v[126:129], v[134:137], v[170:173], v[126:129]
	s_waitcnt lgkmcnt(5)
	v_mfma_f32_16x16x32_bf16 v[122:125], v[138:141], v[166:169], v[122:125]
	v_mfma_f32_16x16x32_bf16 v[122:125], v[142:145], v[170:173], v[122:125]
	s_waitcnt lgkmcnt(3)
	v_mfma_f32_16x16x32_bf16 v[114:117], v[138:141], v[186:189], v[114:117]
	v_mfma_f32_16x16x32_bf16 v[114:117], v[142:145], v[190:193], v[114:117]
	s_waitcnt lgkmcnt(1)
	v_mfma_f32_16x16x32_bf16 v[118:121], v[130:133], v[186:189], v[118:121]
	v_mfma_f32_16x16x32_bf16 v[118:121], v[134:137], v[190:193], v[118:121]
	v_mfma_f32_16x16x32_bf16 v[94:97], v[130:133], v[194:197], v[94:97]
	v_mfma_f32_16x16x32_bf16 v[94:97], v[134:137], v[198:201], v[94:97]
	v_mfma_f32_16x16x32_bf16 v[90:93], v[138:141], v[194:197], v[90:93]
	v_mfma_f32_16x16x32_bf16 v[90:93], v[142:145], v[198:201], v[90:93]
	v_mfma_f32_16x16x32_bf16 v[78:81], v[138:141], v[202:205], v[78:81]
	v_mfma_f32_16x16x32_bf16 v[78:81], v[142:145], v[206:209], v[78:81]
	s_waitcnt lgkmcnt(0)
	v_mfma_f32_16x16x32_bf16 v[86:89], v[130:133], v[202:205], v[86:89]
	v_mfma_f32_16x16x32_bf16 v[86:89], v[134:137], v[206:209], v[86:89]
	s_setprio 0
	s_setprio 1
	v_mfma_f32_16x16x32_bf16 v[110:113], v[146:149], v[166:169], v[110:113]
	v_mfma_f32_16x16x32_bf16 v[110:113], v[150:153], v[170:173], v[110:113]
	v_mfma_f32_16x16x32_bf16 v[106:109], v[154:157], v[166:169], v[106:109]
	v_mfma_f32_16x16x32_bf16 v[106:109], v[158:161], v[170:173], v[106:109]
	v_mfma_f32_16x16x32_bf16 v[98:101], v[154:157], v[186:189], v[98:101]
	v_mfma_f32_16x16x32_bf16 v[98:101], v[158:161], v[190:193], v[98:101]
	v_mfma_f32_16x16x32_bf16 v[102:105], v[146:149], v[186:189], v[102:105]
	v_mfma_f32_16x16x32_bf16 v[102:105], v[150:153], v[190:193], v[102:105]
	v_mfma_f32_16x16x32_bf16 v[82:85], v[146:149], v[194:197], v[82:85]
	v_mfma_f32_16x16x32_bf16 v[82:85], v[150:153], v[198:201], v[82:85]
	v_mfma_f32_16x16x32_bf16 v[74:77], v[154:157], v[194:197], v[74:77]
	v_mfma_f32_16x16x32_bf16 v[74:77], v[158:161], v[198:201], v[74:77]
	v_mfma_f32_16x16x32_bf16 v[66:69], v[154:157], v[202:205], v[66:69]
	v_mfma_f32_16x16x32_bf16 v[66:69], v[158:161], v[206:209], v[66:69]
	s_setprio 2
	s_barrier
	v_mfma_f32_16x16x32_bf16 v[70:73], v[146:149], v[202:205], v[70:73]
	v_mfma_f32_16x16x32_bf16 v[70:73], v[150:153], v[206:209], v[70:73]
	s_setprio 0
	ds_read_b128 v[166:169], v183 offset:49152
	ds_read_b128 v[170:173], v183 offset:50176
	ds_read_b128 v[186:189], v183 offset:51200
	ds_read_b128 v[190:193], v183 offset:52224
	ds_read_b128 v[194:197], v183 offset:53248
	ds_read_b128 v[198:201], v183 offset:54272
	ds_read_b128 v[202:205], v183 offset:55296
	ds_read_b128 v[206:209], v183 offset:56320
	s_add_u32 s24, s22, 0x80
	s_addc_u32 s25, s23, 0
	s_mov_b32 s79, m0
	s_mov_b32 m0, s46
	s_nop 0
	global_load_lds_dwordx4 v176, s[24:25]
	s_mov_b32 m0, s79
	s_add_u32 s22, s22, 0x80080
	s_mov_b32 s79, m0
	s_mov_b32 m0, s47
	s_nop 0
	global_load_lds_dwordx4 v178, s[24:25]
	s_mov_b32 m0, s79
	s_addc_u32 s23, s23, 0
	s_mov_b32 s24, m0
	s_mov_b32 m0, s48
	s_nop 0
	global_load_lds_dwordx4 v176, s[22:23]
	s_mov_b32 m0, s24
	s_nop 0
	s_mov_b32 s24, m0
	s_mov_b32 m0, s49
	s_nop 0
	global_load_lds_dwordx4 v178, s[22:23]
	s_mov_b32 m0, s24
	s_waitcnt vmcnt(4)
	s_waitcnt lgkmcnt(0)
	s_barrier
	s_setprio 1
	s_waitcnt lgkmcnt(7)
	v_mfma_f32_16x16x32_bf16 v[62:65], v[130:133], v[166:169], v[62:65]
	v_mfma_f32_16x16x32_bf16 v[62:65], v[134:137], v[170:173], v[62:65]
	s_waitcnt lgkmcnt(5)
	v_mfma_f32_16x16x32_bf16 v[58:61], v[138:141], v[166:169], v[58:61]
	v_mfma_f32_16x16x32_bf16 v[58:61], v[142:145], v[170:173], v[58:61]
	s_waitcnt lgkmcnt(3)
	v_mfma_f32_16x16x32_bf16 v[42:45], v[138:141], v[186:189], v[42:45]
	v_mfma_f32_16x16x32_bf16 v[42:45], v[142:145], v[190:193], v[42:45]
	s_waitcnt lgkmcnt(1)
	v_mfma_f32_16x16x32_bf16 v[46:49], v[130:133], v[186:189], v[46:49]
	v_mfma_f32_16x16x32_bf16 v[46:49], v[134:137], v[190:193], v[46:49]
	v_mfma_f32_16x16x32_bf16 v[30:33], v[130:133], v[194:197], v[30:33]
	v_mfma_f32_16x16x32_bf16 v[30:33], v[134:137], v[198:201], v[30:33]
	v_mfma_f32_16x16x32_bf16 v[26:29], v[138:141], v[194:197], v[26:29]
	v_mfma_f32_16x16x32_bf16 v[26:29], v[142:145], v[198:201], v[26:29]
	v_mfma_f32_16x16x32_bf16 v[10:13], v[138:141], v[202:205], v[10:13]
	v_mfma_f32_16x16x32_bf16 v[10:13], v[142:145], v[206:209], v[10:13]
	s_waitcnt lgkmcnt(0)
	v_mfma_f32_16x16x32_bf16 v[14:17], v[130:133], v[202:205], v[14:17]
	v_mfma_f32_16x16x32_bf16 v[14:17], v[134:137], v[206:209], v[14:17]
	s_setprio 0
	s_setprio 1
	v_mfma_f32_16x16x32_bf16 v[54:57], v[146:149], v[166:169], v[54:57]
	v_mfma_f32_16x16x32_bf16 v[54:57], v[150:153], v[170:173], v[54:57]
	v_mfma_f32_16x16x32_bf16 v[50:53], v[154:157], v[166:169], v[50:53]
	v_mfma_f32_16x16x32_bf16 v[50:53], v[158:161], v[170:173], v[50:53]
	v_mfma_f32_16x16x32_bf16 v[34:37], v[154:157], v[186:189], v[34:37]
	v_mfma_f32_16x16x32_bf16 v[34:37], v[158:161], v[190:193], v[34:37]
	v_mfma_f32_16x16x32_bf16 v[38:41], v[146:149], v[186:189], v[38:41]
	v_mfma_f32_16x16x32_bf16 v[38:41], v[150:153], v[190:193], v[38:41]
	v_mfma_f32_16x16x32_bf16 v[22:25], v[146:149], v[194:197], v[22:25]
	v_mfma_f32_16x16x32_bf16 v[22:25], v[150:153], v[198:201], v[22:25]
	v_mfma_f32_16x16x32_bf16 v[18:21], v[154:157], v[194:197], v[18:21]
	v_mfma_f32_16x16x32_bf16 v[18:21], v[158:161], v[198:201], v[18:21]
	v_mfma_f32_16x16x32_bf16 v[2:5], v[154:157], v[202:205], v[2:5]
	v_mfma_f32_16x16x32_bf16 v[2:5], v[158:161], v[206:209], v[2:5]
	s_setprio 2
	s_barrier
	v_mfma_f32_16x16x32_bf16 v[6:9], v[146:149], v[202:205], v[6:9]
	v_mfma_f32_16x16x32_bf16 v[6:9], v[150:153], v[206:209], v[6:9]
	s_setprio 0
	s_add_i32 s78, s78, 2
	s_add_u32 s74, s74, 0x100
	s_addc_u32 s75, s75, 0
	s_add_u32 s20, s20, 0x100
	s_addc_u32 s21, s21, 0
	s_add_u32 s76, s76, 0x100
	s_addc_u32 s77, s77, 0
	s_cmp_gt_u32 s78, 29
	s_cbranch_scc0 .LBB0_1053
	s_and_b64 vcc, exec, s[8:9]
	s_cbranch_vccz .LBB0_1056
	s_barrier

.LBB0_1223:
	s_ashr_i32 s11, s10, 31
	s_lshl_b64 s[12:13], s[10:11], 20
	s_add_u32 s12, s26, s12
	s_addc_u32 s13, s27, s13
	s_and_b64 s[14:15], s[2:3], exec
	s_cselect_b32 s11, s13, s21
	s_cselect_b32 s66, s12, s20
	s_ashr_i32 s9, s8, 31
	s_lshl_b64 s[14:15], s[8:9], 20
	s_add_u32 s14, s28, s14
	s_addc_u32 s15, s29, s15
	s_and_b64 s[22:23], s[2:3], exec
	s_cselect_b32 s9, s15, s19
	s_cselect_b32 s67, s14, s18
	s_add_u32 s73, s18, 0x100
	s_addc_u32 s74, s19, 0
	s_add_u32 s18, s20, 0x80080
	s_addc_u32 s19, s21, 0
	s_add_u32 s75, s20, 0x100
	s_addc_u32 s76, s21, 0
	s_mov_b32 s77, -2
	ds_read_b128 v[148:151], v143
	ds_read_b128 v[152:155], v143 offset:1024
	ds_read_b128 v[156:159], v143 offset:2048
	ds_read_b128 v[160:163], v143 offset:3072
	ds_read_b128 v[164:167], v144
	ds_read_b128 v[168:171], v144 offset:1024
	ds_read_b128 v[172:175], v144 offset:2048
	ds_read_b128 v[176:179], v144 offset:3072
	s_cmp_eq_u32 s77, 28
	s_cselect_b32 s21, s9, s74
	s_cselect_b32 s20, s67, s73
	s_cselect_b32 s23, s11, s76
	s_cselect_b32 s22, s66, s75
	ds_read_b128 v[180:183], v145
	ds_read_b128 v[184:187], v145 offset:1024
	ds_read_b128 v[188:191], v145 offset:2048
	ds_read_b128 v[192:195], v145 offset:3072
	ds_read_b128 v[196:199], v145 offset:4096
	ds_read_b128 v[200:203], v145 offset:5120
	ds_read_b128 v[204:207], v145 offset:6144
	ds_read_b128 v[208:211], v145 offset:7168
	s_add_u32 s78, s18, 0xfff80000
	s_addc_u32 s79, s19, -1
	s_mov_b32 s80, m0
	s_mov_b32 m0, s56
	s_nop 0
	global_load_lds_dwordx4 v138, s[78:79]
	s_mov_b32 m0, s80
	s_nop 0
	s_mov_b32 s80, m0
	s_mov_b32 m0, s59
	s_nop 0
	global_load_lds_dwordx4 v140, s[78:79]
	s_mov_b32 m0, s80
	s_mov_b32 s78, m0
	s_mov_b32 m0, s57
	s_nop 0
	global_load_lds_dwordx4 v138, s[18:19]
	s_mov_b32 m0, s78
	s_nop 0
	s_mov_b32 s78, m0
	s_mov_b32 m0, s64
	s_nop 0
	global_load_lds_dwordx4 v140, s[18:19]
	s_mov_b32 m0, s78
	s_waitcnt vmcnt(8)
	s_waitcnt lgkmcnt(0)
	s_barrier
	s_setprio 1
	s_waitcnt lgkmcnt(7)
	v_mfma_f32_16x16x32_bf16 v[126:129], v[148:151], v[180:183], 0
	v_mfma_f32_16x16x32_bf16 v[126:129], v[152:155], v[184:187], v[126:129]
	s_waitcnt lgkmcnt(5)
	v_mfma_f32_16x16x32_bf16 v[122:125], v[156:159], v[180:183], 0
	v_mfma_f32_16x16x32_bf16 v[122:125], v[160:163], v[184:187], v[122:125]
	s_waitcnt lgkmcnt(3)
	v_mfma_f32_16x16x32_bf16 v[106:109], v[156:159], v[188:191], 0
	v_mfma_f32_16x16x32_bf16 v[106:109], v[160:163], v[192:195], v[106:109]
	s_waitcnt lgkmcnt(1)
	v_mfma_f32_16x16x32_bf16 v[110:113], v[148:151], v[188:191], 0
	v_mfma_f32_16x16x32_bf16 v[110:113], v[152:155], v[192:195], v[110:113]
	v_mfma_f32_16x16x32_bf16 v[94:97], v[148:151], v[196:199], 0
	v_mfma_f32_16x16x32_bf16 v[94:97], v[152:155], v[200:203], v[94:97]
	v_mfma_f32_16x16x32_bf16 v[90:93], v[156:159], v[196:199], 0
	v_mfma_f32_16x16x32_bf16 v[90:93], v[160:163], v[200:203], v[90:93]
	v_mfma_f32_16x16x32_bf16 v[74:77], v[156:159], v[204:207], 0
	v_mfma_f32_16x16x32_bf16 v[74:77], v[160:163], v[208:211], v[74:77]
	s_waitcnt lgkmcnt(0)
	v_mfma_f32_16x16x32_bf16 v[78:81], v[148:151], v[204:207], 0
	v_mfma_f32_16x16x32_bf16 v[78:81], v[152:155], v[208:211], v[78:81]
	s_setprio 0
	s_setprio 1
	v_mfma_f32_16x16x32_bf16 v[118:121], v[164:167], v[180:183], 0
	v_mfma_f32_16x16x32_bf16 v[118:121], v[168:171], v[184:187], v[118:121]
	v_mfma_f32_16x16x32_bf16 v[114:117], v[172:175], v[180:183], 0
	v_mfma_f32_16x16x32_bf16 v[114:117], v[176:179], v[184:187], v[114:117]
	v_mfma_f32_16x16x32_bf16 v[98:101], v[172:175], v[188:191], 0
	v_mfma_f32_16x16x32_bf16 v[98:101], v[176:179], v[192:195], v[98:101]
	v_mfma_f32_16x16x32_bf16 v[102:105], v[164:167], v[188:191], 0
	v_mfma_f32_16x16x32_bf16 v[102:105], v[168:171], v[192:195], v[102:105]
	v_mfma_f32_16x16x32_bf16 v[86:89], v[164:167], v[196:199], 0
	v_mfma_f32_16x16x32_bf16 v[86:89], v[168:171], v[200:203], v[86:89]
	v_mfma_f32_16x16x32_bf16 v[82:85], v[172:175], v[196:199], 0
	v_mfma_f32_16x16x32_bf16 v[82:85], v[176:179], v[200:203], v[82:85]
	v_mfma_f32_16x16x32_bf16 v[66:69], v[172:175], v[204:207], 0
	v_mfma_f32_16x16x32_bf16 v[66:69], v[176:179], v[208:211], v[66:69]
	s_setprio 2
	s_barrier
	v_mfma_f32_16x16x32_bf16 v[70:73], v[164:167], v[204:207], 0
	v_mfma_f32_16x16x32_bf16 v[70:73], v[168:171], v[208:211], v[70:73]
	s_setprio 0
	ds_read_b128 v[180:183], v145 offset:16384
	ds_read_b128 v[184:187], v145 offset:17408
	ds_read_b128 v[188:191], v145 offset:18432
	ds_read_b128 v[192:195], v145 offset:19456
	ds_read_b128 v[196:199], v145 offset:20480
	ds_read_b128 v[200:203], v145 offset:21504
	ds_read_b128 v[204:207], v145 offset:22528
	ds_read_b128 v[208:211], v145 offset:23552
	s_mov_b32 s78, m0
	s_mov_b32 m0, s35
	s_nop 0
	global_load_lds_dwordx4 v139, s[20:21]
	s_mov_b32 m0, s78
	s_nop 0
	s_mov_b32 s78, m0
	s_mov_b32 m0, s36
	s_nop 0
	global_load_lds_dwordx4 v141, s[20:21]
	s_mov_b32 m0, s78
	s_add_u32 s78, s20, 0x80000
	s_addc_u32 s79, s21, 0
	s_mov_b32 s80, m0
	s_mov_b32 m0, s37
	s_nop 0
	global_load_lds_dwordx4 v139, s[78:79]
	s_mov_b32 m0, s80
	s_nop 0
	s_mov_b32 s80, m0
	s_mov_b32 m0, s40
	s_nop 0
	global_load_lds_dwordx4 v141, s[78:79]
	s_mov_b32 m0, s80
	s_waitcnt vmcnt(4)
	s_waitcnt lgkmcnt(0)
	s_barrier
	s_setprio 1
	s_waitcnt lgkmcnt(7)
	v_mfma_f32_16x16x32_bf16 v[62:65], v[148:151], v[180:183], 0
	v_mfma_f32_16x16x32_bf16 v[62:65], v[152:155], v[184:187], v[62:65]
	s_waitcnt lgkmcnt(5)
	v_mfma_f32_16x16x32_bf16 v[58:61], v[156:159], v[180:183], 0
	v_mfma_f32_16x16x32_bf16 v[58:61], v[160:163], v[184:187], v[58:61]
	s_waitcnt lgkmcnt(3)
	v_mfma_f32_16x16x32_bf16 v[42:45], v[156:159], v[188:191], 0
	v_mfma_f32_16x16x32_bf16 v[42:45], v[160:163], v[192:195], v[42:45]
	s_waitcnt lgkmcnt(1)
	v_mfma_f32_16x16x32_bf16 v[46:49], v[148:151], v[188:191], 0
	v_mfma_f32_16x16x32_bf16 v[46:49], v[152:155], v[192:195], v[46:49]
	v_mfma_f32_16x16x32_bf16 v[30:33], v[148:151], v[196:199], 0
	v_mfma_f32_16x16x32_bf16 v[30:33], v[152:155], v[200:203], v[30:33]
	v_mfma_f32_16x16x32_bf16 v[26:29], v[156:159], v[196:199], 0
	v_mfma_f32_16x16x32_bf16 v[26:29], v[160:163], v[200:203], v[26:29]
	v_mfma_f32_16x16x32_bf16 v[10:13], v[156:159], v[204:207], 0
	v_mfma_f32_16x16x32_bf16 v[10:13], v[160:163], v[208:211], v[10:13]
	s_waitcnt lgkmcnt(0)
	v_mfma_f32_16x16x32_bf16 v[14:17], v[148:151], v[204:207], 0
	v_mfma_f32_16x16x32_bf16 v[14:17], v[152:155], v[208:211], v[14:17]
	s_setprio 0
	s_setprio 1
	v_mfma_f32_16x16x32_bf16 v[54:57], v[164:167], v[180:183], 0
	v_mfma_f32_16x16x32_bf16 v[54:57], v[168:171], v[184:187], v[54:57]
	v_mfma_f32_16x16x32_bf16 v[50:53], v[172:175], v[180:183], 0
	v_mfma_f32_16x16x32_bf16 v[50:53], v[176:179], v[184:187], v[50:53]
	v_mfma_f32_16x16x32_bf16 v[34:37], v[172:175], v[188:191], 0
	v_mfma_f32_16x16x32_bf16 v[34:37], v[176:179], v[192:195], v[34:37]
	v_mfma_f32_16x16x32_bf16 v[38:41], v[164:167], v[188:191], 0
	v_mfma_f32_16x16x32_bf16 v[38:41], v[168:171], v[192:195], v[38:41]
	v_mfma_f32_16x16x32_bf16 v[22:25], v[164:167], v[196:199], 0
	v_mfma_f32_16x16x32_bf16 v[22:25], v[168:171], v[200:203], v[22:25]
	v_mfma_f32_16x16x32_bf16 v[18:21], v[172:175], v[196:199], 0
	v_mfma_f32_16x16x32_bf16 v[18:21], v[176:179], v[200:203], v[18:21]
	v_mfma_f32_16x16x32_bf16 v[2:5], v[172:175], v[204:207], 0
	v_mfma_f32_16x16x32_bf16 v[2:5], v[176:179], v[208:211], v[2:5]
	s_setprio 2
	s_barrier
	v_mfma_f32_16x16x32_bf16 v[6:9], v[164:167], v[204:207], 0
	v_mfma_f32_16x16x32_bf16 v[6:9], v[168:171], v[208:211], v[6:9]
	s_setprio 0
	ds_read_b128 v[148:151], v146
	ds_read_b128 v[152:155], v146 offset:1024
	ds_read_b128 v[156:159], v146 offset:2048
	ds_read_b128 v[160:163], v146 offset:3072
	ds_read_b128 v[164:167], v147
	ds_read_b128 v[168:171], v147 offset:1024
	ds_read_b128 v[172:175], v147 offset:2048
	ds_read_b128 v[176:179], v147 offset:3072
	ds_read_b128 v[180:183], v145 offset:32768
	ds_read_b128 v[184:187], v145 offset:33792
	ds_read_b128 v[188:191], v145 offset:34816
	ds_read_b128 v[192:195], v145 offset:35840
	ds_read_b128 v[196:199], v145 offset:36864
	ds_read_b128 v[200:203], v145 offset:37888
	ds_read_b128 v[204:207], v145 offset:38912
	ds_read_b128 v[208:211], v145 offset:39936
	s_mov_b32 s78, m0
	s_mov_b32 m0, s31
	s_nop 0
	global_load_lds_dwordx4 v138, s[22:23]
	s_mov_b32 m0, s78
	s_nop 0
	s_mov_b32 s78, m0
	s_mov_b32 m0, s41
	s_nop 0
	global_load_lds_dwordx4 v140, s[22:23]
	s_mov_b32 m0, s78
	s_add_u32 s22, s22, 0x80000
	s_addc_u32 s23, s23, 0
	s_mov_b32 s78, m0
	s_mov_b32 m0, s42
	s_nop 0
	global_load_lds_dwordx4 v138, s[22:23]
	s_mov_b32 m0, s78
	s_nop 0
	s_mov_b32 s78, m0
	s_mov_b32 m0, s43
	s_nop 0
	global_load_lds_dwordx4 v140, s[22:23]
	s_mov_b32 m0, s78
	s_waitcnt vmcnt(8)
	s_waitcnt lgkmcnt(0)
	s_barrier
	s_setprio 1
	s_waitcnt lgkmcnt(7)
	v_mfma_f32_16x16x32_bf16 v[126:129], v[148:151], v[180:183], v[126:129]
	v_mfma_f32_16x16x32_bf16 v[126:129], v[152:155], v[184:187], v[126:129]
	s_waitcnt lgkmcnt(5)
	v_mfma_f32_16x16x32_bf16 v[122:125], v[156:159], v[180:183], v[122:125]
	v_mfma_f32_16x16x32_bf16 v[122:125], v[160:163], v[184:187], v[122:125]
	s_waitcnt lgkmcnt(3)
	v_mfma_f32_16x16x32_bf16 v[106:109], v[156:159], v[188:191], v[106:109]
	v_mfma_f32_16x16x32_bf16 v[106:109], v[160:163], v[192:195], v[106:109]
	s_waitcnt lgkmcnt(1)
	v_mfma_f32_16x16x32_bf16 v[110:113], v[148:151], v[188:191], v[110:113]
	v_mfma_f32_16x16x32_bf16 v[110:113], v[152:155], v[192:195], v[110:113]
	v_mfma_f32_16x16x32_bf16 v[94:97], v[148:151], v[196:199], v[94:97]
	v_mfma_f32_16x16x32_bf16 v[94:97], v[152:155], v[200:203], v[94:97]
	v_mfma_f32_16x16x32_bf16 v[90:93], v[156:159], v[196:199], v[90:93]
	v_mfma_f32_16x16x32_bf16 v[90:93], v[160:163], v[200:203], v[90:93]
	v_mfma_f32_16x16x32_bf16 v[74:77], v[156:159], v[204:207], v[74:77]
	v_mfma_f32_16x16x32_bf16 v[74:77], v[160:163], v[208:211], v[74:77]
	s_waitcnt lgkmcnt(0)
	v_mfma_f32_16x16x32_bf16 v[78:81], v[148:151], v[204:207], v[78:81]
	v_mfma_f32_16x16x32_bf16 v[78:81], v[152:155], v[208:211], v[78:81]
	s_setprio 0
	s_setprio 1
	v_mfma_f32_16x16x32_bf16 v[118:121], v[164:167], v[180:183], v[118:121]
	v_mfma_f32_16x16x32_bf16 v[118:121], v[168:171], v[184:187], v[118:121]
	v_mfma_f32_16x16x32_bf16 v[114:117], v[172:175], v[180:183], v[114:117]
	v_mfma_f32_16x16x32_bf16 v[114:117], v[176:179], v[184:187], v[114:117]
	v_mfma_f32_16x16x32_bf16 v[98:101], v[172:175], v[188:191], v[98:101]
	v_mfma_f32_16x16x32_bf16 v[98:101], v[176:179], v[192:195], v[98:101]
	v_mfma_f32_16x16x32_bf16 v[102:105], v[164:167], v[188:191], v[102:105]
	v_mfma_f32_16x16x32_bf16 v[102:105], v[168:171], v[192:195], v[102:105]
	v_mfma_f32_16x16x32_bf16 v[86:89], v[164:167], v[196:199], v[86:89]
	v_mfma_f32_16x16x32_bf16 v[86:89], v[168:171], v[200:203], v[86:89]
	v_mfma_f32_16x16x32_bf16 v[82:85], v[172:175], v[196:199], v[82:85]
	v_mfma_f32_16x16x32_bf16 v[82:85], v[176:179], v[200:203], v[82:85]
	v_mfma_f32_16x16x32_bf16 v[66:69], v[172:175], v[204:207], v[66:69]
	v_mfma_f32_16x16x32_bf16 v[66:69], v[176:179], v[208:211], v[66:69]
	s_setprio 2
	s_barrier
	v_mfma_f32_16x16x32_bf16 v[70:73], v[164:167], v[204:207], v[70:73]
	v_mfma_f32_16x16x32_bf16 v[70:73], v[168:171], v[208:211], v[70:73]
	s_setprio 0
	ds_read_b128 v[180:183], v145 offset:49152
	ds_read_b128 v[184:187], v145 offset:50176
	ds_read_b128 v[188:191], v145 offset:51200
	ds_read_b128 v[192:195], v145 offset:52224
	ds_read_b128 v[196:199], v145 offset:53248
	ds_read_b128 v[200:203], v145 offset:54272
	ds_read_b128 v[204:207], v145 offset:55296
	ds_read_b128 v[208:211], v145 offset:56320
	s_add_u32 s22, s20, 0x80
	s_addc_u32 s23, s21, 0
	s_mov_b32 s78, m0
	s_mov_b32 m0, s46
	s_nop 0
	global_load_lds_dwordx4 v139, s[22:23]
	s_mov_b32 m0, s78
	s_add_u32 s20, s20, 0x80080
	s_mov_b32 s78, m0
	s_mov_b32 m0, s47
	s_nop 0
	global_load_lds_dwordx4 v141, s[22:23]
	s_mov_b32 m0, s78
	s_addc_u32 s21, s21, 0
	s_mov_b32 s22, m0
	s_mov_b32 m0, s48
	s_nop 0
	global_load_lds_dwordx4 v139, s[20:21]
	s_mov_b32 m0, s22
	s_nop 0
	s_mov_b32 s22, m0
	s_mov_b32 m0, s49
	s_nop 0
	global_load_lds_dwordx4 v141, s[20:21]
	s_mov_b32 m0, s22
	s_waitcnt vmcnt(4)
	s_waitcnt lgkmcnt(0)
	s_barrier
	s_setprio 1
	s_waitcnt lgkmcnt(7)
	v_mfma_f32_16x16x32_bf16 v[62:65], v[148:151], v[180:183], v[62:65]
	v_mfma_f32_16x16x32_bf16 v[62:65], v[152:155], v[184:187], v[62:65]
	s_waitcnt lgkmcnt(5)
	v_mfma_f32_16x16x32_bf16 v[58:61], v[156:159], v[180:183], v[58:61]
	v_mfma_f32_16x16x32_bf16 v[58:61], v[160:163], v[184:187], v[58:61]
	s_waitcnt lgkmcnt(3)
	v_mfma_f32_16x16x32_bf16 v[42:45], v[156:159], v[188:191], v[42:45]
	v_mfma_f32_16x16x32_bf16 v[42:45], v[160:163], v[192:195], v[42:45]
	s_waitcnt lgkmcnt(1)
	v_mfma_f32_16x16x32_bf16 v[46:49], v[148:151], v[188:191], v[46:49]
	v_mfma_f32_16x16x32_bf16 v[46:49], v[152:155], v[192:195], v[46:49]
	v_mfma_f32_16x16x32_bf16 v[30:33], v[148:151], v[196:199], v[30:33]
	v_mfma_f32_16x16x32_bf16 v[30:33], v[152:155], v[200:203], v[30:33]
	v_mfma_f32_16x16x32_bf16 v[26:29], v[156:159], v[196:199], v[26:29]
	v_mfma_f32_16x16x32_bf16 v[26:29], v[160:163], v[200:203], v[26:29]
	v_mfma_f32_16x16x32_bf16 v[10:13], v[156:159], v[204:207], v[10:13]
	v_mfma_f32_16x16x32_bf16 v[10:13], v[160:163], v[208:211], v[10:13]
	s_waitcnt lgkmcnt(0)
	v_mfma_f32_16x16x32_bf16 v[14:17], v[148:151], v[204:207], v[14:17]
	v_mfma_f32_16x16x32_bf16 v[14:17], v[152:155], v[208:211], v[14:17]
	s_setprio 0
	s_setprio 1
	v_mfma_f32_16x16x32_bf16 v[54:57], v[164:167], v[180:183], v[54:57]
	v_mfma_f32_16x16x32_bf16 v[54:57], v[168:171], v[184:187], v[54:57]
	v_mfma_f32_16x16x32_bf16 v[50:53], v[172:175], v[180:183], v[50:53]
	v_mfma_f32_16x16x32_bf16 v[50:53], v[176:179], v[184:187], v[50:53]
	v_mfma_f32_16x16x32_bf16 v[34:37], v[172:175], v[188:191], v[34:37]
	v_mfma_f32_16x16x32_bf16 v[34:37], v[176:179], v[192:195], v[34:37]
	v_mfma_f32_16x16x32_bf16 v[38:41], v[164:167], v[188:191], v[38:41]
	v_mfma_f32_16x16x32_bf16 v[38:41], v[168:171], v[192:195], v[38:41]
	v_mfma_f32_16x16x32_bf16 v[22:25], v[164:167], v[196:199], v[22:25]
	v_mfma_f32_16x16x32_bf16 v[22:25], v[168:171], v[200:203], v[22:25]
	v_mfma_f32_16x16x32_bf16 v[18:21], v[172:175], v[196:199], v[18:21]
	v_mfma_f32_16x16x32_bf16 v[18:21], v[176:179], v[200:203], v[18:21]
	v_mfma_f32_16x16x32_bf16 v[2:5], v[172:175], v[204:207], v[2:5]
	v_mfma_f32_16x16x32_bf16 v[2:5], v[176:179], v[208:211], v[2:5]
	s_setprio 2
	s_barrier
	v_mfma_f32_16x16x32_bf16 v[6:9], v[164:167], v[204:207], v[6:9]
	v_mfma_f32_16x16x32_bf16 v[6:9], v[168:171], v[208:211], v[6:9]
	s_setprio 0
	s_add_i32 s77, s77, 2
	s_add_u32 s73, s73, 0x100
	s_addc_u32 s74, s74, 0
	s_add_u32 s18, s18, 0x100
	s_addc_u32 s19, s19, 0
	s_add_u32 s75, s75, 0x100
	s_addc_u32 s76, s76, 0
	s_cmp_gt_u32 s77, 29
	.p2align 6
.LBB0_1224:
	ds_read_b128 v[148:151], v143
	ds_read_b128 v[152:155], v143 offset:1024
	ds_read_b128 v[156:159], v143 offset:2048
	ds_read_b128 v[160:163], v143 offset:3072
	ds_read_b128 v[164:167], v144
	ds_read_b128 v[168:171], v144 offset:1024
	ds_read_b128 v[172:175], v144 offset:2048
	ds_read_b128 v[176:179], v144 offset:3072
	s_cmp_eq_u32 s77, 28
	s_cselect_b32 s21, s9, s74
	s_cselect_b32 s20, s67, s73
	s_cselect_b32 s23, s11, s76
	s_cselect_b32 s22, s66, s75
	ds_read_b128 v[180:183], v145
	ds_read_b128 v[184:187], v145 offset:1024
	ds_read_b128 v[188:191], v145 offset:2048
	ds_read_b128 v[192:195], v145 offset:3072
	ds_read_b128 v[196:199], v145 offset:4096
	ds_read_b128 v[200:203], v145 offset:5120
	ds_read_b128 v[204:207], v145 offset:6144
	ds_read_b128 v[208:211], v145 offset:7168
	s_add_u32 s78, s18, 0xfff80000
	s_addc_u32 s79, s19, -1
	s_mov_b32 s80, m0
	s_mov_b32 m0, s56
	s_nop 0
	global_load_lds_dwordx4 v138, s[78:79]
	s_mov_b32 m0, s80
	s_nop 0
	s_mov_b32 s80, m0
	s_mov_b32 m0, s59
	s_nop 0
	global_load_lds_dwordx4 v140, s[78:79]
	s_mov_b32 m0, s80
	s_mov_b32 s78, m0
	s_mov_b32 m0, s57
	s_nop 0
	global_load_lds_dwordx4 v138, s[18:19]
	s_mov_b32 m0, s78
	s_nop 0
	s_mov_b32 s78, m0
	s_mov_b32 m0, s64
	s_nop 0
	global_load_lds_dwordx4 v140, s[18:19]
	s_mov_b32 m0, s78
	s_waitcnt vmcnt(8)
	s_waitcnt lgkmcnt(0)
	s_barrier
	s_setprio 1
	s_waitcnt lgkmcnt(7)
	v_mfma_f32_16x16x32_bf16 v[126:129], v[148:151], v[180:183], v[126:129]
	v_mfma_f32_16x16x32_bf16 v[126:129], v[152:155], v[184:187], v[126:129]
	s_waitcnt lgkmcnt(5)
	v_mfma_f32_16x16x32_bf16 v[122:125], v[156:159], v[180:183], v[122:125]
	v_mfma_f32_16x16x32_bf16 v[122:125], v[160:163], v[184:187], v[122:125]
	s_waitcnt lgkmcnt(3)
	v_mfma_f32_16x16x32_bf16 v[106:109], v[156:159], v[188:191], v[106:109]
	v_mfma_f32_16x16x32_bf16 v[106:109], v[160:163], v[192:195], v[106:109]
	s_waitcnt lgkmcnt(1)
	v_mfma_f32_16x16x32_bf16 v[110:113], v[148:151], v[188:191], v[110:113]
	v_mfma_f32_16x16x32_bf16 v[110:113], v[152:155], v[192:195], v[110:113]
	v_mfma_f32_16x16x32_bf16 v[94:97], v[148:151], v[196:199], v[94:97]
	v_mfma_f32_16x16x32_bf16 v[94:97], v[152:155], v[200:203], v[94:97]
	v_mfma_f32_16x16x32_bf16 v[90:93], v[156:159], v[196:199], v[90:93]
	v_mfma_f32_16x16x32_bf16 v[90:93], v[160:163], v[200:203], v[90:93]
	v_mfma_f32_16x16x32_bf16 v[74:77], v[156:159], v[204:207], v[74:77]
	v_mfma_f32_16x16x32_bf16 v[74:77], v[160:163], v[208:211], v[74:77]
	s_waitcnt lgkmcnt(0)
	v_mfma_f32_16x16x32_bf16 v[78:81], v[148:151], v[204:207], v[78:81]
	v_mfma_f32_16x16x32_bf16 v[78:81], v[152:155], v[208:211], v[78:81]
	s_setprio 0
	s_setprio 1
	v_mfma_f32_16x16x32_bf16 v[118:121], v[164:167], v[180:183], v[118:121]
	v_mfma_f32_16x16x32_bf16 v[118:121], v[168:171], v[184:187], v[118:121]
	v_mfma_f32_16x16x32_bf16 v[114:117], v[172:175], v[180:183], v[114:117]
	v_mfma_f32_16x16x32_bf16 v[114:117], v[176:179], v[184:187], v[114:117]
	v_mfma_f32_16x16x32_bf16 v[98:101], v[172:175], v[188:191], v[98:101]
	v_mfma_f32_16x16x32_bf16 v[98:101], v[176:179], v[192:195], v[98:101]
	v_mfma_f32_16x16x32_bf16 v[102:105], v[164:167], v[188:191], v[102:105]
	v_mfma_f32_16x16x32_bf16 v[102:105], v[168:171], v[192:195], v[102:105]
	v_mfma_f32_16x16x32_bf16 v[86:89], v[164:167], v[196:199], v[86:89]
	v_mfma_f32_16x16x32_bf16 v[86:89], v[168:171], v[200:203], v[86:89]
	v_mfma_f32_16x16x32_bf16 v[82:85], v[172:175], v[196:199], v[82:85]
	v_mfma_f32_16x16x32_bf16 v[82:85], v[176:179], v[200:203], v[82:85]
	v_mfma_f32_16x16x32_bf16 v[66:69], v[172:175], v[204:207], v[66:69]
	v_mfma_f32_16x16x32_bf16 v[66:69], v[176:179], v[208:211], v[66:69]
	s_setprio 2
	s_barrier
	v_mfma_f32_16x16x32_bf16 v[70:73], v[164:167], v[204:207], v[70:73]
	v_mfma_f32_16x16x32_bf16 v[70:73], v[168:171], v[208:211], v[70:73]
	s_setprio 0
	ds_read_b128 v[180:183], v145 offset:16384
	ds_read_b128 v[184:187], v145 offset:17408
	ds_read_b128 v[188:191], v145 offset:18432
	ds_read_b128 v[192:195], v145 offset:19456
	ds_read_b128 v[196:199], v145 offset:20480
	ds_read_b128 v[200:203], v145 offset:21504
	ds_read_b128 v[204:207], v145 offset:22528
	ds_read_b128 v[208:211], v145 offset:23552
	s_mov_b32 s78, m0
	s_mov_b32 m0, s35
	s_nop 0
	global_load_lds_dwordx4 v139, s[20:21]
	s_mov_b32 m0, s78
	s_nop 0
	s_mov_b32 s78, m0
	s_mov_b32 m0, s36
	s_nop 0
	global_load_lds_dwordx4 v141, s[20:21]
	s_mov_b32 m0, s78
	s_add_u32 s78, s20, 0x80000
	s_addc_u32 s79, s21, 0
	s_mov_b32 s80, m0
	s_mov_b32 m0, s37
	s_nop 0
	global_load_lds_dwordx4 v139, s[78:79]
	s_mov_b32 m0, s80
	s_nop 0
	s_mov_b32 s80, m0
	s_mov_b32 m0, s40
	s_nop 0
	global_load_lds_dwordx4 v141, s[78:79]
	s_mov_b32 m0, s80
	s_waitcnt vmcnt(4)
	s_waitcnt lgkmcnt(0)
	s_barrier
	s_setprio 1
	s_waitcnt lgkmcnt(7)
	v_mfma_f32_16x16x32_bf16 v[62:65], v[148:151], v[180:183], v[62:65]
	v_mfma_f32_16x16x32_bf16 v[62:65], v[152:155], v[184:187], v[62:65]
	s_waitcnt lgkmcnt(5)
	v_mfma_f32_16x16x32_bf16 v[58:61], v[156:159], v[180:183], v[58:61]
	v_mfma_f32_16x16x32_bf16 v[58:61], v[160:163], v[184:187], v[58:61]
	s_waitcnt lgkmcnt(3)
	v_mfma_f32_16x16x32_bf16 v[42:45], v[156:159], v[188:191], v[42:45]
	v_mfma_f32_16x16x32_bf16 v[42:45], v[160:163], v[192:195], v[42:45]
	s_waitcnt lgkmcnt(1)
	v_mfma_f32_16x16x32_bf16 v[46:49], v[148:151], v[188:191], v[46:49]
	v_mfma_f32_16x16x32_bf16 v[46:49], v[152:155], v[192:195], v[46:49]
	v_mfma_f32_16x16x32_bf16 v[30:33], v[148:151], v[196:199], v[30:33]
	v_mfma_f32_16x16x32_bf16 v[30:33], v[152:155], v[200:203], v[30:33]
	v_mfma_f32_16x16x32_bf16 v[26:29], v[156:159], v[196:199], v[26:29]
	v_mfma_f32_16x16x32_bf16 v[26:29], v[160:163], v[200:203], v[26:29]
	v_mfma_f32_16x16x32_bf16 v[10:13], v[156:159], v[204:207], v[10:13]
	v_mfma_f32_16x16x32_bf16 v[10:13], v[160:163], v[208:211], v[10:13]
	s_waitcnt lgkmcnt(0)
	v_mfma_f32_16x16x32_bf16 v[14:17], v[148:151], v[204:207], v[14:17]
	v_mfma_f32_16x16x32_bf16 v[14:17], v[152:155], v[208:211], v[14:17]
	s_setprio 0
	s_setprio 1
	v_mfma_f32_16x16x32_bf16 v[54:57], v[164:167], v[180:183], v[54:57]
	v_mfma_f32_16x16x32_bf16 v[54:57], v[168:171], v[184:187], v[54:57]
	v_mfma_f32_16x16x32_bf16 v[50:53], v[172:175], v[180:183], v[50:53]
	v_mfma_f32_16x16x32_bf16 v[50:53], v[176:179], v[184:187], v[50:53]
	v_mfma_f32_16x16x32_bf16 v[34:37], v[172:175], v[188:191], v[34:37]
	v_mfma_f32_16x16x32_bf16 v[34:37], v[176:179], v[192:195], v[34:37]
	v_mfma_f32_16x16x32_bf16 v[38:41], v[164:167], v[188:191], v[38:41]
	v_mfma_f32_16x16x32_bf16 v[38:41], v[168:171], v[192:195], v[38:41]
	v_mfma_f32_16x16x32_bf16 v[22:25], v[164:167], v[196:199], v[22:25]
	v_mfma_f32_16x16x32_bf16 v[22:25], v[168:171], v[200:203], v[22:25]
	v_mfma_f32_16x16x32_bf16 v[18:21], v[172:175], v[196:199], v[18:21]
	v_mfma_f32_16x16x32_bf16 v[18:21], v[176:179], v[200:203], v[18:21]
	v_mfma_f32_16x16x32_bf16 v[2:5], v[172:175], v[204:207], v[2:5]
	v_mfma_f32_16x16x32_bf16 v[2:5], v[176:179], v[208:211], v[2:5]
	s_setprio 2
	s_barrier
	v_mfma_f32_16x16x32_bf16 v[6:9], v[164:167], v[204:207], v[6:9]
	v_mfma_f32_16x16x32_bf16 v[6:9], v[168:171], v[208:211], v[6:9]
	s_setprio 0
	ds_read_b128 v[148:151], v146
	ds_read_b128 v[152:155], v146 offset:1024
	ds_read_b128 v[156:159], v146 offset:2048
	ds_read_b128 v[160:163], v146 offset:3072
	ds_read_b128 v[164:167], v147
	ds_read_b128 v[168:171], v147 offset:1024
	ds_read_b128 v[172:175], v147 offset:2048
	ds_read_b128 v[176:179], v147 offset:3072
	ds_read_b128 v[180:183], v145 offset:32768
	ds_read_b128 v[184:187], v145 offset:33792
	ds_read_b128 v[188:191], v145 offset:34816
	ds_read_b128 v[192:195], v145 offset:35840
	ds_read_b128 v[196:199], v145 offset:36864
	ds_read_b128 v[200:203], v145 offset:37888
	ds_read_b128 v[204:207], v145 offset:38912
	ds_read_b128 v[208:211], v145 offset:39936
	s_mov_b32 s78, m0
	s_mov_b32 m0, s31
	s_nop 0
	global_load_lds_dwordx4 v138, s[22:23]
	s_mov_b32 m0, s78
	s_nop 0
	s_mov_b32 s78, m0
	s_mov_b32 m0, s41
	s_nop 0
	global_load_lds_dwordx4 v140, s[22:23]
	s_mov_b32 m0, s78
	s_add_u32 s22, s22, 0x80000
	s_addc_u32 s23, s23, 0
	s_mov_b32 s78, m0
	s_mov_b32 m0, s42
	s_nop 0
	global_load_lds_dwordx4 v138, s[22:23]
	s_mov_b32 m0, s78
	s_nop 0
	s_mov_b32 s78, m0
	s_mov_b32 m0, s43
	s_nop 0
	global_load_lds_dwordx4 v140, s[22:23]
	s_mov_b32 m0, s78
	s_waitcnt vmcnt(8)
	s_waitcnt lgkmcnt(0)
	s_barrier
	s_setprio 1
	s_waitcnt lgkmcnt(7)
	v_mfma_f32_16x16x32_bf16 v[126:129], v[148:151], v[180:183], v[126:129]
	v_mfma_f32_16x16x32_bf16 v[126:129], v[152:155], v[184:187], v[126:129]
	s_waitcnt lgkmcnt(5)
	v_mfma_f32_16x16x32_bf16 v[122:125], v[156:159], v[180:183], v[122:125]
	v_mfma_f32_16x16x32_bf16 v[122:125], v[160:163], v[184:187], v[122:125]
	s_waitcnt lgkmcnt(3)
	v_mfma_f32_16x16x32_bf16 v[106:109], v[156:159], v[188:191], v[106:109]
	v_mfma_f32_16x16x32_bf16 v[106:109], v[160:163], v[192:195], v[106:109]
	s_waitcnt lgkmcnt(1)
	v_mfma_f32_16x16x32_bf16 v[110:113], v[148:151], v[188:191], v[110:113]
	v_mfma_f32_16x16x32_bf16 v[110:113], v[152:155], v[192:195], v[110:113]
	v_mfma_f32_16x16x32_bf16 v[94:97], v[148:151], v[196:199], v[94:97]
	v_mfma_f32_16x16x32_bf16 v[94:97], v[152:155], v[200:203], v[94:97]
	v_mfma_f32_16x16x32_bf16 v[90:93], v[156:159], v[196:199], v[90:93]
	v_mfma_f32_16x16x32_bf16 v[90:93], v[160:163], v[200:203], v[90:93]
	v_mfma_f32_16x16x32_bf16 v[74:77], v[156:159], v[204:207], v[74:77]
	v_mfma_f32_16x16x32_bf16 v[74:77], v[160:163], v[208:211], v[74:77]
	s_waitcnt lgkmcnt(0)
	v_mfma_f32_16x16x32_bf16 v[78:81], v[148:151], v[204:207], v[78:81]
	v_mfma_f32_16x16x32_bf16 v[78:81], v[152:155], v[208:211], v[78:81]
	s_setprio 0
	s_setprio 1
	v_mfma_f32_16x16x32_bf16 v[118:121], v[164:167], v[180:183], v[118:121]
	v_mfma_f32_16x16x32_bf16 v[118:121], v[168:171], v[184:187], v[118:121]
	v_mfma_f32_16x16x32_bf16 v[114:117], v[172:175], v[180:183], v[114:117]
	v_mfma_f32_16x16x32_bf16 v[114:117], v[176:179], v[184:187], v[114:117]
	v_mfma_f32_16x16x32_bf16 v[98:101], v[172:175], v[188:191], v[98:101]
	v_mfma_f32_16x16x32_bf16 v[98:101], v[176:179], v[192:195], v[98:101]
	v_mfma_f32_16x16x32_bf16 v[102:105], v[164:167], v[188:191], v[102:105]
	v_mfma_f32_16x16x32_bf16 v[102:105], v[168:171], v[192:195], v[102:105]
	v_mfma_f32_16x16x32_bf16 v[86:89], v[164:167], v[196:199], v[86:89]
	v_mfma_f32_16x16x32_bf16 v[86:89], v[168:171], v[200:203], v[86:89]
	v_mfma_f32_16x16x32_bf16 v[82:85], v[172:175], v[196:199], v[82:85]
	v_mfma_f32_16x16x32_bf16 v[82:85], v[176:179], v[200:203], v[82:85]
	v_mfma_f32_16x16x32_bf16 v[66:69], v[172:175], v[204:207], v[66:69]
	v_mfma_f32_16x16x32_bf16 v[66:69], v[176:179], v[208:211], v[66:69]
	s_setprio 2
	s_barrier
	v_mfma_f32_16x16x32_bf16 v[70:73], v[164:167], v[204:207], v[70:73]
	v_mfma_f32_16x16x32_bf16 v[70:73], v[168:171], v[208:211], v[70:73]
	s_setprio 0
	ds_read_b128 v[180:183], v145 offset:49152
	ds_read_b128 v[184:187], v145 offset:50176
	ds_read_b128 v[188:191], v145 offset:51200
	ds_read_b128 v[192:195], v145 offset:52224
	ds_read_b128 v[196:199], v145 offset:53248
	ds_read_b128 v[200:203], v145 offset:54272
	ds_read_b128 v[204:207], v145 offset:55296
	ds_read_b128 v[208:211], v145 offset:56320
	s_add_u32 s22, s20, 0x80
	s_addc_u32 s23, s21, 0
	s_mov_b32 s78, m0
	s_mov_b32 m0, s46
	s_nop 0
	global_load_lds_dwordx4 v139, s[22:23]
	s_mov_b32 m0, s78
	s_add_u32 s20, s20, 0x80080
	s_mov_b32 s78, m0
	s_mov_b32 m0, s47
	s_nop 0
	global_load_lds_dwordx4 v141, s[22:23]
	s_mov_b32 m0, s78
	s_addc_u32 s21, s21, 0
	s_mov_b32 s22, m0
	s_mov_b32 m0, s48
	s_nop 0
	global_load_lds_dwordx4 v139, s[20:21]
	s_mov_b32 m0, s22
	s_nop 0
	s_mov_b32 s22, m0
	s_mov_b32 m0, s49
	s_nop 0
	global_load_lds_dwordx4 v141, s[20:21]
	s_mov_b32 m0, s22
	s_waitcnt vmcnt(4)
	s_waitcnt lgkmcnt(0)
	s_barrier
	s_setprio 1
	s_waitcnt lgkmcnt(7)
	v_mfma_f32_16x16x32_bf16 v[62:65], v[148:151], v[180:183], v[62:65]
	v_mfma_f32_16x16x32_bf16 v[62:65], v[152:155], v[184:187], v[62:65]
	s_waitcnt lgkmcnt(5)
	v_mfma_f32_16x16x32_bf16 v[58:61], v[156:159], v[180:183], v[58:61]
	v_mfma_f32_16x16x32_bf16 v[58:61], v[160:163], v[184:187], v[58:61]
	s_waitcnt lgkmcnt(3)
	v_mfma_f32_16x16x32_bf16 v[42:45], v[156:159], v[188:191], v[42:45]
	v_mfma_f32_16x16x32_bf16 v[42:45], v[160:163], v[192:195], v[42:45]
	s_waitcnt lgkmcnt(1)
	v_mfma_f32_16x16x32_bf16 v[46:49], v[148:151], v[188:191], v[46:49]
	v_mfma_f32_16x16x32_bf16 v[46:49], v[152:155], v[192:195], v[46:49]
	v_mfma_f32_16x16x32_bf16 v[30:33], v[148:151], v[196:199], v[30:33]
	v_mfma_f32_16x16x32_bf16 v[30:33], v[152:155], v[200:203], v[30:33]
	v_mfma_f32_16x16x32_bf16 v[26:29], v[156:159], v[196:199], v[26:29]
	v_mfma_f32_16x16x32_bf16 v[26:29], v[160:163], v[200:203], v[26:29]
	v_mfma_f32_16x16x32_bf16 v[10:13], v[156:159], v[204:207], v[10:13]
	v_mfma_f32_16x16x32_bf16 v[10:13], v[160:163], v[208:211], v[10:13]
	s_waitcnt lgkmcnt(0)
	v_mfma_f32_16x16x32_bf16 v[14:17], v[148:151], v[204:207], v[14:17]
	v_mfma_f32_16x16x32_bf16 v[14:17], v[152:155], v[208:211], v[14:17]
	s_setprio 0
	s_setprio 1
	v_mfma_f32_16x16x32_bf16 v[54:57], v[164:167], v[180:183], v[54:57]
	v_mfma_f32_16x16x32_bf16 v[54:57], v[168:171], v[184:187], v[54:57]
	v_mfma_f32_16x16x32_bf16 v[50:53], v[172:175], v[180:183], v[50:53]
	v_mfma_f32_16x16x32_bf16 v[50:53], v[176:179], v[184:187], v[50:53]
	v_mfma_f32_16x16x32_bf16 v[34:37], v[172:175], v[188:191], v[34:37]
	v_mfma_f32_16x16x32_bf16 v[34:37], v[176:179], v[192:195], v[34:37]
	v_mfma_f32_16x16x32_bf16 v[38:41], v[164:167], v[188:191], v[38:41]
	v_mfma_f32_16x16x32_bf16 v[38:41], v[168:171], v[192:195], v[38:41]
	v_mfma_f32_16x16x32_bf16 v[22:25], v[164:167], v[196:199], v[22:25]
	v_mfma_f32_16x16x32_bf16 v[22:25], v[168:171], v[200:203], v[22:25]
	v_mfma_f32_16x16x32_bf16 v[18:21], v[172:175], v[196:199], v[18:21]
	v_mfma_f32_16x16x32_bf16 v[18:21], v[176:179], v[200:203], v[18:21]
	v_mfma_f32_16x16x32_bf16 v[2:5], v[172:175], v[204:207], v[2:5]
	v_mfma_f32_16x16x32_bf16 v[2:5], v[176:179], v[208:211], v[2:5]
	s_setprio 2
	s_barrier
	v_mfma_f32_16x16x32_bf16 v[6:9], v[164:167], v[204:207], v[6:9]
	v_mfma_f32_16x16x32_bf16 v[6:9], v[168:171], v[208:211], v[6:9]
	s_setprio 0
	s_add_i32 s77, s77, 2
	s_add_u32 s73, s73, 0x100
	s_addc_u32 s74, s74, 0
	s_add_u32 s18, s18, 0x100
	s_addc_u32 s19, s19, 0
	s_add_u32 s75, s75, 0x100
	s_addc_u32 s76, s76, 0
	s_cmp_gt_u32 s77, 29
	s_cbranch_scc0 .LBB0_1224
	s_and_b64 vcc, exec, s[6:7]
	s_cbranch_vccz .LBB0_1227
	s_barrier

.LBB0_1356:
	s_ashr_i32 s13, s12, 31
	s_lshl_b64 s[14:15], s[12:13], 15
	s_add_u32 s14, s28, s14
	s_addc_u32 s15, s29, s15
	s_and_b64 s[16:17], s[2:3], exec
	s_cselect_b32 s13, s15, s23
	s_cselect_b32 s67, s14, s22
	s_ashr_i32 s11, s10, 31
	s_lshl_b64 s[16:17], s[10:11], 15
	s_add_u32 s16, s30, s16
	s_addc_u32 s17, s31, s17
	s_and_b64 s[24:25], s[2:3], exec
	s_cselect_b32 s11, s17, s21
	s_cselect_b32 s73, s16, s20
	s_add_u32 s74, s20, 0x80000
	s_addc_u32 s75, s21, 0
	s_add_u32 s20, s22, 0x204000
	s_addc_u32 s21, s23, 0
	s_add_u32 s76, s22, 0x400000
	s_addc_u32 s77, s23, 0
	s_mov_b32 s78, -2
	s_waitcnt vmcnt(25)
	s_waitcnt vmcnt(24)
	s_waitcnt vmcnt(15)
	s_waitcnt vmcnt(14)
	s_waitcnt vmcnt(13)
	s_waitcnt vmcnt(12)
	s_waitcnt vmcnt(11)
	s_waitcnt vmcnt(10)
	s_waitcnt vmcnt(9)
	s_waitcnt vmcnt(8)
	s_waitcnt vmcnt(7)
	s_waitcnt vmcnt(6)
	s_waitcnt vmcnt(5)
	s_waitcnt vmcnt(4)
	s_waitcnt vmcnt(3)
	s_waitcnt vmcnt(2)
	s_waitcnt vmcnt(1)
	s_waitcnt vmcnt(0)
	ds_read_b128 v[130:133], v181
	ds_read_b128 v[134:137], v181 offset:1024
	ds_read_b128 v[138:141], v181 offset:2048
	ds_read_b128 v[142:145], v181 offset:3072
	ds_read_b128 v[150:153], v182
	ds_read_b128 v[154:157], v182 offset:1024
	ds_read_b128 v[158:161], v182 offset:2048
	ds_read_b128 v[162:165], v182 offset:3072
	s_cmpk_eq_i32 s78, 0x52
	s_cselect_b32 s23, s11, s75
	s_cselect_b32 s22, s73, s74
	s_cselect_b32 s25, s13, s77
	s_cselect_b32 s24, s67, s76
	ds_read_b128 v[166:169], v183
	ds_read_b128 v[170:173], v183 offset:1024
	ds_read_b128 v[186:189], v183 offset:2048
	ds_read_b128 v[190:193], v183 offset:3072
	ds_read_b128 v[194:197], v183 offset:4096
	ds_read_b128 v[198:201], v183 offset:5120
	ds_read_b128 v[202:205], v183 offset:6144
	ds_read_b128 v[206:209], v183 offset:7168
	s_add_u32 s80, s20, 0xffffc000
	s_addc_u32 s81, s21, -1
	s_mov_b32 s79, m0
	s_mov_b32 m0, s58
	s_nop 0
	global_load_lds_dwordx4 v1, s[80:81]
	s_mov_b32 m0, s79
	s_nop 0
	s_mov_b32 s79, m0
	s_mov_b32 m0, s64
	s_nop 0
	global_load_lds_dwordx4 v177, s[80:81]
	s_mov_b32 m0, s79
	s_nop 0
	s_mov_b32 s79, m0
	s_mov_b32 m0, s59
	s_nop 0
	global_load_lds_dwordx4 v1, s[20:21]
	s_mov_b32 m0, s79
	s_nop 0
	s_mov_b32 s79, m0
	s_mov_b32 m0, s65
	s_nop 0
	global_load_lds_dwordx4 v177, s[20:21]
	s_mov_b32 m0, s79
	s_waitcnt vmcnt(8)
	s_waitcnt lgkmcnt(0)
	s_barrier
	s_setprio 1
	s_waitcnt lgkmcnt(7)
	v_mfma_f32_16x16x32_bf16 v[126:129], v[130:133], v[166:169], 0
	v_mfma_f32_16x16x32_bf16 v[126:129], v[134:137], v[170:173], v[126:129]
	s_waitcnt lgkmcnt(5)
	v_mfma_f32_16x16x32_bf16 v[122:125], v[138:141], v[166:169], 0
	v_mfma_f32_16x16x32_bf16 v[122:125], v[142:145], v[170:173], v[122:125]
	s_waitcnt lgkmcnt(3)
	v_mfma_f32_16x16x32_bf16 v[110:113], v[138:141], v[186:189], 0
	v_mfma_f32_16x16x32_bf16 v[110:113], v[142:145], v[190:193], v[110:113]
	s_waitcnt lgkmcnt(1)
	v_mfma_f32_16x16x32_bf16 v[118:121], v[130:133], v[186:189], 0
	v_mfma_f32_16x16x32_bf16 v[118:121], v[134:137], v[190:193], v[118:121]
	v_mfma_f32_16x16x32_bf16 v[94:97], v[130:133], v[194:197], 0
	v_mfma_f32_16x16x32_bf16 v[94:97], v[134:137], v[198:201], v[94:97]
	v_mfma_f32_16x16x32_bf16 v[90:93], v[138:141], v[194:197], 0
	v_mfma_f32_16x16x32_bf16 v[90:93], v[142:145], v[198:201], v[90:93]
	v_mfma_f32_16x16x32_bf16 v[78:81], v[138:141], v[202:205], 0
	v_mfma_f32_16x16x32_bf16 v[78:81], v[142:145], v[206:209], v[78:81]
	s_waitcnt lgkmcnt(0)
	v_mfma_f32_16x16x32_bf16 v[86:89], v[130:133], v[202:205], 0
	v_mfma_f32_16x16x32_bf16 v[86:89], v[134:137], v[206:209], v[86:89]
	s_setprio 0
	s_setprio 1
	v_mfma_f32_16x16x32_bf16 v[114:117], v[150:153], v[166:169], 0
	v_mfma_f32_16x16x32_bf16 v[114:117], v[154:157], v[170:173], v[114:117]
	v_mfma_f32_16x16x32_bf16 v[106:109], v[158:161], v[166:169], 0
	v_mfma_f32_16x16x32_bf16 v[106:109], v[162:165], v[170:173], v[106:109]
	v_mfma_f32_16x16x32_bf16 v[98:101], v[158:161], v[186:189], 0
	v_mfma_f32_16x16x32_bf16 v[98:101], v[162:165], v[190:193], v[98:101]
	v_mfma_f32_16x16x32_bf16 v[102:105], v[150:153], v[186:189], 0
	v_mfma_f32_16x16x32_bf16 v[102:105], v[154:157], v[190:193], v[102:105]
	v_mfma_f32_16x16x32_bf16 v[82:85], v[150:153], v[194:197], 0
	v_mfma_f32_16x16x32_bf16 v[82:85], v[154:157], v[198:201], v[82:85]
	v_mfma_f32_16x16x32_bf16 v[74:77], v[158:161], v[194:197], 0
	v_mfma_f32_16x16x32_bf16 v[74:77], v[162:165], v[198:201], v[74:77]
	v_mfma_f32_16x16x32_bf16 v[66:69], v[158:161], v[202:205], 0
	v_mfma_f32_16x16x32_bf16 v[66:69], v[162:165], v[206:209], v[66:69]
	s_setprio 2
	s_barrier
	v_mfma_f32_16x16x32_bf16 v[70:73], v[150:153], v[202:205], 0
	v_mfma_f32_16x16x32_bf16 v[70:73], v[154:157], v[206:209], v[70:73]
	s_setprio 0
	ds_read_b128 v[166:169], v183 offset:16384
	ds_read_b128 v[170:173], v183 offset:17408
	ds_read_b128 v[186:189], v183 offset:18432
	ds_read_b128 v[190:193], v183 offset:19456
	ds_read_b128 v[194:197], v183 offset:20480
	ds_read_b128 v[198:201], v183 offset:21504
	ds_read_b128 v[202:205], v183 offset:22528
	ds_read_b128 v[206:209], v183 offset:23552
	s_mov_b32 s79, m0
	s_mov_b32 m0, s35
	s_nop 0
	global_load_lds_dwordx4 v176, s[22:23]
	s_mov_b32 m0, s79
	s_add_u32 s80, s22, 0x4000
	s_mov_b32 s79, m0
	s_mov_b32 m0, s36
	s_nop 0
	global_load_lds_dwordx4 v178, s[22:23]
	s_mov_b32 m0, s79
	s_addc_u32 s81, s23, 0
	s_mov_b32 s79, m0
	s_mov_b32 m0, s37
	s_nop 0
	global_load_lds_dwordx4 v176, s[80:81]
	s_mov_b32 m0, s79
	s_nop 0
	s_mov_b32 s79, m0
	s_mov_b32 m0, s40
	s_nop 0
	global_load_lds_dwordx4 v178, s[80:81]
	s_mov_b32 m0, s79
	s_waitcnt vmcnt(4)
	s_waitcnt lgkmcnt(0)
	s_barrier
	s_setprio 1
	s_waitcnt lgkmcnt(7)
	v_mfma_f32_16x16x32_bf16 v[62:65], v[130:133], v[166:169], 0
	v_mfma_f32_16x16x32_bf16 v[62:65], v[134:137], v[170:173], v[62:65]
	s_waitcnt lgkmcnt(5)
	v_mfma_f32_16x16x32_bf16 v[58:61], v[138:141], v[166:169], 0
	v_mfma_f32_16x16x32_bf16 v[58:61], v[142:145], v[170:173], v[58:61]
	s_waitcnt lgkmcnt(3)
	v_mfma_f32_16x16x32_bf16 v[42:45], v[138:141], v[186:189], 0
	v_mfma_f32_16x16x32_bf16 v[42:45], v[142:145], v[190:193], v[42:45]
	s_waitcnt lgkmcnt(1)
	v_mfma_f32_16x16x32_bf16 v[46:49], v[130:133], v[186:189], 0
	v_mfma_f32_16x16x32_bf16 v[46:49], v[134:137], v[190:193], v[46:49]
	v_mfma_f32_16x16x32_bf16 v[30:33], v[130:133], v[194:197], 0
	v_mfma_f32_16x16x32_bf16 v[30:33], v[134:137], v[198:201], v[30:33]
	v_mfma_f32_16x16x32_bf16 v[26:29], v[138:141], v[194:197], 0
	v_mfma_f32_16x16x32_bf16 v[26:29], v[142:145], v[198:201], v[26:29]
	v_mfma_f32_16x16x32_bf16 v[10:13], v[138:141], v[202:205], 0
	v_mfma_f32_16x16x32_bf16 v[10:13], v[142:145], v[206:209], v[10:13]
	s_waitcnt lgkmcnt(0)
	v_mfma_f32_16x16x32_bf16 v[14:17], v[130:133], v[202:205], 0
	v_mfma_f32_16x16x32_bf16 v[14:17], v[134:137], v[206:209], v[14:17]
	s_setprio 0
	s_setprio 1
	v_mfma_f32_16x16x32_bf16 v[54:57], v[150:153], v[166:169], 0
	v_mfma_f32_16x16x32_bf16 v[54:57], v[154:157], v[170:173], v[54:57]
	v_mfma_f32_16x16x32_bf16 v[50:53], v[158:161], v[166:169], 0
	v_mfma_f32_16x16x32_bf16 v[50:53], v[162:165], v[170:173], v[50:53]
	v_mfma_f32_16x16x32_bf16 v[34:37], v[158:161], v[186:189], 0
	v_mfma_f32_16x16x32_bf16 v[34:37], v[162:165], v[190:193], v[34:37]
	v_mfma_f32_16x16x32_bf16 v[38:41], v[150:153], v[186:189], 0
	v_mfma_f32_16x16x32_bf16 v[38:41], v[154:157], v[190:193], v[38:41]
	v_mfma_f32_16x16x32_bf16 v[22:25], v[150:153], v[194:197], 0
	v_mfma_f32_16x16x32_bf16 v[22:25], v[154:157], v[198:201], v[22:25]
	v_mfma_f32_16x16x32_bf16 v[18:21], v[158:161], v[194:197], 0
	v_mfma_f32_16x16x32_bf16 v[18:21], v[162:165], v[198:201], v[18:21]
	v_mfma_f32_16x16x32_bf16 v[2:5], v[158:161], v[202:205], 0
	v_mfma_f32_16x16x32_bf16 v[2:5], v[162:165], v[206:209], v[2:5]
	s_setprio 2
	s_barrier
	v_mfma_f32_16x16x32_bf16 v[6:9], v[150:153], v[202:205], 0
	v_mfma_f32_16x16x32_bf16 v[6:9], v[154:157], v[206:209], v[6:9]
	s_setprio 0
	ds_read_b128 v[130:133], v184
	ds_read_b128 v[134:137], v184 offset:1024
	ds_read_b128 v[138:141], v184 offset:2048
	ds_read_b128 v[142:145], v184 offset:3072
	ds_read_b128 v[150:153], v185
	ds_read_b128 v[154:157], v185 offset:1024
	ds_read_b128 v[158:161], v185 offset:2048
	ds_read_b128 v[162:165], v185 offset:3072
	ds_read_b128 v[166:169], v183 offset:32768
	ds_read_b128 v[170:173], v183 offset:33792
	ds_read_b128 v[186:189], v183 offset:34816
	ds_read_b128 v[190:193], v183 offset:35840
	ds_read_b128 v[194:197], v183 offset:36864
	ds_read_b128 v[198:201], v183 offset:37888
	ds_read_b128 v[202:205], v183 offset:38912
	ds_read_b128 v[206:209], v183 offset:39936
	s_mov_b32 s79, m0
	s_mov_b32 m0, s34
	s_nop 0
	global_load_lds_dwordx4 v1, s[24:25]
	s_mov_b32 m0, s79
	s_nop 0
	s_mov_b32 s79, m0
	s_mov_b32 m0, s41
	s_nop 0
	global_load_lds_dwordx4 v177, s[24:25]
	s_mov_b32 m0, s79
	s_add_u32 s24, s24, 0x4000
	s_addc_u32 s25, s25, 0
	s_mov_b32 s79, m0
	s_mov_b32 m0, s42
	s_nop 0
	global_load_lds_dwordx4 v1, s[24:25]
	s_mov_b32 m0, s79
	s_nop 0
	s_mov_b32 s79, m0
	s_mov_b32 m0, s43
	s_nop 0
	global_load_lds_dwordx4 v177, s[24:25]
	s_mov_b32 m0, s79
	s_waitcnt vmcnt(8)
	s_waitcnt lgkmcnt(0)
	s_barrier
	s_setprio 1
	s_waitcnt lgkmcnt(7)
	v_mfma_f32_16x16x32_bf16 v[126:129], v[130:133], v[166:169], v[126:129]
	v_mfma_f32_16x16x32_bf16 v[126:129], v[134:137], v[170:173], v[126:129]
	s_waitcnt lgkmcnt(5)
	v_mfma_f32_16x16x32_bf16 v[122:125], v[138:141], v[166:169], v[122:125]
	v_mfma_f32_16x16x32_bf16 v[122:125], v[142:145], v[170:173], v[122:125]
	s_waitcnt lgkmcnt(3)
	v_mfma_f32_16x16x32_bf16 v[110:113], v[138:141], v[186:189], v[110:113]
	v_mfma_f32_16x16x32_bf16 v[110:113], v[142:145], v[190:193], v[110:113]
	s_waitcnt lgkmcnt(1)
	v_mfma_f32_16x16x32_bf16 v[118:121], v[130:133], v[186:189], v[118:121]
	v_mfma_f32_16x16x32_bf16 v[118:121], v[134:137], v[190:193], v[118:121]
	v_mfma_f32_16x16x32_bf16 v[94:97], v[130:133], v[194:197], v[94:97]
	v_mfma_f32_16x16x32_bf16 v[94:97], v[134:137], v[198:201], v[94:97]
	v_mfma_f32_16x16x32_bf16 v[90:93], v[138:141], v[194:197], v[90:93]
	v_mfma_f32_16x16x32_bf16 v[90:93], v[142:145], v[198:201], v[90:93]
	v_mfma_f32_16x16x32_bf16 v[78:81], v[138:141], v[202:205], v[78:81]
	v_mfma_f32_16x16x32_bf16 v[78:81], v[142:145], v[206:209], v[78:81]
	s_waitcnt lgkmcnt(0)
	v_mfma_f32_16x16x32_bf16 v[86:89], v[130:133], v[202:205], v[86:89]
	v_mfma_f32_16x16x32_bf16 v[86:89], v[134:137], v[206:209], v[86:89]
	s_setprio 0
	s_setprio 1
	v_mfma_f32_16x16x32_bf16 v[114:117], v[150:153], v[166:169], v[114:117]
	v_mfma_f32_16x16x32_bf16 v[114:117], v[154:157], v[170:173], v[114:117]
	v_mfma_f32_16x16x32_bf16 v[106:109], v[158:161], v[166:169], v[106:109]
	v_mfma_f32_16x16x32_bf16 v[106:109], v[162:165], v[170:173], v[106:109]
	v_mfma_f32_16x16x32_bf16 v[98:101], v[158:161], v[186:189], v[98:101]
	v_mfma_f32_16x16x32_bf16 v[98:101], v[162:165], v[190:193], v[98:101]
	v_mfma_f32_16x16x32_bf16 v[102:105], v[150:153], v[186:189], v[102:105]
	v_mfma_f32_16x16x32_bf16 v[102:105], v[154:157], v[190:193], v[102:105]
	v_mfma_f32_16x16x32_bf16 v[82:85], v[150:153], v[194:197], v[82:85]
	v_mfma_f32_16x16x32_bf16 v[82:85], v[154:157], v[198:201], v[82:85]
	v_mfma_f32_16x16x32_bf16 v[74:77], v[158:161], v[194:197], v[74:77]
	v_mfma_f32_16x16x32_bf16 v[74:77], v[162:165], v[198:201], v[74:77]
	v_mfma_f32_16x16x32_bf16 v[66:69], v[158:161], v[202:205], v[66:69]
	v_mfma_f32_16x16x32_bf16 v[66:69], v[162:165], v[206:209], v[66:69]
	s_setprio 2
	s_barrier
	v_mfma_f32_16x16x32_bf16 v[70:73], v[150:153], v[202:205], v[70:73]
	v_mfma_f32_16x16x32_bf16 v[70:73], v[154:157], v[206:209], v[70:73]
	s_setprio 0
	ds_read_b128 v[166:169], v183 offset:49152
	ds_read_b128 v[170:173], v183 offset:50176
	ds_read_b128 v[186:189], v183 offset:51200
	ds_read_b128 v[190:193], v183 offset:52224
	ds_read_b128 v[194:197], v183 offset:53248
	ds_read_b128 v[198:201], v183 offset:54272
	ds_read_b128 v[202:205], v183 offset:55296
	ds_read_b128 v[206:209], v183 offset:56320
	s_add_u32 s24, s22, 0x40000
	s_addc_u32 s25, s23, 0
	s_mov_b32 s79, m0
	s_mov_b32 m0, s46
	s_nop 0
	global_load_lds_dwordx4 v176, s[24:25]
	s_mov_b32 m0, s79
	s_add_u32 s22, s22, 0x44000
	s_mov_b32 s79, m0
	s_mov_b32 m0, s47
	s_nop 0
	global_load_lds_dwordx4 v178, s[24:25]
	s_mov_b32 m0, s79
	s_addc_u32 s23, s23, 0
	s_mov_b32 s24, m0
	s_mov_b32 m0, s48
	s_nop 0
	global_load_lds_dwordx4 v176, s[22:23]
	s_mov_b32 m0, s24
	s_nop 0
	s_mov_b32 s24, m0
	s_mov_b32 m0, s49
	s_nop 0
	global_load_lds_dwordx4 v178, s[22:23]
	s_mov_b32 m0, s24
	s_waitcnt vmcnt(4)
	s_waitcnt lgkmcnt(0)
	s_barrier
	s_setprio 1
	s_waitcnt lgkmcnt(7)
	v_mfma_f32_16x16x32_bf16 v[62:65], v[130:133], v[166:169], v[62:65]
	v_mfma_f32_16x16x32_bf16 v[62:65], v[134:137], v[170:173], v[62:65]
	s_waitcnt lgkmcnt(5)
	v_mfma_f32_16x16x32_bf16 v[58:61], v[138:141], v[166:169], v[58:61]
	v_mfma_f32_16x16x32_bf16 v[58:61], v[142:145], v[170:173], v[58:61]
	s_waitcnt lgkmcnt(3)
	v_mfma_f32_16x16x32_bf16 v[42:45], v[138:141], v[186:189], v[42:45]
	v_mfma_f32_16x16x32_bf16 v[42:45], v[142:145], v[190:193], v[42:45]
	s_waitcnt lgkmcnt(1)
	v_mfma_f32_16x16x32_bf16 v[46:49], v[130:133], v[186:189], v[46:49]
	v_mfma_f32_16x16x32_bf16 v[46:49], v[134:137], v[190:193], v[46:49]
	v_mfma_f32_16x16x32_bf16 v[30:33], v[130:133], v[194:197], v[30:33]
	v_mfma_f32_16x16x32_bf16 v[30:33], v[134:137], v[198:201], v[30:33]
	v_mfma_f32_16x16x32_bf16 v[26:29], v[138:141], v[194:197], v[26:29]
	v_mfma_f32_16x16x32_bf16 v[26:29], v[142:145], v[198:201], v[26:29]
	v_mfma_f32_16x16x32_bf16 v[10:13], v[138:141], v[202:205], v[10:13]
	v_mfma_f32_16x16x32_bf16 v[10:13], v[142:145], v[206:209], v[10:13]
	s_waitcnt lgkmcnt(0)
	v_mfma_f32_16x16x32_bf16 v[14:17], v[130:133], v[202:205], v[14:17]
	v_mfma_f32_16x16x32_bf16 v[14:17], v[134:137], v[206:209], v[14:17]
	s_setprio 0
	s_setprio 1
	v_mfma_f32_16x16x32_bf16 v[54:57], v[150:153], v[166:169], v[54:57]
	v_mfma_f32_16x16x32_bf16 v[54:57], v[154:157], v[170:173], v[54:57]
	v_mfma_f32_16x16x32_bf16 v[50:53], v[158:161], v[166:169], v[50:53]
	v_mfma_f32_16x16x32_bf16 v[50:53], v[162:165], v[170:173], v[50:53]
	v_mfma_f32_16x16x32_bf16 v[34:37], v[158:161], v[186:189], v[34:37]
	v_mfma_f32_16x16x32_bf16 v[34:37], v[162:165], v[190:193], v[34:37]
	v_mfma_f32_16x16x32_bf16 v[38:41], v[150:153], v[186:189], v[38:41]
	v_mfma_f32_16x16x32_bf16 v[38:41], v[154:157], v[190:193], v[38:41]
	v_mfma_f32_16x16x32_bf16 v[22:25], v[150:153], v[194:197], v[22:25]
	v_mfma_f32_16x16x32_bf16 v[22:25], v[154:157], v[198:201], v[22:25]
	v_mfma_f32_16x16x32_bf16 v[18:21], v[158:161], v[194:197], v[18:21]
	v_mfma_f32_16x16x32_bf16 v[18:21], v[162:165], v[198:201], v[18:21]
	v_mfma_f32_16x16x32_bf16 v[2:5], v[158:161], v[202:205], v[2:5]
	v_mfma_f32_16x16x32_bf16 v[2:5], v[162:165], v[206:209], v[2:5]
	s_setprio 2
	s_barrier
	v_mfma_f32_16x16x32_bf16 v[6:9], v[150:153], v[202:205], v[6:9]
	v_mfma_f32_16x16x32_bf16 v[6:9], v[154:157], v[206:209], v[6:9]
	s_setprio 0
	s_add_i32 s78, s78, 2
	s_add_u32 s74, s74, 0x80000
	s_addc_u32 s75, s75, 0
	s_add_u32 s20, s20, 0x400000
	s_addc_u32 s21, s21, 0
	s_add_u32 s76, s76, 0x400000
	s_addc_u32 s77, s77, 0
	s_cmpk_gt_u32 s78, 0x53
	.p2align 6
.LBB0_1357:
	ds_read_b128 v[130:133], v181
	ds_read_b128 v[134:137], v181 offset:1024
	ds_read_b128 v[138:141], v181 offset:2048
	ds_read_b128 v[142:145], v181 offset:3072
	ds_read_b128 v[150:153], v182
	ds_read_b128 v[154:157], v182 offset:1024
	ds_read_b128 v[158:161], v182 offset:2048
	ds_read_b128 v[162:165], v182 offset:3072
	s_cmpk_eq_i32 s78, 0x52
	s_cselect_b32 s23, s11, s75
	s_cselect_b32 s22, s73, s74
	s_cselect_b32 s25, s13, s77
	s_cselect_b32 s24, s67, s76
	ds_read_b128 v[166:169], v183
	ds_read_b128 v[170:173], v183 offset:1024
	ds_read_b128 v[186:189], v183 offset:2048
	ds_read_b128 v[190:193], v183 offset:3072
	ds_read_b128 v[194:197], v183 offset:4096
	ds_read_b128 v[198:201], v183 offset:5120
	ds_read_b128 v[202:205], v183 offset:6144
	ds_read_b128 v[206:209], v183 offset:7168
	s_add_u32 s80, s20, 0xffffc000
	s_addc_u32 s81, s21, -1
	s_mov_b32 s79, m0
	s_mov_b32 m0, s58
	s_nop 0
	global_load_lds_dwordx4 v1, s[80:81]
	s_mov_b32 m0, s79
	s_nop 0
	s_mov_b32 s79, m0
	s_mov_b32 m0, s64
	s_nop 0
	global_load_lds_dwordx4 v177, s[80:81]
	s_mov_b32 m0, s79
	s_nop 0
	s_mov_b32 s79, m0
	s_mov_b32 m0, s59
	s_nop 0
	global_load_lds_dwordx4 v1, s[20:21]
	s_mov_b32 m0, s79
	s_nop 0
	s_mov_b32 s79, m0
	s_mov_b32 m0, s65
	s_nop 0
	global_load_lds_dwordx4 v177, s[20:21]
	s_mov_b32 m0, s79
	s_waitcnt vmcnt(8)
	s_waitcnt lgkmcnt(0)
	s_barrier
	s_setprio 1
	s_waitcnt lgkmcnt(7)
	v_mfma_f32_16x16x32_bf16 v[126:129], v[130:133], v[166:169], v[126:129]
	v_mfma_f32_16x16x32_bf16 v[126:129], v[134:137], v[170:173], v[126:129]
	s_waitcnt lgkmcnt(5)
	v_mfma_f32_16x16x32_bf16 v[122:125], v[138:141], v[166:169], v[122:125]
	v_mfma_f32_16x16x32_bf16 v[122:125], v[142:145], v[170:173], v[122:125]
	s_waitcnt lgkmcnt(3)
	v_mfma_f32_16x16x32_bf16 v[110:113], v[138:141], v[186:189], v[110:113]
	v_mfma_f32_16x16x32_bf16 v[110:113], v[142:145], v[190:193], v[110:113]
	s_waitcnt lgkmcnt(1)
	v_mfma_f32_16x16x32_bf16 v[118:121], v[130:133], v[186:189], v[118:121]
	v_mfma_f32_16x16x32_bf16 v[118:121], v[134:137], v[190:193], v[118:121]
	v_mfma_f32_16x16x32_bf16 v[94:97], v[130:133], v[194:197], v[94:97]
	v_mfma_f32_16x16x32_bf16 v[94:97], v[134:137], v[198:201], v[94:97]
	v_mfma_f32_16x16x32_bf16 v[90:93], v[138:141], v[194:197], v[90:93]
	v_mfma_f32_16x16x32_bf16 v[90:93], v[142:145], v[198:201], v[90:93]
	v_mfma_f32_16x16x32_bf16 v[78:81], v[138:141], v[202:205], v[78:81]
	v_mfma_f32_16x16x32_bf16 v[78:81], v[142:145], v[206:209], v[78:81]
	s_waitcnt lgkmcnt(0)
	v_mfma_f32_16x16x32_bf16 v[86:89], v[130:133], v[202:205], v[86:89]
	v_mfma_f32_16x16x32_bf16 v[86:89], v[134:137], v[206:209], v[86:89]
	s_setprio 0
	s_setprio 1
	v_mfma_f32_16x16x32_bf16 v[114:117], v[150:153], v[166:169], v[114:117]
	v_mfma_f32_16x16x32_bf16 v[114:117], v[154:157], v[170:173], v[114:117]
	v_mfma_f32_16x16x32_bf16 v[106:109], v[158:161], v[166:169], v[106:109]
	v_mfma_f32_16x16x32_bf16 v[106:109], v[162:165], v[170:173], v[106:109]
	v_mfma_f32_16x16x32_bf16 v[98:101], v[158:161], v[186:189], v[98:101]
	v_mfma_f32_16x16x32_bf16 v[98:101], v[162:165], v[190:193], v[98:101]
	v_mfma_f32_16x16x32_bf16 v[102:105], v[150:153], v[186:189], v[102:105]
	v_mfma_f32_16x16x32_bf16 v[102:105], v[154:157], v[190:193], v[102:105]
	v_mfma_f32_16x16x32_bf16 v[82:85], v[150:153], v[194:197], v[82:85]
	v_mfma_f32_16x16x32_bf16 v[82:85], v[154:157], v[198:201], v[82:85]
	v_mfma_f32_16x16x32_bf16 v[74:77], v[158:161], v[194:197], v[74:77]
	v_mfma_f32_16x16x32_bf16 v[74:77], v[162:165], v[198:201], v[74:77]
	v_mfma_f32_16x16x32_bf16 v[66:69], v[158:161], v[202:205], v[66:69]
	v_mfma_f32_16x16x32_bf16 v[66:69], v[162:165], v[206:209], v[66:69]
	s_setprio 2
	s_barrier
	v_mfma_f32_16x16x32_bf16 v[70:73], v[150:153], v[202:205], v[70:73]
	v_mfma_f32_16x16x32_bf16 v[70:73], v[154:157], v[206:209], v[70:73]
	s_setprio 0
	ds_read_b128 v[166:169], v183 offset:16384
	ds_read_b128 v[170:173], v183 offset:17408
	ds_read_b128 v[186:189], v183 offset:18432
	ds_read_b128 v[190:193], v183 offset:19456
	ds_read_b128 v[194:197], v183 offset:20480
	ds_read_b128 v[198:201], v183 offset:21504
	ds_read_b128 v[202:205], v183 offset:22528
	ds_read_b128 v[206:209], v183 offset:23552
	s_mov_b32 s79, m0
	s_mov_b32 m0, s35
	s_nop 0
	global_load_lds_dwordx4 v176, s[22:23]
	s_mov_b32 m0, s79
	s_add_u32 s80, s22, 0x4000
	s_mov_b32 s79, m0
	s_mov_b32 m0, s36
	s_nop 0
	global_load_lds_dwordx4 v178, s[22:23]
	s_mov_b32 m0, s79
	s_addc_u32 s81, s23, 0
	s_mov_b32 s79, m0
	s_mov_b32 m0, s37
	s_nop 0
	global_load_lds_dwordx4 v176, s[80:81]
	s_mov_b32 m0, s79
	s_nop 0
	s_mov_b32 s79, m0
	s_mov_b32 m0, s40
	s_nop 0
	global_load_lds_dwordx4 v178, s[80:81]
	s_mov_b32 m0, s79
	s_waitcnt vmcnt(4)
	s_waitcnt lgkmcnt(0)
	s_barrier
	s_setprio 1
	s_waitcnt lgkmcnt(7)
	v_mfma_f32_16x16x32_bf16 v[62:65], v[130:133], v[166:169], v[62:65]
	v_mfma_f32_16x16x32_bf16 v[62:65], v[134:137], v[170:173], v[62:65]
	s_waitcnt lgkmcnt(5)
	v_mfma_f32_16x16x32_bf16 v[58:61], v[138:141], v[166:169], v[58:61]
	v_mfma_f32_16x16x32_bf16 v[58:61], v[142:145], v[170:173], v[58:61]
	s_waitcnt lgkmcnt(3)
	v_mfma_f32_16x16x32_bf16 v[42:45], v[138:141], v[186:189], v[42:45]
	v_mfma_f32_16x16x32_bf16 v[42:45], v[142:145], v[190:193], v[42:45]
	s_waitcnt lgkmcnt(1)
	v_mfma_f32_16x16x32_bf16 v[46:49], v[130:133], v[186:189], v[46:49]
	v_mfma_f32_16x16x32_bf16 v[46:49], v[134:137], v[190:193], v[46:49]
	v_mfma_f32_16x16x32_bf16 v[30:33], v[130:133], v[194:197], v[30:33]
	v_mfma_f32_16x16x32_bf16 v[30:33], v[134:137], v[198:201], v[30:33]
	v_mfma_f32_16x16x32_bf16 v[26:29], v[138:141], v[194:197], v[26:29]
	v_mfma_f32_16x16x32_bf16 v[26:29], v[142:145], v[198:201], v[26:29]
	v_mfma_f32_16x16x32_bf16 v[10:13], v[138:141], v[202:205], v[10:13]
	v_mfma_f32_16x16x32_bf16 v[10:13], v[142:145], v[206:209], v[10:13]
	s_waitcnt lgkmcnt(0)
	v_mfma_f32_16x16x32_bf16 v[14:17], v[130:133], v[202:205], v[14:17]
	v_mfma_f32_16x16x32_bf16 v[14:17], v[134:137], v[206:209], v[14:17]
	s_setprio 0
	s_setprio 1
	v_mfma_f32_16x16x32_bf16 v[54:57], v[150:153], v[166:169], v[54:57]
	v_mfma_f32_16x16x32_bf16 v[54:57], v[154:157], v[170:173], v[54:57]
	v_mfma_f32_16x16x32_bf16 v[50:53], v[158:161], v[166:169], v[50:53]
	v_mfma_f32_16x16x32_bf16 v[50:53], v[162:165], v[170:173], v[50:53]
	v_mfma_f32_16x16x32_bf16 v[34:37], v[158:161], v[186:189], v[34:37]
	v_mfma_f32_16x16x32_bf16 v[34:37], v[162:165], v[190:193], v[34:37]
	v_mfma_f32_16x16x32_bf16 v[38:41], v[150:153], v[186:189], v[38:41]
	v_mfma_f32_16x16x32_bf16 v[38:41], v[154:157], v[190:193], v[38:41]
	v_mfma_f32_16x16x32_bf16 v[22:25], v[150:153], v[194:197], v[22:25]
	v_mfma_f32_16x16x32_bf16 v[22:25], v[154:157], v[198:201], v[22:25]
	v_mfma_f32_16x16x32_bf16 v[18:21], v[158:161], v[194:197], v[18:21]
	v_mfma_f32_16x16x32_bf16 v[18:21], v[162:165], v[198:201], v[18:21]
	v_mfma_f32_16x16x32_bf16 v[2:5], v[158:161], v[202:205], v[2:5]
	v_mfma_f32_16x16x32_bf16 v[2:5], v[162:165], v[206:209], v[2:5]
	s_setprio 2
	s_barrier
	v_mfma_f32_16x16x32_bf16 v[6:9], v[150:153], v[202:205], v[6:9]
	v_mfma_f32_16x16x32_bf16 v[6:9], v[154:157], v[206:209], v[6:9]
	s_setprio 0
	ds_read_b128 v[130:133], v184
	ds_read_b128 v[134:137], v184 offset:1024
	ds_read_b128 v[138:141], v184 offset:2048
	ds_read_b128 v[142:145], v184 offset:3072
	ds_read_b128 v[150:153], v185
	ds_read_b128 v[154:157], v185 offset:1024
	ds_read_b128 v[158:161], v185 offset:2048
	ds_read_b128 v[162:165], v185 offset:3072
	ds_read_b128 v[166:169], v183 offset:32768
	ds_read_b128 v[170:173], v183 offset:33792
	ds_read_b128 v[186:189], v183 offset:34816
	ds_read_b128 v[190:193], v183 offset:35840
	ds_read_b128 v[194:197], v183 offset:36864
	ds_read_b128 v[198:201], v183 offset:37888
	ds_read_b128 v[202:205], v183 offset:38912
	ds_read_b128 v[206:209], v183 offset:39936
	s_mov_b32 s79, m0
	s_mov_b32 m0, s34
	s_nop 0
	global_load_lds_dwordx4 v1, s[24:25]
	s_mov_b32 m0, s79
	s_nop 0
	s_mov_b32 s79, m0
	s_mov_b32 m0, s41
	s_nop 0
	global_load_lds_dwordx4 v177, s[24:25]
	s_mov_b32 m0, s79
	s_add_u32 s24, s24, 0x4000
	s_addc_u32 s25, s25, 0
	s_mov_b32 s79, m0
	s_mov_b32 m0, s42
	s_nop 0
	global_load_lds_dwordx4 v1, s[24:25]
	s_mov_b32 m0, s79
	s_nop 0
	s_mov_b32 s79, m0
	s_mov_b32 m0, s43
	s_nop 0
	global_load_lds_dwordx4 v177, s[24:25]
	s_mov_b32 m0, s79
	s_waitcnt vmcnt(8)
	s_waitcnt lgkmcnt(0)
	s_barrier
	s_setprio 1
	s_waitcnt lgkmcnt(7)
	v_mfma_f32_16x16x32_bf16 v[126:129], v[130:133], v[166:169], v[126:129]
	v_mfma_f32_16x16x32_bf16 v[126:129], v[134:137], v[170:173], v[126:129]
	s_waitcnt lgkmcnt(5)
	v_mfma_f32_16x16x32_bf16 v[122:125], v[138:141], v[166:169], v[122:125]
	v_mfma_f32_16x16x32_bf16 v[122:125], v[142:145], v[170:173], v[122:125]
	s_waitcnt lgkmcnt(3)
	v_mfma_f32_16x16x32_bf16 v[110:113], v[138:141], v[186:189], v[110:113]
	v_mfma_f32_16x16x32_bf16 v[110:113], v[142:145], v[190:193], v[110:113]
	s_waitcnt lgkmcnt(1)
	v_mfma_f32_16x16x32_bf16 v[118:121], v[130:133], v[186:189], v[118:121]
	v_mfma_f32_16x16x32_bf16 v[118:121], v[134:137], v[190:193], v[118:121]
	v_mfma_f32_16x16x32_bf16 v[94:97], v[130:133], v[194:197], v[94:97]
	v_mfma_f32_16x16x32_bf16 v[94:97], v[134:137], v[198:201], v[94:97]
	v_mfma_f32_16x16x32_bf16 v[90:93], v[138:141], v[194:197], v[90:93]
	v_mfma_f32_16x16x32_bf16 v[90:93], v[142:145], v[198:201], v[90:93]
	v_mfma_f32_16x16x32_bf16 v[78:81], v[138:141], v[202:205], v[78:81]
	v_mfma_f32_16x16x32_bf16 v[78:81], v[142:145], v[206:209], v[78:81]
	s_waitcnt lgkmcnt(0)
	v_mfma_f32_16x16x32_bf16 v[86:89], v[130:133], v[202:205], v[86:89]
	v_mfma_f32_16x16x32_bf16 v[86:89], v[134:137], v[206:209], v[86:89]
	s_setprio 0
	s_setprio 1
	v_mfma_f32_16x16x32_bf16 v[114:117], v[150:153], v[166:169], v[114:117]
	v_mfma_f32_16x16x32_bf16 v[114:117], v[154:157], v[170:173], v[114:117]
	v_mfma_f32_16x16x32_bf16 v[106:109], v[158:161], v[166:169], v[106:109]
	v_mfma_f32_16x16x32_bf16 v[106:109], v[162:165], v[170:173], v[106:109]
	v_mfma_f32_16x16x32_bf16 v[98:101], v[158:161], v[186:189], v[98:101]
	v_mfma_f32_16x16x32_bf16 v[98:101], v[162:165], v[190:193], v[98:101]
	v_mfma_f32_16x16x32_bf16 v[102:105], v[150:153], v[186:189], v[102:105]
	v_mfma_f32_16x16x32_bf16 v[102:105], v[154:157], v[190:193], v[102:105]
	v_mfma_f32_16x16x32_bf16 v[82:85], v[150:153], v[194:197], v[82:85]
	v_mfma_f32_16x16x32_bf16 v[82:85], v[154:157], v[198:201], v[82:85]
	v_mfma_f32_16x16x32_bf16 v[74:77], v[158:161], v[194:197], v[74:77]
	v_mfma_f32_16x16x32_bf16 v[74:77], v[162:165], v[198:201], v[74:77]
	v_mfma_f32_16x16x32_bf16 v[66:69], v[158:161], v[202:205], v[66:69]
	v_mfma_f32_16x16x32_bf16 v[66:69], v[162:165], v[206:209], v[66:69]
	s_setprio 2
	s_barrier
	v_mfma_f32_16x16x32_bf16 v[70:73], v[150:153], v[202:205], v[70:73]
	v_mfma_f32_16x16x32_bf16 v[70:73], v[154:157], v[206:209], v[70:73]
	s_setprio 0
	ds_read_b128 v[166:169], v183 offset:49152
	ds_read_b128 v[170:173], v183 offset:50176
	ds_read_b128 v[186:189], v183 offset:51200
	ds_read_b128 v[190:193], v183 offset:52224
	ds_read_b128 v[194:197], v183 offset:53248
	ds_read_b128 v[198:201], v183 offset:54272
	ds_read_b128 v[202:205], v183 offset:55296
	ds_read_b128 v[206:209], v183 offset:56320
	s_add_u32 s24, s22, 0x40000
	s_addc_u32 s25, s23, 0
	s_mov_b32 s79, m0
	s_mov_b32 m0, s46
	s_nop 0
	global_load_lds_dwordx4 v176, s[24:25]
	s_mov_b32 m0, s79
	s_add_u32 s22, s22, 0x44000
	s_mov_b32 s79, m0
	s_mov_b32 m0, s47
	s_nop 0
	global_load_lds_dwordx4 v178, s[24:25]
	s_mov_b32 m0, s79
	s_addc_u32 s23, s23, 0
	s_mov_b32 s24, m0
	s_mov_b32 m0, s48
	s_nop 0
	global_load_lds_dwordx4 v176, s[22:23]
	s_mov_b32 m0, s24
	s_nop 0
	s_mov_b32 s24, m0
	s_mov_b32 m0, s49
	s_nop 0
	global_load_lds_dwordx4 v178, s[22:23]
	s_mov_b32 m0, s24
	s_waitcnt vmcnt(4)
	s_waitcnt lgkmcnt(0)
	s_barrier
	s_setprio 1
	s_waitcnt lgkmcnt(7)
	v_mfma_f32_16x16x32_bf16 v[62:65], v[130:133], v[166:169], v[62:65]
	v_mfma_f32_16x16x32_bf16 v[62:65], v[134:137], v[170:173], v[62:65]
	s_waitcnt lgkmcnt(5)
	v_mfma_f32_16x16x32_bf16 v[58:61], v[138:141], v[166:169], v[58:61]
	v_mfma_f32_16x16x32_bf16 v[58:61], v[142:145], v[170:173], v[58:61]
	s_waitcnt lgkmcnt(3)
	v_mfma_f32_16x16x32_bf16 v[42:45], v[138:141], v[186:189], v[42:45]
	v_mfma_f32_16x16x32_bf16 v[42:45], v[142:145], v[190:193], v[42:45]
	s_waitcnt lgkmcnt(1)
	v_mfma_f32_16x16x32_bf16 v[46:49], v[130:133], v[186:189], v[46:49]
	v_mfma_f32_16x16x32_bf16 v[46:49], v[134:137], v[190:193], v[46:49]
	v_mfma_f32_16x16x32_bf16 v[30:33], v[130:133], v[194:197], v[30:33]
	v_mfma_f32_16x16x32_bf16 v[30:33], v[134:137], v[198:201], v[30:33]
	v_mfma_f32_16x16x32_bf16 v[26:29], v[138:141], v[194:197], v[26:29]
	v_mfma_f32_16x16x32_bf16 v[26:29], v[142:145], v[198:201], v[26:29]
	v_mfma_f32_16x16x32_bf16 v[10:13], v[138:141], v[202:205], v[10:13]
	v_mfma_f32_16x16x32_bf16 v[10:13], v[142:145], v[206:209], v[10:13]
	s_waitcnt lgkmcnt(0)
	v_mfma_f32_16x16x32_bf16 v[14:17], v[130:133], v[202:205], v[14:17]
	v_mfma_f32_16x16x32_bf16 v[14:17], v[134:137], v[206:209], v[14:17]
	s_setprio 0
	s_setprio 1
	v_mfma_f32_16x16x32_bf16 v[54:57], v[150:153], v[166:169], v[54:57]
	v_mfma_f32_16x16x32_bf16 v[54:57], v[154:157], v[170:173], v[54:57]
	v_mfma_f32_16x16x32_bf16 v[50:53], v[158:161], v[166:169], v[50:53]
	v_mfma_f32_16x16x32_bf16 v[50:53], v[162:165], v[170:173], v[50:53]
	v_mfma_f32_16x16x32_bf16 v[34:37], v[158:161], v[186:189], v[34:37]
	v_mfma_f32_16x16x32_bf16 v[34:37], v[162:165], v[190:193], v[34:37]
	v_mfma_f32_16x16x32_bf16 v[38:41], v[150:153], v[186:189], v[38:41]
	v_mfma_f32_16x16x32_bf16 v[38:41], v[154:157], v[190:193], v[38:41]
	v_mfma_f32_16x16x32_bf16 v[22:25], v[150:153], v[194:197], v[22:25]
	v_mfma_f32_16x16x32_bf16 v[22:25], v[154:157], v[198:201], v[22:25]
	v_mfma_f32_16x16x32_bf16 v[18:21], v[158:161], v[194:197], v[18:21]
	v_mfma_f32_16x16x32_bf16 v[18:21], v[162:165], v[198:201], v[18:21]
	v_mfma_f32_16x16x32_bf16 v[2:5], v[158:161], v[202:205], v[2:5]
	v_mfma_f32_16x16x32_bf16 v[2:5], v[162:165], v[206:209], v[2:5]
	s_setprio 2
	s_barrier
	v_mfma_f32_16x16x32_bf16 v[6:9], v[150:153], v[202:205], v[6:9]
	v_mfma_f32_16x16x32_bf16 v[6:9], v[154:157], v[206:209], v[6:9]
	s_setprio 0
	s_add_i32 s78, s78, 2
	s_add_u32 s74, s74, 0x80000
	s_addc_u32 s75, s75, 0
	s_add_u32 s20, s20, 0x400000
	s_addc_u32 s21, s21, 0
	s_add_u32 s76, s76, 0x400000
	s_addc_u32 s77, s77, 0
	s_cmpk_gt_u32 s78, 0x53
	s_cbranch_scc0 .LBB0_1357
	s_and_b64 vcc, exec, s[8:9]
	s_cbranch_vccz .LBB0_1360
	s_barrier

.LBB0_1784:
	s_ashr_i32 s11, s10, 31
	s_lshl_b64 s[12:13], s[10:11], 20
	s_add_u32 s12, s26, s12
	s_addc_u32 s13, s27, s13
	s_and_b64 s[14:15], s[2:3], exec
	s_cselect_b32 s11, s13, s21
	s_cselect_b32 s64, s12, s20
	s_ashr_i32 s9, s8, 31
	s_lshl_b64 s[14:15], s[8:9], 20
	s_add_u32 s14, s28, s14
	s_addc_u32 s15, s29, s15
	s_and_b64 s[22:23], s[2:3], exec
	s_cselect_b32 s9, s15, s19
	s_cselect_b32 s65, s14, s18
	s_add_u32 s66, s18, 0x100
	s_addc_u32 s67, s19, 0
	s_add_u32 s18, s20, 0x80080
	s_addc_u32 s19, s21, 0
	s_add_u32 s70, s20, 0x100
	s_addc_u32 s71, s21, 0
	s_mov_b32 s73, -2
	ds_read_b128 v[148:151], v143
	ds_read_b128 v[152:155], v143 offset:1024
	ds_read_b128 v[156:159], v143 offset:2048
	ds_read_b128 v[160:163], v143 offset:3072
	ds_read_b128 v[164:167], v144
	ds_read_b128 v[168:171], v144 offset:1024
	ds_read_b128 v[172:175], v144 offset:2048
	ds_read_b128 v[176:179], v144 offset:3072
	s_cmp_eq_u32 s73, 28
	s_cselect_b32 s21, s9, s67
	s_cselect_b32 s20, s65, s66
	s_cselect_b32 s23, s11, s71
	s_cselect_b32 s22, s64, s70
	ds_read_b128 v[180:183], v145
	ds_read_b128 v[184:187], v145 offset:1024
	ds_read_b128 v[188:191], v145 offset:2048
	ds_read_b128 v[192:195], v145 offset:3072
	ds_read_b128 v[196:199], v145 offset:4096
	ds_read_b128 v[200:203], v145 offset:5120
	ds_read_b128 v[204:207], v145 offset:6144
	ds_read_b128 v[208:211], v145 offset:7168
	s_add_u32 s74, s18, 0xfff80000
	s_addc_u32 s75, s19, -1
	s_mov_b32 s76, m0
	s_mov_b32 m0, s56
	s_nop 0
	global_load_lds_dwordx4 v138, s[74:75]
	s_mov_b32 m0, s76
	s_nop 0
	s_mov_b32 s76, m0
	s_mov_b32 m0, s59
	s_nop 0
	global_load_lds_dwordx4 v140, s[74:75]
	s_mov_b32 m0, s76
	s_mov_b32 s74, m0
	s_mov_b32 m0, s57
	s_nop 0
	global_load_lds_dwordx4 v138, s[18:19]
	s_mov_b32 m0, s74
	s_nop 0
	s_mov_b32 s74, m0
	s_mov_b32 m0, s62
	s_nop 0
	global_load_lds_dwordx4 v140, s[18:19]
	s_mov_b32 m0, s74
	s_waitcnt vmcnt(8)
	s_waitcnt lgkmcnt(0)
	s_barrier
	s_setprio 1
	s_waitcnt lgkmcnt(7)
	v_mfma_f32_16x16x32_bf16 v[126:129], v[148:151], v[180:183], 0
	v_mfma_f32_16x16x32_bf16 v[126:129], v[152:155], v[184:187], v[126:129]
	s_waitcnt lgkmcnt(5)
	v_mfma_f32_16x16x32_bf16 v[122:125], v[156:159], v[180:183], 0
	v_mfma_f32_16x16x32_bf16 v[122:125], v[160:163], v[184:187], v[122:125]
	s_waitcnt lgkmcnt(3)
	v_mfma_f32_16x16x32_bf16 v[106:109], v[156:159], v[188:191], 0
	v_mfma_f32_16x16x32_bf16 v[106:109], v[160:163], v[192:195], v[106:109]
	s_waitcnt lgkmcnt(1)
	v_mfma_f32_16x16x32_bf16 v[110:113], v[148:151], v[188:191], 0
	v_mfma_f32_16x16x32_bf16 v[110:113], v[152:155], v[192:195], v[110:113]
	v_mfma_f32_16x16x32_bf16 v[94:97], v[148:151], v[196:199], 0
	v_mfma_f32_16x16x32_bf16 v[94:97], v[152:155], v[200:203], v[94:97]
	v_mfma_f32_16x16x32_bf16 v[90:93], v[156:159], v[196:199], 0
	v_mfma_f32_16x16x32_bf16 v[90:93], v[160:163], v[200:203], v[90:93]
	v_mfma_f32_16x16x32_bf16 v[74:77], v[156:159], v[204:207], 0
	v_mfma_f32_16x16x32_bf16 v[74:77], v[160:163], v[208:211], v[74:77]
	s_waitcnt lgkmcnt(0)
	v_mfma_f32_16x16x32_bf16 v[78:81], v[148:151], v[204:207], 0
	v_mfma_f32_16x16x32_bf16 v[78:81], v[152:155], v[208:211], v[78:81]
	s_setprio 0
	s_setprio 1
	v_mfma_f32_16x16x32_bf16 v[118:121], v[164:167], v[180:183], 0
	v_mfma_f32_16x16x32_bf16 v[118:121], v[168:171], v[184:187], v[118:121]
	v_mfma_f32_16x16x32_bf16 v[114:117], v[172:175], v[180:183], 0
	v_mfma_f32_16x16x32_bf16 v[114:117], v[176:179], v[184:187], v[114:117]
	v_mfma_f32_16x16x32_bf16 v[98:101], v[172:175], v[188:191], 0
	v_mfma_f32_16x16x32_bf16 v[98:101], v[176:179], v[192:195], v[98:101]
	v_mfma_f32_16x16x32_bf16 v[102:105], v[164:167], v[188:191], 0
	v_mfma_f32_16x16x32_bf16 v[102:105], v[168:171], v[192:195], v[102:105]
	v_mfma_f32_16x16x32_bf16 v[86:89], v[164:167], v[196:199], 0
	v_mfma_f32_16x16x32_bf16 v[86:89], v[168:171], v[200:203], v[86:89]
	v_mfma_f32_16x16x32_bf16 v[82:85], v[172:175], v[196:199], 0
	v_mfma_f32_16x16x32_bf16 v[82:85], v[176:179], v[200:203], v[82:85]
	v_mfma_f32_16x16x32_bf16 v[66:69], v[172:175], v[204:207], 0
	v_mfma_f32_16x16x32_bf16 v[66:69], v[176:179], v[208:211], v[66:69]
	s_setprio 2
	s_barrier
	v_mfma_f32_16x16x32_bf16 v[70:73], v[164:167], v[204:207], 0
	v_mfma_f32_16x16x32_bf16 v[70:73], v[168:171], v[208:211], v[70:73]
	s_setprio 0
	ds_read_b128 v[180:183], v145 offset:16384
	ds_read_b128 v[184:187], v145 offset:17408
	ds_read_b128 v[188:191], v145 offset:18432
	ds_read_b128 v[192:195], v145 offset:19456
	ds_read_b128 v[196:199], v145 offset:20480
	ds_read_b128 v[200:203], v145 offset:21504
	ds_read_b128 v[204:207], v145 offset:22528
	ds_read_b128 v[208:211], v145 offset:23552
	s_mov_b32 s74, m0
	s_mov_b32 m0, s35
	s_nop 0
	global_load_lds_dwordx4 v139, s[20:21]
	s_mov_b32 m0, s74
	s_nop 0
	s_mov_b32 s74, m0
	s_mov_b32 m0, s36
	s_nop 0
	global_load_lds_dwordx4 v141, s[20:21]
	s_mov_b32 m0, s74
	s_add_u32 s74, s20, 0x80000
	s_addc_u32 s75, s21, 0
	s_mov_b32 s76, m0
	s_mov_b32 m0, s37
	s_nop 0
	global_load_lds_dwordx4 v139, s[74:75]
	s_mov_b32 m0, s76
	s_nop 0
	s_mov_b32 s76, m0
	s_mov_b32 m0, s40
	s_nop 0
	global_load_lds_dwordx4 v141, s[74:75]
	s_mov_b32 m0, s76
	s_waitcnt vmcnt(4)
	s_waitcnt lgkmcnt(0)
	s_barrier
	s_setprio 1
	s_waitcnt lgkmcnt(7)
	v_mfma_f32_16x16x32_bf16 v[62:65], v[148:151], v[180:183], 0
	v_mfma_f32_16x16x32_bf16 v[62:65], v[152:155], v[184:187], v[62:65]
	s_waitcnt lgkmcnt(5)
	v_mfma_f32_16x16x32_bf16 v[58:61], v[156:159], v[180:183], 0
	v_mfma_f32_16x16x32_bf16 v[58:61], v[160:163], v[184:187], v[58:61]
	s_waitcnt lgkmcnt(3)
	v_mfma_f32_16x16x32_bf16 v[42:45], v[156:159], v[188:191], 0
	v_mfma_f32_16x16x32_bf16 v[42:45], v[160:163], v[192:195], v[42:45]
	s_waitcnt lgkmcnt(1)
	v_mfma_f32_16x16x32_bf16 v[46:49], v[148:151], v[188:191], 0
	v_mfma_f32_16x16x32_bf16 v[46:49], v[152:155], v[192:195], v[46:49]
	v_mfma_f32_16x16x32_bf16 v[30:33], v[148:151], v[196:199], 0
	v_mfma_f32_16x16x32_bf16 v[30:33], v[152:155], v[200:203], v[30:33]
	v_mfma_f32_16x16x32_bf16 v[26:29], v[156:159], v[196:199], 0
	v_mfma_f32_16x16x32_bf16 v[26:29], v[160:163], v[200:203], v[26:29]
	v_mfma_f32_16x16x32_bf16 v[10:13], v[156:159], v[204:207], 0
	v_mfma_f32_16x16x32_bf16 v[10:13], v[160:163], v[208:211], v[10:13]
	s_waitcnt lgkmcnt(0)
	v_mfma_f32_16x16x32_bf16 v[14:17], v[148:151], v[204:207], 0
	v_mfma_f32_16x16x32_bf16 v[14:17], v[152:155], v[208:211], v[14:17]
	s_setprio 0
	s_setprio 1
	v_mfma_f32_16x16x32_bf16 v[54:57], v[164:167], v[180:183], 0
	v_mfma_f32_16x16x32_bf16 v[54:57], v[168:171], v[184:187], v[54:57]
	v_mfma_f32_16x16x32_bf16 v[50:53], v[172:175], v[180:183], 0
	v_mfma_f32_16x16x32_bf16 v[50:53], v[176:179], v[184:187], v[50:53]
	v_mfma_f32_16x16x32_bf16 v[34:37], v[172:175], v[188:191], 0
	v_mfma_f32_16x16x32_bf16 v[34:37], v[176:179], v[192:195], v[34:37]
	v_mfma_f32_16x16x32_bf16 v[38:41], v[164:167], v[188:191], 0
	v_mfma_f32_16x16x32_bf16 v[38:41], v[168:171], v[192:195], v[38:41]
	v_mfma_f32_16x16x32_bf16 v[22:25], v[164:167], v[196:199], 0
	v_mfma_f32_16x16x32_bf16 v[22:25], v[168:171], v[200:203], v[22:25]
	v_mfma_f32_16x16x32_bf16 v[18:21], v[172:175], v[196:199], 0
	v_mfma_f32_16x16x32_bf16 v[18:21], v[176:179], v[200:203], v[18:21]
	v_mfma_f32_16x16x32_bf16 v[2:5], v[172:175], v[204:207], 0
	v_mfma_f32_16x16x32_bf16 v[2:5], v[176:179], v[208:211], v[2:5]
	s_setprio 2
	s_barrier
	v_mfma_f32_16x16x32_bf16 v[6:9], v[164:167], v[204:207], 0
	v_mfma_f32_16x16x32_bf16 v[6:9], v[168:171], v[208:211], v[6:9]
	s_setprio 0
	ds_read_b128 v[148:151], v146
	ds_read_b128 v[152:155], v146 offset:1024
	ds_read_b128 v[156:159], v146 offset:2048
	ds_read_b128 v[160:163], v146 offset:3072
	ds_read_b128 v[164:167], v147
	ds_read_b128 v[168:171], v147 offset:1024
	ds_read_b128 v[172:175], v147 offset:2048
	ds_read_b128 v[176:179], v147 offset:3072
	ds_read_b128 v[180:183], v145 offset:32768
	ds_read_b128 v[184:187], v145 offset:33792
	ds_read_b128 v[188:191], v145 offset:34816
	ds_read_b128 v[192:195], v145 offset:35840
	ds_read_b128 v[196:199], v145 offset:36864
	ds_read_b128 v[200:203], v145 offset:37888
	ds_read_b128 v[204:207], v145 offset:38912
	ds_read_b128 v[208:211], v145 offset:39936
	s_mov_b32 s74, m0
	s_mov_b32 m0, s31
	s_nop 0
	global_load_lds_dwordx4 v138, s[22:23]
	s_mov_b32 m0, s74
	s_nop 0
	s_mov_b32 s74, m0
	s_mov_b32 m0, s41
	s_nop 0
	global_load_lds_dwordx4 v140, s[22:23]
	s_mov_b32 m0, s74
	s_add_u32 s22, s22, 0x80000
	s_addc_u32 s23, s23, 0
	s_mov_b32 s74, m0
	s_mov_b32 m0, s42
	s_nop 0
	global_load_lds_dwordx4 v138, s[22:23]
	s_mov_b32 m0, s74
	s_nop 0
	s_mov_b32 s74, m0
	s_mov_b32 m0, s43
	s_nop 0
	global_load_lds_dwordx4 v140, s[22:23]
	s_mov_b32 m0, s74
	s_waitcnt vmcnt(8)
	s_waitcnt lgkmcnt(0)
	s_barrier
	s_setprio 1
	s_waitcnt lgkmcnt(7)
	v_mfma_f32_16x16x32_bf16 v[126:129], v[148:151], v[180:183], v[126:129]
	v_mfma_f32_16x16x32_bf16 v[126:129], v[152:155], v[184:187], v[126:129]
	s_waitcnt lgkmcnt(5)
	v_mfma_f32_16x16x32_bf16 v[122:125], v[156:159], v[180:183], v[122:125]
	v_mfma_f32_16x16x32_bf16 v[122:125], v[160:163], v[184:187], v[122:125]
	s_waitcnt lgkmcnt(3)
	v_mfma_f32_16x16x32_bf16 v[106:109], v[156:159], v[188:191], v[106:109]
	v_mfma_f32_16x16x32_bf16 v[106:109], v[160:163], v[192:195], v[106:109]
	s_waitcnt lgkmcnt(1)
	v_mfma_f32_16x16x32_bf16 v[110:113], v[148:151], v[188:191], v[110:113]
	v_mfma_f32_16x16x32_bf16 v[110:113], v[152:155], v[192:195], v[110:113]
	v_mfma_f32_16x16x32_bf16 v[94:97], v[148:151], v[196:199], v[94:97]
	v_mfma_f32_16x16x32_bf16 v[94:97], v[152:155], v[200:203], v[94:97]
	v_mfma_f32_16x16x32_bf16 v[90:93], v[156:159], v[196:199], v[90:93]
	v_mfma_f32_16x16x32_bf16 v[90:93], v[160:163], v[200:203], v[90:93]
	v_mfma_f32_16x16x32_bf16 v[74:77], v[156:159], v[204:207], v[74:77]
	v_mfma_f32_16x16x32_bf16 v[74:77], v[160:163], v[208:211], v[74:77]
	s_waitcnt lgkmcnt(0)
	v_mfma_f32_16x16x32_bf16 v[78:81], v[148:151], v[204:207], v[78:81]
	v_mfma_f32_16x16x32_bf16 v[78:81], v[152:155], v[208:211], v[78:81]
	s_setprio 0
	s_setprio 1
	v_mfma_f32_16x16x32_bf16 v[118:121], v[164:167], v[180:183], v[118:121]
	v_mfma_f32_16x16x32_bf16 v[118:121], v[168:171], v[184:187], v[118:121]
	v_mfma_f32_16x16x32_bf16 v[114:117], v[172:175], v[180:183], v[114:117]
	v_mfma_f32_16x16x32_bf16 v[114:117], v[176:179], v[184:187], v[114:117]
	v_mfma_f32_16x16x32_bf16 v[98:101], v[172:175], v[188:191], v[98:101]
	v_mfma_f32_16x16x32_bf16 v[98:101], v[176:179], v[192:195], v[98:101]
	v_mfma_f32_16x16x32_bf16 v[102:105], v[164:167], v[188:191], v[102:105]
	v_mfma_f32_16x16x32_bf16 v[102:105], v[168:171], v[192:195], v[102:105]
	v_mfma_f32_16x16x32_bf16 v[86:89], v[164:167], v[196:199], v[86:89]
	v_mfma_f32_16x16x32_bf16 v[86:89], v[168:171], v[200:203], v[86:89]
	v_mfma_f32_16x16x32_bf16 v[82:85], v[172:175], v[196:199], v[82:85]
	v_mfma_f32_16x16x32_bf16 v[82:85], v[176:179], v[200:203], v[82:85]
	v_mfma_f32_16x16x32_bf16 v[66:69], v[172:175], v[204:207], v[66:69]
	v_mfma_f32_16x16x32_bf16 v[66:69], v[176:179], v[208:211], v[66:69]
	s_setprio 2
	s_barrier
	v_mfma_f32_16x16x32_bf16 v[70:73], v[164:167], v[204:207], v[70:73]
	v_mfma_f32_16x16x32_bf16 v[70:73], v[168:171], v[208:211], v[70:73]
	s_setprio 0
	ds_read_b128 v[180:183], v145 offset:49152
	ds_read_b128 v[184:187], v145 offset:50176
	ds_read_b128 v[188:191], v145 offset:51200
	ds_read_b128 v[192:195], v145 offset:52224
	ds_read_b128 v[196:199], v145 offset:53248
	ds_read_b128 v[200:203], v145 offset:54272
	ds_read_b128 v[204:207], v145 offset:55296
	ds_read_b128 v[208:211], v145 offset:56320
	s_add_u32 s22, s20, 0x80
	s_addc_u32 s23, s21, 0
	s_mov_b32 s74, m0
	s_mov_b32 m0, s46
	s_nop 0
	global_load_lds_dwordx4 v139, s[22:23]
	s_mov_b32 m0, s74
	s_add_u32 s20, s20, 0x80080
	s_mov_b32 s74, m0
	s_mov_b32 m0, s47
	s_nop 0
	global_load_lds_dwordx4 v141, s[22:23]
	s_mov_b32 m0, s74
	s_addc_u32 s21, s21, 0
	s_mov_b32 s22, m0
	s_mov_b32 m0, s48
	s_nop 0
	global_load_lds_dwordx4 v139, s[20:21]
	s_mov_b32 m0, s22
	s_nop 0
	s_mov_b32 s22, m0
	s_mov_b32 m0, s49
	s_nop 0
	global_load_lds_dwordx4 v141, s[20:21]
	s_mov_b32 m0, s22
	s_waitcnt vmcnt(4)
	s_waitcnt lgkmcnt(0)
	s_barrier
	s_setprio 1
	s_waitcnt lgkmcnt(7)
	v_mfma_f32_16x16x32_bf16 v[62:65], v[148:151], v[180:183], v[62:65]
	v_mfma_f32_16x16x32_bf16 v[62:65], v[152:155], v[184:187], v[62:65]
	s_waitcnt lgkmcnt(5)
	v_mfma_f32_16x16x32_bf16 v[58:61], v[156:159], v[180:183], v[58:61]
	v_mfma_f32_16x16x32_bf16 v[58:61], v[160:163], v[184:187], v[58:61]
	s_waitcnt lgkmcnt(3)
	v_mfma_f32_16x16x32_bf16 v[42:45], v[156:159], v[188:191], v[42:45]
	v_mfma_f32_16x16x32_bf16 v[42:45], v[160:163], v[192:195], v[42:45]
	s_waitcnt lgkmcnt(1)
	v_mfma_f32_16x16x32_bf16 v[46:49], v[148:151], v[188:191], v[46:49]
	v_mfma_f32_16x16x32_bf16 v[46:49], v[152:155], v[192:195], v[46:49]
	v_mfma_f32_16x16x32_bf16 v[30:33], v[148:151], v[196:199], v[30:33]
	v_mfma_f32_16x16x32_bf16 v[30:33], v[152:155], v[200:203], v[30:33]
	v_mfma_f32_16x16x32_bf16 v[26:29], v[156:159], v[196:199], v[26:29]
	v_mfma_f32_16x16x32_bf16 v[26:29], v[160:163], v[200:203], v[26:29]
	v_mfma_f32_16x16x32_bf16 v[10:13], v[156:159], v[204:207], v[10:13]
	v_mfma_f32_16x16x32_bf16 v[10:13], v[160:163], v[208:211], v[10:13]
	s_waitcnt lgkmcnt(0)
	v_mfma_f32_16x16x32_bf16 v[14:17], v[148:151], v[204:207], v[14:17]
	v_mfma_f32_16x16x32_bf16 v[14:17], v[152:155], v[208:211], v[14:17]
	s_setprio 0
	s_setprio 1
	v_mfma_f32_16x16x32_bf16 v[54:57], v[164:167], v[180:183], v[54:57]
	v_mfma_f32_16x16x32_bf16 v[54:57], v[168:171], v[184:187], v[54:57]
	v_mfma_f32_16x16x32_bf16 v[50:53], v[172:175], v[180:183], v[50:53]
	v_mfma_f32_16x16x32_bf16 v[50:53], v[176:179], v[184:187], v[50:53]
	v_mfma_f32_16x16x32_bf16 v[34:37], v[172:175], v[188:191], v[34:37]
	v_mfma_f32_16x16x32_bf16 v[34:37], v[176:179], v[192:195], v[34:37]
	v_mfma_f32_16x16x32_bf16 v[38:41], v[164:167], v[188:191], v[38:41]
	v_mfma_f32_16x16x32_bf16 v[38:41], v[168:171], v[192:195], v[38:41]
	v_mfma_f32_16x16x32_bf16 v[22:25], v[164:167], v[196:199], v[22:25]
	v_mfma_f32_16x16x32_bf16 v[22:25], v[168:171], v[200:203], v[22:25]
	v_mfma_f32_16x16x32_bf16 v[18:21], v[172:175], v[196:199], v[18:21]
	v_mfma_f32_16x16x32_bf16 v[18:21], v[176:179], v[200:203], v[18:21]
	v_mfma_f32_16x16x32_bf16 v[2:5], v[172:175], v[204:207], v[2:5]
	v_mfma_f32_16x16x32_bf16 v[2:5], v[176:179], v[208:211], v[2:5]
	s_setprio 2
	s_barrier
	v_mfma_f32_16x16x32_bf16 v[6:9], v[164:167], v[204:207], v[6:9]
	v_mfma_f32_16x16x32_bf16 v[6:9], v[168:171], v[208:211], v[6:9]
	s_setprio 0
	s_add_i32 s73, s73, 2
	s_add_u32 s66, s66, 0x100
	s_addc_u32 s67, s67, 0
	s_add_u32 s18, s18, 0x100
	s_addc_u32 s19, s19, 0
	s_add_u32 s70, s70, 0x100
	s_addc_u32 s71, s71, 0
	s_cmp_gt_u32 s73, 29
	.p2align 6
.LBB0_1785:
	ds_read_b128 v[148:151], v143
	ds_read_b128 v[152:155], v143 offset:1024
	ds_read_b128 v[156:159], v143 offset:2048
	ds_read_b128 v[160:163], v143 offset:3072
	ds_read_b128 v[164:167], v144
	ds_read_b128 v[168:171], v144 offset:1024
	ds_read_b128 v[172:175], v144 offset:2048
	ds_read_b128 v[176:179], v144 offset:3072
	s_cmp_eq_u32 s73, 28
	s_cselect_b32 s21, s9, s67
	s_cselect_b32 s20, s65, s66
	s_cselect_b32 s23, s11, s71
	s_cselect_b32 s22, s64, s70
	ds_read_b128 v[180:183], v145
	ds_read_b128 v[184:187], v145 offset:1024
	ds_read_b128 v[188:191], v145 offset:2048
	ds_read_b128 v[192:195], v145 offset:3072
	ds_read_b128 v[196:199], v145 offset:4096
	ds_read_b128 v[200:203], v145 offset:5120
	ds_read_b128 v[204:207], v145 offset:6144
	ds_read_b128 v[208:211], v145 offset:7168
	s_add_u32 s74, s18, 0xfff80000
	s_addc_u32 s75, s19, -1
	s_mov_b32 s76, m0
	s_mov_b32 m0, s56
	s_nop 0
	global_load_lds_dwordx4 v138, s[74:75]
	s_mov_b32 m0, s76
	s_nop 0
	s_mov_b32 s76, m0
	s_mov_b32 m0, s59
	s_nop 0
	global_load_lds_dwordx4 v140, s[74:75]
	s_mov_b32 m0, s76
	s_mov_b32 s74, m0
	s_mov_b32 m0, s57
	s_nop 0
	global_load_lds_dwordx4 v138, s[18:19]
	s_mov_b32 m0, s74
	s_nop 0
	s_mov_b32 s74, m0
	s_mov_b32 m0, s62
	s_nop 0
	global_load_lds_dwordx4 v140, s[18:19]
	s_mov_b32 m0, s74
	s_waitcnt vmcnt(8)
	s_waitcnt lgkmcnt(0)
	s_barrier
	s_setprio 1
	s_waitcnt lgkmcnt(7)
	v_mfma_f32_16x16x32_bf16 v[126:129], v[148:151], v[180:183], v[126:129]
	v_mfma_f32_16x16x32_bf16 v[126:129], v[152:155], v[184:187], v[126:129]
	s_waitcnt lgkmcnt(5)
	v_mfma_f32_16x16x32_bf16 v[122:125], v[156:159], v[180:183], v[122:125]
	v_mfma_f32_16x16x32_bf16 v[122:125], v[160:163], v[184:187], v[122:125]
	s_waitcnt lgkmcnt(3)
	v_mfma_f32_16x16x32_bf16 v[106:109], v[156:159], v[188:191], v[106:109]
	v_mfma_f32_16x16x32_bf16 v[106:109], v[160:163], v[192:195], v[106:109]
	s_waitcnt lgkmcnt(1)
	v_mfma_f32_16x16x32_bf16 v[110:113], v[148:151], v[188:191], v[110:113]
	v_mfma_f32_16x16x32_bf16 v[110:113], v[152:155], v[192:195], v[110:113]
	v_mfma_f32_16x16x32_bf16 v[94:97], v[148:151], v[196:199], v[94:97]
	v_mfma_f32_16x16x32_bf16 v[94:97], v[152:155], v[200:203], v[94:97]
	v_mfma_f32_16x16x32_bf16 v[90:93], v[156:159], v[196:199], v[90:93]
	v_mfma_f32_16x16x32_bf16 v[90:93], v[160:163], v[200:203], v[90:93]
	v_mfma_f32_16x16x32_bf16 v[74:77], v[156:159], v[204:207], v[74:77]
	v_mfma_f32_16x16x32_bf16 v[74:77], v[160:163], v[208:211], v[74:77]
	s_waitcnt lgkmcnt(0)
	v_mfma_f32_16x16x32_bf16 v[78:81], v[148:151], v[204:207], v[78:81]
	v_mfma_f32_16x16x32_bf16 v[78:81], v[152:155], v[208:211], v[78:81]
	s_setprio 0
	s_setprio 1
	v_mfma_f32_16x16x32_bf16 v[118:121], v[164:167], v[180:183], v[118:121]
	v_mfma_f32_16x16x32_bf16 v[118:121], v[168:171], v[184:187], v[118:121]
	v_mfma_f32_16x16x32_bf16 v[114:117], v[172:175], v[180:183], v[114:117]
	v_mfma_f32_16x16x32_bf16 v[114:117], v[176:179], v[184:187], v[114:117]
	v_mfma_f32_16x16x32_bf16 v[98:101], v[172:175], v[188:191], v[98:101]
	v_mfma_f32_16x16x32_bf16 v[98:101], v[176:179], v[192:195], v[98:101]
	v_mfma_f32_16x16x32_bf16 v[102:105], v[164:167], v[188:191], v[102:105]
	v_mfma_f32_16x16x32_bf16 v[102:105], v[168:171], v[192:195], v[102:105]
	v_mfma_f32_16x16x32_bf16 v[86:89], v[164:167], v[196:199], v[86:89]
	v_mfma_f32_16x16x32_bf16 v[86:89], v[168:171], v[200:203], v[86:89]
	v_mfma_f32_16x16x32_bf16 v[82:85], v[172:175], v[196:199], v[82:85]
	v_mfma_f32_16x16x32_bf16 v[82:85], v[176:179], v[200:203], v[82:85]
	v_mfma_f32_16x16x32_bf16 v[66:69], v[172:175], v[204:207], v[66:69]
	v_mfma_f32_16x16x32_bf16 v[66:69], v[176:179], v[208:211], v[66:69]
	s_setprio 2
	s_barrier
	v_mfma_f32_16x16x32_bf16 v[70:73], v[164:167], v[204:207], v[70:73]
	v_mfma_f32_16x16x32_bf16 v[70:73], v[168:171], v[208:211], v[70:73]
	s_setprio 0
	ds_read_b128 v[180:183], v145 offset:16384
	ds_read_b128 v[184:187], v145 offset:17408
	ds_read_b128 v[188:191], v145 offset:18432
	ds_read_b128 v[192:195], v145 offset:19456
	ds_read_b128 v[196:199], v145 offset:20480
	ds_read_b128 v[200:203], v145 offset:21504
	ds_read_b128 v[204:207], v145 offset:22528
	ds_read_b128 v[208:211], v145 offset:23552
	s_mov_b32 s74, m0
	s_mov_b32 m0, s35
	s_nop 0
	global_load_lds_dwordx4 v139, s[20:21]
	s_mov_b32 m0, s74
	s_nop 0
	s_mov_b32 s74, m0
	s_mov_b32 m0, s36
	s_nop 0
	global_load_lds_dwordx4 v141, s[20:21]
	s_mov_b32 m0, s74
	s_add_u32 s74, s20, 0x80000
	s_addc_u32 s75, s21, 0
	s_mov_b32 s76, m0
	s_mov_b32 m0, s37
	s_nop 0
	global_load_lds_dwordx4 v139, s[74:75]
	s_mov_b32 m0, s76
	s_nop 0
	s_mov_b32 s76, m0
	s_mov_b32 m0, s40
	s_nop 0
	global_load_lds_dwordx4 v141, s[74:75]
	s_mov_b32 m0, s76
	s_waitcnt vmcnt(4)
	s_waitcnt lgkmcnt(0)
	s_barrier
	s_setprio 1
	s_waitcnt lgkmcnt(7)
	v_mfma_f32_16x16x32_bf16 v[62:65], v[148:151], v[180:183], v[62:65]
	v_mfma_f32_16x16x32_bf16 v[62:65], v[152:155], v[184:187], v[62:65]
	s_waitcnt lgkmcnt(5)
	v_mfma_f32_16x16x32_bf16 v[58:61], v[156:159], v[180:183], v[58:61]
	v_mfma_f32_16x16x32_bf16 v[58:61], v[160:163], v[184:187], v[58:61]
	s_waitcnt lgkmcnt(3)
	v_mfma_f32_16x16x32_bf16 v[42:45], v[156:159], v[188:191], v[42:45]
	v_mfma_f32_16x16x32_bf16 v[42:45], v[160:163], v[192:195], v[42:45]
	s_waitcnt lgkmcnt(1)
	v_mfma_f32_16x16x32_bf16 v[46:49], v[148:151], v[188:191], v[46:49]
	v_mfma_f32_16x16x32_bf16 v[46:49], v[152:155], v[192:195], v[46:49]
	v_mfma_f32_16x16x32_bf16 v[30:33], v[148:151], v[196:199], v[30:33]
	v_mfma_f32_16x16x32_bf16 v[30:33], v[152:155], v[200:203], v[30:33]
	v_mfma_f32_16x16x32_bf16 v[26:29], v[156:159], v[196:199], v[26:29]
	v_mfma_f32_16x16x32_bf16 v[26:29], v[160:163], v[200:203], v[26:29]
	v_mfma_f32_16x16x32_bf16 v[10:13], v[156:159], v[204:207], v[10:13]
	v_mfma_f32_16x16x32_bf16 v[10:13], v[160:163], v[208:211], v[10:13]
	s_waitcnt lgkmcnt(0)
	v_mfma_f32_16x16x32_bf16 v[14:17], v[148:151], v[204:207], v[14:17]
	v_mfma_f32_16x16x32_bf16 v[14:17], v[152:155], v[208:211], v[14:17]
	s_setprio 0
	s_setprio 1
	v_mfma_f32_16x16x32_bf16 v[54:57], v[164:167], v[180:183], v[54:57]
	v_mfma_f32_16x16x32_bf16 v[54:57], v[168:171], v[184:187], v[54:57]
	v_mfma_f32_16x16x32_bf16 v[50:53], v[172:175], v[180:183], v[50:53]
	v_mfma_f32_16x16x32_bf16 v[50:53], v[176:179], v[184:187], v[50:53]
	v_mfma_f32_16x16x32_bf16 v[34:37], v[172:175], v[188:191], v[34:37]
	v_mfma_f32_16x16x32_bf16 v[34:37], v[176:179], v[192:195], v[34:37]
	v_mfma_f32_16x16x32_bf16 v[38:41], v[164:167], v[188:191], v[38:41]
	v_mfma_f32_16x16x32_bf16 v[38:41], v[168:171], v[192:195], v[38:41]
	v_mfma_f32_16x16x32_bf16 v[22:25], v[164:167], v[196:199], v[22:25]
	v_mfma_f32_16x16x32_bf16 v[22:25], v[168:171], v[200:203], v[22:25]
	v_mfma_f32_16x16x32_bf16 v[18:21], v[172:175], v[196:199], v[18:21]
	v_mfma_f32_16x16x32_bf16 v[18:21], v[176:179], v[200:203], v[18:21]
	v_mfma_f32_16x16x32_bf16 v[2:5], v[172:175], v[204:207], v[2:5]
	v_mfma_f32_16x16x32_bf16 v[2:5], v[176:179], v[208:211], v[2:5]
	s_setprio 2
	s_barrier
	v_mfma_f32_16x16x32_bf16 v[6:9], v[164:167], v[204:207], v[6:9]
	v_mfma_f32_16x16x32_bf16 v[6:9], v[168:171], v[208:211], v[6:9]
	s_setprio 0
	ds_read_b128 v[148:151], v146
	ds_read_b128 v[152:155], v146 offset:1024
	ds_read_b128 v[156:159], v146 offset:2048
	ds_read_b128 v[160:163], v146 offset:3072
	ds_read_b128 v[164:167], v147
	ds_read_b128 v[168:171], v147 offset:1024
	ds_read_b128 v[172:175], v147 offset:2048
	ds_read_b128 v[176:179], v147 offset:3072
	ds_read_b128 v[180:183], v145 offset:32768
	ds_read_b128 v[184:187], v145 offset:33792
	ds_read_b128 v[188:191], v145 offset:34816
	ds_read_b128 v[192:195], v145 offset:35840
	ds_read_b128 v[196:199], v145 offset:36864
	ds_read_b128 v[200:203], v145 offset:37888
	ds_read_b128 v[204:207], v145 offset:38912
	ds_read_b128 v[208:211], v145 offset:39936
	s_mov_b32 s74, m0
	s_mov_b32 m0, s31
	s_nop 0
	global_load_lds_dwordx4 v138, s[22:23]
	s_mov_b32 m0, s74
	s_nop 0
	s_mov_b32 s74, m0
	s_mov_b32 m0, s41
	s_nop 0
	global_load_lds_dwordx4 v140, s[22:23]
	s_mov_b32 m0, s74
	s_add_u32 s22, s22, 0x80000
	s_addc_u32 s23, s23, 0
	s_mov_b32 s74, m0
	s_mov_b32 m0, s42
	s_nop 0
	global_load_lds_dwordx4 v138, s[22:23]
	s_mov_b32 m0, s74
	s_nop 0
	s_mov_b32 s74, m0
	s_mov_b32 m0, s43
	s_nop 0
	global_load_lds_dwordx4 v140, s[22:23]
	s_mov_b32 m0, s74
	s_waitcnt vmcnt(8)
	s_waitcnt lgkmcnt(0)
	s_barrier
	s_setprio 1
	s_waitcnt lgkmcnt(7)
	v_mfma_f32_16x16x32_bf16 v[126:129], v[148:151], v[180:183], v[126:129]
	v_mfma_f32_16x16x32_bf16 v[126:129], v[152:155], v[184:187], v[126:129]
	s_waitcnt lgkmcnt(5)
	v_mfma_f32_16x16x32_bf16 v[122:125], v[156:159], v[180:183], v[122:125]
	v_mfma_f32_16x16x32_bf16 v[122:125], v[160:163], v[184:187], v[122:125]
	s_waitcnt lgkmcnt(3)
	v_mfma_f32_16x16x32_bf16 v[106:109], v[156:159], v[188:191], v[106:109]
	v_mfma_f32_16x16x32_bf16 v[106:109], v[160:163], v[192:195], v[106:109]
	s_waitcnt lgkmcnt(1)
	v_mfma_f32_16x16x32_bf16 v[110:113], v[148:151], v[188:191], v[110:113]
	v_mfma_f32_16x16x32_bf16 v[110:113], v[152:155], v[192:195], v[110:113]
	v_mfma_f32_16x16x32_bf16 v[94:97], v[148:151], v[196:199], v[94:97]
	v_mfma_f32_16x16x32_bf16 v[94:97], v[152:155], v[200:203], v[94:97]
	v_mfma_f32_16x16x32_bf16 v[90:93], v[156:159], v[196:199], v[90:93]
	v_mfma_f32_16x16x32_bf16 v[90:93], v[160:163], v[200:203], v[90:93]
	v_mfma_f32_16x16x32_bf16 v[74:77], v[156:159], v[204:207], v[74:77]
	v_mfma_f32_16x16x32_bf16 v[74:77], v[160:163], v[208:211], v[74:77]
	s_waitcnt lgkmcnt(0)
	v_mfma_f32_16x16x32_bf16 v[78:81], v[148:151], v[204:207], v[78:81]
	v_mfma_f32_16x16x32_bf16 v[78:81], v[152:155], v[208:211], v[78:81]
	s_setprio 0
	s_setprio 1
	v_mfma_f32_16x16x32_bf16 v[118:121], v[164:167], v[180:183], v[118:121]
	v_mfma_f32_16x16x32_bf16 v[118:121], v[168:171], v[184:187], v[118:121]
	v_mfma_f32_16x16x32_bf16 v[114:117], v[172:175], v[180:183], v[114:117]
	v_mfma_f32_16x16x32_bf16 v[114:117], v[176:179], v[184:187], v[114:117]
	v_mfma_f32_16x16x32_bf16 v[98:101], v[172:175], v[188:191], v[98:101]
	v_mfma_f32_16x16x32_bf16 v[98:101], v[176:179], v[192:195], v[98:101]
	v_mfma_f32_16x16x32_bf16 v[102:105], v[164:167], v[188:191], v[102:105]
	v_mfma_f32_16x16x32_bf16 v[102:105], v[168:171], v[192:195], v[102:105]
	v_mfma_f32_16x16x32_bf16 v[86:89], v[164:167], v[196:199], v[86:89]
	v_mfma_f32_16x16x32_bf16 v[86:89], v[168:171], v[200:203], v[86:89]
	v_mfma_f32_16x16x32_bf16 v[82:85], v[172:175], v[196:199], v[82:85]
	v_mfma_f32_16x16x32_bf16 v[82:85], v[176:179], v[200:203], v[82:85]
	v_mfma_f32_16x16x32_bf16 v[66:69], v[172:175], v[204:207], v[66:69]
	v_mfma_f32_16x16x32_bf16 v[66:69], v[176:179], v[208:211], v[66:69]
	s_setprio 2
	s_barrier
	v_mfma_f32_16x16x32_bf16 v[70:73], v[164:167], v[204:207], v[70:73]
	v_mfma_f32_16x16x32_bf16 v[70:73], v[168:171], v[208:211], v[70:73]
	s_setprio 0
	ds_read_b128 v[180:183], v145 offset:49152
	ds_read_b128 v[184:187], v145 offset:50176
	ds_read_b128 v[188:191], v145 offset:51200
	ds_read_b128 v[192:195], v145 offset:52224
	ds_read_b128 v[196:199], v145 offset:53248
	ds_read_b128 v[200:203], v145 offset:54272
	ds_read_b128 v[204:207], v145 offset:55296
	ds_read_b128 v[208:211], v145 offset:56320
	s_add_u32 s22, s20, 0x80
	s_addc_u32 s23, s21, 0
	s_mov_b32 s74, m0
	s_mov_b32 m0, s46
	s_nop 0
	global_load_lds_dwordx4 v139, s[22:23]
	s_mov_b32 m0, s74
	s_add_u32 s20, s20, 0x80080
	s_mov_b32 s74, m0
	s_mov_b32 m0, s47
	s_nop 0
	global_load_lds_dwordx4 v141, s[22:23]
	s_mov_b32 m0, s74
	s_addc_u32 s21, s21, 0
	s_mov_b32 s22, m0
	s_mov_b32 m0, s48
	s_nop 0
	global_load_lds_dwordx4 v139, s[20:21]
	s_mov_b32 m0, s22
	s_nop 0
	s_mov_b32 s22, m0
	s_mov_b32 m0, s49
	s_nop 0
	global_load_lds_dwordx4 v141, s[20:21]
	s_mov_b32 m0, s22
	s_waitcnt vmcnt(4)
	s_waitcnt lgkmcnt(0)
	s_barrier
	s_setprio 1
	s_waitcnt lgkmcnt(7)
	v_mfma_f32_16x16x32_bf16 v[62:65], v[148:151], v[180:183], v[62:65]
	v_mfma_f32_16x16x32_bf16 v[62:65], v[152:155], v[184:187], v[62:65]
	s_waitcnt lgkmcnt(5)
	v_mfma_f32_16x16x32_bf16 v[58:61], v[156:159], v[180:183], v[58:61]
	v_mfma_f32_16x16x32_bf16 v[58:61], v[160:163], v[184:187], v[58:61]
	s_waitcnt lgkmcnt(3)
	v_mfma_f32_16x16x32_bf16 v[42:45], v[156:159], v[188:191], v[42:45]
	v_mfma_f32_16x16x32_bf16 v[42:45], v[160:163], v[192:195], v[42:45]
	s_waitcnt lgkmcnt(1)
	v_mfma_f32_16x16x32_bf16 v[46:49], v[148:151], v[188:191], v[46:49]
	v_mfma_f32_16x16x32_bf16 v[46:49], v[152:155], v[192:195], v[46:49]
	v_mfma_f32_16x16x32_bf16 v[30:33], v[148:151], v[196:199], v[30:33]
	v_mfma_f32_16x16x32_bf16 v[30:33], v[152:155], v[200:203], v[30:33]
	v_mfma_f32_16x16x32_bf16 v[26:29], v[156:159], v[196:199], v[26:29]
	v_mfma_f32_16x16x32_bf16 v[26:29], v[160:163], v[200:203], v[26:29]
	v_mfma_f32_16x16x32_bf16 v[10:13], v[156:159], v[204:207], v[10:13]
	v_mfma_f32_16x16x32_bf16 v[10:13], v[160:163], v[208:211], v[10:13]
	s_waitcnt lgkmcnt(0)
	v_mfma_f32_16x16x32_bf16 v[14:17], v[148:151], v[204:207], v[14:17]
	v_mfma_f32_16x16x32_bf16 v[14:17], v[152:155], v[208:211], v[14:17]
	s_setprio 0
	s_setprio 1
	v_mfma_f32_16x16x32_bf16 v[54:57], v[164:167], v[180:183], v[54:57]
	v_mfma_f32_16x16x32_bf16 v[54:57], v[168:171], v[184:187], v[54:57]
	v_mfma_f32_16x16x32_bf16 v[50:53], v[172:175], v[180:183], v[50:53]
	v_mfma_f32_16x16x32_bf16 v[50:53], v[176:179], v[184:187], v[50:53]
	v_mfma_f32_16x16x32_bf16 v[34:37], v[172:175], v[188:191], v[34:37]
	v_mfma_f32_16x16x32_bf16 v[34:37], v[176:179], v[192:195], v[34:37]
	v_mfma_f32_16x16x32_bf16 v[38:41], v[164:167], v[188:191], v[38:41]
	v_mfma_f32_16x16x32_bf16 v[38:41], v[168:171], v[192:195], v[38:41]
	v_mfma_f32_16x16x32_bf16 v[22:25], v[164:167], v[196:199], v[22:25]
	v_mfma_f32_16x16x32_bf16 v[22:25], v[168:171], v[200:203], v[22:25]
	v_mfma_f32_16x16x32_bf16 v[18:21], v[172:175], v[196:199], v[18:21]
	v_mfma_f32_16x16x32_bf16 v[18:21], v[176:179], v[200:203], v[18:21]
	v_mfma_f32_16x16x32_bf16 v[2:5], v[172:175], v[204:207], v[2:5]
	v_mfma_f32_16x16x32_bf16 v[2:5], v[176:179], v[208:211], v[2:5]
	s_setprio 2
	s_barrier
	v_mfma_f32_16x16x32_bf16 v[6:9], v[164:167], v[204:207], v[6:9]
	v_mfma_f32_16x16x32_bf16 v[6:9], v[168:171], v[208:211], v[6:9]
	s_setprio 0
	s_add_i32 s73, s73, 2
	s_add_u32 s66, s66, 0x100
	s_addc_u32 s67, s67, 0
	s_add_u32 s18, s18, 0x100
	s_addc_u32 s19, s19, 0
	s_add_u32 s70, s70, 0x100
	s_addc_u32 s71, s71, 0
	s_cmp_gt_u32 s73, 29
	s_cbranch_scc0 .LBB0_1785
	s_and_b64 vcc, exec, s[6:7]
	s_cbranch_vccz .LBB0_1788
	s_barrier

.LBB0_1951:
	s_ashr_i32 s13, s12, 31
	s_lshl_b64 s[14:15], s[12:13], 15
	s_add_u32 s14, s28, s14
	s_addc_u32 s15, s29, s15
	s_and_b64 s[16:17], s[2:3], exec
	s_cselect_b32 s13, s15, s23
	s_cselect_b32 s65, s14, s22
	s_ashr_i32 s11, s10, 31
	s_lshl_b64 s[16:17], s[10:11], 15
	s_add_u32 s16, s30, s16
	s_addc_u32 s17, s31, s17
	s_and_b64 s[24:25], s[2:3], exec
	s_cselect_b32 s11, s17, s21
	s_cselect_b32 s66, s16, s20
	s_add_u32 s67, s20, 0x80000
	s_addc_u32 s70, s21, 0
	s_add_u32 s20, s22, 0x204000
	s_addc_u32 s21, s23, 0
	s_add_u32 s71, s22, 0x400000
	s_addc_u32 s73, s23, 0
	s_mov_b32 s74, -2
	s_waitcnt vmcnt(25)
	s_waitcnt vmcnt(24)
	s_waitcnt vmcnt(4)
	s_waitcnt vmcnt(2)
	s_waitcnt vmcnt(1)
	s_waitcnt vmcnt(0)
	ds_read_b128 v[130:133], v181
	ds_read_b128 v[134:137], v181 offset:1024
	ds_read_b128 v[138:141], v181 offset:2048
	ds_read_b128 v[142:145], v181 offset:3072
	ds_read_b128 v[150:153], v182
	ds_read_b128 v[154:157], v182 offset:1024
	ds_read_b128 v[158:161], v182 offset:2048
	ds_read_b128 v[162:165], v182 offset:3072
	s_cmpk_eq_i32 s74, 0x52
	s_cselect_b32 s23, s11, s70
	s_cselect_b32 s22, s66, s67
	s_cselect_b32 s25, s13, s73
	s_cselect_b32 s24, s65, s71
	ds_read_b128 v[166:169], v183
	ds_read_b128 v[170:173], v183 offset:1024
	ds_read_b128 v[186:189], v183 offset:2048
	ds_read_b128 v[190:193], v183 offset:3072
	ds_read_b128 v[194:197], v183 offset:4096
	ds_read_b128 v[198:201], v183 offset:5120
	ds_read_b128 v[202:205], v183 offset:6144
	ds_read_b128 v[206:209], v183 offset:7168
	s_add_u32 s76, s20, 0xffffc000
	s_addc_u32 s77, s21, -1
	s_mov_b32 s75, m0
	s_mov_b32 m0, s58
	s_nop 0
	global_load_lds_dwordx4 v1, s[76:77]
	s_mov_b32 m0, s75
	s_nop 0
	s_mov_b32 s75, m0
	s_mov_b32 m0, s62
	s_nop 0
	global_load_lds_dwordx4 v177, s[76:77]
	s_mov_b32 m0, s75
	s_nop 0
	s_mov_b32 s75, m0
	s_mov_b32 m0, s59
	s_nop 0
	global_load_lds_dwordx4 v1, s[20:21]
	s_mov_b32 m0, s75
	s_nop 0
	s_mov_b32 s75, m0
	s_mov_b32 m0, s63
	s_nop 0
	global_load_lds_dwordx4 v177, s[20:21]
	s_mov_b32 m0, s75
	s_waitcnt vmcnt(8)
	s_waitcnt lgkmcnt(0)
	s_barrier
	s_setprio 1
	s_waitcnt lgkmcnt(7)
	v_mfma_f32_16x16x32_bf16 v[126:129], v[130:133], v[166:169], 0
	v_mfma_f32_16x16x32_bf16 v[126:129], v[134:137], v[170:173], v[126:129]
	s_waitcnt lgkmcnt(5)
	v_mfma_f32_16x16x32_bf16 v[122:125], v[138:141], v[166:169], 0
	v_mfma_f32_16x16x32_bf16 v[122:125], v[142:145], v[170:173], v[122:125]
	s_waitcnt lgkmcnt(3)
	v_mfma_f32_16x16x32_bf16 v[110:113], v[138:141], v[186:189], 0
	v_mfma_f32_16x16x32_bf16 v[110:113], v[142:145], v[190:193], v[110:113]
	s_waitcnt lgkmcnt(1)
	v_mfma_f32_16x16x32_bf16 v[118:121], v[130:133], v[186:189], 0
	v_mfma_f32_16x16x32_bf16 v[118:121], v[134:137], v[190:193], v[118:121]
	v_mfma_f32_16x16x32_bf16 v[94:97], v[130:133], v[194:197], 0
	v_mfma_f32_16x16x32_bf16 v[94:97], v[134:137], v[198:201], v[94:97]
	v_mfma_f32_16x16x32_bf16 v[90:93], v[138:141], v[194:197], 0
	v_mfma_f32_16x16x32_bf16 v[90:93], v[142:145], v[198:201], v[90:93]
	v_mfma_f32_16x16x32_bf16 v[78:81], v[138:141], v[202:205], 0
	v_mfma_f32_16x16x32_bf16 v[78:81], v[142:145], v[206:209], v[78:81]
	s_waitcnt lgkmcnt(0)
	v_mfma_f32_16x16x32_bf16 v[86:89], v[130:133], v[202:205], 0
	v_mfma_f32_16x16x32_bf16 v[86:89], v[134:137], v[206:209], v[86:89]
	s_setprio 0
	s_setprio 1
	v_mfma_f32_16x16x32_bf16 v[114:117], v[150:153], v[166:169], 0
	v_mfma_f32_16x16x32_bf16 v[114:117], v[154:157], v[170:173], v[114:117]
	v_mfma_f32_16x16x32_bf16 v[106:109], v[158:161], v[166:169], 0
	v_mfma_f32_16x16x32_bf16 v[106:109], v[162:165], v[170:173], v[106:109]
	v_mfma_f32_16x16x32_bf16 v[98:101], v[158:161], v[186:189], 0
	v_mfma_f32_16x16x32_bf16 v[98:101], v[162:165], v[190:193], v[98:101]
	v_mfma_f32_16x16x32_bf16 v[102:105], v[150:153], v[186:189], 0
	v_mfma_f32_16x16x32_bf16 v[102:105], v[154:157], v[190:193], v[102:105]
	v_mfma_f32_16x16x32_bf16 v[82:85], v[150:153], v[194:197], 0
	v_mfma_f32_16x16x32_bf16 v[82:85], v[154:157], v[198:201], v[82:85]
	v_mfma_f32_16x16x32_bf16 v[74:77], v[158:161], v[194:197], 0
	v_mfma_f32_16x16x32_bf16 v[74:77], v[162:165], v[198:201], v[74:77]
	v_mfma_f32_16x16x32_bf16 v[66:69], v[158:161], v[202:205], 0
	v_mfma_f32_16x16x32_bf16 v[66:69], v[162:165], v[206:209], v[66:69]
	s_setprio 2
	s_barrier
	v_mfma_f32_16x16x32_bf16 v[70:73], v[150:153], v[202:205], 0
	v_mfma_f32_16x16x32_bf16 v[70:73], v[154:157], v[206:209], v[70:73]
	s_setprio 0
	ds_read_b128 v[166:169], v183 offset:16384
	ds_read_b128 v[170:173], v183 offset:17408
	ds_read_b128 v[186:189], v183 offset:18432
	ds_read_b128 v[190:193], v183 offset:19456
	ds_read_b128 v[194:197], v183 offset:20480
	ds_read_b128 v[198:201], v183 offset:21504
	ds_read_b128 v[202:205], v183 offset:22528
	ds_read_b128 v[206:209], v183 offset:23552
	s_mov_b32 s75, m0
	s_mov_b32 m0, s35
	s_nop 0
	global_load_lds_dwordx4 v176, s[22:23]
	s_mov_b32 m0, s75
	s_add_u32 s76, s22, 0x4000
	s_mov_b32 s75, m0
	s_mov_b32 m0, s36
	s_nop 0
	global_load_lds_dwordx4 v178, s[22:23]
	s_mov_b32 m0, s75
	s_addc_u32 s77, s23, 0
	s_mov_b32 s75, m0
	s_mov_b32 m0, s37
	s_nop 0
	global_load_lds_dwordx4 v176, s[76:77]
	s_mov_b32 m0, s75
	s_nop 0
	s_mov_b32 s75, m0
	s_mov_b32 m0, s40
	s_nop 0
	global_load_lds_dwordx4 v178, s[76:77]
	s_mov_b32 m0, s75
	s_waitcnt vmcnt(4)
	s_waitcnt lgkmcnt(0)
	s_barrier
	s_setprio 1
	s_waitcnt lgkmcnt(7)
	v_mfma_f32_16x16x32_bf16 v[62:65], v[130:133], v[166:169], 0
	v_mfma_f32_16x16x32_bf16 v[62:65], v[134:137], v[170:173], v[62:65]
	s_waitcnt lgkmcnt(5)
	v_mfma_f32_16x16x32_bf16 v[58:61], v[138:141], v[166:169], 0
	v_mfma_f32_16x16x32_bf16 v[58:61], v[142:145], v[170:173], v[58:61]
	s_waitcnt lgkmcnt(3)
	v_mfma_f32_16x16x32_bf16 v[42:45], v[138:141], v[186:189], 0
	v_mfma_f32_16x16x32_bf16 v[42:45], v[142:145], v[190:193], v[42:45]
	s_waitcnt lgkmcnt(1)
	v_mfma_f32_16x16x32_bf16 v[46:49], v[130:133], v[186:189], 0
	v_mfma_f32_16x16x32_bf16 v[46:49], v[134:137], v[190:193], v[46:49]
	v_mfma_f32_16x16x32_bf16 v[30:33], v[130:133], v[194:197], 0
	v_mfma_f32_16x16x32_bf16 v[30:33], v[134:137], v[198:201], v[30:33]
	v_mfma_f32_16x16x32_bf16 v[26:29], v[138:141], v[194:197], 0
	v_mfma_f32_16x16x32_bf16 v[26:29], v[142:145], v[198:201], v[26:29]
	v_mfma_f32_16x16x32_bf16 v[10:13], v[138:141], v[202:205], 0
	v_mfma_f32_16x16x32_bf16 v[10:13], v[142:145], v[206:209], v[10:13]
	s_waitcnt lgkmcnt(0)
	v_mfma_f32_16x16x32_bf16 v[14:17], v[130:133], v[202:205], 0
	v_mfma_f32_16x16x32_bf16 v[14:17], v[134:137], v[206:209], v[14:17]
	s_setprio 0
	s_setprio 1
	v_mfma_f32_16x16x32_bf16 v[54:57], v[150:153], v[166:169], 0
	v_mfma_f32_16x16x32_bf16 v[54:57], v[154:157], v[170:173], v[54:57]
	v_mfma_f32_16x16x32_bf16 v[50:53], v[158:161], v[166:169], 0
	v_mfma_f32_16x16x32_bf16 v[50:53], v[162:165], v[170:173], v[50:53]
	v_mfma_f32_16x16x32_bf16 v[34:37], v[158:161], v[186:189], 0
	v_mfma_f32_16x16x32_bf16 v[34:37], v[162:165], v[190:193], v[34:37]
	v_mfma_f32_16x16x32_bf16 v[38:41], v[150:153], v[186:189], 0
	v_mfma_f32_16x16x32_bf16 v[38:41], v[154:157], v[190:193], v[38:41]
	v_mfma_f32_16x16x32_bf16 v[22:25], v[150:153], v[194:197], 0
	v_mfma_f32_16x16x32_bf16 v[22:25], v[154:157], v[198:201], v[22:25]
	v_mfma_f32_16x16x32_bf16 v[18:21], v[158:161], v[194:197], 0
	v_mfma_f32_16x16x32_bf16 v[18:21], v[162:165], v[198:201], v[18:21]
	v_mfma_f32_16x16x32_bf16 v[2:5], v[158:161], v[202:205], 0
	v_mfma_f32_16x16x32_bf16 v[2:5], v[162:165], v[206:209], v[2:5]
	s_setprio 2
	s_barrier
	v_mfma_f32_16x16x32_bf16 v[6:9], v[150:153], v[202:205], 0
	v_mfma_f32_16x16x32_bf16 v[6:9], v[154:157], v[206:209], v[6:9]
	s_setprio 0
	ds_read_b128 v[130:133], v184
	ds_read_b128 v[134:137], v184 offset:1024
	ds_read_b128 v[138:141], v184 offset:2048
	ds_read_b128 v[142:145], v184 offset:3072
	ds_read_b128 v[150:153], v185
	ds_read_b128 v[154:157], v185 offset:1024
	ds_read_b128 v[158:161], v185 offset:2048
	ds_read_b128 v[162:165], v185 offset:3072
	ds_read_b128 v[166:169], v183 offset:32768
	ds_read_b128 v[170:173], v183 offset:33792
	ds_read_b128 v[186:189], v183 offset:34816
	ds_read_b128 v[190:193], v183 offset:35840
	ds_read_b128 v[194:197], v183 offset:36864
	ds_read_b128 v[198:201], v183 offset:37888
	ds_read_b128 v[202:205], v183 offset:38912
	ds_read_b128 v[206:209], v183 offset:39936
	s_mov_b32 s75, m0
	s_mov_b32 m0, s34
	s_nop 0
	global_load_lds_dwordx4 v1, s[24:25]
	s_mov_b32 m0, s75
	s_nop 0
	s_mov_b32 s75, m0
	s_mov_b32 m0, s41
	s_nop 0
	global_load_lds_dwordx4 v177, s[24:25]
	s_mov_b32 m0, s75
	s_add_u32 s24, s24, 0x4000
	s_addc_u32 s25, s25, 0
	s_mov_b32 s75, m0
	s_mov_b32 m0, s42
	s_nop 0
	global_load_lds_dwordx4 v1, s[24:25]
	s_mov_b32 m0, s75
	s_nop 0
	s_mov_b32 s75, m0
	s_mov_b32 m0, s43
	s_nop 0
	global_load_lds_dwordx4 v177, s[24:25]
	s_mov_b32 m0, s75
	s_waitcnt vmcnt(8)
	s_waitcnt lgkmcnt(0)
	s_barrier
	s_setprio 1
	s_waitcnt lgkmcnt(7)
	v_mfma_f32_16x16x32_bf16 v[126:129], v[130:133], v[166:169], v[126:129]
	v_mfma_f32_16x16x32_bf16 v[126:129], v[134:137], v[170:173], v[126:129]
	s_waitcnt lgkmcnt(5)
	v_mfma_f32_16x16x32_bf16 v[122:125], v[138:141], v[166:169], v[122:125]
	v_mfma_f32_16x16x32_bf16 v[122:125], v[142:145], v[170:173], v[122:125]
	s_waitcnt lgkmcnt(3)
	v_mfma_f32_16x16x32_bf16 v[110:113], v[138:141], v[186:189], v[110:113]
	v_mfma_f32_16x16x32_bf16 v[110:113], v[142:145], v[190:193], v[110:113]
	s_waitcnt lgkmcnt(1)
	v_mfma_f32_16x16x32_bf16 v[118:121], v[130:133], v[186:189], v[118:121]
	v_mfma_f32_16x16x32_bf16 v[118:121], v[134:137], v[190:193], v[118:121]
	v_mfma_f32_16x16x32_bf16 v[94:97], v[130:133], v[194:197], v[94:97]
	v_mfma_f32_16x16x32_bf16 v[94:97], v[134:137], v[198:201], v[94:97]
	v_mfma_f32_16x16x32_bf16 v[90:93], v[138:141], v[194:197], v[90:93]
	v_mfma_f32_16x16x32_bf16 v[90:93], v[142:145], v[198:201], v[90:93]
	v_mfma_f32_16x16x32_bf16 v[78:81], v[138:141], v[202:205], v[78:81]
	v_mfma_f32_16x16x32_bf16 v[78:81], v[142:145], v[206:209], v[78:81]
	s_waitcnt lgkmcnt(0)
	v_mfma_f32_16x16x32_bf16 v[86:89], v[130:133], v[202:205], v[86:89]
	v_mfma_f32_16x16x32_bf16 v[86:89], v[134:137], v[206:209], v[86:89]
	s_setprio 0
	s_setprio 1
	v_mfma_f32_16x16x32_bf16 v[114:117], v[150:153], v[166:169], v[114:117]
	v_mfma_f32_16x16x32_bf16 v[114:117], v[154:157], v[170:173], v[114:117]
	v_mfma_f32_16x16x32_bf16 v[106:109], v[158:161], v[166:169], v[106:109]
	v_mfma_f32_16x16x32_bf16 v[106:109], v[162:165], v[170:173], v[106:109]
	v_mfma_f32_16x16x32_bf16 v[98:101], v[158:161], v[186:189], v[98:101]
	v_mfma_f32_16x16x32_bf16 v[98:101], v[162:165], v[190:193], v[98:101]
	v_mfma_f32_16x16x32_bf16 v[102:105], v[150:153], v[186:189], v[102:105]
	v_mfma_f32_16x16x32_bf16 v[102:105], v[154:157], v[190:193], v[102:105]
	v_mfma_f32_16x16x32_bf16 v[82:85], v[150:153], v[194:197], v[82:85]
	v_mfma_f32_16x16x32_bf16 v[82:85], v[154:157], v[198:201], v[82:85]
	v_mfma_f32_16x16x32_bf16 v[74:77], v[158:161], v[194:197], v[74:77]
	v_mfma_f32_16x16x32_bf16 v[74:77], v[162:165], v[198:201], v[74:77]
	v_mfma_f32_16x16x32_bf16 v[66:69], v[158:161], v[202:205], v[66:69]
	v_mfma_f32_16x16x32_bf16 v[66:69], v[162:165], v[206:209], v[66:69]
	s_setprio 2
	s_barrier
	v_mfma_f32_16x16x32_bf16 v[70:73], v[150:153], v[202:205], v[70:73]
	v_mfma_f32_16x16x32_bf16 v[70:73], v[154:157], v[206:209], v[70:73]
	s_setprio 0
	ds_read_b128 v[166:169], v183 offset:49152
	ds_read_b128 v[170:173], v183 offset:50176
	ds_read_b128 v[186:189], v183 offset:51200
	ds_read_b128 v[190:193], v183 offset:52224
	ds_read_b128 v[194:197], v183 offset:53248
	ds_read_b128 v[198:201], v183 offset:54272
	ds_read_b128 v[202:205], v183 offset:55296
	ds_read_b128 v[206:209], v183 offset:56320
	s_add_u32 s24, s22, 0x40000
	s_addc_u32 s25, s23, 0
	s_mov_b32 s75, m0
	s_mov_b32 m0, s46
	s_nop 0
	global_load_lds_dwordx4 v176, s[24:25]
	s_mov_b32 m0, s75
	s_add_u32 s22, s22, 0x44000
	s_mov_b32 s75, m0
	s_mov_b32 m0, s47
	s_nop 0
	global_load_lds_dwordx4 v178, s[24:25]
	s_mov_b32 m0, s75
	s_addc_u32 s23, s23, 0
	s_mov_b32 s24, m0
	s_mov_b32 m0, s48
	s_nop 0
	global_load_lds_dwordx4 v176, s[22:23]
	s_mov_b32 m0, s24
	s_nop 0
	s_mov_b32 s24, m0
	s_mov_b32 m0, s49
	s_nop 0
	global_load_lds_dwordx4 v178, s[22:23]
	s_mov_b32 m0, s24
	s_waitcnt vmcnt(4)
	s_waitcnt lgkmcnt(0)
	s_barrier
	s_setprio 1
	s_waitcnt lgkmcnt(7)
	v_mfma_f32_16x16x32_bf16 v[62:65], v[130:133], v[166:169], v[62:65]
	v_mfma_f32_16x16x32_bf16 v[62:65], v[134:137], v[170:173], v[62:65]
	s_waitcnt lgkmcnt(5)
	v_mfma_f32_16x16x32_bf16 v[58:61], v[138:141], v[166:169], v[58:61]
	v_mfma_f32_16x16x32_bf16 v[58:61], v[142:145], v[170:173], v[58:61]
	s_waitcnt lgkmcnt(3)
	v_mfma_f32_16x16x32_bf16 v[42:45], v[138:141], v[186:189], v[42:45]
	v_mfma_f32_16x16x32_bf16 v[42:45], v[142:145], v[190:193], v[42:45]
	s_waitcnt lgkmcnt(1)
	v_mfma_f32_16x16x32_bf16 v[46:49], v[130:133], v[186:189], v[46:49]
	v_mfma_f32_16x16x32_bf16 v[46:49], v[134:137], v[190:193], v[46:49]
	v_mfma_f32_16x16x32_bf16 v[30:33], v[130:133], v[194:197], v[30:33]
	v_mfma_f32_16x16x32_bf16 v[30:33], v[134:137], v[198:201], v[30:33]
	v_mfma_f32_16x16x32_bf16 v[26:29], v[138:141], v[194:197], v[26:29]
	v_mfma_f32_16x16x32_bf16 v[26:29], v[142:145], v[198:201], v[26:29]
	v_mfma_f32_16x16x32_bf16 v[10:13], v[138:141], v[202:205], v[10:13]
	v_mfma_f32_16x16x32_bf16 v[10:13], v[142:145], v[206:209], v[10:13]
	s_waitcnt lgkmcnt(0)
	v_mfma_f32_16x16x32_bf16 v[14:17], v[130:133], v[202:205], v[14:17]
	v_mfma_f32_16x16x32_bf16 v[14:17], v[134:137], v[206:209], v[14:17]
	s_setprio 0
	s_setprio 1
	v_mfma_f32_16x16x32_bf16 v[54:57], v[150:153], v[166:169], v[54:57]
	v_mfma_f32_16x16x32_bf16 v[54:57], v[154:157], v[170:173], v[54:57]
	v_mfma_f32_16x16x32_bf16 v[50:53], v[158:161], v[166:169], v[50:53]
	v_mfma_f32_16x16x32_bf16 v[50:53], v[162:165], v[170:173], v[50:53]
	v_mfma_f32_16x16x32_bf16 v[34:37], v[158:161], v[186:189], v[34:37]
	v_mfma_f32_16x16x32_bf16 v[34:37], v[162:165], v[190:193], v[34:37]
	v_mfma_f32_16x16x32_bf16 v[38:41], v[150:153], v[186:189], v[38:41]
	v_mfma_f32_16x16x32_bf16 v[38:41], v[154:157], v[190:193], v[38:41]
	v_mfma_f32_16x16x32_bf16 v[22:25], v[150:153], v[194:197], v[22:25]
	v_mfma_f32_16x16x32_bf16 v[22:25], v[154:157], v[198:201], v[22:25]
	v_mfma_f32_16x16x32_bf16 v[18:21], v[158:161], v[194:197], v[18:21]
	v_mfma_f32_16x16x32_bf16 v[18:21], v[162:165], v[198:201], v[18:21]
	v_mfma_f32_16x16x32_bf16 v[2:5], v[158:161], v[202:205], v[2:5]
	v_mfma_f32_16x16x32_bf16 v[2:5], v[162:165], v[206:209], v[2:5]
	s_setprio 2
	s_barrier
	v_mfma_f32_16x16x32_bf16 v[6:9], v[150:153], v[202:205], v[6:9]
	v_mfma_f32_16x16x32_bf16 v[6:9], v[154:157], v[206:209], v[6:9]
	s_setprio 0
	s_add_i32 s74, s74, 2
	s_add_u32 s67, s67, 0x80000
	s_addc_u32 s70, s70, 0
	s_add_u32 s20, s20, 0x400000
	s_addc_u32 s21, s21, 0
	s_add_u32 s71, s71, 0x400000
	s_addc_u32 s73, s73, 0
	s_cmpk_gt_u32 s74, 0x53
	.p2align 6
.LBB0_1952:
	ds_read_b128 v[130:133], v181
	ds_read_b128 v[134:137], v181 offset:1024
	ds_read_b128 v[138:141], v181 offset:2048
	ds_read_b128 v[142:145], v181 offset:3072
	ds_read_b128 v[150:153], v182
	ds_read_b128 v[154:157], v182 offset:1024
	ds_read_b128 v[158:161], v182 offset:2048
	ds_read_b128 v[162:165], v182 offset:3072
	s_cmpk_eq_i32 s74, 0x52
	s_cselect_b32 s23, s11, s70
	s_cselect_b32 s22, s66, s67
	s_cselect_b32 s25, s13, s73
	s_cselect_b32 s24, s65, s71
	ds_read_b128 v[166:169], v183
	ds_read_b128 v[170:173], v183 offset:1024
	ds_read_b128 v[186:189], v183 offset:2048
	ds_read_b128 v[190:193], v183 offset:3072
	ds_read_b128 v[194:197], v183 offset:4096
	ds_read_b128 v[198:201], v183 offset:5120
	ds_read_b128 v[202:205], v183 offset:6144
	ds_read_b128 v[206:209], v183 offset:7168
	s_add_u32 s76, s20, 0xffffc000
	s_addc_u32 s77, s21, -1
	s_mov_b32 s75, m0
	s_mov_b32 m0, s58
	s_nop 0
	global_load_lds_dwordx4 v1, s[76:77]
	s_mov_b32 m0, s75
	s_nop 0
	s_mov_b32 s75, m0
	s_mov_b32 m0, s62
	s_nop 0
	global_load_lds_dwordx4 v177, s[76:77]
	s_mov_b32 m0, s75
	s_nop 0
	s_mov_b32 s75, m0
	s_mov_b32 m0, s59
	s_nop 0
	global_load_lds_dwordx4 v1, s[20:21]
	s_mov_b32 m0, s75
	s_nop 0
	s_mov_b32 s75, m0
	s_mov_b32 m0, s63
	s_nop 0
	global_load_lds_dwordx4 v177, s[20:21]
	s_mov_b32 m0, s75
	s_waitcnt vmcnt(8)
	s_waitcnt lgkmcnt(0)
	s_barrier
	s_setprio 1
	s_waitcnt lgkmcnt(7)
	v_mfma_f32_16x16x32_bf16 v[126:129], v[130:133], v[166:169], v[126:129]
	v_mfma_f32_16x16x32_bf16 v[126:129], v[134:137], v[170:173], v[126:129]
	s_waitcnt lgkmcnt(5)
	v_mfma_f32_16x16x32_bf16 v[122:125], v[138:141], v[166:169], v[122:125]
	v_mfma_f32_16x16x32_bf16 v[122:125], v[142:145], v[170:173], v[122:125]
	s_waitcnt lgkmcnt(3)
	v_mfma_f32_16x16x32_bf16 v[110:113], v[138:141], v[186:189], v[110:113]
	v_mfma_f32_16x16x32_bf16 v[110:113], v[142:145], v[190:193], v[110:113]
	s_waitcnt lgkmcnt(1)
	v_mfma_f32_16x16x32_bf16 v[118:121], v[130:133], v[186:189], v[118:121]
	v_mfma_f32_16x16x32_bf16 v[118:121], v[134:137], v[190:193], v[118:121]
	v_mfma_f32_16x16x32_bf16 v[94:97], v[130:133], v[194:197], v[94:97]
	v_mfma_f32_16x16x32_bf16 v[94:97], v[134:137], v[198:201], v[94:97]
	v_mfma_f32_16x16x32_bf16 v[90:93], v[138:141], v[194:197], v[90:93]
	v_mfma_f32_16x16x32_bf16 v[90:93], v[142:145], v[198:201], v[90:93]
	v_mfma_f32_16x16x32_bf16 v[78:81], v[138:141], v[202:205], v[78:81]
	v_mfma_f32_16x16x32_bf16 v[78:81], v[142:145], v[206:209], v[78:81]
	s_waitcnt lgkmcnt(0)
	v_mfma_f32_16x16x32_bf16 v[86:89], v[130:133], v[202:205], v[86:89]
	v_mfma_f32_16x16x32_bf16 v[86:89], v[134:137], v[206:209], v[86:89]
	s_setprio 0
	s_setprio 1
	v_mfma_f32_16x16x32_bf16 v[114:117], v[150:153], v[166:169], v[114:117]
	v_mfma_f32_16x16x32_bf16 v[114:117], v[154:157], v[170:173], v[114:117]
	v_mfma_f32_16x16x32_bf16 v[106:109], v[158:161], v[166:169], v[106:109]
	v_mfma_f32_16x16x32_bf16 v[106:109], v[162:165], v[170:173], v[106:109]
	v_mfma_f32_16x16x32_bf16 v[98:101], v[158:161], v[186:189], v[98:101]
	v_mfma_f32_16x16x32_bf16 v[98:101], v[162:165], v[190:193], v[98:101]
	v_mfma_f32_16x16x32_bf16 v[102:105], v[150:153], v[186:189], v[102:105]
	v_mfma_f32_16x16x32_bf16 v[102:105], v[154:157], v[190:193], v[102:105]
	v_mfma_f32_16x16x32_bf16 v[82:85], v[150:153], v[194:197], v[82:85]
	v_mfma_f32_16x16x32_bf16 v[82:85], v[154:157], v[198:201], v[82:85]
	v_mfma_f32_16x16x32_bf16 v[74:77], v[158:161], v[194:197], v[74:77]
	v_mfma_f32_16x16x32_bf16 v[74:77], v[162:165], v[198:201], v[74:77]
	v_mfma_f32_16x16x32_bf16 v[66:69], v[158:161], v[202:205], v[66:69]
	v_mfma_f32_16x16x32_bf16 v[66:69], v[162:165], v[206:209], v[66:69]
	s_setprio 2
	s_barrier
	v_mfma_f32_16x16x32_bf16 v[70:73], v[150:153], v[202:205], v[70:73]
	v_mfma_f32_16x16x32_bf16 v[70:73], v[154:157], v[206:209], v[70:73]
	s_setprio 0
	ds_read_b128 v[166:169], v183 offset:16384
	ds_read_b128 v[170:173], v183 offset:17408
	ds_read_b128 v[186:189], v183 offset:18432
	ds_read_b128 v[190:193], v183 offset:19456
	ds_read_b128 v[194:197], v183 offset:20480
	ds_read_b128 v[198:201], v183 offset:21504
	ds_read_b128 v[202:205], v183 offset:22528
	ds_read_b128 v[206:209], v183 offset:23552
	s_mov_b32 s75, m0
	s_mov_b32 m0, s35
	s_nop 0
	global_load_lds_dwordx4 v176, s[22:23]
	s_mov_b32 m0, s75
	s_add_u32 s76, s22, 0x4000
	s_mov_b32 s75, m0
	s_mov_b32 m0, s36
	s_nop 0
	global_load_lds_dwordx4 v178, s[22:23]
	s_mov_b32 m0, s75
	s_addc_u32 s77, s23, 0
	s_mov_b32 s75, m0
	s_mov_b32 m0, s37
	s_nop 0
	global_load_lds_dwordx4 v176, s[76:77]
	s_mov_b32 m0, s75
	s_nop 0
	s_mov_b32 s75, m0
	s_mov_b32 m0, s40
	s_nop 0
	global_load_lds_dwordx4 v178, s[76:77]
	s_mov_b32 m0, s75
	s_waitcnt vmcnt(4)
	s_waitcnt lgkmcnt(0)
	s_barrier
	s_setprio 1
	s_waitcnt lgkmcnt(7)
	v_mfma_f32_16x16x32_bf16 v[62:65], v[130:133], v[166:169], v[62:65]
	v_mfma_f32_16x16x32_bf16 v[62:65], v[134:137], v[170:173], v[62:65]
	s_waitcnt lgkmcnt(5)
	v_mfma_f32_16x16x32_bf16 v[58:61], v[138:141], v[166:169], v[58:61]
	v_mfma_f32_16x16x32_bf16 v[58:61], v[142:145], v[170:173], v[58:61]
	s_waitcnt lgkmcnt(3)
	v_mfma_f32_16x16x32_bf16 v[42:45], v[138:141], v[186:189], v[42:45]
	v_mfma_f32_16x16x32_bf16 v[42:45], v[142:145], v[190:193], v[42:45]
	s_waitcnt lgkmcnt(1)
	v_mfma_f32_16x16x32_bf16 v[46:49], v[130:133], v[186:189], v[46:49]
	v_mfma_f32_16x16x32_bf16 v[46:49], v[134:137], v[190:193], v[46:49]
	v_mfma_f32_16x16x32_bf16 v[30:33], v[130:133], v[194:197], v[30:33]
	v_mfma_f32_16x16x32_bf16 v[30:33], v[134:137], v[198:201], v[30:33]
	v_mfma_f32_16x16x32_bf16 v[26:29], v[138:141], v[194:197], v[26:29]
	v_mfma_f32_16x16x32_bf16 v[26:29], v[142:145], v[198:201], v[26:29]
	v_mfma_f32_16x16x32_bf16 v[10:13], v[138:141], v[202:205], v[10:13]
	v_mfma_f32_16x16x32_bf16 v[10:13], v[142:145], v[206:209], v[10:13]
	s_waitcnt lgkmcnt(0)
	v_mfma_f32_16x16x32_bf16 v[14:17], v[130:133], v[202:205], v[14:17]
	v_mfma_f32_16x16x32_bf16 v[14:17], v[134:137], v[206:209], v[14:17]
	s_setprio 0
	s_setprio 1
	v_mfma_f32_16x16x32_bf16 v[54:57], v[150:153], v[166:169], v[54:57]
	v_mfma_f32_16x16x32_bf16 v[54:57], v[154:157], v[170:173], v[54:57]
	v_mfma_f32_16x16x32_bf16 v[50:53], v[158:161], v[166:169], v[50:53]
	v_mfma_f32_16x16x32_bf16 v[50:53], v[162:165], v[170:173], v[50:53]
	v_mfma_f32_16x16x32_bf16 v[34:37], v[158:161], v[186:189], v[34:37]
	v_mfma_f32_16x16x32_bf16 v[34:37], v[162:165], v[190:193], v[34:37]
	v_mfma_f32_16x16x32_bf16 v[38:41], v[150:153], v[186:189], v[38:41]
	v_mfma_f32_16x16x32_bf16 v[38:41], v[154:157], v[190:193], v[38:41]
	v_mfma_f32_16x16x32_bf16 v[22:25], v[150:153], v[194:197], v[22:25]
	v_mfma_f32_16x16x32_bf16 v[22:25], v[154:157], v[198:201], v[22:25]
	v_mfma_f32_16x16x32_bf16 v[18:21], v[158:161], v[194:197], v[18:21]
	v_mfma_f32_16x16x32_bf16 v[18:21], v[162:165], v[198:201], v[18:21]
	v_mfma_f32_16x16x32_bf16 v[2:5], v[158:161], v[202:205], v[2:5]
	v_mfma_f32_16x16x32_bf16 v[2:5], v[162:165], v[206:209], v[2:5]
	s_setprio 2
	s_barrier
	v_mfma_f32_16x16x32_bf16 v[6:9], v[150:153], v[202:205], v[6:9]
	v_mfma_f32_16x16x32_bf16 v[6:9], v[154:157], v[206:209], v[6:9]
	s_setprio 0
	ds_read_b128 v[130:133], v184
	ds_read_b128 v[134:137], v184 offset:1024
	ds_read_b128 v[138:141], v184 offset:2048
	ds_read_b128 v[142:145], v184 offset:3072
	ds_read_b128 v[150:153], v185
	ds_read_b128 v[154:157], v185 offset:1024
	ds_read_b128 v[158:161], v185 offset:2048
	ds_read_b128 v[162:165], v185 offset:3072
	ds_read_b128 v[166:169], v183 offset:32768
	ds_read_b128 v[170:173], v183 offset:33792
	ds_read_b128 v[186:189], v183 offset:34816
	ds_read_b128 v[190:193], v183 offset:35840
	ds_read_b128 v[194:197], v183 offset:36864
	ds_read_b128 v[198:201], v183 offset:37888
	ds_read_b128 v[202:205], v183 offset:38912
	ds_read_b128 v[206:209], v183 offset:39936
	s_mov_b32 s75, m0
	s_mov_b32 m0, s34
	s_nop 0
	global_load_lds_dwordx4 v1, s[24:25]
	s_mov_b32 m0, s75
	s_nop 0
	s_mov_b32 s75, m0
	s_mov_b32 m0, s41
	s_nop 0
	global_load_lds_dwordx4 v177, s[24:25]
	s_mov_b32 m0, s75
	s_add_u32 s24, s24, 0x4000
	s_addc_u32 s25, s25, 0
	s_mov_b32 s75, m0
	s_mov_b32 m0, s42
	s_nop 0
	global_load_lds_dwordx4 v1, s[24:25]
	s_mov_b32 m0, s75
	s_nop 0
	s_mov_b32 s75, m0
	s_mov_b32 m0, s43
	s_nop 0
	global_load_lds_dwordx4 v177, s[24:25]
	s_mov_b32 m0, s75
	s_waitcnt vmcnt(8)
	s_waitcnt lgkmcnt(0)
	s_barrier
	s_setprio 1
	s_waitcnt lgkmcnt(7)
	v_mfma_f32_16x16x32_bf16 v[126:129], v[130:133], v[166:169], v[126:129]
	v_mfma_f32_16x16x32_bf16 v[126:129], v[134:137], v[170:173], v[126:129]
	s_waitcnt lgkmcnt(5)
	v_mfma_f32_16x16x32_bf16 v[122:125], v[138:141], v[166:169], v[122:125]
	v_mfma_f32_16x16x32_bf16 v[122:125], v[142:145], v[170:173], v[122:125]
	s_waitcnt lgkmcnt(3)
	v_mfma_f32_16x16x32_bf16 v[110:113], v[138:141], v[186:189], v[110:113]
	v_mfma_f32_16x16x32_bf16 v[110:113], v[142:145], v[190:193], v[110:113]
	s_waitcnt lgkmcnt(1)
	v_mfma_f32_16x16x32_bf16 v[118:121], v[130:133], v[186:189], v[118:121]
	v_mfma_f32_16x16x32_bf16 v[118:121], v[134:137], v[190:193], v[118:121]
	v_mfma_f32_16x16x32_bf16 v[94:97], v[130:133], v[194:197], v[94:97]
	v_mfma_f32_16x16x32_bf16 v[94:97], v[134:137], v[198:201], v[94:97]
	v_mfma_f32_16x16x32_bf16 v[90:93], v[138:141], v[194:197], v[90:93]
	v_mfma_f32_16x16x32_bf16 v[90:93], v[142:145], v[198:201], v[90:93]
	v_mfma_f32_16x16x32_bf16 v[78:81], v[138:141], v[202:205], v[78:81]
	v_mfma_f32_16x16x32_bf16 v[78:81], v[142:145], v[206:209], v[78:81]
	s_waitcnt lgkmcnt(0)
	v_mfma_f32_16x16x32_bf16 v[86:89], v[130:133], v[202:205], v[86:89]
	v_mfma_f32_16x16x32_bf16 v[86:89], v[134:137], v[206:209], v[86:89]
	s_setprio 0
	s_setprio 1
	v_mfma_f32_16x16x32_bf16 v[114:117], v[150:153], v[166:169], v[114:117]
	v_mfma_f32_16x16x32_bf16 v[114:117], v[154:157], v[170:173], v[114:117]
	v_mfma_f32_16x16x32_bf16 v[106:109], v[158:161], v[166:169], v[106:109]
	v_mfma_f32_16x16x32_bf16 v[106:109], v[162:165], v[170:173], v[106:109]
	v_mfma_f32_16x16x32_bf16 v[98:101], v[158:161], v[186:189], v[98:101]
	v_mfma_f32_16x16x32_bf16 v[98:101], v[162:165], v[190:193], v[98:101]
	v_mfma_f32_16x16x32_bf16 v[102:105], v[150:153], v[186:189], v[102:105]
	v_mfma_f32_16x16x32_bf16 v[102:105], v[154:157], v[190:193], v[102:105]
	v_mfma_f32_16x16x32_bf16 v[82:85], v[150:153], v[194:197], v[82:85]
	v_mfma_f32_16x16x32_bf16 v[82:85], v[154:157], v[198:201], v[82:85]
	v_mfma_f32_16x16x32_bf16 v[74:77], v[158:161], v[194:197], v[74:77]
	v_mfma_f32_16x16x32_bf16 v[74:77], v[162:165], v[198:201], v[74:77]
	v_mfma_f32_16x16x32_bf16 v[66:69], v[158:161], v[202:205], v[66:69]
	v_mfma_f32_16x16x32_bf16 v[66:69], v[162:165], v[206:209], v[66:69]
	s_setprio 2
	s_barrier
	v_mfma_f32_16x16x32_bf16 v[70:73], v[150:153], v[202:205], v[70:73]
	v_mfma_f32_16x16x32_bf16 v[70:73], v[154:157], v[206:209], v[70:73]
	s_setprio 0
	ds_read_b128 v[166:169], v183 offset:49152
	ds_read_b128 v[170:173], v183 offset:50176
	ds_read_b128 v[186:189], v183 offset:51200
	ds_read_b128 v[190:193], v183 offset:52224
	ds_read_b128 v[194:197], v183 offset:53248
	ds_read_b128 v[198:201], v183 offset:54272
	ds_read_b128 v[202:205], v183 offset:55296
	ds_read_b128 v[206:209], v183 offset:56320
	s_add_u32 s24, s22, 0x40000
	s_addc_u32 s25, s23, 0
	s_mov_b32 s75, m0
	s_mov_b32 m0, s46
	s_nop 0
	global_load_lds_dwordx4 v176, s[24:25]
	s_mov_b32 m0, s75
	s_add_u32 s22, s22, 0x44000
	s_mov_b32 s75, m0
	s_mov_b32 m0, s47
	s_nop 0
	global_load_lds_dwordx4 v178, s[24:25]
	s_mov_b32 m0, s75
	s_addc_u32 s23, s23, 0
	s_mov_b32 s24, m0
	s_mov_b32 m0, s48
	s_nop 0
	global_load_lds_dwordx4 v176, s[22:23]
	s_mov_b32 m0, s24
	s_nop 0
	s_mov_b32 s24, m0
	s_mov_b32 m0, s49
	s_nop 0
	global_load_lds_dwordx4 v178, s[22:23]
	s_mov_b32 m0, s24
	s_waitcnt vmcnt(4)
	s_waitcnt lgkmcnt(0)
	s_barrier
	s_setprio 1
	s_waitcnt lgkmcnt(7)
	v_mfma_f32_16x16x32_bf16 v[62:65], v[130:133], v[166:169], v[62:65]
	v_mfma_f32_16x16x32_bf16 v[62:65], v[134:137], v[170:173], v[62:65]
	s_waitcnt lgkmcnt(5)
	v_mfma_f32_16x16x32_bf16 v[58:61], v[138:141], v[166:169], v[58:61]
	v_mfma_f32_16x16x32_bf16 v[58:61], v[142:145], v[170:173], v[58:61]
	s_waitcnt lgkmcnt(3)
	v_mfma_f32_16x16x32_bf16 v[42:45], v[138:141], v[186:189], v[42:45]
	v_mfma_f32_16x16x32_bf16 v[42:45], v[142:145], v[190:193], v[42:45]
	s_waitcnt lgkmcnt(1)
	v_mfma_f32_16x16x32_bf16 v[46:49], v[130:133], v[186:189], v[46:49]
	v_mfma_f32_16x16x32_bf16 v[46:49], v[134:137], v[190:193], v[46:49]
	v_mfma_f32_16x16x32_bf16 v[30:33], v[130:133], v[194:197], v[30:33]
	v_mfma_f32_16x16x32_bf16 v[30:33], v[134:137], v[198:201], v[30:33]
	v_mfma_f32_16x16x32_bf16 v[26:29], v[138:141], v[194:197], v[26:29]
	v_mfma_f32_16x16x32_bf16 v[26:29], v[142:145], v[198:201], v[26:29]
	v_mfma_f32_16x16x32_bf16 v[10:13], v[138:141], v[202:205], v[10:13]
	v_mfma_f32_16x16x32_bf16 v[10:13], v[142:145], v[206:209], v[10:13]
	s_waitcnt lgkmcnt(0)
	v_mfma_f32_16x16x32_bf16 v[14:17], v[130:133], v[202:205], v[14:17]
	v_mfma_f32_16x16x32_bf16 v[14:17], v[134:137], v[206:209], v[14:17]
	s_setprio 0
	s_setprio 1
	v_mfma_f32_16x16x32_bf16 v[54:57], v[150:153], v[166:169], v[54:57]
	v_mfma_f32_16x16x32_bf16 v[54:57], v[154:157], v[170:173], v[54:57]
	v_mfma_f32_16x16x32_bf16 v[50:53], v[158:161], v[166:169], v[50:53]
	v_mfma_f32_16x16x32_bf16 v[50:53], v[162:165], v[170:173], v[50:53]
	v_mfma_f32_16x16x32_bf16 v[34:37], v[158:161], v[186:189], v[34:37]
	v_mfma_f32_16x16x32_bf16 v[34:37], v[162:165], v[190:193], v[34:37]
	v_mfma_f32_16x16x32_bf16 v[38:41], v[150:153], v[186:189], v[38:41]
	v_mfma_f32_16x16x32_bf16 v[38:41], v[154:157], v[190:193], v[38:41]
	v_mfma_f32_16x16x32_bf16 v[22:25], v[150:153], v[194:197], v[22:25]
	v_mfma_f32_16x16x32_bf16 v[22:25], v[154:157], v[198:201], v[22:25]
	v_mfma_f32_16x16x32_bf16 v[18:21], v[158:161], v[194:197], v[18:21]
	v_mfma_f32_16x16x32_bf16 v[18:21], v[162:165], v[198:201], v[18:21]
	v_mfma_f32_16x16x32_bf16 v[2:5], v[158:161], v[202:205], v[2:5]
	v_mfma_f32_16x16x32_bf16 v[2:5], v[162:165], v[206:209], v[2:5]
	s_setprio 2
	s_barrier
	v_mfma_f32_16x16x32_bf16 v[6:9], v[150:153], v[202:205], v[6:9]
	v_mfma_f32_16x16x32_bf16 v[6:9], v[154:157], v[206:209], v[6:9]
	s_setprio 0
	s_add_i32 s74, s74, 2
	s_add_u32 s67, s67, 0x80000
	s_addc_u32 s70, s70, 0
	s_add_u32 s20, s20, 0x400000
	s_addc_u32 s21, s21, 0
	s_add_u32 s71, s71, 0x400000
	s_addc_u32 s73, s73, 0
	s_cmpk_gt_u32 s74, 0x53
	s_cbranch_scc0 .LBB0_1952
	s_and_b64 vcc, exec, s[8:9]
	s_cbranch_vccz .LBB0_1955
	s_barrier

.LBB0_2409:
	s_ashr_i32 s17, s16, 31
	s_lshl_b64 s[18:19], s[16:17], 20
	s_add_u32 s18, s33, s18
	s_addc_u32 s19, s34, s19
	s_and_b64 s[20:21], s[2:3], exec
	s_cselect_b32 s17, s19, s27
	s_cselect_b32 s71, s18, s26
	s_ashr_i32 s15, s14, 31
	s_lshl_b64 s[20:21], s[14:15], 20
	s_add_u32 s20, s35, s20
	s_addc_u32 s21, s36, s21
	s_and_b64 s[28:29], s[2:3], exec
	s_cselect_b32 s15, s21, s25
	s_cselect_b32 s73, s20, s24
	s_add_u32 s74, s24, 0x100
	s_addc_u32 s75, s25, 0
	s_add_u32 s24, s26, 0x80080
	s_addc_u32 s25, s27, 0
	s_add_u32 s76, s26, 0x100
	s_addc_u32 s77, s27, 0
	s_mov_b32 s78, -2
	s_waitcnt vmcnt(25)
	s_waitcnt vmcnt(24)
	s_waitcnt vmcnt(4)
	s_waitcnt vmcnt(2)
	s_waitcnt vmcnt(1)
	s_waitcnt vmcnt(0)
	ds_read_b128 v[130:133], v181
	ds_read_b128 v[134:137], v181 offset:1024
	ds_read_b128 v[138:141], v181 offset:2048
	ds_read_b128 v[142:145], v181 offset:3072
	ds_read_b128 v[146:149], v182
	ds_read_b128 v[150:153], v182 offset:1024
	ds_read_b128 v[154:157], v182 offset:2048
	ds_read_b128 v[158:161], v182 offset:3072
	s_cmp_eq_u32 s78, 28
	s_cselect_b32 s27, s15, s75
	s_cselect_b32 s26, s73, s74
	s_cselect_b32 s29, s17, s77
	s_cselect_b32 s28, s71, s76
	ds_read_b128 v[166:169], v183
	ds_read_b128 v[170:173], v183 offset:1024
	ds_read_b128 v[186:189], v183 offset:2048
	ds_read_b128 v[190:193], v183 offset:3072
	ds_read_b128 v[194:197], v183 offset:4096
	ds_read_b128 v[198:201], v183 offset:5120
	ds_read_b128 v[202:205], v183 offset:6144
	ds_read_b128 v[206:209], v183 offset:7168
	s_add_u32 s80, s24, 0xfff80000
	s_addc_u32 s81, s25, -1
	s_mov_b32 s79, m0
	s_mov_b32 m0, s64
	s_nop 0
	global_load_lds_dwordx4 v1, s[80:81]
	s_mov_b32 m0, s79
	s_nop 0
	s_mov_b32 s79, m0
	s_mov_b32 m0, s66
	s_nop 0
	global_load_lds_dwordx4 v177, s[80:81]
	s_mov_b32 m0, s79
	s_nop 0
	s_mov_b32 s79, m0
	s_mov_b32 m0, s65
	s_nop 0
	global_load_lds_dwordx4 v1, s[24:25]
	s_mov_b32 m0, s79
	s_nop 0
	s_mov_b32 s79, m0
	s_mov_b32 m0, s67
	s_nop 0
	global_load_lds_dwordx4 v177, s[24:25]
	s_mov_b32 m0, s79
	s_waitcnt vmcnt(8)
	s_waitcnt lgkmcnt(0)
	s_barrier
	s_setprio 1
	s_waitcnt lgkmcnt(7)
	v_mfma_f32_16x16x32_bf16 v[126:129], v[130:133], v[166:169], 0
	v_mfma_f32_16x16x32_bf16 v[126:129], v[134:137], v[170:173], v[126:129]
	s_waitcnt lgkmcnt(5)
	v_mfma_f32_16x16x32_bf16 v[122:125], v[138:141], v[166:169], 0
	v_mfma_f32_16x16x32_bf16 v[122:125], v[142:145], v[170:173], v[122:125]
	s_waitcnt lgkmcnt(3)
	v_mfma_f32_16x16x32_bf16 v[114:117], v[138:141], v[186:189], 0
	v_mfma_f32_16x16x32_bf16 v[114:117], v[142:145], v[190:193], v[114:117]
	s_waitcnt lgkmcnt(1)
	v_mfma_f32_16x16x32_bf16 v[118:121], v[130:133], v[186:189], 0
	v_mfma_f32_16x16x32_bf16 v[118:121], v[134:137], v[190:193], v[118:121]
	v_mfma_f32_16x16x32_bf16 v[94:97], v[130:133], v[194:197], 0
	v_mfma_f32_16x16x32_bf16 v[94:97], v[134:137], v[198:201], v[94:97]
	v_mfma_f32_16x16x32_bf16 v[90:93], v[138:141], v[194:197], 0
	v_mfma_f32_16x16x32_bf16 v[90:93], v[142:145], v[198:201], v[90:93]
	v_mfma_f32_16x16x32_bf16 v[78:81], v[138:141], v[202:205], 0
	v_mfma_f32_16x16x32_bf16 v[78:81], v[142:145], v[206:209], v[78:81]
	s_waitcnt lgkmcnt(0)
	v_mfma_f32_16x16x32_bf16 v[86:89], v[130:133], v[202:205], 0
	v_mfma_f32_16x16x32_bf16 v[86:89], v[134:137], v[206:209], v[86:89]
	s_setprio 0
	s_setprio 1
	v_mfma_f32_16x16x32_bf16 v[110:113], v[146:149], v[166:169], 0
	v_mfma_f32_16x16x32_bf16 v[110:113], v[150:153], v[170:173], v[110:113]
	v_mfma_f32_16x16x32_bf16 v[106:109], v[154:157], v[166:169], 0
	v_mfma_f32_16x16x32_bf16 v[106:109], v[158:161], v[170:173], v[106:109]
	v_mfma_f32_16x16x32_bf16 v[98:101], v[154:157], v[186:189], 0
	v_mfma_f32_16x16x32_bf16 v[98:101], v[158:161], v[190:193], v[98:101]
	v_mfma_f32_16x16x32_bf16 v[102:105], v[146:149], v[186:189], 0
	v_mfma_f32_16x16x32_bf16 v[102:105], v[150:153], v[190:193], v[102:105]
	v_mfma_f32_16x16x32_bf16 v[82:85], v[146:149], v[194:197], 0
	v_mfma_f32_16x16x32_bf16 v[82:85], v[150:153], v[198:201], v[82:85]
	v_mfma_f32_16x16x32_bf16 v[74:77], v[154:157], v[194:197], 0
	v_mfma_f32_16x16x32_bf16 v[74:77], v[158:161], v[198:201], v[74:77]
	v_mfma_f32_16x16x32_bf16 v[66:69], v[154:157], v[202:205], 0
	v_mfma_f32_16x16x32_bf16 v[66:69], v[158:161], v[206:209], v[66:69]
	s_setprio 2
	s_barrier
	v_mfma_f32_16x16x32_bf16 v[70:73], v[146:149], v[202:205], 0
	v_mfma_f32_16x16x32_bf16 v[70:73], v[150:153], v[206:209], v[70:73]
	s_setprio 0
	ds_read_b128 v[166:169], v183 offset:16384
	ds_read_b128 v[170:173], v183 offset:17408
	ds_read_b128 v[186:189], v183 offset:18432
	ds_read_b128 v[190:193], v183 offset:19456
	ds_read_b128 v[194:197], v183 offset:20480
	ds_read_b128 v[198:201], v183 offset:21504
	ds_read_b128 v[202:205], v183 offset:22528
	ds_read_b128 v[206:209], v183 offset:23552
	s_mov_b32 s79, m0
	s_mov_b32 m0, s41
	s_nop 0
	global_load_lds_dwordx4 v176, s[26:27]
	s_mov_b32 m0, s79
	s_add_u32 s80, s26, 0x80000
	s_mov_b32 s79, m0
	s_mov_b32 m0, s42
	s_nop 0
	global_load_lds_dwordx4 v178, s[26:27]
	s_mov_b32 m0, s79
	s_addc_u32 s81, s27, 0
	s_mov_b32 s79, m0
	s_mov_b32 m0, s43
	s_nop 0
	global_load_lds_dwordx4 v176, s[80:81]
	s_mov_b32 m0, s79
	s_nop 0
	s_mov_b32 s79, m0
	s_mov_b32 m0, s46
	s_nop 0
	global_load_lds_dwordx4 v178, s[80:81]
	s_mov_b32 m0, s79
	s_waitcnt vmcnt(4)
	s_waitcnt lgkmcnt(0)
	s_barrier
	s_setprio 1
	s_waitcnt lgkmcnt(7)
	v_mfma_f32_16x16x32_bf16 v[62:65], v[130:133], v[166:169], 0
	v_mfma_f32_16x16x32_bf16 v[62:65], v[134:137], v[170:173], v[62:65]
	s_waitcnt lgkmcnt(5)
	v_mfma_f32_16x16x32_bf16 v[58:61], v[138:141], v[166:169], 0
	v_mfma_f32_16x16x32_bf16 v[58:61], v[142:145], v[170:173], v[58:61]
	s_waitcnt lgkmcnt(3)
	v_mfma_f32_16x16x32_bf16 v[42:45], v[138:141], v[186:189], 0
	v_mfma_f32_16x16x32_bf16 v[42:45], v[142:145], v[190:193], v[42:45]
	s_waitcnt lgkmcnt(1)
	v_mfma_f32_16x16x32_bf16 v[46:49], v[130:133], v[186:189], 0
	v_mfma_f32_16x16x32_bf16 v[46:49], v[134:137], v[190:193], v[46:49]
	v_mfma_f32_16x16x32_bf16 v[30:33], v[130:133], v[194:197], 0
	v_mfma_f32_16x16x32_bf16 v[30:33], v[134:137], v[198:201], v[30:33]
	v_mfma_f32_16x16x32_bf16 v[26:29], v[138:141], v[194:197], 0
	v_mfma_f32_16x16x32_bf16 v[26:29], v[142:145], v[198:201], v[26:29]
	v_mfma_f32_16x16x32_bf16 v[10:13], v[138:141], v[202:205], 0
	v_mfma_f32_16x16x32_bf16 v[10:13], v[142:145], v[206:209], v[10:13]
	s_waitcnt lgkmcnt(0)
	v_mfma_f32_16x16x32_bf16 v[14:17], v[130:133], v[202:205], 0
	v_mfma_f32_16x16x32_bf16 v[14:17], v[134:137], v[206:209], v[14:17]
	s_setprio 0
	s_setprio 1
	v_mfma_f32_16x16x32_bf16 v[54:57], v[146:149], v[166:169], 0
	v_mfma_f32_16x16x32_bf16 v[54:57], v[150:153], v[170:173], v[54:57]
	v_mfma_f32_16x16x32_bf16 v[50:53], v[154:157], v[166:169], 0
	v_mfma_f32_16x16x32_bf16 v[50:53], v[158:161], v[170:173], v[50:53]
	v_mfma_f32_16x16x32_bf16 v[34:37], v[154:157], v[186:189], 0
	v_mfma_f32_16x16x32_bf16 v[34:37], v[158:161], v[190:193], v[34:37]
	v_mfma_f32_16x16x32_bf16 v[38:41], v[146:149], v[186:189], 0
	v_mfma_f32_16x16x32_bf16 v[38:41], v[150:153], v[190:193], v[38:41]
	v_mfma_f32_16x16x32_bf16 v[22:25], v[146:149], v[194:197], 0
	v_mfma_f32_16x16x32_bf16 v[22:25], v[150:153], v[198:201], v[22:25]
	v_mfma_f32_16x16x32_bf16 v[18:21], v[154:157], v[194:197], 0
	v_mfma_f32_16x16x32_bf16 v[18:21], v[158:161], v[198:201], v[18:21]
	v_mfma_f32_16x16x32_bf16 v[2:5], v[154:157], v[202:205], 0
	v_mfma_f32_16x16x32_bf16 v[2:5], v[158:161], v[206:209], v[2:5]
	s_setprio 2
	s_barrier
	v_mfma_f32_16x16x32_bf16 v[6:9], v[146:149], v[202:205], 0
	v_mfma_f32_16x16x32_bf16 v[6:9], v[150:153], v[206:209], v[6:9]
	s_setprio 0
	ds_read_b128 v[130:133], v184
	ds_read_b128 v[134:137], v184 offset:1024
	ds_read_b128 v[138:141], v184 offset:2048
	ds_read_b128 v[142:145], v184 offset:3072
	ds_read_b128 v[146:149], v185
	ds_read_b128 v[150:153], v185 offset:1024
	ds_read_b128 v[154:157], v185 offset:2048
	ds_read_b128 v[158:161], v185 offset:3072
	ds_read_b128 v[166:169], v183 offset:32768
	ds_read_b128 v[170:173], v183 offset:33792
	ds_read_b128 v[186:189], v183 offset:34816
	ds_read_b128 v[190:193], v183 offset:35840
	ds_read_b128 v[194:197], v183 offset:36864
	ds_read_b128 v[198:201], v183 offset:37888
	ds_read_b128 v[202:205], v183 offset:38912
	ds_read_b128 v[206:209], v183 offset:39936
	s_mov_b32 s79, m0
	s_mov_b32 m0, s40
	s_nop 0
	global_load_lds_dwordx4 v1, s[28:29]
	s_mov_b32 m0, s79
	s_nop 0
	s_mov_b32 s79, m0
	s_mov_b32 m0, s47
	s_nop 0
	global_load_lds_dwordx4 v177, s[28:29]
	s_mov_b32 m0, s79
	s_add_u32 s28, s28, 0x80000
	s_addc_u32 s29, s29, 0
	s_mov_b32 s79, m0
	s_mov_b32 m0, s48
	s_nop 0
	global_load_lds_dwordx4 v1, s[28:29]
	s_mov_b32 m0, s79
	s_nop 0
	s_mov_b32 s79, m0
	s_mov_b32 m0, s49
	s_nop 0
	global_load_lds_dwordx4 v177, s[28:29]
	s_mov_b32 m0, s79
	s_waitcnt vmcnt(8)
	s_waitcnt lgkmcnt(0)
	s_barrier
	s_setprio 1
	s_waitcnt lgkmcnt(7)
	v_mfma_f32_16x16x32_bf16 v[126:129], v[130:133], v[166:169], v[126:129]
	v_mfma_f32_16x16x32_bf16 v[126:129], v[134:137], v[170:173], v[126:129]
	s_waitcnt lgkmcnt(5)
	v_mfma_f32_16x16x32_bf16 v[122:125], v[138:141], v[166:169], v[122:125]
	v_mfma_f32_16x16x32_bf16 v[122:125], v[142:145], v[170:173], v[122:125]
	s_waitcnt lgkmcnt(3)
	v_mfma_f32_16x16x32_bf16 v[114:117], v[138:141], v[186:189], v[114:117]
	v_mfma_f32_16x16x32_bf16 v[114:117], v[142:145], v[190:193], v[114:117]
	s_waitcnt lgkmcnt(1)
	v_mfma_f32_16x16x32_bf16 v[118:121], v[130:133], v[186:189], v[118:121]
	v_mfma_f32_16x16x32_bf16 v[118:121], v[134:137], v[190:193], v[118:121]
	v_mfma_f32_16x16x32_bf16 v[94:97], v[130:133], v[194:197], v[94:97]
	v_mfma_f32_16x16x32_bf16 v[94:97], v[134:137], v[198:201], v[94:97]
	v_mfma_f32_16x16x32_bf16 v[90:93], v[138:141], v[194:197], v[90:93]
	v_mfma_f32_16x16x32_bf16 v[90:93], v[142:145], v[198:201], v[90:93]
	v_mfma_f32_16x16x32_bf16 v[78:81], v[138:141], v[202:205], v[78:81]
	v_mfma_f32_16x16x32_bf16 v[78:81], v[142:145], v[206:209], v[78:81]
	s_waitcnt lgkmcnt(0)
	v_mfma_f32_16x16x32_bf16 v[86:89], v[130:133], v[202:205], v[86:89]
	v_mfma_f32_16x16x32_bf16 v[86:89], v[134:137], v[206:209], v[86:89]
	s_setprio 0
	s_setprio 1
	v_mfma_f32_16x16x32_bf16 v[110:113], v[146:149], v[166:169], v[110:113]
	v_mfma_f32_16x16x32_bf16 v[110:113], v[150:153], v[170:173], v[110:113]
	v_mfma_f32_16x16x32_bf16 v[106:109], v[154:157], v[166:169], v[106:109]
	v_mfma_f32_16x16x32_bf16 v[106:109], v[158:161], v[170:173], v[106:109]
	v_mfma_f32_16x16x32_bf16 v[98:101], v[154:157], v[186:189], v[98:101]
	v_mfma_f32_16x16x32_bf16 v[98:101], v[158:161], v[190:193], v[98:101]
	v_mfma_f32_16x16x32_bf16 v[102:105], v[146:149], v[186:189], v[102:105]
	v_mfma_f32_16x16x32_bf16 v[102:105], v[150:153], v[190:193], v[102:105]
	v_mfma_f32_16x16x32_bf16 v[82:85], v[146:149], v[194:197], v[82:85]
	v_mfma_f32_16x16x32_bf16 v[82:85], v[150:153], v[198:201], v[82:85]
	v_mfma_f32_16x16x32_bf16 v[74:77], v[154:157], v[194:197], v[74:77]
	v_mfma_f32_16x16x32_bf16 v[74:77], v[158:161], v[198:201], v[74:77]
	v_mfma_f32_16x16x32_bf16 v[66:69], v[154:157], v[202:205], v[66:69]
	v_mfma_f32_16x16x32_bf16 v[66:69], v[158:161], v[206:209], v[66:69]
	s_setprio 2
	s_barrier
	v_mfma_f32_16x16x32_bf16 v[70:73], v[146:149], v[202:205], v[70:73]
	v_mfma_f32_16x16x32_bf16 v[70:73], v[150:153], v[206:209], v[70:73]
	s_setprio 0
	ds_read_b128 v[166:169], v183 offset:49152
	ds_read_b128 v[170:173], v183 offset:50176
	ds_read_b128 v[186:189], v183 offset:51200
	ds_read_b128 v[190:193], v183 offset:52224
	ds_read_b128 v[194:197], v183 offset:53248
	ds_read_b128 v[198:201], v183 offset:54272
	ds_read_b128 v[202:205], v183 offset:55296
	ds_read_b128 v[206:209], v183 offset:56320
	s_add_u32 s28, s26, 0x80
	s_addc_u32 s29, s27, 0
	s_mov_b32 s79, m0
	s_mov_b32 m0, s56
	s_nop 0
	global_load_lds_dwordx4 v176, s[28:29]
	s_mov_b32 m0, s79
	s_add_u32 s26, s26, 0x80080
	s_mov_b32 s79, m0
	s_mov_b32 m0, s57
	s_nop 0
	global_load_lds_dwordx4 v178, s[28:29]
	s_mov_b32 m0, s79
	s_addc_u32 s27, s27, 0
	s_mov_b32 s28, m0
	s_mov_b32 m0, s58
	s_nop 0
	global_load_lds_dwordx4 v176, s[26:27]
	s_mov_b32 m0, s28
	s_nop 0
	s_mov_b32 s28, m0
	s_mov_b32 m0, s59
	s_nop 0
	global_load_lds_dwordx4 v178, s[26:27]
	s_mov_b32 m0, s28
	s_waitcnt vmcnt(4)
	s_waitcnt lgkmcnt(0)
	s_barrier
	s_setprio 1
	s_waitcnt lgkmcnt(7)
	v_mfma_f32_16x16x32_bf16 v[62:65], v[130:133], v[166:169], v[62:65]
	v_mfma_f32_16x16x32_bf16 v[62:65], v[134:137], v[170:173], v[62:65]
	s_waitcnt lgkmcnt(5)
	v_mfma_f32_16x16x32_bf16 v[58:61], v[138:141], v[166:169], v[58:61]
	v_mfma_f32_16x16x32_bf16 v[58:61], v[142:145], v[170:173], v[58:61]
	s_waitcnt lgkmcnt(3)
	v_mfma_f32_16x16x32_bf16 v[42:45], v[138:141], v[186:189], v[42:45]
	v_mfma_f32_16x16x32_bf16 v[42:45], v[142:145], v[190:193], v[42:45]
	s_waitcnt lgkmcnt(1)
	v_mfma_f32_16x16x32_bf16 v[46:49], v[130:133], v[186:189], v[46:49]
	v_mfma_f32_16x16x32_bf16 v[46:49], v[134:137], v[190:193], v[46:49]
	v_mfma_f32_16x16x32_bf16 v[30:33], v[130:133], v[194:197], v[30:33]
	v_mfma_f32_16x16x32_bf16 v[30:33], v[134:137], v[198:201], v[30:33]
	v_mfma_f32_16x16x32_bf16 v[26:29], v[138:141], v[194:197], v[26:29]
	v_mfma_f32_16x16x32_bf16 v[26:29], v[142:145], v[198:201], v[26:29]
	v_mfma_f32_16x16x32_bf16 v[10:13], v[138:141], v[202:205], v[10:13]
	v_mfma_f32_16x16x32_bf16 v[10:13], v[142:145], v[206:209], v[10:13]
	s_waitcnt lgkmcnt(0)
	v_mfma_f32_16x16x32_bf16 v[14:17], v[130:133], v[202:205], v[14:17]
	v_mfma_f32_16x16x32_bf16 v[14:17], v[134:137], v[206:209], v[14:17]
	s_setprio 0
	s_setprio 1
	v_mfma_f32_16x16x32_bf16 v[54:57], v[146:149], v[166:169], v[54:57]
	v_mfma_f32_16x16x32_bf16 v[54:57], v[150:153], v[170:173], v[54:57]
	v_mfma_f32_16x16x32_bf16 v[50:53], v[154:157], v[166:169], v[50:53]
	v_mfma_f32_16x16x32_bf16 v[50:53], v[158:161], v[170:173], v[50:53]
	v_mfma_f32_16x16x32_bf16 v[34:37], v[154:157], v[186:189], v[34:37]
	v_mfma_f32_16x16x32_bf16 v[34:37], v[158:161], v[190:193], v[34:37]
	v_mfma_f32_16x16x32_bf16 v[38:41], v[146:149], v[186:189], v[38:41]
	v_mfma_f32_16x16x32_bf16 v[38:41], v[150:153], v[190:193], v[38:41]
	v_mfma_f32_16x16x32_bf16 v[22:25], v[146:149], v[194:197], v[22:25]
	v_mfma_f32_16x16x32_bf16 v[22:25], v[150:153], v[198:201], v[22:25]
	v_mfma_f32_16x16x32_bf16 v[18:21], v[154:157], v[194:197], v[18:21]
	v_mfma_f32_16x16x32_bf16 v[18:21], v[158:161], v[198:201], v[18:21]
	v_mfma_f32_16x16x32_bf16 v[2:5], v[154:157], v[202:205], v[2:5]
	v_mfma_f32_16x16x32_bf16 v[2:5], v[158:161], v[206:209], v[2:5]
	s_setprio 2
	s_barrier
	v_mfma_f32_16x16x32_bf16 v[6:9], v[146:149], v[202:205], v[6:9]
	v_mfma_f32_16x16x32_bf16 v[6:9], v[150:153], v[206:209], v[6:9]
	s_setprio 0
	s_add_i32 s78, s78, 2
	s_add_u32 s74, s74, 0x100
	s_addc_u32 s75, s75, 0
	s_add_u32 s24, s24, 0x100
	s_addc_u32 s25, s25, 0
	s_add_u32 s76, s76, 0x100
	s_addc_u32 s77, s77, 0
	s_cmp_gt_u32 s78, 29
	.p2align 6
.LBB0_2410:
	ds_read_b128 v[130:133], v181
	ds_read_b128 v[134:137], v181 offset:1024
	ds_read_b128 v[138:141], v181 offset:2048
	ds_read_b128 v[142:145], v181 offset:3072
	ds_read_b128 v[146:149], v182
	ds_read_b128 v[150:153], v182 offset:1024
	ds_read_b128 v[154:157], v182 offset:2048
	ds_read_b128 v[158:161], v182 offset:3072
	s_cmp_eq_u32 s78, 28
	s_cselect_b32 s27, s15, s75
	s_cselect_b32 s26, s73, s74
	s_cselect_b32 s29, s17, s77
	s_cselect_b32 s28, s71, s76
	ds_read_b128 v[166:169], v183
	ds_read_b128 v[170:173], v183 offset:1024
	ds_read_b128 v[186:189], v183 offset:2048
	ds_read_b128 v[190:193], v183 offset:3072
	ds_read_b128 v[194:197], v183 offset:4096
	ds_read_b128 v[198:201], v183 offset:5120
	ds_read_b128 v[202:205], v183 offset:6144
	ds_read_b128 v[206:209], v183 offset:7168
	s_add_u32 s80, s24, 0xfff80000
	s_addc_u32 s81, s25, -1
	s_mov_b32 s79, m0
	s_mov_b32 m0, s64
	s_nop 0
	global_load_lds_dwordx4 v1, s[80:81]
	s_mov_b32 m0, s79
	s_nop 0
	s_mov_b32 s79, m0
	s_mov_b32 m0, s66
	s_nop 0
	global_load_lds_dwordx4 v177, s[80:81]
	s_mov_b32 m0, s79
	s_nop 0
	s_mov_b32 s79, m0
	s_mov_b32 m0, s65
	s_nop 0
	global_load_lds_dwordx4 v1, s[24:25]
	s_mov_b32 m0, s79
	s_nop 0
	s_mov_b32 s79, m0
	s_mov_b32 m0, s67
	s_nop 0
	global_load_lds_dwordx4 v177, s[24:25]
	s_mov_b32 m0, s79
	s_waitcnt vmcnt(8)
	s_waitcnt lgkmcnt(0)
	s_barrier
	s_setprio 1
	s_waitcnt lgkmcnt(7)
	v_mfma_f32_16x16x32_bf16 v[126:129], v[130:133], v[166:169], v[126:129]
	v_mfma_f32_16x16x32_bf16 v[126:129], v[134:137], v[170:173], v[126:129]
	s_waitcnt lgkmcnt(5)
	v_mfma_f32_16x16x32_bf16 v[122:125], v[138:141], v[166:169], v[122:125]
	v_mfma_f32_16x16x32_bf16 v[122:125], v[142:145], v[170:173], v[122:125]
	s_waitcnt lgkmcnt(3)
	v_mfma_f32_16x16x32_bf16 v[114:117], v[138:141], v[186:189], v[114:117]
	v_mfma_f32_16x16x32_bf16 v[114:117], v[142:145], v[190:193], v[114:117]
	s_waitcnt lgkmcnt(1)
	v_mfma_f32_16x16x32_bf16 v[118:121], v[130:133], v[186:189], v[118:121]
	v_mfma_f32_16x16x32_bf16 v[118:121], v[134:137], v[190:193], v[118:121]
	v_mfma_f32_16x16x32_bf16 v[94:97], v[130:133], v[194:197], v[94:97]
	v_mfma_f32_16x16x32_bf16 v[94:97], v[134:137], v[198:201], v[94:97]
	v_mfma_f32_16x16x32_bf16 v[90:93], v[138:141], v[194:197], v[90:93]
	v_mfma_f32_16x16x32_bf16 v[90:93], v[142:145], v[198:201], v[90:93]
	v_mfma_f32_16x16x32_bf16 v[78:81], v[138:141], v[202:205], v[78:81]
	v_mfma_f32_16x16x32_bf16 v[78:81], v[142:145], v[206:209], v[78:81]
	s_waitcnt lgkmcnt(0)
	v_mfma_f32_16x16x32_bf16 v[86:89], v[130:133], v[202:205], v[86:89]
	v_mfma_f32_16x16x32_bf16 v[86:89], v[134:137], v[206:209], v[86:89]
	s_setprio 0
	s_setprio 1
	v_mfma_f32_16x16x32_bf16 v[110:113], v[146:149], v[166:169], v[110:113]
	v_mfma_f32_16x16x32_bf16 v[110:113], v[150:153], v[170:173], v[110:113]
	v_mfma_f32_16x16x32_bf16 v[106:109], v[154:157], v[166:169], v[106:109]
	v_mfma_f32_16x16x32_bf16 v[106:109], v[158:161], v[170:173], v[106:109]
	v_mfma_f32_16x16x32_bf16 v[98:101], v[154:157], v[186:189], v[98:101]
	v_mfma_f32_16x16x32_bf16 v[98:101], v[158:161], v[190:193], v[98:101]
	v_mfma_f32_16x16x32_bf16 v[102:105], v[146:149], v[186:189], v[102:105]
	v_mfma_f32_16x16x32_bf16 v[102:105], v[150:153], v[190:193], v[102:105]
	v_mfma_f32_16x16x32_bf16 v[82:85], v[146:149], v[194:197], v[82:85]
	v_mfma_f32_16x16x32_bf16 v[82:85], v[150:153], v[198:201], v[82:85]
	v_mfma_f32_16x16x32_bf16 v[74:77], v[154:157], v[194:197], v[74:77]
	v_mfma_f32_16x16x32_bf16 v[74:77], v[158:161], v[198:201], v[74:77]
	v_mfma_f32_16x16x32_bf16 v[66:69], v[154:157], v[202:205], v[66:69]
	v_mfma_f32_16x16x32_bf16 v[66:69], v[158:161], v[206:209], v[66:69]
	s_setprio 2
	s_barrier
	v_mfma_f32_16x16x32_bf16 v[70:73], v[146:149], v[202:205], v[70:73]
	v_mfma_f32_16x16x32_bf16 v[70:73], v[150:153], v[206:209], v[70:73]
	s_setprio 0
	ds_read_b128 v[166:169], v183 offset:16384
	ds_read_b128 v[170:173], v183 offset:17408
	ds_read_b128 v[186:189], v183 offset:18432
	ds_read_b128 v[190:193], v183 offset:19456
	ds_read_b128 v[194:197], v183 offset:20480
	ds_read_b128 v[198:201], v183 offset:21504
	ds_read_b128 v[202:205], v183 offset:22528
	ds_read_b128 v[206:209], v183 offset:23552
	s_mov_b32 s79, m0
	s_mov_b32 m0, s41
	s_nop 0
	global_load_lds_dwordx4 v176, s[26:27]
	s_mov_b32 m0, s79
	s_add_u32 s80, s26, 0x80000
	s_mov_b32 s79, m0
	s_mov_b32 m0, s42
	s_nop 0
	global_load_lds_dwordx4 v178, s[26:27]
	s_mov_b32 m0, s79
	s_addc_u32 s81, s27, 0
	s_mov_b32 s79, m0
	s_mov_b32 m0, s43
	s_nop 0
	global_load_lds_dwordx4 v176, s[80:81]
	s_mov_b32 m0, s79
	s_nop 0
	s_mov_b32 s79, m0
	s_mov_b32 m0, s46
	s_nop 0
	global_load_lds_dwordx4 v178, s[80:81]
	s_mov_b32 m0, s79
	s_waitcnt vmcnt(4)
	s_waitcnt lgkmcnt(0)
	s_barrier
	s_setprio 1
	s_waitcnt lgkmcnt(7)
	v_mfma_f32_16x16x32_bf16 v[62:65], v[130:133], v[166:169], v[62:65]
	v_mfma_f32_16x16x32_bf16 v[62:65], v[134:137], v[170:173], v[62:65]
	s_waitcnt lgkmcnt(5)
	v_mfma_f32_16x16x32_bf16 v[58:61], v[138:141], v[166:169], v[58:61]
	v_mfma_f32_16x16x32_bf16 v[58:61], v[142:145], v[170:173], v[58:61]
	s_waitcnt lgkmcnt(3)
	v_mfma_f32_16x16x32_bf16 v[42:45], v[138:141], v[186:189], v[42:45]
	v_mfma_f32_16x16x32_bf16 v[42:45], v[142:145], v[190:193], v[42:45]
	s_waitcnt lgkmcnt(1)
	v_mfma_f32_16x16x32_bf16 v[46:49], v[130:133], v[186:189], v[46:49]
	v_mfma_f32_16x16x32_bf16 v[46:49], v[134:137], v[190:193], v[46:49]
	v_mfma_f32_16x16x32_bf16 v[30:33], v[130:133], v[194:197], v[30:33]
	v_mfma_f32_16x16x32_bf16 v[30:33], v[134:137], v[198:201], v[30:33]
	v_mfma_f32_16x16x32_bf16 v[26:29], v[138:141], v[194:197], v[26:29]
	v_mfma_f32_16x16x32_bf16 v[26:29], v[142:145], v[198:201], v[26:29]
	v_mfma_f32_16x16x32_bf16 v[10:13], v[138:141], v[202:205], v[10:13]
	v_mfma_f32_16x16x32_bf16 v[10:13], v[142:145], v[206:209], v[10:13]
	s_waitcnt lgkmcnt(0)
	v_mfma_f32_16x16x32_bf16 v[14:17], v[130:133], v[202:205], v[14:17]
	v_mfma_f32_16x16x32_bf16 v[14:17], v[134:137], v[206:209], v[14:17]
	s_setprio 0
	s_setprio 1
	v_mfma_f32_16x16x32_bf16 v[54:57], v[146:149], v[166:169], v[54:57]
	v_mfma_f32_16x16x32_bf16 v[54:57], v[150:153], v[170:173], v[54:57]
	v_mfma_f32_16x16x32_bf16 v[50:53], v[154:157], v[166:169], v[50:53]
	v_mfma_f32_16x16x32_bf16 v[50:53], v[158:161], v[170:173], v[50:53]
	v_mfma_f32_16x16x32_bf16 v[34:37], v[154:157], v[186:189], v[34:37]
	v_mfma_f32_16x16x32_bf16 v[34:37], v[158:161], v[190:193], v[34:37]
	v_mfma_f32_16x16x32_bf16 v[38:41], v[146:149], v[186:189], v[38:41]
	v_mfma_f32_16x16x32_bf16 v[38:41], v[150:153], v[190:193], v[38:41]
	v_mfma_f32_16x16x32_bf16 v[22:25], v[146:149], v[194:197], v[22:25]
	v_mfma_f32_16x16x32_bf16 v[22:25], v[150:153], v[198:201], v[22:25]
	v_mfma_f32_16x16x32_bf16 v[18:21], v[154:157], v[194:197], v[18:21]
	v_mfma_f32_16x16x32_bf16 v[18:21], v[158:161], v[198:201], v[18:21]
	v_mfma_f32_16x16x32_bf16 v[2:5], v[154:157], v[202:205], v[2:5]
	v_mfma_f32_16x16x32_bf16 v[2:5], v[158:161], v[206:209], v[2:5]
	s_setprio 2
	s_barrier
	v_mfma_f32_16x16x32_bf16 v[6:9], v[146:149], v[202:205], v[6:9]
	v_mfma_f32_16x16x32_bf16 v[6:9], v[150:153], v[206:209], v[6:9]
	s_setprio 0
	ds_read_b128 v[130:133], v184
	ds_read_b128 v[134:137], v184 offset:1024
	ds_read_b128 v[138:141], v184 offset:2048
	ds_read_b128 v[142:145], v184 offset:3072
	ds_read_b128 v[146:149], v185
	ds_read_b128 v[150:153], v185 offset:1024
	ds_read_b128 v[154:157], v185 offset:2048
	ds_read_b128 v[158:161], v185 offset:3072
	ds_read_b128 v[166:169], v183 offset:32768
	ds_read_b128 v[170:173], v183 offset:33792
	ds_read_b128 v[186:189], v183 offset:34816
	ds_read_b128 v[190:193], v183 offset:35840
	ds_read_b128 v[194:197], v183 offset:36864
	ds_read_b128 v[198:201], v183 offset:37888
	ds_read_b128 v[202:205], v183 offset:38912
	ds_read_b128 v[206:209], v183 offset:39936
	s_mov_b32 s79, m0
	s_mov_b32 m0, s40
	s_nop 0
	global_load_lds_dwordx4 v1, s[28:29]
	s_mov_b32 m0, s79
	s_nop 0
	s_mov_b32 s79, m0
	s_mov_b32 m0, s47
	s_nop 0
	global_load_lds_dwordx4 v177, s[28:29]
	s_mov_b32 m0, s79
	s_add_u32 s28, s28, 0x80000
	s_addc_u32 s29, s29, 0
	s_mov_b32 s79, m0
	s_mov_b32 m0, s48
	s_nop 0
	global_load_lds_dwordx4 v1, s[28:29]
	s_mov_b32 m0, s79
	s_nop 0
	s_mov_b32 s79, m0
	s_mov_b32 m0, s49
	s_nop 0
	global_load_lds_dwordx4 v177, s[28:29]
	s_mov_b32 m0, s79
	s_waitcnt vmcnt(8)
	s_waitcnt lgkmcnt(0)
	s_barrier
	s_setprio 1
	s_waitcnt lgkmcnt(7)
	v_mfma_f32_16x16x32_bf16 v[126:129], v[130:133], v[166:169], v[126:129]
	v_mfma_f32_16x16x32_bf16 v[126:129], v[134:137], v[170:173], v[126:129]
	s_waitcnt lgkmcnt(5)
	v_mfma_f32_16x16x32_bf16 v[122:125], v[138:141], v[166:169], v[122:125]
	v_mfma_f32_16x16x32_bf16 v[122:125], v[142:145], v[170:173], v[122:125]
	s_waitcnt lgkmcnt(3)
	v_mfma_f32_16x16x32_bf16 v[114:117], v[138:141], v[186:189], v[114:117]
	v_mfma_f32_16x16x32_bf16 v[114:117], v[142:145], v[190:193], v[114:117]
	s_waitcnt lgkmcnt(1)
	v_mfma_f32_16x16x32_bf16 v[118:121], v[130:133], v[186:189], v[118:121]
	v_mfma_f32_16x16x32_bf16 v[118:121], v[134:137], v[190:193], v[118:121]
	v_mfma_f32_16x16x32_bf16 v[94:97], v[130:133], v[194:197], v[94:97]
	v_mfma_f32_16x16x32_bf16 v[94:97], v[134:137], v[198:201], v[94:97]
	v_mfma_f32_16x16x32_bf16 v[90:93], v[138:141], v[194:197], v[90:93]
	v_mfma_f32_16x16x32_bf16 v[90:93], v[142:145], v[198:201], v[90:93]
	v_mfma_f32_16x16x32_bf16 v[78:81], v[138:141], v[202:205], v[78:81]
	v_mfma_f32_16x16x32_bf16 v[78:81], v[142:145], v[206:209], v[78:81]
	s_waitcnt lgkmcnt(0)
	v_mfma_f32_16x16x32_bf16 v[86:89], v[130:133], v[202:205], v[86:89]
	v_mfma_f32_16x16x32_bf16 v[86:89], v[134:137], v[206:209], v[86:89]
	s_setprio 0
	s_setprio 1
	v_mfma_f32_16x16x32_bf16 v[110:113], v[146:149], v[166:169], v[110:113]
	v_mfma_f32_16x16x32_bf16 v[110:113], v[150:153], v[170:173], v[110:113]
	v_mfma_f32_16x16x32_bf16 v[106:109], v[154:157], v[166:169], v[106:109]
	v_mfma_f32_16x16x32_bf16 v[106:109], v[158:161], v[170:173], v[106:109]
	v_mfma_f32_16x16x32_bf16 v[98:101], v[154:157], v[186:189], v[98:101]
	v_mfma_f32_16x16x32_bf16 v[98:101], v[158:161], v[190:193], v[98:101]
	v_mfma_f32_16x16x32_bf16 v[102:105], v[146:149], v[186:189], v[102:105]
	v_mfma_f32_16x16x32_bf16 v[102:105], v[150:153], v[190:193], v[102:105]
	v_mfma_f32_16x16x32_bf16 v[82:85], v[146:149], v[194:197], v[82:85]
	v_mfma_f32_16x16x32_bf16 v[82:85], v[150:153], v[198:201], v[82:85]
	v_mfma_f32_16x16x32_bf16 v[74:77], v[154:157], v[194:197], v[74:77]
	v_mfma_f32_16x16x32_bf16 v[74:77], v[158:161], v[198:201], v[74:77]
	v_mfma_f32_16x16x32_bf16 v[66:69], v[154:157], v[202:205], v[66:69]
	v_mfma_f32_16x16x32_bf16 v[66:69], v[158:161], v[206:209], v[66:69]
	s_setprio 2
	s_barrier
	v_mfma_f32_16x16x32_bf16 v[70:73], v[146:149], v[202:205], v[70:73]
	v_mfma_f32_16x16x32_bf16 v[70:73], v[150:153], v[206:209], v[70:73]
	s_setprio 0
	ds_read_b128 v[166:169], v183 offset:49152
	ds_read_b128 v[170:173], v183 offset:50176
	ds_read_b128 v[186:189], v183 offset:51200
	ds_read_b128 v[190:193], v183 offset:52224
	ds_read_b128 v[194:197], v183 offset:53248
	ds_read_b128 v[198:201], v183 offset:54272
	ds_read_b128 v[202:205], v183 offset:55296
	ds_read_b128 v[206:209], v183 offset:56320
	s_add_u32 s28, s26, 0x80
	s_addc_u32 s29, s27, 0
	s_mov_b32 s79, m0
	s_mov_b32 m0, s56
	s_nop 0
	global_load_lds_dwordx4 v176, s[28:29]
	s_mov_b32 m0, s79
	s_add_u32 s26, s26, 0x80080
	s_mov_b32 s79, m0
	s_mov_b32 m0, s57
	s_nop 0
	global_load_lds_dwordx4 v178, s[28:29]
	s_mov_b32 m0, s79
	s_addc_u32 s27, s27, 0
	s_mov_b32 s28, m0
	s_mov_b32 m0, s58
	s_nop 0
	global_load_lds_dwordx4 v176, s[26:27]
	s_mov_b32 m0, s28
	s_nop 0
	s_mov_b32 s28, m0
	s_mov_b32 m0, s59
	s_nop 0
	global_load_lds_dwordx4 v178, s[26:27]
	s_mov_b32 m0, s28
	s_waitcnt vmcnt(4)
	s_waitcnt lgkmcnt(0)
	s_barrier
	s_setprio 1
	s_waitcnt lgkmcnt(7)
	v_mfma_f32_16x16x32_bf16 v[62:65], v[130:133], v[166:169], v[62:65]
	v_mfma_f32_16x16x32_bf16 v[62:65], v[134:137], v[170:173], v[62:65]
	s_waitcnt lgkmcnt(5)
	v_mfma_f32_16x16x32_bf16 v[58:61], v[138:141], v[166:169], v[58:61]
	v_mfma_f32_16x16x32_bf16 v[58:61], v[142:145], v[170:173], v[58:61]
	s_waitcnt lgkmcnt(3)
	v_mfma_f32_16x16x32_bf16 v[42:45], v[138:141], v[186:189], v[42:45]
	v_mfma_f32_16x16x32_bf16 v[42:45], v[142:145], v[190:193], v[42:45]
	s_waitcnt lgkmcnt(1)
	v_mfma_f32_16x16x32_bf16 v[46:49], v[130:133], v[186:189], v[46:49]
	v_mfma_f32_16x16x32_bf16 v[46:49], v[134:137], v[190:193], v[46:49]
	v_mfma_f32_16x16x32_bf16 v[30:33], v[130:133], v[194:197], v[30:33]
	v_mfma_f32_16x16x32_bf16 v[30:33], v[134:137], v[198:201], v[30:33]
	v_mfma_f32_16x16x32_bf16 v[26:29], v[138:141], v[194:197], v[26:29]
	v_mfma_f32_16x16x32_bf16 v[26:29], v[142:145], v[198:201], v[26:29]
	v_mfma_f32_16x16x32_bf16 v[10:13], v[138:141], v[202:205], v[10:13]
	v_mfma_f32_16x16x32_bf16 v[10:13], v[142:145], v[206:209], v[10:13]
	s_waitcnt lgkmcnt(0)
	v_mfma_f32_16x16x32_bf16 v[14:17], v[130:133], v[202:205], v[14:17]
	v_mfma_f32_16x16x32_bf16 v[14:17], v[134:137], v[206:209], v[14:17]
	s_setprio 0
	s_setprio 1
	v_mfma_f32_16x16x32_bf16 v[54:57], v[146:149], v[166:169], v[54:57]
	v_mfma_f32_16x16x32_bf16 v[54:57], v[150:153], v[170:173], v[54:57]
	v_mfma_f32_16x16x32_bf16 v[50:53], v[154:157], v[166:169], v[50:53]
	v_mfma_f32_16x16x32_bf16 v[50:53], v[158:161], v[170:173], v[50:53]
	v_mfma_f32_16x16x32_bf16 v[34:37], v[154:157], v[186:189], v[34:37]
	v_mfma_f32_16x16x32_bf16 v[34:37], v[158:161], v[190:193], v[34:37]
	v_mfma_f32_16x16x32_bf16 v[38:41], v[146:149], v[186:189], v[38:41]
	v_mfma_f32_16x16x32_bf16 v[38:41], v[150:153], v[190:193], v[38:41]
	v_mfma_f32_16x16x32_bf16 v[22:25], v[146:149], v[194:197], v[22:25]
	v_mfma_f32_16x16x32_bf16 v[22:25], v[150:153], v[198:201], v[22:25]
	v_mfma_f32_16x16x32_bf16 v[18:21], v[154:157], v[194:197], v[18:21]
	v_mfma_f32_16x16x32_bf16 v[18:21], v[158:161], v[198:201], v[18:21]
	v_mfma_f32_16x16x32_bf16 v[2:5], v[154:157], v[202:205], v[2:5]
	v_mfma_f32_16x16x32_bf16 v[2:5], v[158:161], v[206:209], v[2:5]
	s_setprio 2
	s_barrier
	v_mfma_f32_16x16x32_bf16 v[6:9], v[146:149], v[202:205], v[6:9]
	v_mfma_f32_16x16x32_bf16 v[6:9], v[150:153], v[206:209], v[6:9]
	s_setprio 0
	s_add_i32 s78, s78, 2
	s_add_u32 s74, s74, 0x100
	s_addc_u32 s75, s75, 0
	s_add_u32 s24, s24, 0x100
	s_addc_u32 s25, s25, 0
	s_add_u32 s76, s76, 0x100
	s_addc_u32 s77, s77, 0
	s_cmp_gt_u32 s78, 29
	s_cbranch_scc0 .LBB0_2410
	s_and_b64 vcc, exec, s[8:9]
	s_cbranch_vccz .LBB0_2413
	s_barrier

.LBB0_2593:
	s_ashr_i32 s11, s10, 31
	s_lshl_b64 s[12:13], s[10:11], 20
	s_add_u32 s12, s26, s12
	s_addc_u32 s13, s27, s13
	s_and_b64 s[14:15], s[2:3], exec
	s_cselect_b32 s11, s13, s21
	s_cselect_b32 s62, s12, s20
	s_ashr_i32 s9, s8, 31
	s_lshl_b64 s[14:15], s[8:9], 20
	s_add_u32 s14, s28, s14
	s_addc_u32 s15, s29, s15
	s_and_b64 s[22:23], s[2:3], exec
	s_cselect_b32 s9, s15, s19
	s_cselect_b32 s63, s14, s18
	s_add_u32 s64, s18, 0x100
	s_addc_u32 s65, s19, 0
	s_add_u32 s18, s20, 0x80080
	s_addc_u32 s19, s21, 0
	s_add_u32 s66, s20, 0x100
	s_addc_u32 s67, s21, 0
	s_mov_b32 s70, -2
	ds_read_b128 v[148:151], v143
	ds_read_b128 v[152:155], v143 offset:1024
	ds_read_b128 v[156:159], v143 offset:2048
	ds_read_b128 v[160:163], v143 offset:3072
	ds_read_b128 v[164:167], v144
	ds_read_b128 v[168:171], v144 offset:1024
	ds_read_b128 v[172:175], v144 offset:2048
	ds_read_b128 v[176:179], v144 offset:3072
	s_cmp_eq_u32 s70, 28
	s_cselect_b32 s21, s9, s65
	s_cselect_b32 s20, s63, s64
	s_cselect_b32 s23, s11, s67
	s_cselect_b32 s22, s62, s66
	ds_read_b128 v[180:183], v145
	ds_read_b128 v[184:187], v145 offset:1024
	ds_read_b128 v[188:191], v145 offset:2048
	ds_read_b128 v[192:195], v145 offset:3072
	ds_read_b128 v[196:199], v145 offset:4096
	ds_read_b128 v[200:203], v145 offset:5120
	ds_read_b128 v[204:207], v145 offset:6144
	ds_read_b128 v[208:211], v145 offset:7168
	s_add_u32 s74, s18, 0xfff80000
	s_addc_u32 s75, s19, -1
	s_mov_b32 s71, m0
	s_mov_b32 m0, s48
	s_nop 0
	global_load_lds_dwordx4 v138, s[74:75]
	s_mov_b32 m0, s71
	s_nop 0
	s_mov_b32 s71, m0
	s_mov_b32 m0, s57
	s_nop 0
	global_load_lds_dwordx4 v140, s[74:75]
	s_mov_b32 m0, s71
	s_nop 0
	s_mov_b32 s71, m0
	s_mov_b32 m0, s49
	s_nop 0
	global_load_lds_dwordx4 v138, s[18:19]
	s_mov_b32 m0, s71
	s_nop 0
	s_mov_b32 s71, m0
	s_mov_b32 m0, s58
	s_nop 0
	global_load_lds_dwordx4 v140, s[18:19]
	s_mov_b32 m0, s71
	s_waitcnt vmcnt(8)
	s_waitcnt lgkmcnt(0)
	s_barrier
	s_setprio 1
	s_waitcnt lgkmcnt(7)
	v_mfma_f32_16x16x32_bf16 v[126:129], v[148:151], v[180:183], 0
	v_mfma_f32_16x16x32_bf16 v[126:129], v[152:155], v[184:187], v[126:129]
	s_waitcnt lgkmcnt(5)
	v_mfma_f32_16x16x32_bf16 v[122:125], v[156:159], v[180:183], 0
	v_mfma_f32_16x16x32_bf16 v[122:125], v[160:163], v[184:187], v[122:125]
	s_waitcnt lgkmcnt(3)
	v_mfma_f32_16x16x32_bf16 v[106:109], v[156:159], v[188:191], 0
	v_mfma_f32_16x16x32_bf16 v[106:109], v[160:163], v[192:195], v[106:109]
	s_waitcnt lgkmcnt(1)
	v_mfma_f32_16x16x32_bf16 v[110:113], v[148:151], v[188:191], 0
	v_mfma_f32_16x16x32_bf16 v[110:113], v[152:155], v[192:195], v[110:113]
	v_mfma_f32_16x16x32_bf16 v[94:97], v[148:151], v[196:199], 0
	v_mfma_f32_16x16x32_bf16 v[94:97], v[152:155], v[200:203], v[94:97]
	v_mfma_f32_16x16x32_bf16 v[90:93], v[156:159], v[196:199], 0
	v_mfma_f32_16x16x32_bf16 v[90:93], v[160:163], v[200:203], v[90:93]
	v_mfma_f32_16x16x32_bf16 v[74:77], v[156:159], v[204:207], 0
	v_mfma_f32_16x16x32_bf16 v[74:77], v[160:163], v[208:211], v[74:77]
	s_waitcnt lgkmcnt(0)
	v_mfma_f32_16x16x32_bf16 v[78:81], v[148:151], v[204:207], 0
	v_mfma_f32_16x16x32_bf16 v[78:81], v[152:155], v[208:211], v[78:81]
	s_setprio 0
	s_setprio 1
	v_mfma_f32_16x16x32_bf16 v[118:121], v[164:167], v[180:183], 0
	v_mfma_f32_16x16x32_bf16 v[118:121], v[168:171], v[184:187], v[118:121]
	v_mfma_f32_16x16x32_bf16 v[114:117], v[172:175], v[180:183], 0
	v_mfma_f32_16x16x32_bf16 v[114:117], v[176:179], v[184:187], v[114:117]
	v_mfma_f32_16x16x32_bf16 v[98:101], v[172:175], v[188:191], 0
	v_mfma_f32_16x16x32_bf16 v[98:101], v[176:179], v[192:195], v[98:101]
	v_mfma_f32_16x16x32_bf16 v[102:105], v[164:167], v[188:191], 0
	v_mfma_f32_16x16x32_bf16 v[102:105], v[168:171], v[192:195], v[102:105]
	v_mfma_f32_16x16x32_bf16 v[86:89], v[164:167], v[196:199], 0
	v_mfma_f32_16x16x32_bf16 v[86:89], v[168:171], v[200:203], v[86:89]
	v_mfma_f32_16x16x32_bf16 v[82:85], v[172:175], v[196:199], 0
	v_mfma_f32_16x16x32_bf16 v[82:85], v[176:179], v[200:203], v[82:85]
	v_mfma_f32_16x16x32_bf16 v[66:69], v[172:175], v[204:207], 0
	v_mfma_f32_16x16x32_bf16 v[66:69], v[176:179], v[208:211], v[66:69]
	s_setprio 2
	s_barrier
	v_mfma_f32_16x16x32_bf16 v[70:73], v[164:167], v[204:207], 0
	v_mfma_f32_16x16x32_bf16 v[70:73], v[168:171], v[208:211], v[70:73]
	s_setprio 0
	ds_read_b128 v[180:183], v145 offset:16384
	ds_read_b128 v[184:187], v145 offset:17408
	ds_read_b128 v[188:191], v145 offset:18432
	ds_read_b128 v[192:195], v145 offset:19456
	ds_read_b128 v[196:199], v145 offset:20480
	ds_read_b128 v[200:203], v145 offset:21504
	ds_read_b128 v[204:207], v145 offset:22528
	ds_read_b128 v[208:211], v145 offset:23552
	s_mov_b32 s71, m0
	s_mov_b32 m0, s35
	s_nop 0
	global_load_lds_dwordx4 v139, s[20:21]
	s_mov_b32 m0, s71
	s_add_u32 s74, s20, 0x80000
	s_mov_b32 s71, m0
	s_mov_b32 m0, s36
	s_nop 0
	global_load_lds_dwordx4 v141, s[20:21]
	s_mov_b32 m0, s71
	s_addc_u32 s75, s21, 0
	s_mov_b32 s71, m0
	s_mov_b32 m0, s37
	s_nop 0
	global_load_lds_dwordx4 v139, s[74:75]
	s_mov_b32 m0, s71
	s_nop 0
	s_mov_b32 s71, m0
	s_mov_b32 m0, s40
	s_nop 0
	global_load_lds_dwordx4 v141, s[74:75]
	s_mov_b32 m0, s71
	s_waitcnt vmcnt(4)
	s_waitcnt lgkmcnt(0)
	s_barrier
	s_setprio 1
	s_waitcnt lgkmcnt(7)
	v_mfma_f32_16x16x32_bf16 v[62:65], v[148:151], v[180:183], 0
	v_mfma_f32_16x16x32_bf16 v[62:65], v[152:155], v[184:187], v[62:65]
	s_waitcnt lgkmcnt(5)
	v_mfma_f32_16x16x32_bf16 v[58:61], v[156:159], v[180:183], 0
	v_mfma_f32_16x16x32_bf16 v[58:61], v[160:163], v[184:187], v[58:61]
	s_waitcnt lgkmcnt(3)
	v_mfma_f32_16x16x32_bf16 v[42:45], v[156:159], v[188:191], 0
	v_mfma_f32_16x16x32_bf16 v[42:45], v[160:163], v[192:195], v[42:45]
	s_waitcnt lgkmcnt(1)
	v_mfma_f32_16x16x32_bf16 v[46:49], v[148:151], v[188:191], 0
	v_mfma_f32_16x16x32_bf16 v[46:49], v[152:155], v[192:195], v[46:49]
	v_mfma_f32_16x16x32_bf16 v[30:33], v[148:151], v[196:199], 0
	v_mfma_f32_16x16x32_bf16 v[30:33], v[152:155], v[200:203], v[30:33]
	v_mfma_f32_16x16x32_bf16 v[26:29], v[156:159], v[196:199], 0
	v_mfma_f32_16x16x32_bf16 v[26:29], v[160:163], v[200:203], v[26:29]
	v_mfma_f32_16x16x32_bf16 v[10:13], v[156:159], v[204:207], 0
	v_mfma_f32_16x16x32_bf16 v[10:13], v[160:163], v[208:211], v[10:13]
	s_waitcnt lgkmcnt(0)
	v_mfma_f32_16x16x32_bf16 v[14:17], v[148:151], v[204:207], 0
	v_mfma_f32_16x16x32_bf16 v[14:17], v[152:155], v[208:211], v[14:17]
	s_setprio 0
	s_setprio 1
	v_mfma_f32_16x16x32_bf16 v[54:57], v[164:167], v[180:183], 0
	v_mfma_f32_16x16x32_bf16 v[54:57], v[168:171], v[184:187], v[54:57]
	v_mfma_f32_16x16x32_bf16 v[50:53], v[172:175], v[180:183], 0
	v_mfma_f32_16x16x32_bf16 v[50:53], v[176:179], v[184:187], v[50:53]
	v_mfma_f32_16x16x32_bf16 v[34:37], v[172:175], v[188:191], 0
	v_mfma_f32_16x16x32_bf16 v[34:37], v[176:179], v[192:195], v[34:37]
	v_mfma_f32_16x16x32_bf16 v[38:41], v[164:167], v[188:191], 0
	v_mfma_f32_16x16x32_bf16 v[38:41], v[168:171], v[192:195], v[38:41]
	v_mfma_f32_16x16x32_bf16 v[22:25], v[164:167], v[196:199], 0
	v_mfma_f32_16x16x32_bf16 v[22:25], v[168:171], v[200:203], v[22:25]
	v_mfma_f32_16x16x32_bf16 v[18:21], v[172:175], v[196:199], 0
	v_mfma_f32_16x16x32_bf16 v[18:21], v[176:179], v[200:203], v[18:21]
	v_mfma_f32_16x16x32_bf16 v[2:5], v[172:175], v[204:207], 0
	v_mfma_f32_16x16x32_bf16 v[2:5], v[176:179], v[208:211], v[2:5]
	s_setprio 2
	s_barrier
	v_mfma_f32_16x16x32_bf16 v[6:9], v[164:167], v[204:207], 0
	v_mfma_f32_16x16x32_bf16 v[6:9], v[168:171], v[208:211], v[6:9]
	s_setprio 0
	ds_read_b128 v[148:151], v146
	ds_read_b128 v[152:155], v146 offset:1024
	ds_read_b128 v[156:159], v146 offset:2048
	ds_read_b128 v[160:163], v146 offset:3072
	ds_read_b128 v[164:167], v147
	ds_read_b128 v[168:171], v147 offset:1024
	ds_read_b128 v[172:175], v147 offset:2048
	ds_read_b128 v[176:179], v147 offset:3072
	ds_read_b128 v[180:183], v145 offset:32768
	ds_read_b128 v[184:187], v145 offset:33792
	ds_read_b128 v[188:191], v145 offset:34816
	ds_read_b128 v[192:195], v145 offset:35840
	ds_read_b128 v[196:199], v145 offset:36864
	ds_read_b128 v[200:203], v145 offset:37888
	ds_read_b128 v[204:207], v145 offset:38912
	ds_read_b128 v[208:211], v145 offset:39936
	s_mov_b32 s71, m0
	s_mov_b32 m0, s31
	s_nop 0
	global_load_lds_dwordx4 v138, s[22:23]
	s_mov_b32 m0, s71
	s_nop 0
	s_mov_b32 s71, m0
	s_mov_b32 m0, s41
	s_nop 0
	global_load_lds_dwordx4 v140, s[22:23]
	s_mov_b32 m0, s71
	s_add_u32 s22, s22, 0x80000
	s_addc_u32 s23, s23, 0
	s_mov_b32 s71, m0
	s_mov_b32 m0, s42
	s_nop 0
	global_load_lds_dwordx4 v138, s[22:23]
	s_mov_b32 m0, s71
	s_nop 0
	s_mov_b32 s71, m0
	s_mov_b32 m0, s43
	s_nop 0
	global_load_lds_dwordx4 v140, s[22:23]
	s_mov_b32 m0, s71
	s_waitcnt vmcnt(8)
	s_waitcnt lgkmcnt(0)
	s_barrier
	s_setprio 1
	s_waitcnt lgkmcnt(7)
	v_mfma_f32_16x16x32_bf16 v[126:129], v[148:151], v[180:183], v[126:129]
	v_mfma_f32_16x16x32_bf16 v[126:129], v[152:155], v[184:187], v[126:129]
	s_waitcnt lgkmcnt(5)
	v_mfma_f32_16x16x32_bf16 v[122:125], v[156:159], v[180:183], v[122:125]
	v_mfma_f32_16x16x32_bf16 v[122:125], v[160:163], v[184:187], v[122:125]
	s_waitcnt lgkmcnt(3)
	v_mfma_f32_16x16x32_bf16 v[106:109], v[156:159], v[188:191], v[106:109]
	v_mfma_f32_16x16x32_bf16 v[106:109], v[160:163], v[192:195], v[106:109]
	s_waitcnt lgkmcnt(1)
	v_mfma_f32_16x16x32_bf16 v[110:113], v[148:151], v[188:191], v[110:113]
	v_mfma_f32_16x16x32_bf16 v[110:113], v[152:155], v[192:195], v[110:113]
	v_mfma_f32_16x16x32_bf16 v[94:97], v[148:151], v[196:199], v[94:97]
	v_mfma_f32_16x16x32_bf16 v[94:97], v[152:155], v[200:203], v[94:97]
	v_mfma_f32_16x16x32_bf16 v[90:93], v[156:159], v[196:199], v[90:93]
	v_mfma_f32_16x16x32_bf16 v[90:93], v[160:163], v[200:203], v[90:93]
	v_mfma_f32_16x16x32_bf16 v[74:77], v[156:159], v[204:207], v[74:77]
	v_mfma_f32_16x16x32_bf16 v[74:77], v[160:163], v[208:211], v[74:77]
	s_waitcnt lgkmcnt(0)
	v_mfma_f32_16x16x32_bf16 v[78:81], v[148:151], v[204:207], v[78:81]
	v_mfma_f32_16x16x32_bf16 v[78:81], v[152:155], v[208:211], v[78:81]
	s_setprio 0
	s_setprio 1
	v_mfma_f32_16x16x32_bf16 v[118:121], v[164:167], v[180:183], v[118:121]
	v_mfma_f32_16x16x32_bf16 v[118:121], v[168:171], v[184:187], v[118:121]
	v_mfma_f32_16x16x32_bf16 v[114:117], v[172:175], v[180:183], v[114:117]
	v_mfma_f32_16x16x32_bf16 v[114:117], v[176:179], v[184:187], v[114:117]
	v_mfma_f32_16x16x32_bf16 v[98:101], v[172:175], v[188:191], v[98:101]
	v_mfma_f32_16x16x32_bf16 v[98:101], v[176:179], v[192:195], v[98:101]
	v_mfma_f32_16x16x32_bf16 v[102:105], v[164:167], v[188:191], v[102:105]
	v_mfma_f32_16x16x32_bf16 v[102:105], v[168:171], v[192:195], v[102:105]
	v_mfma_f32_16x16x32_bf16 v[86:89], v[164:167], v[196:199], v[86:89]
	v_mfma_f32_16x16x32_bf16 v[86:89], v[168:171], v[200:203], v[86:89]
	v_mfma_f32_16x16x32_bf16 v[82:85], v[172:175], v[196:199], v[82:85]
	v_mfma_f32_16x16x32_bf16 v[82:85], v[176:179], v[200:203], v[82:85]
	v_mfma_f32_16x16x32_bf16 v[66:69], v[172:175], v[204:207], v[66:69]
	v_mfma_f32_16x16x32_bf16 v[66:69], v[176:179], v[208:211], v[66:69]
	s_setprio 2
	s_barrier
	v_mfma_f32_16x16x32_bf16 v[70:73], v[164:167], v[204:207], v[70:73]
	v_mfma_f32_16x16x32_bf16 v[70:73], v[168:171], v[208:211], v[70:73]
	s_setprio 0
	ds_read_b128 v[180:183], v145 offset:49152
	ds_read_b128 v[184:187], v145 offset:50176
	ds_read_b128 v[188:191], v145 offset:51200
	ds_read_b128 v[192:195], v145 offset:52224
	ds_read_b128 v[196:199], v145 offset:53248
	ds_read_b128 v[200:203], v145 offset:54272
	ds_read_b128 v[204:207], v145 offset:55296
	ds_read_b128 v[208:211], v145 offset:56320
	s_add_u32 s22, s20, 0x80
	s_addc_u32 s23, s21, 0
	s_mov_b32 s71, m0
	s_mov_b32 m0, s44
	s_nop 0
	global_load_lds_dwordx4 v139, s[22:23]
	s_mov_b32 m0, s71
	s_add_u32 s20, s20, 0x80080
	s_mov_b32 s71, m0
	s_mov_b32 m0, s45
	s_nop 0
	global_load_lds_dwordx4 v141, s[22:23]
	s_mov_b32 m0, s71
	s_addc_u32 s21, s21, 0
	s_mov_b32 s22, m0
	s_mov_b32 m0, s46
	s_nop 0
	global_load_lds_dwordx4 v139, s[20:21]
	s_mov_b32 m0, s22
	s_nop 0
	s_mov_b32 s22, m0
	s_mov_b32 m0, s47
	s_nop 0
	global_load_lds_dwordx4 v141, s[20:21]
	s_mov_b32 m0, s22
	s_waitcnt vmcnt(4)
	s_waitcnt lgkmcnt(0)
	s_barrier
	s_setprio 1
	s_waitcnt lgkmcnt(7)
	v_mfma_f32_16x16x32_bf16 v[62:65], v[148:151], v[180:183], v[62:65]
	v_mfma_f32_16x16x32_bf16 v[62:65], v[152:155], v[184:187], v[62:65]
	s_waitcnt lgkmcnt(5)
	v_mfma_f32_16x16x32_bf16 v[58:61], v[156:159], v[180:183], v[58:61]
	v_mfma_f32_16x16x32_bf16 v[58:61], v[160:163], v[184:187], v[58:61]
	s_waitcnt lgkmcnt(3)
	v_mfma_f32_16x16x32_bf16 v[42:45], v[156:159], v[188:191], v[42:45]
	v_mfma_f32_16x16x32_bf16 v[42:45], v[160:163], v[192:195], v[42:45]
	s_waitcnt lgkmcnt(1)
	v_mfma_f32_16x16x32_bf16 v[46:49], v[148:151], v[188:191], v[46:49]
	v_mfma_f32_16x16x32_bf16 v[46:49], v[152:155], v[192:195], v[46:49]
	v_mfma_f32_16x16x32_bf16 v[30:33], v[148:151], v[196:199], v[30:33]
	v_mfma_f32_16x16x32_bf16 v[30:33], v[152:155], v[200:203], v[30:33]
	v_mfma_f32_16x16x32_bf16 v[26:29], v[156:159], v[196:199], v[26:29]
	v_mfma_f32_16x16x32_bf16 v[26:29], v[160:163], v[200:203], v[26:29]
	v_mfma_f32_16x16x32_bf16 v[10:13], v[156:159], v[204:207], v[10:13]
	v_mfma_f32_16x16x32_bf16 v[10:13], v[160:163], v[208:211], v[10:13]
	s_waitcnt lgkmcnt(0)
	v_mfma_f32_16x16x32_bf16 v[14:17], v[148:151], v[204:207], v[14:17]
	v_mfma_f32_16x16x32_bf16 v[14:17], v[152:155], v[208:211], v[14:17]
	s_setprio 0
	s_setprio 1
	v_mfma_f32_16x16x32_bf16 v[54:57], v[164:167], v[180:183], v[54:57]
	v_mfma_f32_16x16x32_bf16 v[54:57], v[168:171], v[184:187], v[54:57]
	v_mfma_f32_16x16x32_bf16 v[50:53], v[172:175], v[180:183], v[50:53]
	v_mfma_f32_16x16x32_bf16 v[50:53], v[176:179], v[184:187], v[50:53]
	v_mfma_f32_16x16x32_bf16 v[34:37], v[172:175], v[188:191], v[34:37]
	v_mfma_f32_16x16x32_bf16 v[34:37], v[176:179], v[192:195], v[34:37]
	v_mfma_f32_16x16x32_bf16 v[38:41], v[164:167], v[188:191], v[38:41]
	v_mfma_f32_16x16x32_bf16 v[38:41], v[168:171], v[192:195], v[38:41]
	v_mfma_f32_16x16x32_bf16 v[22:25], v[164:167], v[196:199], v[22:25]
	v_mfma_f32_16x16x32_bf16 v[22:25], v[168:171], v[200:203], v[22:25]
	v_mfma_f32_16x16x32_bf16 v[18:21], v[172:175], v[196:199], v[18:21]
	v_mfma_f32_16x16x32_bf16 v[18:21], v[176:179], v[200:203], v[18:21]
	v_mfma_f32_16x16x32_bf16 v[2:5], v[172:175], v[204:207], v[2:5]
	v_mfma_f32_16x16x32_bf16 v[2:5], v[176:179], v[208:211], v[2:5]
	s_setprio 2
	s_barrier
	v_mfma_f32_16x16x32_bf16 v[6:9], v[164:167], v[204:207], v[6:9]
	v_mfma_f32_16x16x32_bf16 v[6:9], v[168:171], v[208:211], v[6:9]
	s_setprio 0
	s_add_i32 s70, s70, 2
	s_add_u32 s64, s64, 0x100
	s_addc_u32 s65, s65, 0
	s_add_u32 s18, s18, 0x100
	s_addc_u32 s19, s19, 0
	s_add_u32 s66, s66, 0x100
	s_addc_u32 s67, s67, 0
	s_cmp_gt_u32 s70, 29
	.p2align 6
.LBB0_2594:
	ds_read_b128 v[148:151], v143
	ds_read_b128 v[152:155], v143 offset:1024
	ds_read_b128 v[156:159], v143 offset:2048
	ds_read_b128 v[160:163], v143 offset:3072
	ds_read_b128 v[164:167], v144
	ds_read_b128 v[168:171], v144 offset:1024
	ds_read_b128 v[172:175], v144 offset:2048
	ds_read_b128 v[176:179], v144 offset:3072
	s_cmp_eq_u32 s70, 28
	s_cselect_b32 s21, s9, s65
	s_cselect_b32 s20, s63, s64
	s_cselect_b32 s23, s11, s67
	s_cselect_b32 s22, s62, s66
	ds_read_b128 v[180:183], v145
	ds_read_b128 v[184:187], v145 offset:1024
	ds_read_b128 v[188:191], v145 offset:2048
	ds_read_b128 v[192:195], v145 offset:3072
	ds_read_b128 v[196:199], v145 offset:4096
	ds_read_b128 v[200:203], v145 offset:5120
	ds_read_b128 v[204:207], v145 offset:6144
	ds_read_b128 v[208:211], v145 offset:7168
	s_add_u32 s74, s18, 0xfff80000
	s_addc_u32 s75, s19, -1
	s_mov_b32 s71, m0
	s_mov_b32 m0, s48
	s_nop 0
	global_load_lds_dwordx4 v138, s[74:75]
	s_mov_b32 m0, s71
	s_nop 0
	s_mov_b32 s71, m0
	s_mov_b32 m0, s57
	s_nop 0
	global_load_lds_dwordx4 v140, s[74:75]
	s_mov_b32 m0, s71
	s_nop 0
	s_mov_b32 s71, m0
	s_mov_b32 m0, s49
	s_nop 0
	global_load_lds_dwordx4 v138, s[18:19]
	s_mov_b32 m0, s71
	s_nop 0
	s_mov_b32 s71, m0
	s_mov_b32 m0, s58
	s_nop 0
	global_load_lds_dwordx4 v140, s[18:19]
	s_mov_b32 m0, s71
	s_waitcnt vmcnt(8)
	s_waitcnt lgkmcnt(0)
	s_barrier
	s_setprio 1
	s_waitcnt lgkmcnt(7)
	v_mfma_f32_16x16x32_bf16 v[126:129], v[148:151], v[180:183], v[126:129]
	v_mfma_f32_16x16x32_bf16 v[126:129], v[152:155], v[184:187], v[126:129]
	s_waitcnt lgkmcnt(5)
	v_mfma_f32_16x16x32_bf16 v[122:125], v[156:159], v[180:183], v[122:125]
	v_mfma_f32_16x16x32_bf16 v[122:125], v[160:163], v[184:187], v[122:125]
	s_waitcnt lgkmcnt(3)
	v_mfma_f32_16x16x32_bf16 v[106:109], v[156:159], v[188:191], v[106:109]
	v_mfma_f32_16x16x32_bf16 v[106:109], v[160:163], v[192:195], v[106:109]
	s_waitcnt lgkmcnt(1)
	v_mfma_f32_16x16x32_bf16 v[110:113], v[148:151], v[188:191], v[110:113]
	v_mfma_f32_16x16x32_bf16 v[110:113], v[152:155], v[192:195], v[110:113]
	v_mfma_f32_16x16x32_bf16 v[94:97], v[148:151], v[196:199], v[94:97]
	v_mfma_f32_16x16x32_bf16 v[94:97], v[152:155], v[200:203], v[94:97]
	v_mfma_f32_16x16x32_bf16 v[90:93], v[156:159], v[196:199], v[90:93]
	v_mfma_f32_16x16x32_bf16 v[90:93], v[160:163], v[200:203], v[90:93]
	v_mfma_f32_16x16x32_bf16 v[74:77], v[156:159], v[204:207], v[74:77]
	v_mfma_f32_16x16x32_bf16 v[74:77], v[160:163], v[208:211], v[74:77]
	s_waitcnt lgkmcnt(0)
	v_mfma_f32_16x16x32_bf16 v[78:81], v[148:151], v[204:207], v[78:81]
	v_mfma_f32_16x16x32_bf16 v[78:81], v[152:155], v[208:211], v[78:81]
	s_setprio 0
	s_setprio 1
	v_mfma_f32_16x16x32_bf16 v[118:121], v[164:167], v[180:183], v[118:121]
	v_mfma_f32_16x16x32_bf16 v[118:121], v[168:171], v[184:187], v[118:121]
	v_mfma_f32_16x16x32_bf16 v[114:117], v[172:175], v[180:183], v[114:117]
	v_mfma_f32_16x16x32_bf16 v[114:117], v[176:179], v[184:187], v[114:117]
	v_mfma_f32_16x16x32_bf16 v[98:101], v[172:175], v[188:191], v[98:101]
	v_mfma_f32_16x16x32_bf16 v[98:101], v[176:179], v[192:195], v[98:101]
	v_mfma_f32_16x16x32_bf16 v[102:105], v[164:167], v[188:191], v[102:105]
	v_mfma_f32_16x16x32_bf16 v[102:105], v[168:171], v[192:195], v[102:105]
	v_mfma_f32_16x16x32_bf16 v[86:89], v[164:167], v[196:199], v[86:89]
	v_mfma_f32_16x16x32_bf16 v[86:89], v[168:171], v[200:203], v[86:89]
	v_mfma_f32_16x16x32_bf16 v[82:85], v[172:175], v[196:199], v[82:85]
	v_mfma_f32_16x16x32_bf16 v[82:85], v[176:179], v[200:203], v[82:85]
	v_mfma_f32_16x16x32_bf16 v[66:69], v[172:175], v[204:207], v[66:69]
	v_mfma_f32_16x16x32_bf16 v[66:69], v[176:179], v[208:211], v[66:69]
	s_setprio 2
	s_barrier
	v_mfma_f32_16x16x32_bf16 v[70:73], v[164:167], v[204:207], v[70:73]
	v_mfma_f32_16x16x32_bf16 v[70:73], v[168:171], v[208:211], v[70:73]
	s_setprio 0
	ds_read_b128 v[180:183], v145 offset:16384
	ds_read_b128 v[184:187], v145 offset:17408
	ds_read_b128 v[188:191], v145 offset:18432
	ds_read_b128 v[192:195], v145 offset:19456
	ds_read_b128 v[196:199], v145 offset:20480
	ds_read_b128 v[200:203], v145 offset:21504
	ds_read_b128 v[204:207], v145 offset:22528
	ds_read_b128 v[208:211], v145 offset:23552
	s_mov_b32 s71, m0
	s_mov_b32 m0, s35
	s_nop 0
	global_load_lds_dwordx4 v139, s[20:21]
	s_mov_b32 m0, s71
	s_add_u32 s74, s20, 0x80000
	s_mov_b32 s71, m0
	s_mov_b32 m0, s36
	s_nop 0
	global_load_lds_dwordx4 v141, s[20:21]
	s_mov_b32 m0, s71
	s_addc_u32 s75, s21, 0
	s_mov_b32 s71, m0
	s_mov_b32 m0, s37
	s_nop 0
	global_load_lds_dwordx4 v139, s[74:75]
	s_mov_b32 m0, s71
	s_nop 0
	s_mov_b32 s71, m0
	s_mov_b32 m0, s40
	s_nop 0
	global_load_lds_dwordx4 v141, s[74:75]
	s_mov_b32 m0, s71
	s_waitcnt vmcnt(4)
	s_waitcnt lgkmcnt(0)
	s_barrier
	s_setprio 1
	s_waitcnt lgkmcnt(7)
	v_mfma_f32_16x16x32_bf16 v[62:65], v[148:151], v[180:183], v[62:65]
	v_mfma_f32_16x16x32_bf16 v[62:65], v[152:155], v[184:187], v[62:65]
	s_waitcnt lgkmcnt(5)
	v_mfma_f32_16x16x32_bf16 v[58:61], v[156:159], v[180:183], v[58:61]
	v_mfma_f32_16x16x32_bf16 v[58:61], v[160:163], v[184:187], v[58:61]
	s_waitcnt lgkmcnt(3)
	v_mfma_f32_16x16x32_bf16 v[42:45], v[156:159], v[188:191], v[42:45]
	v_mfma_f32_16x16x32_bf16 v[42:45], v[160:163], v[192:195], v[42:45]
	s_waitcnt lgkmcnt(1)
	v_mfma_f32_16x16x32_bf16 v[46:49], v[148:151], v[188:191], v[46:49]
	v_mfma_f32_16x16x32_bf16 v[46:49], v[152:155], v[192:195], v[46:49]
	v_mfma_f32_16x16x32_bf16 v[30:33], v[148:151], v[196:199], v[30:33]
	v_mfma_f32_16x16x32_bf16 v[30:33], v[152:155], v[200:203], v[30:33]
	v_mfma_f32_16x16x32_bf16 v[26:29], v[156:159], v[196:199], v[26:29]
	v_mfma_f32_16x16x32_bf16 v[26:29], v[160:163], v[200:203], v[26:29]
	v_mfma_f32_16x16x32_bf16 v[10:13], v[156:159], v[204:207], v[10:13]
	v_mfma_f32_16x16x32_bf16 v[10:13], v[160:163], v[208:211], v[10:13]
	s_waitcnt lgkmcnt(0)
	v_mfma_f32_16x16x32_bf16 v[14:17], v[148:151], v[204:207], v[14:17]
	v_mfma_f32_16x16x32_bf16 v[14:17], v[152:155], v[208:211], v[14:17]
	s_setprio 0
	s_setprio 1
	v_mfma_f32_16x16x32_bf16 v[54:57], v[164:167], v[180:183], v[54:57]
	v_mfma_f32_16x16x32_bf16 v[54:57], v[168:171], v[184:187], v[54:57]
	v_mfma_f32_16x16x32_bf16 v[50:53], v[172:175], v[180:183], v[50:53]
	v_mfma_f32_16x16x32_bf16 v[50:53], v[176:179], v[184:187], v[50:53]
	v_mfma_f32_16x16x32_bf16 v[34:37], v[172:175], v[188:191], v[34:37]
	v_mfma_f32_16x16x32_bf16 v[34:37], v[176:179], v[192:195], v[34:37]
	v_mfma_f32_16x16x32_bf16 v[38:41], v[164:167], v[188:191], v[38:41]
	v_mfma_f32_16x16x32_bf16 v[38:41], v[168:171], v[192:195], v[38:41]
	v_mfma_f32_16x16x32_bf16 v[22:25], v[164:167], v[196:199], v[22:25]
	v_mfma_f32_16x16x32_bf16 v[22:25], v[168:171], v[200:203], v[22:25]
	v_mfma_f32_16x16x32_bf16 v[18:21], v[172:175], v[196:199], v[18:21]
	v_mfma_f32_16x16x32_bf16 v[18:21], v[176:179], v[200:203], v[18:21]
	v_mfma_f32_16x16x32_bf16 v[2:5], v[172:175], v[204:207], v[2:5]
	v_mfma_f32_16x16x32_bf16 v[2:5], v[176:179], v[208:211], v[2:5]
	s_setprio 2
	s_barrier
	v_mfma_f32_16x16x32_bf16 v[6:9], v[164:167], v[204:207], v[6:9]
	v_mfma_f32_16x16x32_bf16 v[6:9], v[168:171], v[208:211], v[6:9]
	s_setprio 0
	ds_read_b128 v[148:151], v146
	ds_read_b128 v[152:155], v146 offset:1024
	ds_read_b128 v[156:159], v146 offset:2048
	ds_read_b128 v[160:163], v146 offset:3072
	ds_read_b128 v[164:167], v147
	ds_read_b128 v[168:171], v147 offset:1024
	ds_read_b128 v[172:175], v147 offset:2048
	ds_read_b128 v[176:179], v147 offset:3072
	ds_read_b128 v[180:183], v145 offset:32768
	ds_read_b128 v[184:187], v145 offset:33792
	ds_read_b128 v[188:191], v145 offset:34816
	ds_read_b128 v[192:195], v145 offset:35840
	ds_read_b128 v[196:199], v145 offset:36864
	ds_read_b128 v[200:203], v145 offset:37888
	ds_read_b128 v[204:207], v145 offset:38912
	ds_read_b128 v[208:211], v145 offset:39936
	s_mov_b32 s71, m0
	s_mov_b32 m0, s31
	s_nop 0
	global_load_lds_dwordx4 v138, s[22:23]
	s_mov_b32 m0, s71
	s_nop 0
	s_mov_b32 s71, m0
	s_mov_b32 m0, s41
	s_nop 0
	global_load_lds_dwordx4 v140, s[22:23]
	s_mov_b32 m0, s71
	s_add_u32 s22, s22, 0x80000
	s_addc_u32 s23, s23, 0
	s_mov_b32 s71, m0
	s_mov_b32 m0, s42
	s_nop 0
	global_load_lds_dwordx4 v138, s[22:23]
	s_mov_b32 m0, s71
	s_nop 0
	s_mov_b32 s71, m0
	s_mov_b32 m0, s43
	s_nop 0
	global_load_lds_dwordx4 v140, s[22:23]
	s_mov_b32 m0, s71
	s_waitcnt vmcnt(8)
	s_waitcnt lgkmcnt(0)
	s_barrier
	s_setprio 1
	s_waitcnt lgkmcnt(7)
	v_mfma_f32_16x16x32_bf16 v[126:129], v[148:151], v[180:183], v[126:129]
	v_mfma_f32_16x16x32_bf16 v[126:129], v[152:155], v[184:187], v[126:129]
	s_waitcnt lgkmcnt(5)
	v_mfma_f32_16x16x32_bf16 v[122:125], v[156:159], v[180:183], v[122:125]
	v_mfma_f32_16x16x32_bf16 v[122:125], v[160:163], v[184:187], v[122:125]
	s_waitcnt lgkmcnt(3)
	v_mfma_f32_16x16x32_bf16 v[106:109], v[156:159], v[188:191], v[106:109]
	v_mfma_f32_16x16x32_bf16 v[106:109], v[160:163], v[192:195], v[106:109]
	s_waitcnt lgkmcnt(1)
	v_mfma_f32_16x16x32_bf16 v[110:113], v[148:151], v[188:191], v[110:113]
	v_mfma_f32_16x16x32_bf16 v[110:113], v[152:155], v[192:195], v[110:113]
	v_mfma_f32_16x16x32_bf16 v[94:97], v[148:151], v[196:199], v[94:97]
	v_mfma_f32_16x16x32_bf16 v[94:97], v[152:155], v[200:203], v[94:97]
	v_mfma_f32_16x16x32_bf16 v[90:93], v[156:159], v[196:199], v[90:93]
	v_mfma_f32_16x16x32_bf16 v[90:93], v[160:163], v[200:203], v[90:93]
	v_mfma_f32_16x16x32_bf16 v[74:77], v[156:159], v[204:207], v[74:77]
	v_mfma_f32_16x16x32_bf16 v[74:77], v[160:163], v[208:211], v[74:77]
	s_waitcnt lgkmcnt(0)
	v_mfma_f32_16x16x32_bf16 v[78:81], v[148:151], v[204:207], v[78:81]
	v_mfma_f32_16x16x32_bf16 v[78:81], v[152:155], v[208:211], v[78:81]
	s_setprio 0
	s_setprio 1
	v_mfma_f32_16x16x32_bf16 v[118:121], v[164:167], v[180:183], v[118:121]
	v_mfma_f32_16x16x32_bf16 v[118:121], v[168:171], v[184:187], v[118:121]
	v_mfma_f32_16x16x32_bf16 v[114:117], v[172:175], v[180:183], v[114:117]
	v_mfma_f32_16x16x32_bf16 v[114:117], v[176:179], v[184:187], v[114:117]
	v_mfma_f32_16x16x32_bf16 v[98:101], v[172:175], v[188:191], v[98:101]
	v_mfma_f32_16x16x32_bf16 v[98:101], v[176:179], v[192:195], v[98:101]
	v_mfma_f32_16x16x32_bf16 v[102:105], v[164:167], v[188:191], v[102:105]
	v_mfma_f32_16x16x32_bf16 v[102:105], v[168:171], v[192:195], v[102:105]
	v_mfma_f32_16x16x32_bf16 v[86:89], v[164:167], v[196:199], v[86:89]
	v_mfma_f32_16x16x32_bf16 v[86:89], v[168:171], v[200:203], v[86:89]
	v_mfma_f32_16x16x32_bf16 v[82:85], v[172:175], v[196:199], v[82:85]
	v_mfma_f32_16x16x32_bf16 v[82:85], v[176:179], v[200:203], v[82:85]
	v_mfma_f32_16x16x32_bf16 v[66:69], v[172:175], v[204:207], v[66:69]
	v_mfma_f32_16x16x32_bf16 v[66:69], v[176:179], v[208:211], v[66:69]
	s_setprio 2
	s_barrier
	v_mfma_f32_16x16x32_bf16 v[70:73], v[164:167], v[204:207], v[70:73]
	v_mfma_f32_16x16x32_bf16 v[70:73], v[168:171], v[208:211], v[70:73]
	s_setprio 0
	ds_read_b128 v[180:183], v145 offset:49152
	ds_read_b128 v[184:187], v145 offset:50176
	ds_read_b128 v[188:191], v145 offset:51200
	ds_read_b128 v[192:195], v145 offset:52224
	ds_read_b128 v[196:199], v145 offset:53248
	ds_read_b128 v[200:203], v145 offset:54272
	ds_read_b128 v[204:207], v145 offset:55296
	ds_read_b128 v[208:211], v145 offset:56320
	s_add_u32 s22, s20, 0x80
	s_addc_u32 s23, s21, 0
	s_mov_b32 s71, m0
	s_mov_b32 m0, s44
	s_nop 0
	global_load_lds_dwordx4 v139, s[22:23]
	s_mov_b32 m0, s71
	s_add_u32 s20, s20, 0x80080
	s_mov_b32 s71, m0
	s_mov_b32 m0, s45
	s_nop 0
	global_load_lds_dwordx4 v141, s[22:23]
	s_mov_b32 m0, s71
	s_addc_u32 s21, s21, 0
	s_mov_b32 s22, m0
	s_mov_b32 m0, s46
	s_nop 0
	global_load_lds_dwordx4 v139, s[20:21]
	s_mov_b32 m0, s22
	s_nop 0
	s_mov_b32 s22, m0
	s_mov_b32 m0, s47
	s_nop 0
	global_load_lds_dwordx4 v141, s[20:21]
	s_mov_b32 m0, s22
	s_waitcnt vmcnt(4)
	s_waitcnt lgkmcnt(0)
	s_barrier
	s_setprio 1
	s_waitcnt lgkmcnt(7)
	v_mfma_f32_16x16x32_bf16 v[62:65], v[148:151], v[180:183], v[62:65]
	v_mfma_f32_16x16x32_bf16 v[62:65], v[152:155], v[184:187], v[62:65]
	s_waitcnt lgkmcnt(5)
	v_mfma_f32_16x16x32_bf16 v[58:61], v[156:159], v[180:183], v[58:61]
	v_mfma_f32_16x16x32_bf16 v[58:61], v[160:163], v[184:187], v[58:61]
	s_waitcnt lgkmcnt(3)
	v_mfma_f32_16x16x32_bf16 v[42:45], v[156:159], v[188:191], v[42:45]
	v_mfma_f32_16x16x32_bf16 v[42:45], v[160:163], v[192:195], v[42:45]
	s_waitcnt lgkmcnt(1)
	v_mfma_f32_16x16x32_bf16 v[46:49], v[148:151], v[188:191], v[46:49]
	v_mfma_f32_16x16x32_bf16 v[46:49], v[152:155], v[192:195], v[46:49]
	v_mfma_f32_16x16x32_bf16 v[30:33], v[148:151], v[196:199], v[30:33]
	v_mfma_f32_16x16x32_bf16 v[30:33], v[152:155], v[200:203], v[30:33]
	v_mfma_f32_16x16x32_bf16 v[26:29], v[156:159], v[196:199], v[26:29]
	v_mfma_f32_16x16x32_bf16 v[26:29], v[160:163], v[200:203], v[26:29]
	v_mfma_f32_16x16x32_bf16 v[10:13], v[156:159], v[204:207], v[10:13]
	v_mfma_f32_16x16x32_bf16 v[10:13], v[160:163], v[208:211], v[10:13]
	s_waitcnt lgkmcnt(0)
	v_mfma_f32_16x16x32_bf16 v[14:17], v[148:151], v[204:207], v[14:17]
	v_mfma_f32_16x16x32_bf16 v[14:17], v[152:155], v[208:211], v[14:17]
	s_setprio 0
	s_setprio 1
	v_mfma_f32_16x16x32_bf16 v[54:57], v[164:167], v[180:183], v[54:57]
	v_mfma_f32_16x16x32_bf16 v[54:57], v[168:171], v[184:187], v[54:57]
	v_mfma_f32_16x16x32_bf16 v[50:53], v[172:175], v[180:183], v[50:53]
	v_mfma_f32_16x16x32_bf16 v[50:53], v[176:179], v[184:187], v[50:53]
	v_mfma_f32_16x16x32_bf16 v[34:37], v[172:175], v[188:191], v[34:37]
	v_mfma_f32_16x16x32_bf16 v[34:37], v[176:179], v[192:195], v[34:37]
	v_mfma_f32_16x16x32_bf16 v[38:41], v[164:167], v[188:191], v[38:41]
	v_mfma_f32_16x16x32_bf16 v[38:41], v[168:171], v[192:195], v[38:41]
	v_mfma_f32_16x16x32_bf16 v[22:25], v[164:167], v[196:199], v[22:25]
	v_mfma_f32_16x16x32_bf16 v[22:25], v[168:171], v[200:203], v[22:25]
	v_mfma_f32_16x16x32_bf16 v[18:21], v[172:175], v[196:199], v[18:21]
	v_mfma_f32_16x16x32_bf16 v[18:21], v[176:179], v[200:203], v[18:21]
	v_mfma_f32_16x16x32_bf16 v[2:5], v[172:175], v[204:207], v[2:5]
	v_mfma_f32_16x16x32_bf16 v[2:5], v[176:179], v[208:211], v[2:5]
	s_setprio 2
	s_barrier
	v_mfma_f32_16x16x32_bf16 v[6:9], v[164:167], v[204:207], v[6:9]
	v_mfma_f32_16x16x32_bf16 v[6:9], v[168:171], v[208:211], v[6:9]
	s_setprio 0
	s_add_i32 s70, s70, 2
	s_add_u32 s64, s64, 0x100
	s_addc_u32 s65, s65, 0
	s_add_u32 s18, s18, 0x100
	s_addc_u32 s19, s19, 0
	s_add_u32 s66, s66, 0x100
	s_addc_u32 s67, s67, 0
	s_cmp_gt_u32 s70, 29
	s_cbranch_scc0 .LBB0_2594
	s_and_b64 vcc, exec, s[6:7]
	s_cbranch_vccz .LBB0_2597
	s_barrier

.LBB0_2791:
	s_ashr_i32 s21, s20, 31
	s_lshl_b64 s[22:23], s[20:21], 15
	s_add_u32 s22, s37, s22
	s_addc_u32 s23, s40, s23
	s_and_b64 s[24:25], s[2:3], exec
	s_cselect_b32 s21, s23, s31
	s_cselect_b32 s63, s22, s30
	s_ashr_i32 s19, s18, 31
	s_lshl_b64 s[24:25], s[18:19], 15
	s_add_u32 s24, s41, s24
	s_addc_u32 s25, s42, s25
	s_and_b64 s[34:35], s[2:3], exec
	s_cselect_b32 s19, s25, s29
	s_cselect_b32 s64, s24, s28
	s_add_u32 s65, s28, 0x80000
	s_addc_u32 s66, s29, 0
	s_add_u32 s28, s30, 0x204000
	s_addc_u32 s29, s31, 0
	s_add_u32 s67, s30, 0x400000
	s_addc_u32 s68, s31, 0
	s_mov_b32 s69, -2
	s_waitcnt vmcnt(25)
	s_waitcnt vmcnt(24)
	s_waitcnt vmcnt(4)
	s_waitcnt vmcnt(2)
	s_waitcnt vmcnt(1)
	s_waitcnt vmcnt(0)
	ds_read_b128 v[130:133], v181
	ds_read_b128 v[134:137], v181 offset:1024
	ds_read_b128 v[138:141], v181 offset:2048
	ds_read_b128 v[142:145], v181 offset:3072
	ds_read_b128 v[150:153], v182
	ds_read_b128 v[154:157], v182 offset:1024
	ds_read_b128 v[158:161], v182 offset:2048
	ds_read_b128 v[162:165], v182 offset:3072
	s_cmpk_eq_i32 s69, 0x52
	s_cselect_b32 s31, s19, s66
	s_cselect_b32 s30, s64, s65
	s_cselect_b32 s35, s21, s68
	s_cselect_b32 s34, s63, s67
	ds_read_b128 v[166:169], v183
	ds_read_b128 v[170:173], v183 offset:1024
	ds_read_b128 v[186:189], v183 offset:2048
	ds_read_b128 v[190:193], v183 offset:3072
	ds_read_b128 v[194:197], v183 offset:4096
	ds_read_b128 v[198:201], v183 offset:5120
	ds_read_b128 v[202:205], v183 offset:6144
	ds_read_b128 v[206:209], v183 offset:7168
	s_add_u32 s70, s28, 0xffffc000
	s_addc_u32 s71, s29, -1
	s_mov_b32 s73, m0
	s_mov_b32 m0, s57
	s_nop 0
	global_load_lds_dwordx4 v1, s[70:71]
	s_mov_b32 m0, s73
	s_nop 0
	s_mov_b32 s73, m0
	s_mov_b32 m0, s59
	s_nop 0
	global_load_lds_dwordx4 v177, s[70:71]
	s_mov_b32 m0, s73
	s_mov_b32 s70, m0
	s_mov_b32 m0, s58
	s_nop 0
	global_load_lds_dwordx4 v1, s[28:29]
	s_mov_b32 m0, s70
	s_nop 0
	s_mov_b32 s70, m0
	s_mov_b32 m0, s60
	s_nop 0
	global_load_lds_dwordx4 v177, s[28:29]
	s_mov_b32 m0, s70
	s_waitcnt vmcnt(8)
	s_waitcnt lgkmcnt(0)
	s_barrier
	s_setprio 1
	s_waitcnt lgkmcnt(7)
	v_mfma_f32_16x16x32_bf16 v[126:129], v[130:133], v[166:169], 0
	v_mfma_f32_16x16x32_bf16 v[126:129], v[134:137], v[170:173], v[126:129]
	s_waitcnt lgkmcnt(5)
	v_mfma_f32_16x16x32_bf16 v[122:125], v[138:141], v[166:169], 0
	v_mfma_f32_16x16x32_bf16 v[122:125], v[142:145], v[170:173], v[122:125]
	s_waitcnt lgkmcnt(3)
	v_mfma_f32_16x16x32_bf16 v[110:113], v[138:141], v[186:189], 0
	v_mfma_f32_16x16x32_bf16 v[110:113], v[142:145], v[190:193], v[110:113]
	s_waitcnt lgkmcnt(1)
	v_mfma_f32_16x16x32_bf16 v[118:121], v[130:133], v[186:189], 0
	v_mfma_f32_16x16x32_bf16 v[118:121], v[134:137], v[190:193], v[118:121]
	v_mfma_f32_16x16x32_bf16 v[94:97], v[130:133], v[194:197], 0
	v_mfma_f32_16x16x32_bf16 v[94:97], v[134:137], v[198:201], v[94:97]
	v_mfma_f32_16x16x32_bf16 v[90:93], v[138:141], v[194:197], 0
	v_mfma_f32_16x16x32_bf16 v[90:93], v[142:145], v[198:201], v[90:93]
	v_mfma_f32_16x16x32_bf16 v[78:81], v[138:141], v[202:205], 0
	v_mfma_f32_16x16x32_bf16 v[78:81], v[142:145], v[206:209], v[78:81]
	s_waitcnt lgkmcnt(0)
	v_mfma_f32_16x16x32_bf16 v[86:89], v[130:133], v[202:205], 0
	v_mfma_f32_16x16x32_bf16 v[86:89], v[134:137], v[206:209], v[86:89]
	s_setprio 0
	s_setprio 1
	v_mfma_f32_16x16x32_bf16 v[114:117], v[150:153], v[166:169], 0
	v_mfma_f32_16x16x32_bf16 v[114:117], v[154:157], v[170:173], v[114:117]
	v_mfma_f32_16x16x32_bf16 v[106:109], v[158:161], v[166:169], 0
	v_mfma_f32_16x16x32_bf16 v[106:109], v[162:165], v[170:173], v[106:109]
	v_mfma_f32_16x16x32_bf16 v[98:101], v[158:161], v[186:189], 0
	v_mfma_f32_16x16x32_bf16 v[98:101], v[162:165], v[190:193], v[98:101]
	v_mfma_f32_16x16x32_bf16 v[102:105], v[150:153], v[186:189], 0
	v_mfma_f32_16x16x32_bf16 v[102:105], v[154:157], v[190:193], v[102:105]
	v_mfma_f32_16x16x32_bf16 v[82:85], v[150:153], v[194:197], 0
	v_mfma_f32_16x16x32_bf16 v[82:85], v[154:157], v[198:201], v[82:85]
	v_mfma_f32_16x16x32_bf16 v[74:77], v[158:161], v[194:197], 0
	v_mfma_f32_16x16x32_bf16 v[74:77], v[162:165], v[198:201], v[74:77]
	v_mfma_f32_16x16x32_bf16 v[66:69], v[158:161], v[202:205], 0
	v_mfma_f32_16x16x32_bf16 v[66:69], v[162:165], v[206:209], v[66:69]
	s_setprio 2
	s_barrier
	v_mfma_f32_16x16x32_bf16 v[70:73], v[150:153], v[202:205], 0
	v_mfma_f32_16x16x32_bf16 v[70:73], v[154:157], v[206:209], v[70:73]
	s_setprio 0
	ds_read_b128 v[166:169], v183 offset:16384
	ds_read_b128 v[170:173], v183 offset:17408
	ds_read_b128 v[186:189], v183 offset:18432
	ds_read_b128 v[190:193], v183 offset:19456
	ds_read_b128 v[194:197], v183 offset:20480
	ds_read_b128 v[198:201], v183 offset:21504
	ds_read_b128 v[202:205], v183 offset:22528
	ds_read_b128 v[206:209], v183 offset:23552
	s_mov_b32 s70, m0
	s_mov_b32 m0, s27
	s_nop 0
	global_load_lds_dwordx4 v176, s[30:31]
	s_mov_b32 m0, s70
	s_nop 0
	s_mov_b32 s70, m0
	s_mov_b32 m0, s45
	s_nop 0
	global_load_lds_dwordx4 v178, s[30:31]
	s_mov_b32 m0, s70
	s_add_u32 s70, s30, 0x4000
	s_addc_u32 s71, s31, 0
	s_mov_b32 s73, m0
	s_mov_b32 m0, s46
	s_nop 0
	global_load_lds_dwordx4 v176, s[70:71]
	s_mov_b32 m0, s73
	s_nop 0
	s_mov_b32 s73, m0
	s_mov_b32 m0, s47
	s_nop 0
	global_load_lds_dwordx4 v178, s[70:71]
	s_mov_b32 m0, s73
	s_waitcnt vmcnt(4)
	s_waitcnt lgkmcnt(0)
	s_barrier
	s_setprio 1
	s_waitcnt lgkmcnt(7)
	v_mfma_f32_16x16x32_bf16 v[62:65], v[130:133], v[166:169], 0
	v_mfma_f32_16x16x32_bf16 v[62:65], v[134:137], v[170:173], v[62:65]
	s_waitcnt lgkmcnt(5)
	v_mfma_f32_16x16x32_bf16 v[58:61], v[138:141], v[166:169], 0
	v_mfma_f32_16x16x32_bf16 v[58:61], v[142:145], v[170:173], v[58:61]
	s_waitcnt lgkmcnt(3)
	v_mfma_f32_16x16x32_bf16 v[42:45], v[138:141], v[186:189], 0
	v_mfma_f32_16x16x32_bf16 v[42:45], v[142:145], v[190:193], v[42:45]
	s_waitcnt lgkmcnt(1)
	v_mfma_f32_16x16x32_bf16 v[46:49], v[130:133], v[186:189], 0
	v_mfma_f32_16x16x32_bf16 v[46:49], v[134:137], v[190:193], v[46:49]
	v_mfma_f32_16x16x32_bf16 v[30:33], v[130:133], v[194:197], 0
	v_mfma_f32_16x16x32_bf16 v[30:33], v[134:137], v[198:201], v[30:33]
	v_mfma_f32_16x16x32_bf16 v[26:29], v[138:141], v[194:197], 0
	v_mfma_f32_16x16x32_bf16 v[26:29], v[142:145], v[198:201], v[26:29]
	v_mfma_f32_16x16x32_bf16 v[10:13], v[138:141], v[202:205], 0
	v_mfma_f32_16x16x32_bf16 v[10:13], v[142:145], v[206:209], v[10:13]
	s_waitcnt lgkmcnt(0)
	v_mfma_f32_16x16x32_bf16 v[14:17], v[130:133], v[202:205], 0
	v_mfma_f32_16x16x32_bf16 v[14:17], v[134:137], v[206:209], v[14:17]
	s_setprio 0
	s_setprio 1
	v_mfma_f32_16x16x32_bf16 v[54:57], v[150:153], v[166:169], 0
	v_mfma_f32_16x16x32_bf16 v[54:57], v[154:157], v[170:173], v[54:57]
	v_mfma_f32_16x16x32_bf16 v[50:53], v[158:161], v[166:169], 0
	v_mfma_f32_16x16x32_bf16 v[50:53], v[162:165], v[170:173], v[50:53]
	v_mfma_f32_16x16x32_bf16 v[34:37], v[158:161], v[186:189], 0
	v_mfma_f32_16x16x32_bf16 v[34:37], v[162:165], v[190:193], v[34:37]
	v_mfma_f32_16x16x32_bf16 v[38:41], v[150:153], v[186:189], 0
	v_mfma_f32_16x16x32_bf16 v[38:41], v[154:157], v[190:193], v[38:41]
	v_mfma_f32_16x16x32_bf16 v[22:25], v[150:153], v[194:197], 0
	v_mfma_f32_16x16x32_bf16 v[22:25], v[154:157], v[198:201], v[22:25]
	v_mfma_f32_16x16x32_bf16 v[18:21], v[158:161], v[194:197], 0
	v_mfma_f32_16x16x32_bf16 v[18:21], v[162:165], v[198:201], v[18:21]
	v_mfma_f32_16x16x32_bf16 v[2:5], v[158:161], v[202:205], 0
	v_mfma_f32_16x16x32_bf16 v[2:5], v[162:165], v[206:209], v[2:5]
	s_setprio 2
	s_barrier
	v_mfma_f32_16x16x32_bf16 v[6:9], v[150:153], v[202:205], 0
	v_mfma_f32_16x16x32_bf16 v[6:9], v[154:157], v[206:209], v[6:9]
	s_setprio 0
	ds_read_b128 v[130:133], v184
	ds_read_b128 v[134:137], v184 offset:1024
	ds_read_b128 v[138:141], v184 offset:2048
	ds_read_b128 v[142:145], v184 offset:3072
	ds_read_b128 v[150:153], v185
	ds_read_b128 v[154:157], v185 offset:1024
	ds_read_b128 v[158:161], v185 offset:2048
	ds_read_b128 v[162:165], v185 offset:3072
	ds_read_b128 v[166:169], v183 offset:32768
	ds_read_b128 v[170:173], v183 offset:33792
	ds_read_b128 v[186:189], v183 offset:34816
	ds_read_b128 v[190:193], v183 offset:35840
	ds_read_b128 v[194:197], v183 offset:36864
	ds_read_b128 v[198:201], v183 offset:37888
	ds_read_b128 v[202:205], v183 offset:38912
	ds_read_b128 v[206:209], v183 offset:39936
	s_mov_b32 s70, m0
	s_mov_b32 m0, s44
	s_nop 0
	global_load_lds_dwordx4 v1, s[34:35]
	s_mov_b32 m0, s70
	s_nop 0
	s_mov_b32 s70, m0
	s_mov_b32 m0, s48
	s_nop 0
	global_load_lds_dwordx4 v177, s[34:35]
	s_mov_b32 m0, s70
	s_add_u32 s34, s34, 0x4000
	s_addc_u32 s35, s35, 0
	s_mov_b32 s70, m0
	s_mov_b32 m0, s49
	s_nop 0
	global_load_lds_dwordx4 v1, s[34:35]
	s_mov_b32 m0, s70
	s_nop 0
	s_mov_b32 s70, m0
	s_mov_b32 m0, s50
	s_nop 0
	global_load_lds_dwordx4 v177, s[34:35]
	s_mov_b32 m0, s70
	s_waitcnt vmcnt(8)
	s_waitcnt lgkmcnt(0)
	s_barrier
	s_setprio 1
	s_waitcnt lgkmcnt(7)
	v_mfma_f32_16x16x32_bf16 v[126:129], v[130:133], v[166:169], v[126:129]
	v_mfma_f32_16x16x32_bf16 v[126:129], v[134:137], v[170:173], v[126:129]
	s_waitcnt lgkmcnt(5)
	v_mfma_f32_16x16x32_bf16 v[122:125], v[138:141], v[166:169], v[122:125]
	v_mfma_f32_16x16x32_bf16 v[122:125], v[142:145], v[170:173], v[122:125]
	s_waitcnt lgkmcnt(3)
	v_mfma_f32_16x16x32_bf16 v[110:113], v[138:141], v[186:189], v[110:113]
	v_mfma_f32_16x16x32_bf16 v[110:113], v[142:145], v[190:193], v[110:113]
	s_waitcnt lgkmcnt(1)
	v_mfma_f32_16x16x32_bf16 v[118:121], v[130:133], v[186:189], v[118:121]
	v_mfma_f32_16x16x32_bf16 v[118:121], v[134:137], v[190:193], v[118:121]
	v_mfma_f32_16x16x32_bf16 v[94:97], v[130:133], v[194:197], v[94:97]
	v_mfma_f32_16x16x32_bf16 v[94:97], v[134:137], v[198:201], v[94:97]
	v_mfma_f32_16x16x32_bf16 v[90:93], v[138:141], v[194:197], v[90:93]
	v_mfma_f32_16x16x32_bf16 v[90:93], v[142:145], v[198:201], v[90:93]
	v_mfma_f32_16x16x32_bf16 v[78:81], v[138:141], v[202:205], v[78:81]
	v_mfma_f32_16x16x32_bf16 v[78:81], v[142:145], v[206:209], v[78:81]
	s_waitcnt lgkmcnt(0)
	v_mfma_f32_16x16x32_bf16 v[86:89], v[130:133], v[202:205], v[86:89]
	v_mfma_f32_16x16x32_bf16 v[86:89], v[134:137], v[206:209], v[86:89]
	s_setprio 0
	s_setprio 1
	v_mfma_f32_16x16x32_bf16 v[114:117], v[150:153], v[166:169], v[114:117]
	v_mfma_f32_16x16x32_bf16 v[114:117], v[154:157], v[170:173], v[114:117]
	v_mfma_f32_16x16x32_bf16 v[106:109], v[158:161], v[166:169], v[106:109]
	v_mfma_f32_16x16x32_bf16 v[106:109], v[162:165], v[170:173], v[106:109]
	v_mfma_f32_16x16x32_bf16 v[98:101], v[158:161], v[186:189], v[98:101]
	v_mfma_f32_16x16x32_bf16 v[98:101], v[162:165], v[190:193], v[98:101]
	v_mfma_f32_16x16x32_bf16 v[102:105], v[150:153], v[186:189], v[102:105]
	v_mfma_f32_16x16x32_bf16 v[102:105], v[154:157], v[190:193], v[102:105]
	v_mfma_f32_16x16x32_bf16 v[82:85], v[150:153], v[194:197], v[82:85]
	v_mfma_f32_16x16x32_bf16 v[82:85], v[154:157], v[198:201], v[82:85]
	v_mfma_f32_16x16x32_bf16 v[74:77], v[158:161], v[194:197], v[74:77]
	v_mfma_f32_16x16x32_bf16 v[74:77], v[162:165], v[198:201], v[74:77]
	v_mfma_f32_16x16x32_bf16 v[66:69], v[158:161], v[202:205], v[66:69]
	v_mfma_f32_16x16x32_bf16 v[66:69], v[162:165], v[206:209], v[66:69]
	s_setprio 2
	s_barrier
	v_mfma_f32_16x16x32_bf16 v[70:73], v[150:153], v[202:205], v[70:73]
	v_mfma_f32_16x16x32_bf16 v[70:73], v[154:157], v[206:209], v[70:73]
	s_setprio 0
	ds_read_b128 v[166:169], v183 offset:49152
	ds_read_b128 v[170:173], v183 offset:50176
	ds_read_b128 v[186:189], v183 offset:51200
	ds_read_b128 v[190:193], v183 offset:52224
	ds_read_b128 v[194:197], v183 offset:53248
	ds_read_b128 v[198:201], v183 offset:54272
	ds_read_b128 v[202:205], v183 offset:55296
	ds_read_b128 v[206:209], v183 offset:56320
	s_add_u32 s34, s30, 0x40000
	s_addc_u32 s35, s31, 0
	s_mov_b32 s70, m0
	s_mov_b32 m0, s51
	s_nop 0
	global_load_lds_dwordx4 v176, s[34:35]
	s_mov_b32 m0, s70
	s_add_u32 s30, s30, 0x44000
	s_mov_b32 s70, m0
	s_mov_b32 m0, s52
	s_nop 0
	global_load_lds_dwordx4 v178, s[34:35]
	s_mov_b32 m0, s70
	s_addc_u32 s31, s31, 0
	s_mov_b32 s34, m0
	s_mov_b32 m0, s53
	s_nop 0
	global_load_lds_dwordx4 v176, s[30:31]
	s_mov_b32 m0, s34
	s_nop 0
	s_mov_b32 s34, m0
	s_mov_b32 m0, s54
	s_nop 0
	global_load_lds_dwordx4 v178, s[30:31]
	s_mov_b32 m0, s34
	s_waitcnt vmcnt(4)
	s_waitcnt lgkmcnt(0)
	s_barrier
	s_setprio 1
	s_waitcnt lgkmcnt(7)
	v_mfma_f32_16x16x32_bf16 v[62:65], v[130:133], v[166:169], v[62:65]
	v_mfma_f32_16x16x32_bf16 v[62:65], v[134:137], v[170:173], v[62:65]
	s_waitcnt lgkmcnt(5)
	v_mfma_f32_16x16x32_bf16 v[58:61], v[138:141], v[166:169], v[58:61]
	v_mfma_f32_16x16x32_bf16 v[58:61], v[142:145], v[170:173], v[58:61]
	s_waitcnt lgkmcnt(3)
	v_mfma_f32_16x16x32_bf16 v[42:45], v[138:141], v[186:189], v[42:45]
	v_mfma_f32_16x16x32_bf16 v[42:45], v[142:145], v[190:193], v[42:45]
	s_waitcnt lgkmcnt(1)
	v_mfma_f32_16x16x32_bf16 v[46:49], v[130:133], v[186:189], v[46:49]
	v_mfma_f32_16x16x32_bf16 v[46:49], v[134:137], v[190:193], v[46:49]
	v_mfma_f32_16x16x32_bf16 v[30:33], v[130:133], v[194:197], v[30:33]
	v_mfma_f32_16x16x32_bf16 v[30:33], v[134:137], v[198:201], v[30:33]
	v_mfma_f32_16x16x32_bf16 v[26:29], v[138:141], v[194:197], v[26:29]
	v_mfma_f32_16x16x32_bf16 v[26:29], v[142:145], v[198:201], v[26:29]
	v_mfma_f32_16x16x32_bf16 v[10:13], v[138:141], v[202:205], v[10:13]
	v_mfma_f32_16x16x32_bf16 v[10:13], v[142:145], v[206:209], v[10:13]
	s_waitcnt lgkmcnt(0)
	v_mfma_f32_16x16x32_bf16 v[14:17], v[130:133], v[202:205], v[14:17]
	v_mfma_f32_16x16x32_bf16 v[14:17], v[134:137], v[206:209], v[14:17]
	s_setprio 0
	s_setprio 1
	v_mfma_f32_16x16x32_bf16 v[54:57], v[150:153], v[166:169], v[54:57]
	v_mfma_f32_16x16x32_bf16 v[54:57], v[154:157], v[170:173], v[54:57]
	v_mfma_f32_16x16x32_bf16 v[50:53], v[158:161], v[166:169], v[50:53]
	v_mfma_f32_16x16x32_bf16 v[50:53], v[162:165], v[170:173], v[50:53]
	v_mfma_f32_16x16x32_bf16 v[34:37], v[158:161], v[186:189], v[34:37]
	v_mfma_f32_16x16x32_bf16 v[34:37], v[162:165], v[190:193], v[34:37]
	v_mfma_f32_16x16x32_bf16 v[38:41], v[150:153], v[186:189], v[38:41]
	v_mfma_f32_16x16x32_bf16 v[38:41], v[154:157], v[190:193], v[38:41]
	v_mfma_f32_16x16x32_bf16 v[22:25], v[150:153], v[194:197], v[22:25]
	v_mfma_f32_16x16x32_bf16 v[22:25], v[154:157], v[198:201], v[22:25]
	v_mfma_f32_16x16x32_bf16 v[18:21], v[158:161], v[194:197], v[18:21]
	v_mfma_f32_16x16x32_bf16 v[18:21], v[162:165], v[198:201], v[18:21]
	v_mfma_f32_16x16x32_bf16 v[2:5], v[158:161], v[202:205], v[2:5]
	v_mfma_f32_16x16x32_bf16 v[2:5], v[162:165], v[206:209], v[2:5]
	s_setprio 2
	s_barrier
	v_mfma_f32_16x16x32_bf16 v[6:9], v[150:153], v[202:205], v[6:9]
	v_mfma_f32_16x16x32_bf16 v[6:9], v[154:157], v[206:209], v[6:9]
	s_setprio 0
	s_add_i32 s69, s69, 2
	s_add_u32 s65, s65, 0x80000
	s_addc_u32 s66, s66, 0
	s_add_u32 s28, s28, 0x400000
	s_addc_u32 s29, s29, 0
	s_add_u32 s67, s67, 0x400000
	s_addc_u32 s68, s68, 0
	s_cmpk_gt_u32 s69, 0x53
	.p2align 6
.LBB0_2792:
	ds_read_b128 v[130:133], v181
	ds_read_b128 v[134:137], v181 offset:1024
	ds_read_b128 v[138:141], v181 offset:2048
	ds_read_b128 v[142:145], v181 offset:3072
	ds_read_b128 v[150:153], v182
	ds_read_b128 v[154:157], v182 offset:1024
	ds_read_b128 v[158:161], v182 offset:2048
	ds_read_b128 v[162:165], v182 offset:3072
	s_cmpk_eq_i32 s69, 0x52
	s_cselect_b32 s31, s19, s66
	s_cselect_b32 s30, s64, s65
	s_cselect_b32 s35, s21, s68
	s_cselect_b32 s34, s63, s67
	ds_read_b128 v[166:169], v183
	ds_read_b128 v[170:173], v183 offset:1024
	ds_read_b128 v[186:189], v183 offset:2048
	ds_read_b128 v[190:193], v183 offset:3072
	ds_read_b128 v[194:197], v183 offset:4096
	ds_read_b128 v[198:201], v183 offset:5120
	ds_read_b128 v[202:205], v183 offset:6144
	ds_read_b128 v[206:209], v183 offset:7168
	s_add_u32 s70, s28, 0xffffc000
	s_addc_u32 s71, s29, -1
	s_mov_b32 s73, m0
	s_mov_b32 m0, s57
	s_nop 0
	global_load_lds_dwordx4 v1, s[70:71]
	s_mov_b32 m0, s73
	s_nop 0
	s_mov_b32 s73, m0
	s_mov_b32 m0, s59
	s_nop 0
	global_load_lds_dwordx4 v177, s[70:71]
	s_mov_b32 m0, s73
	s_mov_b32 s70, m0
	s_mov_b32 m0, s58
	s_nop 0
	global_load_lds_dwordx4 v1, s[28:29]
	s_mov_b32 m0, s70
	s_nop 0
	s_mov_b32 s70, m0
	s_mov_b32 m0, s60
	s_nop 0
	global_load_lds_dwordx4 v177, s[28:29]
	s_mov_b32 m0, s70
	s_waitcnt vmcnt(8)
	s_waitcnt lgkmcnt(0)
	s_barrier
	s_setprio 1
	s_waitcnt lgkmcnt(7)
	v_mfma_f32_16x16x32_bf16 v[126:129], v[130:133], v[166:169], v[126:129]
	v_mfma_f32_16x16x32_bf16 v[126:129], v[134:137], v[170:173], v[126:129]
	s_waitcnt lgkmcnt(5)
	v_mfma_f32_16x16x32_bf16 v[122:125], v[138:141], v[166:169], v[122:125]
	v_mfma_f32_16x16x32_bf16 v[122:125], v[142:145], v[170:173], v[122:125]
	s_waitcnt lgkmcnt(3)
	v_mfma_f32_16x16x32_bf16 v[110:113], v[138:141], v[186:189], v[110:113]
	v_mfma_f32_16x16x32_bf16 v[110:113], v[142:145], v[190:193], v[110:113]
	s_waitcnt lgkmcnt(1)
	v_mfma_f32_16x16x32_bf16 v[118:121], v[130:133], v[186:189], v[118:121]
	v_mfma_f32_16x16x32_bf16 v[118:121], v[134:137], v[190:193], v[118:121]
	v_mfma_f32_16x16x32_bf16 v[94:97], v[130:133], v[194:197], v[94:97]
	v_mfma_f32_16x16x32_bf16 v[94:97], v[134:137], v[198:201], v[94:97]
	v_mfma_f32_16x16x32_bf16 v[90:93], v[138:141], v[194:197], v[90:93]
	v_mfma_f32_16x16x32_bf16 v[90:93], v[142:145], v[198:201], v[90:93]
	v_mfma_f32_16x16x32_bf16 v[78:81], v[138:141], v[202:205], v[78:81]
	v_mfma_f32_16x16x32_bf16 v[78:81], v[142:145], v[206:209], v[78:81]
	s_waitcnt lgkmcnt(0)
	v_mfma_f32_16x16x32_bf16 v[86:89], v[130:133], v[202:205], v[86:89]
	v_mfma_f32_16x16x32_bf16 v[86:89], v[134:137], v[206:209], v[86:89]
	s_setprio 0
	s_setprio 1
	v_mfma_f32_16x16x32_bf16 v[114:117], v[150:153], v[166:169], v[114:117]
	v_mfma_f32_16x16x32_bf16 v[114:117], v[154:157], v[170:173], v[114:117]
	v_mfma_f32_16x16x32_bf16 v[106:109], v[158:161], v[166:169], v[106:109]
	v_mfma_f32_16x16x32_bf16 v[106:109], v[162:165], v[170:173], v[106:109]
	v_mfma_f32_16x16x32_bf16 v[98:101], v[158:161], v[186:189], v[98:101]
	v_mfma_f32_16x16x32_bf16 v[98:101], v[162:165], v[190:193], v[98:101]
	v_mfma_f32_16x16x32_bf16 v[102:105], v[150:153], v[186:189], v[102:105]
	v_mfma_f32_16x16x32_bf16 v[102:105], v[154:157], v[190:193], v[102:105]
	v_mfma_f32_16x16x32_bf16 v[82:85], v[150:153], v[194:197], v[82:85]
	v_mfma_f32_16x16x32_bf16 v[82:85], v[154:157], v[198:201], v[82:85]
	v_mfma_f32_16x16x32_bf16 v[74:77], v[158:161], v[194:197], v[74:77]
	v_mfma_f32_16x16x32_bf16 v[74:77], v[162:165], v[198:201], v[74:77]
	v_mfma_f32_16x16x32_bf16 v[66:69], v[158:161], v[202:205], v[66:69]
	v_mfma_f32_16x16x32_bf16 v[66:69], v[162:165], v[206:209], v[66:69]
	s_setprio 2
	s_barrier
	v_mfma_f32_16x16x32_bf16 v[70:73], v[150:153], v[202:205], v[70:73]
	v_mfma_f32_16x16x32_bf16 v[70:73], v[154:157], v[206:209], v[70:73]
	s_setprio 0
	ds_read_b128 v[166:169], v183 offset:16384
	ds_read_b128 v[170:173], v183 offset:17408
	ds_read_b128 v[186:189], v183 offset:18432
	ds_read_b128 v[190:193], v183 offset:19456
	ds_read_b128 v[194:197], v183 offset:20480
	ds_read_b128 v[198:201], v183 offset:21504
	ds_read_b128 v[202:205], v183 offset:22528
	ds_read_b128 v[206:209], v183 offset:23552
	s_mov_b32 s70, m0
	s_mov_b32 m0, s27
	s_nop 0
	global_load_lds_dwordx4 v176, s[30:31]
	s_mov_b32 m0, s70
	s_nop 0
	s_mov_b32 s70, m0
	s_mov_b32 m0, s45
	s_nop 0
	global_load_lds_dwordx4 v178, s[30:31]
	s_mov_b32 m0, s70
	s_add_u32 s70, s30, 0x4000
	s_addc_u32 s71, s31, 0
	s_mov_b32 s73, m0
	s_mov_b32 m0, s46
	s_nop 0
	global_load_lds_dwordx4 v176, s[70:71]
	s_mov_b32 m0, s73
	s_nop 0
	s_mov_b32 s73, m0
	s_mov_b32 m0, s47
	s_nop 0
	global_load_lds_dwordx4 v178, s[70:71]
	s_mov_b32 m0, s73
	s_waitcnt vmcnt(4)
	s_waitcnt lgkmcnt(0)
	s_barrier
	s_setprio 1
	s_waitcnt lgkmcnt(7)
	v_mfma_f32_16x16x32_bf16 v[62:65], v[130:133], v[166:169], v[62:65]
	v_mfma_f32_16x16x32_bf16 v[62:65], v[134:137], v[170:173], v[62:65]
	s_waitcnt lgkmcnt(5)
	v_mfma_f32_16x16x32_bf16 v[58:61], v[138:141], v[166:169], v[58:61]
	v_mfma_f32_16x16x32_bf16 v[58:61], v[142:145], v[170:173], v[58:61]
	s_waitcnt lgkmcnt(3)
	v_mfma_f32_16x16x32_bf16 v[42:45], v[138:141], v[186:189], v[42:45]
	v_mfma_f32_16x16x32_bf16 v[42:45], v[142:145], v[190:193], v[42:45]
	s_waitcnt lgkmcnt(1)
	v_mfma_f32_16x16x32_bf16 v[46:49], v[130:133], v[186:189], v[46:49]
	v_mfma_f32_16x16x32_bf16 v[46:49], v[134:137], v[190:193], v[46:49]
	v_mfma_f32_16x16x32_bf16 v[30:33], v[130:133], v[194:197], v[30:33]
	v_mfma_f32_16x16x32_bf16 v[30:33], v[134:137], v[198:201], v[30:33]
	v_mfma_f32_16x16x32_bf16 v[26:29], v[138:141], v[194:197], v[26:29]
	v_mfma_f32_16x16x32_bf16 v[26:29], v[142:145], v[198:201], v[26:29]
	v_mfma_f32_16x16x32_bf16 v[10:13], v[138:141], v[202:205], v[10:13]
	v_mfma_f32_16x16x32_bf16 v[10:13], v[142:145], v[206:209], v[10:13]
	s_waitcnt lgkmcnt(0)
	v_mfma_f32_16x16x32_bf16 v[14:17], v[130:133], v[202:205], v[14:17]
	v_mfma_f32_16x16x32_bf16 v[14:17], v[134:137], v[206:209], v[14:17]
	s_setprio 0
	s_setprio 1
	v_mfma_f32_16x16x32_bf16 v[54:57], v[150:153], v[166:169], v[54:57]
	v_mfma_f32_16x16x32_bf16 v[54:57], v[154:157], v[170:173], v[54:57]
	v_mfma_f32_16x16x32_bf16 v[50:53], v[158:161], v[166:169], v[50:53]
	v_mfma_f32_16x16x32_bf16 v[50:53], v[162:165], v[170:173], v[50:53]
	v_mfma_f32_16x16x32_bf16 v[34:37], v[158:161], v[186:189], v[34:37]
	v_mfma_f32_16x16x32_bf16 v[34:37], v[162:165], v[190:193], v[34:37]
	v_mfma_f32_16x16x32_bf16 v[38:41], v[150:153], v[186:189], v[38:41]
	v_mfma_f32_16x16x32_bf16 v[38:41], v[154:157], v[190:193], v[38:41]
	v_mfma_f32_16x16x32_bf16 v[22:25], v[150:153], v[194:197], v[22:25]
	v_mfma_f32_16x16x32_bf16 v[22:25], v[154:157], v[198:201], v[22:25]
	v_mfma_f32_16x16x32_bf16 v[18:21], v[158:161], v[194:197], v[18:21]
	v_mfma_f32_16x16x32_bf16 v[18:21], v[162:165], v[198:201], v[18:21]
	v_mfma_f32_16x16x32_bf16 v[2:5], v[158:161], v[202:205], v[2:5]
	v_mfma_f32_16x16x32_bf16 v[2:5], v[162:165], v[206:209], v[2:5]
	s_setprio 2
	s_barrier
	v_mfma_f32_16x16x32_bf16 v[6:9], v[150:153], v[202:205], v[6:9]
	v_mfma_f32_16x16x32_bf16 v[6:9], v[154:157], v[206:209], v[6:9]
	s_setprio 0
	ds_read_b128 v[130:133], v184
	ds_read_b128 v[134:137], v184 offset:1024
	ds_read_b128 v[138:141], v184 offset:2048
	ds_read_b128 v[142:145], v184 offset:3072
	ds_read_b128 v[150:153], v185
	ds_read_b128 v[154:157], v185 offset:1024
	ds_read_b128 v[158:161], v185 offset:2048
	ds_read_b128 v[162:165], v185 offset:3072
	ds_read_b128 v[166:169], v183 offset:32768
	ds_read_b128 v[170:173], v183 offset:33792
	ds_read_b128 v[186:189], v183 offset:34816
	ds_read_b128 v[190:193], v183 offset:35840
	ds_read_b128 v[194:197], v183 offset:36864
	ds_read_b128 v[198:201], v183 offset:37888
	ds_read_b128 v[202:205], v183 offset:38912
	ds_read_b128 v[206:209], v183 offset:39936
	s_mov_b32 s70, m0
	s_mov_b32 m0, s44
	s_nop 0
	global_load_lds_dwordx4 v1, s[34:35]
	s_mov_b32 m0, s70
	s_nop 0
	s_mov_b32 s70, m0
	s_mov_b32 m0, s48
	s_nop 0
	global_load_lds_dwordx4 v177, s[34:35]
	s_mov_b32 m0, s70
	s_add_u32 s34, s34, 0x4000
	s_addc_u32 s35, s35, 0
	s_mov_b32 s70, m0
	s_mov_b32 m0, s49
	s_nop 0
	global_load_lds_dwordx4 v1, s[34:35]
	s_mov_b32 m0, s70
	s_nop 0
	s_mov_b32 s70, m0
	s_mov_b32 m0, s50
	s_nop 0
	global_load_lds_dwordx4 v177, s[34:35]
	s_mov_b32 m0, s70
	s_waitcnt vmcnt(8)
	s_waitcnt lgkmcnt(0)
	s_barrier
	s_setprio 1
	s_waitcnt lgkmcnt(7)
	v_mfma_f32_16x16x32_bf16 v[126:129], v[130:133], v[166:169], v[126:129]
	v_mfma_f32_16x16x32_bf16 v[126:129], v[134:137], v[170:173], v[126:129]
	s_waitcnt lgkmcnt(5)
	v_mfma_f32_16x16x32_bf16 v[122:125], v[138:141], v[166:169], v[122:125]
	v_mfma_f32_16x16x32_bf16 v[122:125], v[142:145], v[170:173], v[122:125]
	s_waitcnt lgkmcnt(3)
	v_mfma_f32_16x16x32_bf16 v[110:113], v[138:141], v[186:189], v[110:113]
	v_mfma_f32_16x16x32_bf16 v[110:113], v[142:145], v[190:193], v[110:113]
	s_waitcnt lgkmcnt(1)
	v_mfma_f32_16x16x32_bf16 v[118:121], v[130:133], v[186:189], v[118:121]
	v_mfma_f32_16x16x32_bf16 v[118:121], v[134:137], v[190:193], v[118:121]
	v_mfma_f32_16x16x32_bf16 v[94:97], v[130:133], v[194:197], v[94:97]
	v_mfma_f32_16x16x32_bf16 v[94:97], v[134:137], v[198:201], v[94:97]
	v_mfma_f32_16x16x32_bf16 v[90:93], v[138:141], v[194:197], v[90:93]
	v_mfma_f32_16x16x32_bf16 v[90:93], v[142:145], v[198:201], v[90:93]
	v_mfma_f32_16x16x32_bf16 v[78:81], v[138:141], v[202:205], v[78:81]
	v_mfma_f32_16x16x32_bf16 v[78:81], v[142:145], v[206:209], v[78:81]
	s_waitcnt lgkmcnt(0)
	v_mfma_f32_16x16x32_bf16 v[86:89], v[130:133], v[202:205], v[86:89]
	v_mfma_f32_16x16x32_bf16 v[86:89], v[134:137], v[206:209], v[86:89]
	s_setprio 0
	s_setprio 1
	v_mfma_f32_16x16x32_bf16 v[114:117], v[150:153], v[166:169], v[114:117]
	v_mfma_f32_16x16x32_bf16 v[114:117], v[154:157], v[170:173], v[114:117]
	v_mfma_f32_16x16x32_bf16 v[106:109], v[158:161], v[166:169], v[106:109]
	v_mfma_f32_16x16x32_bf16 v[106:109], v[162:165], v[170:173], v[106:109]
	v_mfma_f32_16x16x32_bf16 v[98:101], v[158:161], v[186:189], v[98:101]
	v_mfma_f32_16x16x32_bf16 v[98:101], v[162:165], v[190:193], v[98:101]
	v_mfma_f32_16x16x32_bf16 v[102:105], v[150:153], v[186:189], v[102:105]
	v_mfma_f32_16x16x32_bf16 v[102:105], v[154:157], v[190:193], v[102:105]
	v_mfma_f32_16x16x32_bf16 v[82:85], v[150:153], v[194:197], v[82:85]
	v_mfma_f32_16x16x32_bf16 v[82:85], v[154:157], v[198:201], v[82:85]
	v_mfma_f32_16x16x32_bf16 v[74:77], v[158:161], v[194:197], v[74:77]
	v_mfma_f32_16x16x32_bf16 v[74:77], v[162:165], v[198:201], v[74:77]
	v_mfma_f32_16x16x32_bf16 v[66:69], v[158:161], v[202:205], v[66:69]
	v_mfma_f32_16x16x32_bf16 v[66:69], v[162:165], v[206:209], v[66:69]
	s_setprio 2
	s_barrier
	v_mfma_f32_16x16x32_bf16 v[70:73], v[150:153], v[202:205], v[70:73]
	v_mfma_f32_16x16x32_bf16 v[70:73], v[154:157], v[206:209], v[70:73]
	s_setprio 0
	ds_read_b128 v[166:169], v183 offset:49152
	ds_read_b128 v[170:173], v183 offset:50176
	ds_read_b128 v[186:189], v183 offset:51200
	ds_read_b128 v[190:193], v183 offset:52224
	ds_read_b128 v[194:197], v183 offset:53248
	ds_read_b128 v[198:201], v183 offset:54272
	ds_read_b128 v[202:205], v183 offset:55296
	ds_read_b128 v[206:209], v183 offset:56320
	s_add_u32 s34, s30, 0x40000
	s_addc_u32 s35, s31, 0
	s_mov_b32 s70, m0
	s_mov_b32 m0, s51
	s_nop 0
	global_load_lds_dwordx4 v176, s[34:35]
	s_mov_b32 m0, s70
	s_add_u32 s30, s30, 0x44000
	s_mov_b32 s70, m0
	s_mov_b32 m0, s52
	s_nop 0
	global_load_lds_dwordx4 v178, s[34:35]
	s_mov_b32 m0, s70
	s_addc_u32 s31, s31, 0
	s_mov_b32 s34, m0
	s_mov_b32 m0, s53
	s_nop 0
	global_load_lds_dwordx4 v176, s[30:31]
	s_mov_b32 m0, s34
	s_nop 0
	s_mov_b32 s34, m0
	s_mov_b32 m0, s54
	s_nop 0
	global_load_lds_dwordx4 v178, s[30:31]
	s_mov_b32 m0, s34
	s_waitcnt vmcnt(4)
	s_waitcnt lgkmcnt(0)
	s_barrier
	s_setprio 1
	s_waitcnt lgkmcnt(7)
	v_mfma_f32_16x16x32_bf16 v[62:65], v[130:133], v[166:169], v[62:65]
	v_mfma_f32_16x16x32_bf16 v[62:65], v[134:137], v[170:173], v[62:65]
	s_waitcnt lgkmcnt(5)
	v_mfma_f32_16x16x32_bf16 v[58:61], v[138:141], v[166:169], v[58:61]
	v_mfma_f32_16x16x32_bf16 v[58:61], v[142:145], v[170:173], v[58:61]
	s_waitcnt lgkmcnt(3)
	v_mfma_f32_16x16x32_bf16 v[42:45], v[138:141], v[186:189], v[42:45]
	v_mfma_f32_16x16x32_bf16 v[42:45], v[142:145], v[190:193], v[42:45]
	s_waitcnt lgkmcnt(1)
	v_mfma_f32_16x16x32_bf16 v[46:49], v[130:133], v[186:189], v[46:49]
	v_mfma_f32_16x16x32_bf16 v[46:49], v[134:137], v[190:193], v[46:49]
	v_mfma_f32_16x16x32_bf16 v[30:33], v[130:133], v[194:197], v[30:33]
	v_mfma_f32_16x16x32_bf16 v[30:33], v[134:137], v[198:201], v[30:33]
	v_mfma_f32_16x16x32_bf16 v[26:29], v[138:141], v[194:197], v[26:29]
	v_mfma_f32_16x16x32_bf16 v[26:29], v[142:145], v[198:201], v[26:29]
	v_mfma_f32_16x16x32_bf16 v[10:13], v[138:141], v[202:205], v[10:13]
	v_mfma_f32_16x16x32_bf16 v[10:13], v[142:145], v[206:209], v[10:13]
	s_waitcnt lgkmcnt(0)
	v_mfma_f32_16x16x32_bf16 v[14:17], v[130:133], v[202:205], v[14:17]
	v_mfma_f32_16x16x32_bf16 v[14:17], v[134:137], v[206:209], v[14:17]
	s_setprio 0
	s_setprio 1
	v_mfma_f32_16x16x32_bf16 v[54:57], v[150:153], v[166:169], v[54:57]
	v_mfma_f32_16x16x32_bf16 v[54:57], v[154:157], v[170:173], v[54:57]
	v_mfma_f32_16x16x32_bf16 v[50:53], v[158:161], v[166:169], v[50:53]
	v_mfma_f32_16x16x32_bf16 v[50:53], v[162:165], v[170:173], v[50:53]
	v_mfma_f32_16x16x32_bf16 v[34:37], v[158:161], v[186:189], v[34:37]
	v_mfma_f32_16x16x32_bf16 v[34:37], v[162:165], v[190:193], v[34:37]
	v_mfma_f32_16x16x32_bf16 v[38:41], v[150:153], v[186:189], v[38:41]
	v_mfma_f32_16x16x32_bf16 v[38:41], v[154:157], v[190:193], v[38:41]
	v_mfma_f32_16x16x32_bf16 v[22:25], v[150:153], v[194:197], v[22:25]
	v_mfma_f32_16x16x32_bf16 v[22:25], v[154:157], v[198:201], v[22:25]
	v_mfma_f32_16x16x32_bf16 v[18:21], v[158:161], v[194:197], v[18:21]
	v_mfma_f32_16x16x32_bf16 v[18:21], v[162:165], v[198:201], v[18:21]
	v_mfma_f32_16x16x32_bf16 v[2:5], v[158:161], v[202:205], v[2:5]
	v_mfma_f32_16x16x32_bf16 v[2:5], v[162:165], v[206:209], v[2:5]
	s_setprio 2
	s_barrier
	v_mfma_f32_16x16x32_bf16 v[6:9], v[150:153], v[202:205], v[6:9]
	v_mfma_f32_16x16x32_bf16 v[6:9], v[154:157], v[206:209], v[6:9]
	s_setprio 0
	s_add_i32 s69, s69, 2
	s_add_u32 s65, s65, 0x80000
	s_addc_u32 s66, s66, 0
	s_add_u32 s28, s28, 0x400000
	s_addc_u32 s29, s29, 0
	s_add_u32 s67, s67, 0x400000
	s_addc_u32 s68, s68, 0
	s_cmpk_gt_u32 s69, 0x53
	s_cbranch_scc0 .LBB0_2792
	s_and_b64 vcc, exec, s[8:9]
	s_cbranch_vccz .LBB0_2795
	s_barrier
